# v15 + every global store write-through (sc1) incl. weight conversion, conv, qk_prep, SSQ partials; attention epilogue 16-byte stores via LDS transpose
# baseline (speedup 1.0000x reference)
.LBB0_17:
	s_mul_i32 s9, s14, 0x2100000
	s_waitcnt vmcnt(30)
	ds_write2_b32 v46, v6, v7 offset1:66
	s_waitcnt vmcnt(28)
	ds_write2_b32 v46, v10, v11 offset0:132 offset1:198
	v_add_u32_e32 v6, 0x400, v46
	s_mul_hi_i32 s7, s14, 0x2100000
	s_add_u32 s9, s22, s9
	s_sext_i32_i16 s14, s55
	s_waitcnt vmcnt(26)
	ds_write2_b32 v6, v8, v9 offset0:8 offset1:74
	s_waitcnt vmcnt(24)
	ds_write2_b32 v6, v12, v13 offset0:140 offset1:206
	v_add_u32_e32 v6, 0x800, v46
	s_addc_u32 s7, s23, s7
	s_mul_hi_i32 s15, s14, 0x1080000
	s_mul_i32 s14, s14, 0x1080000
	s_waitcnt vmcnt(22)
	ds_write2_b32 v6, v14, v15 offset0:16 offset1:82
	s_waitcnt vmcnt(20)
	ds_write2_b32 v6, v18, v19 offset0:148 offset1:214
	v_add_u32_e32 v6, 0xc00, v46
	s_add_u32 s9, s9, s14
	s_waitcnt vmcnt(18)
	ds_write2_b32 v6, v16, v17 offset0:24 offset1:90
	s_waitcnt vmcnt(16)
	ds_write2_b32 v6, v20, v21 offset0:156 offset1:222
	v_add_u32_e32 v6, 0x1000, v46
	s_addc_u32 s7, s7, s15
	s_bfe_i32 s14, s2, 0x80000
	s_waitcnt vmcnt(14)
	ds_write2_b32 v6, v22, v23 offset0:32 offset1:98
	s_waitcnt vmcnt(12)
	ds_write2_b32 v6, v26, v27 offset0:164 offset1:230
	v_add_u32_e32 v6, 0x1400, v46
	s_bfe_u32 s14, s14, 0x2000d
	s_waitcnt vmcnt(10)
	ds_write2_b32 v6, v24, v25 offset0:40 offset1:106
	s_waitcnt vmcnt(8)
	ds_write2_b32 v6, v28, v29 offset0:172 offset1:238
	v_add_u32_e32 v6, 0x1800, v46
	s_add_i32 s2, s2, s14
	s_waitcnt vmcnt(6)
	ds_write2_b32 v6, v30, v31 offset0:48 offset1:114
	s_waitcnt vmcnt(4)
	ds_write2_b32 v6, v36, v37 offset0:180 offset1:246
	v_add_u32_e32 v6, 0x1c00, v46
	s_waitcnt vmcnt(2)
	ds_write2_b32 v6, v34, v35 offset0:56 offset1:122
	s_waitcnt vmcnt(0)
	ds_write2_b32 v6, v32, v33 offset0:188 offset1:254
	s_bfe_i32 s2, s2, 0x80000
	s_bfe_u32 s14, s6, 0x70018
	s_waitcnt lgkmcnt(0)
	s_sext_i32_i16 s2, s2
	s_add_i32 s14, s6, s14
	ds_read2_b32 v[6:7], v48 offset1:33
	s_lshl_b32 s2, s2, 6
	s_and_b32 s14, s14, 0xff80
	s_and_b32 s2, s2, 0xffffff00
	s_waitcnt lgkmcnt(0)
	v_cvt_pk_bf16_f32 v6, v6, v7
	ds_read2_b32 v[8:9], v48 offset0:66 offset1:99
	s_sub_i32 s6, s6, s14
	s_lshl_b32 s14, s54, 7
	s_waitcnt lgkmcnt(0)
	v_cvt_pk_bf16_f32 v7, v8, v9
	ds_read2_b32 v[8:9], v48 offset0:132 offset1:165
	s_sext_i32_i16 s6, s6
	s_add_i32 s2, s2, s14
	s_add_i32 s2, s2, s6
	s_waitcnt lgkmcnt(0)
	v_cvt_pk_bf16_f32 v8, v8, v9
	ds_read2_b32 v[10:11], v48 offset0:198 offset1:231
	s_lshl_b64 s[4:5], s[4:5], 1
	s_add_u32 s4, s9, s4
	s_waitcnt lgkmcnt(0)
	v_cvt_pk_bf16_f32 v9, v10, v11
	v_or_b32_e32 v10, s2, v47
	s_addc_u32 s5, s7, s5
	v_ashrrev_i32_e32 v11, 31, v10
	v_lshl_add_u64 v[12:13], s[4:5], 0, v[2:3]
	v_lshlrev_b64 v[10:11], 11, v[10:11]
	v_lshl_add_u64 v[10:11], v[12:13], 0, v[10:11]
	ds_read2_b32 v[14:15], v48 offset0:8 offset1:41
	global_store_dwordx4 v[10:11], v[6:9], off sc1
	s_add_i32 s53, s53, s10
	s_cmpk_lt_i32 s53, 0xb00
	s_waitcnt lgkmcnt(0)
	v_cvt_pk_bf16_f32 v6, v14, v15
	ds_read2_b32 v[8:9], v48 offset0:74 offset1:107
	s_waitcnt lgkmcnt(0)
	v_cvt_pk_bf16_f32 v7, v8, v9
	ds_read2_b32 v[8:9], v48 offset0:140 offset1:173
	s_waitcnt lgkmcnt(0)
	v_cvt_pk_bf16_f32 v8, v8, v9
	ds_read2_b32 v[10:11], v48 offset0:206 offset1:239
	s_waitcnt lgkmcnt(0)
	v_cvt_pk_bf16_f32 v9, v10, v11
	v_or_b32_e32 v10, s2, v49
	v_ashrrev_i32_e32 v11, 31, v10
	v_lshlrev_b64 v[10:11], 11, v[10:11]
	v_lshl_add_u64 v[10:11], v[12:13], 0, v[10:11]
	ds_read2_b32 v[14:15], v48 offset0:16 offset1:49
	global_store_dwordx4 v[10:11], v[6:9], off sc1
	s_waitcnt lgkmcnt(0)
	s_nop 0
	v_cvt_pk_bf16_f32 v6, v14, v15
	ds_read2_b32 v[8:9], v48 offset0:82 offset1:115
	s_waitcnt lgkmcnt(0)
	v_cvt_pk_bf16_f32 v7, v8, v9
	ds_read2_b32 v[8:9], v48 offset0:148 offset1:181
	s_waitcnt lgkmcnt(0)
	v_cvt_pk_bf16_f32 v8, v8, v9
	ds_read2_b32 v[10:11], v48 offset0:214 offset1:247
	s_waitcnt lgkmcnt(0)
	v_cvt_pk_bf16_f32 v9, v10, v11
	v_or_b32_e32 v10, s2, v50
	v_ashrrev_i32_e32 v11, 31, v10
	v_lshlrev_b64 v[10:11], 11, v[10:11]
	v_lshl_add_u64 v[10:11], v[12:13], 0, v[10:11]
	ds_read2_b32 v[14:15], v48 offset0:24 offset1:57
	global_store_dwordx4 v[10:11], v[6:9], off sc1
	s_waitcnt lgkmcnt(0)
	s_nop 0
	v_cvt_pk_bf16_f32 v6, v14, v15
	ds_read2_b32 v[8:9], v48 offset0:90 offset1:123
	s_waitcnt lgkmcnt(0)
	v_cvt_pk_bf16_f32 v7, v8, v9
	ds_read2_b32 v[8:9], v48 offset0:156 offset1:189
	s_waitcnt lgkmcnt(0)
	v_cvt_pk_bf16_f32 v8, v8, v9
	ds_read2_b32 v[10:11], v48 offset0:222 offset1:255
	s_waitcnt lgkmcnt(0)
	v_cvt_pk_bf16_f32 v9, v10, v11
	v_or_b32_e32 v10, s2, v51
	v_ashrrev_i32_e32 v11, 31, v10
	v_lshlrev_b64 v[10:11], 11, v[10:11]
	v_lshl_add_u64 v[10:11], v[12:13], 0, v[10:11]
	global_store_dwordx4 v[10:11], v[6:9], off sc1
	s_waitcnt lgkmcnt(0)
	s_cbranch_scc0 .LBB0_20

.LBB0_22:
	s_bfe_i32 s4, s14, 0x80000
	s_bfe_u32 s4, s4, 0x2000d
	s_add_i32 s14, s14, s4
	s_bfe_i32 s4, s14, 0x80000
	s_waitcnt vmcnt(30)
	ds_write2_b32 v46, v12, v13 offset1:66
	s_waitcnt vmcnt(28)
	ds_write2_b32 v46, v14, v15 offset0:132 offset1:198
	s_waitcnt vmcnt(26)
	ds_write2_b32 v52, v16, v17 offset0:8 offset1:74
	s_waitcnt vmcnt(24)
	ds_write2_b32 v52, v18, v19 offset0:140 offset1:206
	s_waitcnt vmcnt(22)
	ds_write2_b32 v53, v20, v21 offset0:16 offset1:82
	s_waitcnt vmcnt(20)
	ds_write2_b32 v53, v22, v23 offset0:148 offset1:214
	s_waitcnt vmcnt(18)
	ds_write2_b32 v54, v24, v25 offset0:24 offset1:90
	s_waitcnt vmcnt(16)
	ds_write2_b32 v54, v26, v27 offset0:156 offset1:222
	s_waitcnt vmcnt(14)
	ds_write2_b32 v55, v28, v29 offset0:32 offset1:98
	s_waitcnt vmcnt(12)
	ds_write2_b32 v55, v30, v31 offset0:164 offset1:230
	s_waitcnt vmcnt(10)
	ds_write2_b32 v56, v32, v33 offset0:40 offset1:106
	s_waitcnt vmcnt(8)
	ds_write2_b32 v56, v34, v35 offset0:172 offset1:238
	s_waitcnt vmcnt(6)
	ds_write2_b32 v57, v36, v37 offset0:48 offset1:114
	s_waitcnt vmcnt(4)
	ds_write2_b32 v57, v38, v39 offset0:180 offset1:246
	s_waitcnt vmcnt(2)
	ds_write2_b32 v58, v42, v43 offset0:56 offset1:122
	s_waitcnt vmcnt(0)
	ds_write2_b32 v58, v40, v41 offset0:188 offset1:254
	s_bfe_u32 s5, s16, 0x70018
	s_waitcnt lgkmcnt(0)
	s_sext_i32_i16 s4, s4
	s_add_i32 s5, s16, s5
	ds_read2_b32 v[12:13], v48 offset1:33
	s_lshl_b32 s4, s4, 6
	s_and_b32 s5, s5, 0xff80
	s_and_b32 s4, s4, 0xffffff00
	s_waitcnt lgkmcnt(0)
	v_cvt_pk_bf16_f32 v12, v12, v13
	ds_read2_b32 v[14:15], v48 offset0:66 offset1:99
	s_sub_i32 s5, s16, s5
	s_lshl_b32 s9, s95, 7
	s_sext_i32_i16 s5, s5
	s_waitcnt lgkmcnt(0)
	v_cvt_pk_bf16_f32 v13, v14, v15
	ds_read2_b32 v[14:15], v48 offset0:132 offset1:165
	s_add_i32 s4, s4, s9
	s_add_i32 s9, s4, s5
	s_lshl_b64 s[4:5], s[6:7], 1
	s_waitcnt lgkmcnt(0)
	v_cvt_pk_bf16_f32 v14, v14, v15
	ds_read2_b32 v[16:17], v48 offset0:198 offset1:231
	s_add_u32 s4, s93, s4
	s_waitcnt lgkmcnt(0)
	v_cvt_pk_bf16_f32 v15, v16, v17
	v_or_b32_e32 v16, s9, v47
	s_addc_u32 s5, s94, s5
	v_mov_b32_e32 v3, v5
	v_ashrrev_i32_e32 v17, 31, v16
	v_lshl_add_u64 v[18:19], s[4:5], 0, v[2:3]
	v_lshlrev_b64 v[16:17], 11, v[16:17]
	v_lshl_add_u64 v[16:17], v[18:19], 0, v[16:17]
	ds_read2_b32 v[20:21], v48 offset0:8 offset1:41
	global_store_dwordx4 v[16:17], v[12:15], off sc1
	s_waitcnt lgkmcnt(0)
	s_nop 0
	v_cvt_pk_bf16_f32 v12, v20, v21
	ds_read2_b32 v[14:15], v48 offset0:74 offset1:107
	s_waitcnt lgkmcnt(0)
	v_cvt_pk_bf16_f32 v13, v14, v15
	ds_read2_b32 v[14:15], v48 offset0:140 offset1:173
	s_waitcnt lgkmcnt(0)
	v_cvt_pk_bf16_f32 v14, v14, v15
	ds_read2_b32 v[16:17], v48 offset0:206 offset1:239
	s_waitcnt lgkmcnt(0)
	v_cvt_pk_bf16_f32 v15, v16, v17
	v_or_b32_e32 v16, s9, v49
	v_ashrrev_i32_e32 v17, 31, v16
	v_lshlrev_b64 v[16:17], 11, v[16:17]
	v_lshl_add_u64 v[16:17], v[18:19], 0, v[16:17]
	ds_read2_b32 v[20:21], v48 offset0:16 offset1:49
	global_store_dwordx4 v[16:17], v[12:15], off sc1
	s_waitcnt lgkmcnt(0)
	s_nop 0
	v_cvt_pk_bf16_f32 v12, v20, v21
	ds_read2_b32 v[14:15], v48 offset0:82 offset1:115
	s_waitcnt lgkmcnt(0)
	v_cvt_pk_bf16_f32 v13, v14, v15
	ds_read2_b32 v[14:15], v48 offset0:148 offset1:181
	s_waitcnt lgkmcnt(0)
	v_cvt_pk_bf16_f32 v14, v14, v15
	ds_read2_b32 v[16:17], v48 offset0:214 offset1:247
	s_waitcnt lgkmcnt(0)
	v_cvt_pk_bf16_f32 v15, v16, v17
	v_or_b32_e32 v16, s9, v50
	v_ashrrev_i32_e32 v17, 31, v16
	v_lshlrev_b64 v[16:17], 11, v[16:17]
	v_lshl_add_u64 v[16:17], v[18:19], 0, v[16:17]
	ds_read2_b32 v[20:21], v48 offset0:24 offset1:57
	global_store_dwordx4 v[16:17], v[12:15], off sc1
	s_waitcnt lgkmcnt(0)
	s_nop 0
	v_cvt_pk_bf16_f32 v12, v20, v21
	ds_read2_b32 v[14:15], v48 offset0:90 offset1:123
	s_waitcnt lgkmcnt(0)
	v_cvt_pk_bf16_f32 v13, v14, v15
	ds_read2_b32 v[14:15], v48 offset0:156 offset1:189
	s_waitcnt lgkmcnt(0)
	v_cvt_pk_bf16_f32 v14, v14, v15
	ds_read2_b32 v[16:17], v48 offset0:222 offset1:255
	s_waitcnt lgkmcnt(0)
	v_cvt_pk_bf16_f32 v15, v16, v17
	v_or_b32_e32 v16, s9, v51
	v_ashrrev_i32_e32 v17, 31, v16
	v_lshlrev_b64 v[16:17], 11, v[16:17]
	v_lshl_add_u64 v[16:17], v[18:19], 0, v[16:17]
	global_store_dwordx4 v[16:17], v[12:15], off sc1
	s_waitcnt lgkmcnt(0)

.LBB0_24:
	s_cmp_gt_i32 s22, 0x83ff
	s_mov_b64 s[4:5], -1
	s_cbranch_scc0 .LBB0_44
	s_add_i32 s16, s22, 0xffff7c00
	s_cmpk_gt_u32 s16, 0x24f
	s_cbranch_scc0 .LBB0_39
	s_cmpk_gt_u32 s16, 0x2df
	s_cbranch_scc0 .LBB0_34
	s_cmpk_gt_u32 s16, 0x35f
	s_cbranch_scc0 .LBB0_29
	s_load_dwordx2 s[18:19], s[12:13], 0x98
	s_and_b32 s4, s25, 0xfc0
	s_addk_i32 s4, 0xfb40
	v_or_b32_e32 v12, s4, v45
	v_mov_b32_e32 v13, v5
	s_and_b32 s6, s27, 0x3e0
	v_lshlrev_b64 v[12:13], 12, v[12:13]
	s_waitcnt lgkmcnt(0)
	v_lshl_add_u64 v[12:13], s[18:19], 0, v[12:13]
	s_lshl_b32 s14, s6, 2
	v_lshl_add_u64 v[12:13], v[12:13], 0, s[14:15]
	v_lshl_add_u64 v[12:13], v[12:13], 0, v[4:5]
	v_add_co_u32_e32 v14, vcc, s31, v12
	s_mov_b32 s5, s15
	s_nop 0
	v_addc_co_u32_e32 v15, vcc, 0, v13, vcc
	v_add_co_u32_e32 v16, vcc, s34, v12
	s_nop 1
	v_addc_co_u32_e32 v17, vcc, 0, v13, vcc
	v_add_co_u32_e32 v18, vcc, s35, v12
	s_nop 1
	v_addc_co_u32_e32 v19, vcc, 0, v13, vcc
	v_add_co_u32_e32 v20, vcc, s36, v12
	s_nop 1
	v_addc_co_u32_e32 v21, vcc, 0, v13, vcc
	v_add_co_u32_e32 v22, vcc, s37, v12
	s_nop 1
	v_addc_co_u32_e32 v23, vcc, 0, v13, vcc
	v_add_co_u32_e32 v24, vcc, s38, v12
	s_nop 1
	v_addc_co_u32_e32 v25, vcc, 0, v13, vcc
	v_add_co_u32_e32 v26, vcc, s39, v12
	s_nop 1
	v_addc_co_u32_e32 v27, vcc, 0, v13, vcc
	global_load_dword v3, v[12:13], off
	global_load_dword v30, v[14:15], off
	global_load_dword v31, v[16:17], off
	global_load_dword v32, v[18:19], off
	global_load_dword v33, v[20:21], off
	global_load_dword v34, v[22:23], off
	global_load_dword v35, v[24:25], off
	global_load_dword v36, v[26:27], off
	v_add_co_u32_e32 v14, vcc, s40, v12
	s_nop 1
	v_addc_co_u32_e32 v15, vcc, 0, v13, vcc
	v_add_co_u32_e32 v16, vcc, s41, v12
	s_nop 1
	v_addc_co_u32_e32 v17, vcc, 0, v13, vcc
	v_add_co_u32_e32 v18, vcc, s42, v12
	s_nop 1
	v_addc_co_u32_e32 v19, vcc, 0, v13, vcc
	v_add_co_u32_e32 v20, vcc, s43, v12
	s_nop 1
	v_addc_co_u32_e32 v21, vcc, 0, v13, vcc
	v_add_co_u32_e32 v22, vcc, s44, v12
	s_nop 1
	v_addc_co_u32_e32 v23, vcc, 0, v13, vcc
	v_add_co_u32_e32 v24, vcc, s45, v12
	s_nop 1
	v_addc_co_u32_e32 v25, vcc, 0, v13, vcc
	v_add_co_u32_e32 v26, vcc, s46, v12
	s_nop 1
	v_addc_co_u32_e32 v27, vcc, 0, v13, vcc
	v_add_co_u32_e32 v28, vcc, s47, v12
	s_nop 1
	v_addc_co_u32_e32 v29, vcc, 0, v13, vcc
	global_load_dword v37, v[14:15], off
	global_load_dword v38, v[16:17], off
	global_load_dword v39, v[18:19], off
	global_load_dword v40, v[20:21], off
	global_load_dword v41, v[22:23], off
	global_load_dword v42, v[24:25], off
	global_load_dword v43, v[26:27], off
	global_load_dword v59, v[28:29], off
	v_add_co_u32_e32 v14, vcc, s48, v12
	s_nop 1
	v_addc_co_u32_e32 v15, vcc, 0, v13, vcc
	v_add_co_u32_e32 v16, vcc, s49, v12
	s_nop 1
	v_addc_co_u32_e32 v17, vcc, 0, v13, vcc
	v_add_co_u32_e32 v18, vcc, s50, v12
	s_nop 1
	v_addc_co_u32_e32 v19, vcc, 0, v13, vcc
	v_add_co_u32_e32 v20, vcc, s51, v12
	s_nop 1
	v_addc_co_u32_e32 v21, vcc, 0, v13, vcc
	v_add_co_u32_e32 v22, vcc, s52, v12
	s_nop 1
	v_addc_co_u32_e32 v23, vcc, 0, v13, vcc
	v_add_co_u32_e32 v24, vcc, s53, v12
	s_nop 1
	v_addc_co_u32_e32 v25, vcc, 0, v13, vcc
	v_add_co_u32_e32 v26, vcc, s54, v12
	s_nop 1
	v_addc_co_u32_e32 v27, vcc, 0, v13, vcc
	v_add_co_u32_e32 v28, vcc, s55, v12
	s_nop 1
	v_addc_co_u32_e32 v29, vcc, 0, v13, vcc
	global_load_dword v60, v[14:15], off
	global_load_dword v61, v[16:17], off
	global_load_dword v62, v[18:19], off
	global_load_dword v63, v[20:21], off
	global_load_dword v64, v[22:23], off
	global_load_dword v65, v[24:25], off
	global_load_dword v66, v[26:27], off
	s_nop 0
	global_load_dword v28, v[28:29], off
	v_add_co_u32_e32 v14, vcc, s56, v12
	s_nop 1
	v_addc_co_u32_e32 v15, vcc, 0, v13, vcc
	v_add_co_u32_e32 v16, vcc, s57, v12
	s_nop 1
	v_addc_co_u32_e32 v17, vcc, 0, v13, vcc
	v_add_co_u32_e32 v18, vcc, s58, v12
	s_nop 1
	v_addc_co_u32_e32 v19, vcc, 0, v13, vcc
	v_add_co_u32_e32 v20, vcc, s59, v12
	s_nop 1
	v_addc_co_u32_e32 v21, vcc, 0, v13, vcc
	v_add_co_u32_e32 v22, vcc, s60, v12
	s_nop 1
	v_addc_co_u32_e32 v23, vcc, 0, v13, vcc
	v_add_co_u32_e32 v24, vcc, s61, v12
	s_nop 1
	v_addc_co_u32_e32 v25, vcc, 0, v13, vcc
	v_add_co_u32_e32 v26, vcc, s62, v12
	s_nop 1
	v_addc_co_u32_e32 v27, vcc, 0, v13, vcc
	v_add_co_u32_e32 v12, vcc, s63, v12
	s_nop 1
	v_addc_co_u32_e32 v13, vcc, 0, v13, vcc
	global_load_dword v14, v[14:15], off
	s_nop 0
	global_load_dword v15, v[16:17], off
	s_nop 0
	global_load_dword v16, v[18:19], off
	global_load_dword v17, v[20:21], off
	s_nop 0
	global_load_dword v18, v[22:23], off
	global_load_dword v19, v[24:25], off
	global_load_dword v20, v[26:27], off
	s_nop 0
	global_load_dword v12, v[12:13], off
	s_waitcnt vmcnt(30)
	ds_write2_b32 v46, v3, v30 offset1:66
	s_waitcnt vmcnt(28)
	ds_write2_b32 v46, v31, v32 offset0:132 offset1:198
	s_waitcnt vmcnt(26)
	ds_write2_b32 v52, v33, v34 offset0:8 offset1:74
	s_waitcnt vmcnt(24)
	ds_write2_b32 v52, v35, v36 offset0:140 offset1:206
	s_waitcnt vmcnt(22)
	ds_write2_b32 v53, v37, v38 offset0:16 offset1:82
	s_waitcnt vmcnt(20)
	ds_write2_b32 v53, v39, v40 offset0:148 offset1:214
	s_waitcnt vmcnt(18)
	ds_write2_b32 v54, v41, v42 offset0:24 offset1:90
	s_waitcnt vmcnt(16)
	ds_write2_b32 v54, v43, v59 offset0:156 offset1:222
	s_waitcnt vmcnt(14)
	ds_write2_b32 v55, v60, v61 offset0:32 offset1:98
	s_waitcnt vmcnt(12)
	ds_write2_b32 v55, v62, v63 offset0:164 offset1:230
	s_waitcnt vmcnt(10)
	ds_write2_b32 v56, v64, v65 offset0:40 offset1:106
	s_waitcnt vmcnt(8)
	ds_write2_b32 v56, v66, v28 offset0:172 offset1:238
	s_waitcnt vmcnt(6)
	ds_write2_b32 v57, v14, v15 offset0:48 offset1:114
	s_waitcnt vmcnt(4)
	ds_write2_b32 v57, v16, v17 offset0:180 offset1:246
	s_waitcnt vmcnt(2)
	ds_write2_b32 v58, v18, v19 offset0:56 offset1:122
	s_waitcnt vmcnt(0)
	ds_write2_b32 v58, v20, v12 offset0:188 offset1:254
	s_waitcnt lgkmcnt(0)
	ds_read2_b32 v[12:13], v48 offset1:33
	s_waitcnt lgkmcnt(0)
	v_cvt_pk_bf16_f32 v12, v12, v13
	ds_read2_b32 v[14:15], v48 offset0:66 offset1:99
	v_or_b32_e32 v3, s6, v47
	s_waitcnt lgkmcnt(0)
	v_cvt_pk_bf16_f32 v13, v14, v15
	ds_read2_b32 v[14:15], v48 offset0:132 offset1:165
	v_lshl_add_u64 v[18:19], s[4:5], 1, v[8:9]
	v_lshlrev_b32_e32 v20, 11, v3
	v_mov_b32_e32 v21, v5
	s_waitcnt lgkmcnt(0)
	v_cvt_pk_bf16_f32 v14, v14, v15
	ds_read2_b32 v[16:17], v48 offset0:198 offset1:231
	s_waitcnt lgkmcnt(0)
	v_cvt_pk_bf16_f32 v15, v16, v17
	v_lshl_add_u64 v[20:21], v[18:19], 0, v[20:21]
	ds_read2_b32 v[16:17], v48 offset0:8 offset1:41
	global_store_dwordx4 v[20:21], v[12:15], off sc1
	v_or_b32_e32 v3, s6, v49
	v_lshlrev_b32_e32 v20, 11, v3
	s_waitcnt lgkmcnt(0)
	v_cvt_pk_bf16_f32 v12, v16, v17
	ds_read2_b32 v[14:15], v48 offset0:74 offset1:107
	s_waitcnt lgkmcnt(0)
	v_cvt_pk_bf16_f32 v13, v14, v15
	ds_read2_b32 v[14:15], v48 offset0:140 offset1:173
	v_mov_b32_e32 v21, v5
	s_waitcnt lgkmcnt(0)
	v_cvt_pk_bf16_f32 v14, v14, v15
	ds_read2_b32 v[16:17], v48 offset0:206 offset1:239
	s_waitcnt lgkmcnt(0)
	v_cvt_pk_bf16_f32 v15, v16, v17
	v_lshl_add_u64 v[20:21], v[18:19], 0, v[20:21]
	ds_read2_b32 v[16:17], v48 offset0:16 offset1:49
	global_store_dwordx4 v[20:21], v[12:15], off sc1
	v_or_b32_e32 v3, s6, v50
	v_lshlrev_b32_e32 v20, 11, v3
	s_waitcnt lgkmcnt(0)
	v_cvt_pk_bf16_f32 v12, v16, v17
	ds_read2_b32 v[14:15], v48 offset0:82 offset1:115
	s_waitcnt lgkmcnt(0)
	v_cvt_pk_bf16_f32 v13, v14, v15
	ds_read2_b32 v[14:15], v48 offset0:148 offset1:181
	v_mov_b32_e32 v21, v5
	s_waitcnt lgkmcnt(0)
	v_cvt_pk_bf16_f32 v14, v14, v15
	ds_read2_b32 v[16:17], v48 offset0:214 offset1:247
	s_waitcnt lgkmcnt(0)
	v_cvt_pk_bf16_f32 v15, v16, v17
	v_lshl_add_u64 v[20:21], v[18:19], 0, v[20:21]
	ds_read2_b32 v[16:17], v48 offset0:24 offset1:57
	global_store_dwordx4 v[20:21], v[12:15], off sc1
	v_or_b32_e32 v3, s6, v51
	s_mov_b64 s[4:5], 0
	s_waitcnt lgkmcnt(0)
	v_cvt_pk_bf16_f32 v12, v16, v17
	ds_read2_b32 v[14:15], v48 offset0:90 offset1:123
	s_waitcnt lgkmcnt(0)
	v_cvt_pk_bf16_f32 v13, v14, v15
	ds_read2_b32 v[14:15], v48 offset0:156 offset1:189
	s_waitcnt lgkmcnt(0)
	v_cvt_pk_bf16_f32 v14, v14, v15
	ds_read2_b32 v[16:17], v48 offset0:222 offset1:255
	s_waitcnt lgkmcnt(0)
	v_cvt_pk_bf16_f32 v15, v16, v17
	v_lshlrev_b32_e32 v16, 11, v3
	v_mov_b32_e32 v17, v5
	v_lshl_add_u64 v[16:17], v[18:19], 0, v[16:17]
	global_store_dwordx4 v[16:17], v[12:15], off sc1
	s_waitcnt lgkmcnt(0)

.LBB0_32:
	s_bitcmp0_b32 s22, 1
	s_mov_b32 s4, 0x310000
	s_cselect_b32 s4, s4, 0x350000
	s_add_u32 s6, s2, s4
	s_addc_u32 s7, s3, 0
	s_and_b32 s4, s29, 0x1c0
	s_and_b32 s5, s27, 32
	s_waitcnt vmcnt(30)
	ds_write2_b32 v46, v12, v13 offset1:66
	s_waitcnt vmcnt(28)
	ds_write2_b32 v46, v14, v15 offset0:132 offset1:198
	s_waitcnt vmcnt(26)
	ds_write2_b32 v52, v16, v17 offset0:8 offset1:74
	s_waitcnt vmcnt(24)
	ds_write2_b32 v52, v18, v19 offset0:140 offset1:206
	s_waitcnt vmcnt(22)
	ds_write2_b32 v53, v20, v21 offset0:16 offset1:82
	s_waitcnt vmcnt(20)
	ds_write2_b32 v53, v22, v23 offset0:148 offset1:214
	s_waitcnt vmcnt(18)
	ds_write2_b32 v54, v24, v25 offset0:24 offset1:90
	s_waitcnt vmcnt(16)
	ds_write2_b32 v54, v26, v27 offset0:156 offset1:222
	s_waitcnt vmcnt(14)
	ds_write2_b32 v55, v28, v29 offset0:32 offset1:98
	s_waitcnt vmcnt(12)
	ds_write2_b32 v55, v30, v31 offset0:164 offset1:230
	s_waitcnt vmcnt(10)
	ds_write2_b32 v56, v32, v33 offset0:40 offset1:106
	s_waitcnt vmcnt(8)
	ds_write2_b32 v56, v34, v35 offset0:172 offset1:238
	s_waitcnt vmcnt(6)
	ds_write2_b32 v57, v36, v37 offset0:48 offset1:114
	s_waitcnt vmcnt(4)
	ds_write2_b32 v57, v38, v39 offset0:180 offset1:246
	s_waitcnt vmcnt(2)
	ds_write2_b32 v58, v42, v43 offset0:56 offset1:122
	s_waitcnt vmcnt(0)
	ds_write2_b32 v58, v40, v41 offset0:188 offset1:254
	s_or_b32 s9, s4, s5
	s_lshl_b64 s[4:5], s[14:15], 1
	s_waitcnt lgkmcnt(0)
	s_add_u32 s4, s6, s4
	ds_read2_b32 v[12:13], v48 offset1:33
	s_addc_u32 s5, s7, s5
	v_mov_b32_e32 v3, v5
	s_waitcnt lgkmcnt(0)
	v_cvt_pk_bf16_f32 v12, v12, v13
	ds_read2_b32 v[14:15], v48 offset0:66 offset1:99
	v_lshl_add_u64 v[18:19], s[4:5], 0, v[2:3]
	v_or_b32_e32 v3, s9, v47
	s_waitcnt lgkmcnt(0)
	v_cvt_pk_bf16_f32 v13, v14, v15
	ds_read2_b32 v[14:15], v48 offset0:132 offset1:165
	v_lshlrev_b32_e32 v20, 9, v3
	v_mov_b32_e32 v21, v5
	s_waitcnt lgkmcnt(0)
	v_cvt_pk_bf16_f32 v14, v14, v15
	ds_read2_b32 v[16:17], v48 offset0:198 offset1:231
	s_waitcnt lgkmcnt(0)
	v_cvt_pk_bf16_f32 v15, v16, v17
	v_lshl_add_u64 v[20:21], v[18:19], 0, v[20:21]
	ds_read2_b32 v[16:17], v48 offset0:8 offset1:41
	global_store_dwordx4 v[20:21], v[12:15], off sc1
	v_or_b32_e32 v3, s9, v49
	v_lshlrev_b32_e32 v20, 9, v3
	s_waitcnt lgkmcnt(0)
	v_cvt_pk_bf16_f32 v12, v16, v17
	ds_read2_b32 v[14:15], v48 offset0:74 offset1:107
	s_waitcnt lgkmcnt(0)
	v_cvt_pk_bf16_f32 v13, v14, v15
	ds_read2_b32 v[14:15], v48 offset0:140 offset1:173
	v_mov_b32_e32 v21, v5
	s_waitcnt lgkmcnt(0)
	v_cvt_pk_bf16_f32 v14, v14, v15
	ds_read2_b32 v[16:17], v48 offset0:206 offset1:239
	s_waitcnt lgkmcnt(0)
	v_cvt_pk_bf16_f32 v15, v16, v17
	v_lshl_add_u64 v[20:21], v[18:19], 0, v[20:21]
	ds_read2_b32 v[16:17], v48 offset0:16 offset1:49
	global_store_dwordx4 v[20:21], v[12:15], off sc1
	v_or_b32_e32 v3, s9, v50
	v_lshlrev_b32_e32 v20, 9, v3
	s_waitcnt lgkmcnt(0)
	v_cvt_pk_bf16_f32 v12, v16, v17
	ds_read2_b32 v[14:15], v48 offset0:82 offset1:115
	s_waitcnt lgkmcnt(0)
	v_cvt_pk_bf16_f32 v13, v14, v15
	ds_read2_b32 v[14:15], v48 offset0:148 offset1:181
	v_mov_b32_e32 v21, v5
	s_waitcnt lgkmcnt(0)
	v_cvt_pk_bf16_f32 v14, v14, v15
	ds_read2_b32 v[16:17], v48 offset0:214 offset1:247
	s_waitcnt lgkmcnt(0)
	v_cvt_pk_bf16_f32 v15, v16, v17
	v_lshl_add_u64 v[20:21], v[18:19], 0, v[20:21]
	ds_read2_b32 v[16:17], v48 offset0:24 offset1:57
	global_store_dwordx4 v[20:21], v[12:15], off sc1
	v_or_b32_e32 v3, s9, v51
	v_mov_b32_e32 v21, v5
	s_waitcnt lgkmcnt(0)
	v_cvt_pk_bf16_f32 v12, v16, v17
	ds_read2_b32 v[14:15], v48 offset0:90 offset1:123
	s_waitcnt lgkmcnt(0)
	v_cvt_pk_bf16_f32 v13, v14, v15
	ds_read2_b32 v[14:15], v48 offset0:156 offset1:189
	s_waitcnt lgkmcnt(0)
	v_cvt_pk_bf16_f32 v14, v14, v15
	ds_read2_b32 v[16:17], v48 offset0:222 offset1:255
	v_lshlrev_b32_e32 v20, 9, v3
	s_waitcnt lgkmcnt(0)
	v_cvt_pk_bf16_f32 v15, v16, v17
	v_lshl_add_u64 v[16:17], v[18:19], 0, v[20:21]
	global_store_dwordx4 v[16:17], v[12:15], off sc1
	s_waitcnt lgkmcnt(0)

.LBB0_37:
	s_waitcnt vmcnt(30)
	ds_write2_b32 v46, v12, v13 offset1:66
	s_waitcnt vmcnt(28)
	ds_write2_b32 v46, v14, v15 offset0:132 offset1:198
	s_waitcnt vmcnt(26)
	ds_write2_b32 v52, v16, v17 offset0:8 offset1:74
	s_waitcnt vmcnt(24)
	ds_write2_b32 v52, v18, v19 offset0:140 offset1:206
	s_waitcnt vmcnt(22)
	ds_write2_b32 v53, v20, v21 offset0:16 offset1:82
	s_waitcnt vmcnt(20)
	ds_write2_b32 v53, v22, v23 offset0:148 offset1:214
	s_waitcnt vmcnt(18)
	ds_write2_b32 v54, v24, v25 offset0:24 offset1:90
	s_waitcnt vmcnt(16)
	ds_write2_b32 v54, v26, v27 offset0:156 offset1:222
	s_waitcnt vmcnt(14)
	ds_write2_b32 v55, v28, v29 offset0:32 offset1:98
	s_waitcnt vmcnt(12)
	ds_write2_b32 v55, v30, v31 offset0:164 offset1:230
	s_waitcnt vmcnt(10)
	ds_write2_b32 v56, v32, v33 offset0:40 offset1:106
	s_waitcnt vmcnt(8)
	ds_write2_b32 v56, v34, v35 offset0:172 offset1:238
	s_waitcnt vmcnt(6)
	ds_write2_b32 v57, v36, v37 offset0:48 offset1:114
	s_waitcnt vmcnt(4)
	ds_write2_b32 v57, v38, v39 offset0:180 offset1:246
	s_waitcnt vmcnt(2)
	ds_write2_b32 v58, v42, v43 offset0:56 offset1:122
	s_waitcnt vmcnt(0)
	ds_write2_b32 v58, v40, v41 offset0:188 offset1:254
	s_waitcnt lgkmcnt(0)
	s_lshl_b32 s4, s17, 5
	ds_read2_b32 v[12:13], v48 offset1:33
	v_or_b32_e32 v3, s4, v47
	s_waitcnt lgkmcnt(0)
	v_cvt_pk_bf16_f32 v12, v12, v13
	ds_read2_b32 v[14:15], v48 offset0:66 offset1:99
	s_lshl_b32 s14, s18, 1
	v_mul_u32_u24_e32 v3, 0x180, v3
	s_waitcnt lgkmcnt(0)
	v_cvt_pk_bf16_f32 v13, v14, v15
	ds_read2_b32 v[14:15], v48 offset0:132 offset1:165
	v_lshl_add_u64 v[18:19], v[10:11], 0, s[14:15]
	v_lshlrev_b32_e32 v20, 1, v3
	v_mov_b32_e32 v21, v5
	s_waitcnt lgkmcnt(0)
	v_cvt_pk_bf16_f32 v14, v14, v15
	ds_read2_b32 v[16:17], v48 offset0:198 offset1:231
	s_waitcnt lgkmcnt(0)
	v_cvt_pk_bf16_f32 v15, v16, v17
	v_lshl_add_u64 v[20:21], v[18:19], 0, v[20:21]
	v_or_b32_e32 v3, s4, v49
	ds_read2_b32 v[16:17], v48 offset0:8 offset1:41
	global_store_dwordx4 v[20:21], v[12:15], off sc1
	v_mul_u32_u24_e32 v3, 0x180, v3
	v_lshlrev_b32_e32 v20, 1, v3
	s_waitcnt lgkmcnt(0)
	v_cvt_pk_bf16_f32 v12, v16, v17
	ds_read2_b32 v[14:15], v48 offset0:74 offset1:107
	s_waitcnt lgkmcnt(0)
	v_cvt_pk_bf16_f32 v13, v14, v15
	ds_read2_b32 v[14:15], v48 offset0:140 offset1:173
	v_mov_b32_e32 v21, v5
	s_waitcnt lgkmcnt(0)
	v_cvt_pk_bf16_f32 v14, v14, v15
	ds_read2_b32 v[16:17], v48 offset0:206 offset1:239
	s_waitcnt lgkmcnt(0)
	v_cvt_pk_bf16_f32 v15, v16, v17
	v_lshl_add_u64 v[20:21], v[18:19], 0, v[20:21]
	v_or_b32_e32 v3, s4, v50
	ds_read2_b32 v[16:17], v48 offset0:16 offset1:49
	global_store_dwordx4 v[20:21], v[12:15], off sc1
	v_mul_u32_u24_e32 v3, 0x180, v3
	v_mov_b32_e32 v21, v5
	s_waitcnt lgkmcnt(0)
	v_cvt_pk_bf16_f32 v12, v16, v17
	ds_read2_b32 v[14:15], v48 offset0:82 offset1:115
	s_waitcnt lgkmcnt(0)
	v_cvt_pk_bf16_f32 v13, v14, v15
	ds_read2_b32 v[14:15], v48 offset0:148 offset1:181
	v_lshlrev_b32_e32 v20, 1, v3
	s_waitcnt lgkmcnt(0)
	v_cvt_pk_bf16_f32 v14, v14, v15
	ds_read2_b32 v[16:17], v48 offset0:214 offset1:247
	s_waitcnt lgkmcnt(0)
	v_cvt_pk_bf16_f32 v15, v16, v17
	v_lshl_add_u64 v[20:21], v[18:19], 0, v[20:21]
	ds_read2_b32 v[16:17], v48 offset0:24 offset1:57
	global_store_dwordx4 v[20:21], v[12:15], off sc1
	v_or_b32_e32 v3, s4, v51
	v_mul_u32_u24_e32 v3, 0x180, v3
	s_waitcnt lgkmcnt(0)
	v_cvt_pk_bf16_f32 v12, v16, v17
	ds_read2_b32 v[14:15], v48 offset0:90 offset1:123
	s_waitcnt lgkmcnt(0)
	v_cvt_pk_bf16_f32 v13, v14, v15
	ds_read2_b32 v[14:15], v48 offset0:156 offset1:189
	s_waitcnt lgkmcnt(0)
	v_cvt_pk_bf16_f32 v14, v14, v15
	ds_read2_b32 v[16:17], v48 offset0:222 offset1:255
	v_mov_b32_e32 v21, v5
	v_lshlrev_b32_e32 v20, 1, v3
	s_waitcnt lgkmcnt(0)
	v_cvt_pk_bf16_f32 v15, v16, v17
	v_lshl_add_u64 v[16:17], v[18:19], 0, v[20:21]
	global_store_dwordx4 v[16:17], v[12:15], off sc1
	s_waitcnt lgkmcnt(0)

.LBB0_42:
	s_waitcnt vmcnt(30)
	ds_write2_b32 v46, v12, v13 offset1:66
	s_waitcnt vmcnt(28)
	ds_write2_b32 v46, v14, v15 offset0:132 offset1:198
	s_waitcnt vmcnt(26)
	ds_write2_b32 v52, v16, v17 offset0:8 offset1:74
	s_waitcnt vmcnt(24)
	ds_write2_b32 v52, v18, v19 offset0:140 offset1:206
	s_waitcnt vmcnt(22)
	ds_write2_b32 v53, v20, v21 offset0:16 offset1:82
	s_waitcnt vmcnt(20)
	ds_write2_b32 v53, v22, v23 offset0:148 offset1:214
	s_waitcnt vmcnt(18)
	ds_write2_b32 v54, v24, v25 offset0:24 offset1:90
	s_waitcnt vmcnt(16)
	ds_write2_b32 v54, v26, v27 offset0:156 offset1:222
	s_waitcnt vmcnt(14)
	ds_write2_b32 v55, v28, v29 offset0:32 offset1:98
	s_waitcnt vmcnt(12)
	ds_write2_b32 v55, v30, v31 offset0:164 offset1:230
	s_waitcnt vmcnt(10)
	ds_write2_b32 v56, v32, v33 offset0:40 offset1:106
	s_waitcnt vmcnt(8)
	ds_write2_b32 v56, v34, v35 offset0:172 offset1:238
	s_waitcnt vmcnt(6)
	ds_write2_b32 v57, v36, v37 offset0:48 offset1:114
	s_waitcnt vmcnt(4)
	ds_write2_b32 v57, v38, v39 offset0:180 offset1:246
	s_waitcnt vmcnt(2)
	ds_write2_b32 v58, v42, v43 offset0:56 offset1:122
	s_waitcnt vmcnt(0)
	ds_write2_b32 v58, v40, v41 offset0:188 offset1:254
	s_waitcnt lgkmcnt(0)
	s_lshl_b32 s4, s16, 5
	ds_read2_b32 v[12:13], v48 offset1:33
	s_and_b32 s4, 0xffff, s4
	s_waitcnt lgkmcnt(0)
	v_cvt_pk_bf16_f32 v12, v12, v13
	ds_read2_b32 v[14:15], v48 offset0:66 offset1:99
	s_lshl_b32 s14, s17, 1
	v_or_b32_e32 v3, s4, v47
	s_waitcnt lgkmcnt(0)
	v_cvt_pk_bf16_f32 v13, v14, v15
	ds_read2_b32 v[14:15], v48 offset0:132 offset1:165
	v_lshl_add_u64 v[18:19], v[6:7], 0, s[14:15]
	v_lshlrev_b32_e32 v20, 11, v3
	v_mov_b32_e32 v21, v5
	s_waitcnt lgkmcnt(0)
	v_cvt_pk_bf16_f32 v14, v14, v15
	ds_read2_b32 v[16:17], v48 offset0:198 offset1:231
	s_waitcnt lgkmcnt(0)
	v_cvt_pk_bf16_f32 v15, v16, v17
	v_lshl_add_u64 v[20:21], v[18:19], 0, v[20:21]
	ds_read2_b32 v[16:17], v48 offset0:8 offset1:41
	global_store_dwordx4 v[20:21], v[12:15], off sc1
	v_or_b32_e32 v3, s4, v49
	v_lshlrev_b32_e32 v20, 11, v3
	s_waitcnt lgkmcnt(0)
	v_cvt_pk_bf16_f32 v12, v16, v17
	ds_read2_b32 v[14:15], v48 offset0:74 offset1:107
	s_waitcnt lgkmcnt(0)
	v_cvt_pk_bf16_f32 v13, v14, v15
	ds_read2_b32 v[14:15], v48 offset0:140 offset1:173
	v_mov_b32_e32 v21, v5
	s_waitcnt lgkmcnt(0)
	v_cvt_pk_bf16_f32 v14, v14, v15
	ds_read2_b32 v[16:17], v48 offset0:206 offset1:239
	s_waitcnt lgkmcnt(0)
	v_cvt_pk_bf16_f32 v15, v16, v17
	v_lshl_add_u64 v[20:21], v[18:19], 0, v[20:21]
	ds_read2_b32 v[16:17], v48 offset0:16 offset1:49
	global_store_dwordx4 v[20:21], v[12:15], off sc1
	v_or_b32_e32 v3, s4, v50
	v_mov_b32_e32 v21, v5
	s_waitcnt lgkmcnt(0)
	v_cvt_pk_bf16_f32 v12, v16, v17
	ds_read2_b32 v[14:15], v48 offset0:82 offset1:115
	s_waitcnt lgkmcnt(0)
	v_cvt_pk_bf16_f32 v13, v14, v15
	ds_read2_b32 v[14:15], v48 offset0:148 offset1:181
	v_lshlrev_b32_e32 v20, 11, v3
	s_waitcnt lgkmcnt(0)
	v_cvt_pk_bf16_f32 v14, v14, v15
	ds_read2_b32 v[16:17], v48 offset0:214 offset1:247
	s_waitcnt lgkmcnt(0)
	v_cvt_pk_bf16_f32 v15, v16, v17
	v_lshl_add_u64 v[20:21], v[18:19], 0, v[20:21]
	ds_read2_b32 v[16:17], v48 offset0:24 offset1:57
	global_store_dwordx4 v[20:21], v[12:15], off sc1
	v_or_b32_e32 v3, s4, v51
	v_mov_b32_e32 v21, v5
	s_waitcnt lgkmcnt(0)
	v_cvt_pk_bf16_f32 v12, v16, v17
	ds_read2_b32 v[14:15], v48 offset0:90 offset1:123
	s_waitcnt lgkmcnt(0)
	v_cvt_pk_bf16_f32 v13, v14, v15
	ds_read2_b32 v[14:15], v48 offset0:156 offset1:189
	s_waitcnt lgkmcnt(0)
	v_cvt_pk_bf16_f32 v14, v14, v15
	ds_read2_b32 v[16:17], v48 offset0:222 offset1:255
	v_lshlrev_b32_e32 v20, 11, v3
	s_waitcnt lgkmcnt(0)
	v_cvt_pk_bf16_f32 v15, v16, v17
	v_lshl_add_u64 v[16:17], v[18:19], 0, v[20:21]
	global_store_dwordx4 v[16:17], v[12:15], off sc1
	s_waitcnt lgkmcnt(0)

.LBB0_44:
	s_andn2_b64 vcc, exec, s[4:5]
	s_cbranch_vccnz .LBB0_23
	s_mul_hi_i32 s4, s22, 0x3e0f83e1
	s_lshr_b32 s5, s4, 31
	s_ashr_i32 s4, s4, 11
	s_add_i32 s4, s4, s5
	s_mul_i32 s5, s4, 0xffffdf00
	s_add_i32 s6, s22, s5
	s_mul_i32 s5, s6, 0x3e1
	s_lshr_b32 s7, s5, 31
	s_ashr_i32 s5, s5, 22
	s_add_i32 s7, s5, s7
	s_mul_i32 s5, s7, 0x1080
	s_sub_i32 s5, s6, s5
	s_sext_i32_i16 s9, s5
	s_mul_i32 s14, s9, 0xba3
	s_lshr_b32 s16, s14, 31
	s_ashr_i32 s18, s14, 22
	s_add_i32 s18, s18, s16
	s_mul_i32 s14, s18, 0x580
	s_sub_i32 s96, s5, s14
	s_ashr_i32 s5, s4, 31
	s_mul_i32 s16, s4, 0x2100000
	s_mul_hi_i32 s14, s4, 0x2100000
	s_add_u32 s16, s23, s16
	s_sext_i32_i16 s7, s7
	s_addc_u32 s14, s24, s14
	s_mul_hi_i32 s17, s7, 0x1080000
	s_mul_i32 s7, s7, 0x1080000
	s_add_u32 s93, s16, s7
	s_addc_u32 s94, s14, s17
	s_addk_i32 s6, 0x107f
	s_cmpk_lt_u32 s6, 0x20ff
	s_cselect_b64 s[6:7], -1, 0
	s_mov_b64 s[16:17], -1
	s_cmpk_gt_i32 s9, 0xaff
	s_mul_hi_i32 s97, s4, 0xb00000
	s_mul_i32 s9, s4, 0xb00000
	s_cbranch_scc0 .LBB0_47
	s_and_b32 s14, 0xffff, s96
	s_and_b64 s[16:17], s[6:7], exec
	s_cselect_b32 s16, 32, 0x48
	s_add_u32 s16, s12, s16
	s_addc_u32 s17, s13, 0
	s_load_dwordx2 s[16:17], s[16:17], 0x0
	v_mov_b32_e32 v13, v5
	s_waitcnt lgkmcnt(0)
	s_add_u32 vcc_lo, s16, s9
	s_addc_u32 vcc_hi, s17, s97
	s_lshl_b32 s16, s14, 1
	s_and_b32 s17, s16, 0xfc0
	s_lshl_b32 s14, s14, 5
	v_or_b32_e32 v3, s17, v45
	s_and_b32 s16, s14, 0x3e0
	v_lshlrev_b32_e32 v12, 12, v3
	v_lshl_add_u64 v[12:13], vcc, 0, v[12:13]
	s_lshl_b32 s14, s16, 2
	v_lshl_add_u64 v[12:13], v[12:13], 0, s[14:15]
	v_lshl_add_u64 v[12:13], v[12:13], 0, v[4:5]
	v_add_co_u32_e32 v14, vcc, s31, v12
	s_lshl_b32 s14, s17, 1
	s_nop 0
	v_addc_co_u32_e32 v15, vcc, 0, v13, vcc
	v_add_co_u32_e32 v16, vcc, s34, v12
	s_nop 1
	v_addc_co_u32_e32 v17, vcc, 0, v13, vcc
	v_add_co_u32_e32 v18, vcc, s35, v12
	s_nop 1
	v_addc_co_u32_e32 v19, vcc, 0, v13, vcc
	v_add_co_u32_e32 v20, vcc, s36, v12
	s_nop 1
	v_addc_co_u32_e32 v21, vcc, 0, v13, vcc
	v_add_co_u32_e32 v22, vcc, s37, v12
	s_nop 1
	v_addc_co_u32_e32 v23, vcc, 0, v13, vcc
	v_add_co_u32_e32 v24, vcc, s38, v12
	s_nop 1
	v_addc_co_u32_e32 v25, vcc, 0, v13, vcc
	v_add_co_u32_e32 v26, vcc, s39, v12
	s_nop 1
	v_addc_co_u32_e32 v27, vcc, 0, v13, vcc
	global_load_dword v3, v[12:13], off
	global_load_dword v30, v[14:15], off
	global_load_dword v31, v[16:17], off
	global_load_dword v32, v[18:19], off
	global_load_dword v33, v[20:21], off
	global_load_dword v34, v[22:23], off
	global_load_dword v35, v[24:25], off
	global_load_dword v36, v[26:27], off
	v_add_co_u32_e32 v14, vcc, s40, v12
	s_nop 1
	v_addc_co_u32_e32 v15, vcc, 0, v13, vcc
	v_add_co_u32_e32 v16, vcc, s41, v12
	s_nop 1
	v_addc_co_u32_e32 v17, vcc, 0, v13, vcc
	v_add_co_u32_e32 v18, vcc, s42, v12
	s_nop 1
	v_addc_co_u32_e32 v19, vcc, 0, v13, vcc
	v_add_co_u32_e32 v20, vcc, s43, v12
	s_nop 1
	v_addc_co_u32_e32 v21, vcc, 0, v13, vcc
	v_add_co_u32_e32 v22, vcc, s44, v12
	s_nop 1
	v_addc_co_u32_e32 v23, vcc, 0, v13, vcc
	v_add_co_u32_e32 v24, vcc, s45, v12
	s_nop 1
	v_addc_co_u32_e32 v25, vcc, 0, v13, vcc
	v_add_co_u32_e32 v26, vcc, s46, v12
	s_nop 1
	v_addc_co_u32_e32 v27, vcc, 0, v13, vcc
	v_add_co_u32_e32 v28, vcc, s47, v12
	s_nop 1
	v_addc_co_u32_e32 v29, vcc, 0, v13, vcc
	global_load_dword v37, v[14:15], off
	global_load_dword v38, v[16:17], off
	global_load_dword v39, v[18:19], off
	global_load_dword v40, v[20:21], off
	global_load_dword v41, v[22:23], off
	global_load_dword v42, v[24:25], off
	global_load_dword v43, v[26:27], off
	global_load_dword v59, v[28:29], off
	v_add_co_u32_e32 v14, vcc, s48, v12
	s_nop 1
	v_addc_co_u32_e32 v15, vcc, 0, v13, vcc
	v_add_co_u32_e32 v16, vcc, s49, v12
	s_nop 1
	v_addc_co_u32_e32 v17, vcc, 0, v13, vcc
	v_add_co_u32_e32 v18, vcc, s50, v12
	s_nop 1
	v_addc_co_u32_e32 v19, vcc, 0, v13, vcc
	v_add_co_u32_e32 v20, vcc, s51, v12
	s_nop 1
	v_addc_co_u32_e32 v21, vcc, 0, v13, vcc
	v_add_co_u32_e32 v22, vcc, s52, v12
	s_nop 1
	v_addc_co_u32_e32 v23, vcc, 0, v13, vcc
	v_add_co_u32_e32 v24, vcc, s53, v12
	s_nop 1
	v_addc_co_u32_e32 v25, vcc, 0, v13, vcc
	v_add_co_u32_e32 v26, vcc, s54, v12
	s_nop 1
	v_addc_co_u32_e32 v27, vcc, 0, v13, vcc
	v_add_co_u32_e32 v28, vcc, s55, v12
	s_nop 1
	v_addc_co_u32_e32 v29, vcc, 0, v13, vcc
	global_load_dword v60, v[14:15], off
	global_load_dword v61, v[16:17], off
	global_load_dword v62, v[18:19], off
	global_load_dword v63, v[20:21], off
	global_load_dword v64, v[22:23], off
	global_load_dword v65, v[24:25], off
	global_load_dword v66, v[26:27], off
	s_nop 0
	global_load_dword v28, v[28:29], off
	v_add_co_u32_e32 v14, vcc, s56, v12
	s_nop 1
	v_addc_co_u32_e32 v15, vcc, 0, v13, vcc
	v_add_co_u32_e32 v16, vcc, s57, v12
	s_nop 1
	v_addc_co_u32_e32 v17, vcc, 0, v13, vcc
	v_add_co_u32_e32 v18, vcc, s58, v12
	s_nop 1
	v_addc_co_u32_e32 v19, vcc, 0, v13, vcc
	v_add_co_u32_e32 v20, vcc, s59, v12
	s_nop 1
	v_addc_co_u32_e32 v21, vcc, 0, v13, vcc
	v_add_co_u32_e32 v22, vcc, s60, v12
	s_nop 1
	v_addc_co_u32_e32 v23, vcc, 0, v13, vcc
	v_add_co_u32_e32 v24, vcc, s61, v12
	s_nop 1
	v_addc_co_u32_e32 v25, vcc, 0, v13, vcc
	v_add_co_u32_e32 v26, vcc, s62, v12
	s_nop 1
	v_addc_co_u32_e32 v27, vcc, 0, v13, vcc
	v_add_co_u32_e32 v12, vcc, s63, v12
	s_nop 1
	v_addc_co_u32_e32 v13, vcc, 0, v13, vcc
	global_load_dword v14, v[14:15], off
	s_nop 0
	global_load_dword v15, v[16:17], off
	s_nop 0
	global_load_dword v16, v[18:19], off
	global_load_dword v17, v[20:21], off
	s_nop 0
	global_load_dword v18, v[22:23], off
	global_load_dword v19, v[24:25], off
	global_load_dword v20, v[26:27], off
	s_nop 0
	global_load_dword v12, v[12:13], off
	s_waitcnt vmcnt(30)
	ds_write2_b32 v46, v3, v30 offset1:66
	s_waitcnt vmcnt(28)
	ds_write2_b32 v46, v31, v32 offset0:132 offset1:198
	s_waitcnt vmcnt(26)
	ds_write2_b32 v52, v33, v34 offset0:8 offset1:74
	s_waitcnt vmcnt(24)
	ds_write2_b32 v52, v35, v36 offset0:140 offset1:206
	s_waitcnt vmcnt(22)
	ds_write2_b32 v53, v37, v38 offset0:16 offset1:82
	s_waitcnt vmcnt(20)
	ds_write2_b32 v53, v39, v40 offset0:148 offset1:214
	s_waitcnt vmcnt(18)
	ds_write2_b32 v54, v41, v42 offset0:24 offset1:90
	s_waitcnt vmcnt(16)
	ds_write2_b32 v54, v43, v59 offset0:156 offset1:222
	s_waitcnt vmcnt(14)
	ds_write2_b32 v55, v60, v61 offset0:32 offset1:98
	s_waitcnt vmcnt(12)
	ds_write2_b32 v55, v62, v63 offset0:164 offset1:230
	s_waitcnt vmcnt(10)
	ds_write2_b32 v56, v64, v65 offset0:40 offset1:106
	s_waitcnt vmcnt(8)
	ds_write2_b32 v56, v66, v28 offset0:172 offset1:238
	s_waitcnt vmcnt(6)
	ds_write2_b32 v57, v14, v15 offset0:48 offset1:114
	s_waitcnt vmcnt(4)
	ds_write2_b32 v57, v16, v17 offset0:180 offset1:246
	s_waitcnt vmcnt(2)
	ds_write2_b32 v58, v18, v19 offset0:56 offset1:122
	s_waitcnt vmcnt(0)
	ds_write2_b32 v58, v20, v12 offset0:188 offset1:254
	s_add_u32 vcc_lo, s93, s14
	s_waitcnt lgkmcnt(0)
	s_addc_u32 vcc_hi, s94, 0
	v_mov_b32_e32 v3, v5
	ds_read2_b32 v[12:13], v48 offset1:33
	v_lshl_add_u64 v[18:19], vcc, 0, v[2:3]
	v_or_b32_e32 v3, s16, v47
	s_waitcnt lgkmcnt(0)
	v_cvt_pk_bf16_f32 v12, v12, v13
	ds_read2_b32 v[14:15], v48 offset0:66 offset1:99
	s_mov_b64 vcc, 0xb00000
	v_mul_u32_u24_e32 v3, 0xb00, v3
	s_waitcnt lgkmcnt(0)
	v_cvt_pk_bf16_f32 v13, v14, v15
	ds_read2_b32 v[14:15], v48 offset0:132 offset1:165
	v_lshl_add_u64 v[18:19], v[18:19], 0, vcc
	v_lshlrev_b32_e32 v20, 1, v3
	v_mov_b32_e32 v21, v5
	s_waitcnt lgkmcnt(0)
	v_cvt_pk_bf16_f32 v14, v14, v15
	ds_read2_b32 v[16:17], v48 offset0:198 offset1:231
	s_waitcnt lgkmcnt(0)
	v_cvt_pk_bf16_f32 v15, v16, v17
	v_lshl_add_u64 v[20:21], v[18:19], 0, v[20:21]
	v_or_b32_e32 v3, s16, v49
	ds_read2_b32 v[16:17], v48 offset0:8 offset1:41
	global_store_dwordx4 v[20:21], v[12:15], off sc1
	v_mul_u32_u24_e32 v3, 0xb00, v3
	v_lshlrev_b32_e32 v20, 1, v3
	s_waitcnt lgkmcnt(0)
	v_cvt_pk_bf16_f32 v12, v16, v17
	ds_read2_b32 v[14:15], v48 offset0:74 offset1:107
	s_waitcnt lgkmcnt(0)
	v_cvt_pk_bf16_f32 v13, v14, v15
	ds_read2_b32 v[14:15], v48 offset0:140 offset1:173
	v_mov_b32_e32 v21, v5
	s_waitcnt lgkmcnt(0)
	v_cvt_pk_bf16_f32 v14, v14, v15
	ds_read2_b32 v[16:17], v48 offset0:206 offset1:239
	s_waitcnt lgkmcnt(0)
	v_cvt_pk_bf16_f32 v15, v16, v17
	v_lshl_add_u64 v[20:21], v[18:19], 0, v[20:21]
	v_or_b32_e32 v3, s16, v50
	ds_read2_b32 v[16:17], v48 offset0:16 offset1:49
	global_store_dwordx4 v[20:21], v[12:15], off sc1
	v_mul_u32_u24_e32 v3, 0xb00, v3
	v_lshlrev_b32_e32 v20, 1, v3
	s_waitcnt lgkmcnt(0)
	v_cvt_pk_bf16_f32 v12, v16, v17
	ds_read2_b32 v[14:15], v48 offset0:82 offset1:115
	s_waitcnt lgkmcnt(0)
	v_cvt_pk_bf16_f32 v13, v14, v15
	ds_read2_b32 v[14:15], v48 offset0:148 offset1:181
	v_mov_b32_e32 v21, v5
	s_waitcnt lgkmcnt(0)
	v_cvt_pk_bf16_f32 v14, v14, v15
	ds_read2_b32 v[16:17], v48 offset0:214 offset1:247
	s_waitcnt lgkmcnt(0)
	v_cvt_pk_bf16_f32 v15, v16, v17
	v_lshl_add_u64 v[20:21], v[18:19], 0, v[20:21]
	ds_read2_b32 v[16:17], v48 offset0:24 offset1:57
	global_store_dwordx4 v[20:21], v[12:15], off sc1
	v_or_b32_e32 v3, s16, v51
	v_mul_u32_u24_e32 v3, 0xb00, v3
	s_waitcnt lgkmcnt(0)
	v_cvt_pk_bf16_f32 v12, v16, v17
	ds_read2_b32 v[14:15], v48 offset0:90 offset1:123
	s_waitcnt lgkmcnt(0)
	v_cvt_pk_bf16_f32 v13, v14, v15
	ds_read2_b32 v[14:15], v48 offset0:156 offset1:189
	s_waitcnt lgkmcnt(0)
	v_cvt_pk_bf16_f32 v14, v14, v15
	ds_read2_b32 v[16:17], v48 offset0:222 offset1:255
	s_waitcnt lgkmcnt(0)
	v_cvt_pk_bf16_f32 v15, v16, v17
	v_lshlrev_b32_e32 v16, 1, v3
	v_mov_b32_e32 v17, v5
	v_lshl_add_u64 v[16:17], v[18:19], 0, v[16:17]
	global_store_dwordx4 v[16:17], v[12:15], off sc1
	s_waitcnt lgkmcnt(0)
	s_mov_b64 s[16:17], 0

.LBB0_54:
	v_add_co_u32_e32 v20, vcc, 0xffff1000, v10
	v_mov_b32_e32 v2, s25
	s_nop 0
	v_addc_co_u32_e32 v21, vcc, -1, v11, vcc
	v_add_co_u32_e32 v24, vcc, 0xffff2000, v10
	v_mov_b32_e32 v22, v18
	s_nop 0
	v_addc_co_u32_e32 v25, vcc, -1, v11, vcc
	v_add_co_u32_e32 v26, vcc, 0xffff3000, v10
	global_load_dword v154, v[20:21], off
	global_load_dword v156, v[24:25], off
	v_addc_co_u32_e32 v27, vcc, -1, v11, vcc
	v_add_co_u32_e32 v20, vcc, 0xffff4000, v10
	s_add_i32 s14, s14, 16
	s_nop 0
	v_addc_co_u32_e32 v21, vcc, -1, v11, vcc
	v_add_co_u32_e32 v24, vcc, 0xffff5000, v10
	global_load_dword v157, v[26:27], off
	global_load_dword v155, v[20:21], off
	v_addc_co_u32_e32 v25, vcc, -1, v11, vcc
	v_add_co_u32_e32 v20, vcc, 0xffff6000, v10
	s_add_i32 s25, s25, 64
	s_nop 0
	v_addc_co_u32_e32 v21, vcc, -1, v11, vcc
	v_add_co_u32_e32 v26, vcc, 0xffff7000, v10
	global_load_dword v158, v[24:25], off
	global_load_dword v159, v[20:21], off
	v_addc_co_u32_e32 v27, vcc, -1, v11, vcc
	v_add_co_u32_e32 v20, vcc, 0xffff8000, v10
	s_cmpk_lt_u32 s14, 0x70
	s_nop 0
	v_addc_co_u32_e32 v21, vcc, -1, v11, vcc
	v_add_co_u32_e32 v24, vcc, 0xffff9000, v10
	global_load_dword v160, v[26:27], off
	global_load_dword v161, v[20:21], off
	v_addc_co_u32_e32 v25, vcc, -1, v11, vcc
	v_add_co_u32_e32 v20, vcc, 0xffffa000, v10
	s_nop 1
	v_addc_co_u32_e32 v21, vcc, -1, v11, vcc
	v_add_co_u32_e32 v26, vcc, 0xffffb000, v10
	global_load_dword v162, v[24:25], off
	global_load_dword v163, v[20:21], off
	v_addc_co_u32_e32 v27, vcc, -1, v11, vcc
	v_add_co_u32_e32 v20, vcc, 0xffffc000, v10
	s_nop 1
	v_addc_co_u32_e32 v21, vcc, -1, v11, vcc
	v_add_co_u32_e32 v24, vcc, 0xffffd000, v10
	global_load_dword v164, v[26:27], off
	global_load_dword v165, v[20:21], off
	v_addc_co_u32_e32 v25, vcc, -1, v11, vcc
	v_add_co_u32_e32 v20, vcc, 0xffffe000, v10
	s_nop 1
	v_addc_co_u32_e32 v21, vcc, -1, v11, vcc
	global_load_dword v166, v[24:25], off
	global_load_dword v168, v[20:21], off
	global_load_dword v170, v[10:11], off offset:-4096
	global_load_dword v172, v[10:11], off
	ds_read_b128 v[24:27], v2
	ds_read_b128 v[28:31], v2 offset:16
	ds_read_b128 v[32:35], v2 offset:32
	ds_read_b128 v[36:39], v2 offset:48
	ds_read_b128 v[40:43], v2 offset:512
	ds_read_b128 v[46:49], v2 offset:528
	ds_read_b128 v[50:53], v2 offset:1024
	ds_read_b128 v[54:57], v2 offset:1040
	ds_read_b128 v[58:61], v2 offset:1536
	ds_read_b128 v[62:65], v2 offset:1552
	ds_read_b128 v[66:69], v2 offset:544
	ds_read_b128 v[70:73], v2 offset:560
	ds_read_b128 v[74:77], v2 offset:1056
	ds_read_b128 v[78:81], v2 offset:1072
	ds_read_b128 v[82:85], v2 offset:1568
	ds_read_b128 v[86:89], v2 offset:1584
	ds_read_b128 v[90:93], v2 offset:2048
	ds_read_b128 v[94:97], v2 offset:2064
	ds_read_b128 v[98:101], v2 offset:2560
	ds_read_b128 v[102:105], v2 offset:2576
	ds_read_b128 v[106:109], v2 offset:2080
	ds_read_b128 v[110:113], v2 offset:2096
	ds_read_b128 v[114:117], v2 offset:2592
	ds_read_b128 v[118:121], v2 offset:2608
	ds_read_b128 v[122:125], v2 offset:3072
	ds_read_b128 v[126:129], v2 offset:3088
	ds_read_b128 v[130:133], v2 offset:3584
	ds_read_b128 v[134:137], v2 offset:3600
	ds_read_b128 v[138:141], v2 offset:3104
	ds_read_b128 v[142:145], v2 offset:3120
	ds_read_b128 v[146:149], v2 offset:3616
	ds_read_b128 v[150:153], v2 offset:3632
	s_waitcnt lgkmcnt(14)
	v_mov_b32_e32 v21, v40
	v_mov_b32_e32 v40, v25
	v_mov_b32_e32 v25, v42
	v_mov_b32_e32 v42, v27
	v_mov_b32_e32 v27, v46
	v_mov_b32_e32 v46, v29
	v_mov_b32_e32 v29, v48
	v_mov_b32_e32 v48, v31
	v_mov_b32_e32 v31, v66
	v_mov_b32_e32 v66, v33
	v_mov_b32_e32 v33, v68
	v_mov_b32_e32 v68, v35
	v_mov_b32_e32 v35, v70
	v_mov_b32_e32 v70, v37
	v_mov_b32_e32 v37, v72
	v_mov_b32_e32 v72, v39
	v_mov_b32_e32 v39, v58
	v_mov_b32_e32 v58, v51
	v_mov_b32_e32 v20, v24
	v_mov_b32_e32 v24, v26
	v_mov_b32_e32 v26, v28
	v_mov_b32_e32 v28, v30
	v_mov_b32_e32 v30, v32
	v_mov_b32_e32 v32, v34
	v_mov_b32_e32 v34, v36
	v_mov_b32_e32 v36, v38
	v_mov_b32_e32 v38, v50
	v_mov_b32_e32 v51, v60
	s_waitcnt vmcnt(13)
	v_pk_mul_f32 v[58:59], v[156:157], v[58:59] op_sel_hi:[0,1]
	v_mov_b32_e32 v60, v53
	v_mov_b32_e32 v53, v62
	v_mov_b32_e32 v62, v55
	v_mov_b32_e32 v55, v64
	v_mov_b32_e32 v64, v57
	v_mov_b32_e32 v57, v82
	v_mov_b32_e32 v82, v75
	v_mov_b32_e32 v75, v84
	v_mov_b32_e32 v84, v77
	v_mov_b32_e32 v77, v86
	v_mov_b32_e32 v86, v79
	v_mov_b32_e32 v79, v88
	v_mov_b32_e32 v88, v81
	s_waitcnt lgkmcnt(13)
	v_mov_b32_e32 v81, v98
	v_mov_b32_e32 v98, v91
	v_mov_b32_e32 v91, v100
	v_mov_b32_e32 v100, v93
	s_waitcnt vmcnt(12)
	v_pk_fma_f32 v[38:39], v[154:155], v[38:39], v[58:59] op_sel_hi:[0,1,1]
	v_mov_b32_e32 v58, v155
	v_mov_b32_e32 v50, v52
	v_mov_b32_e32 v52, v54
	v_mov_b32_e32 v54, v56
	v_mov_b32_e32 v56, v74
	v_mov_b32_e32 v74, v76
	v_mov_b32_e32 v76, v78
	v_mov_b32_e32 v78, v80
	v_mov_b32_e32 v80, v90
	v_mov_b32_e32 v90, v92
	s_waitcnt lgkmcnt(12)
	v_mov_b32_e32 v93, v102
	v_mov_b32_e32 v102, v95
	v_mov_b32_e32 v95, v104
	v_mov_b32_e32 v104, v97
	s_waitcnt lgkmcnt(9)
	v_mov_b32_e32 v97, v114
	v_mov_b32_e32 v114, v107
	v_mov_b32_e32 v107, v116
	v_mov_b32_e32 v116, v109
	s_waitcnt lgkmcnt(8)
	v_mov_b32_e32 v109, v118
	v_mov_b32_e32 v118, v111
	v_mov_b32_e32 v111, v120
	v_mov_b32_e32 v120, v113
	s_waitcnt lgkmcnt(7)
	v_mov_b32_e32 v113, v124
	s_waitcnt lgkmcnt(5)
	v_mov_b32_e32 v124, v131
	v_mov_b32_e32 v131, v133
	v_pk_mul_f32 v[40:41], v[156:157], v[40:41] op_sel_hi:[0,1]
	v_pk_mul_f32 v[98:99], v[156:157], v[98:99] op_sel_hi:[0,1]
	v_mov_b32_e32 v2, v157
	v_pk_mul_f32 v[42:43], v[58:59], v[42:43] op_sel_hi:[0,1]
	v_pk_mul_f32 v[60:61], v[58:59], v[60:61] op_sel_hi:[0,1]
	v_pk_mul_f32 v[58:59], v[58:59], v[100:101] op_sel_hi:[0,1]
	v_mov_b32_e32 v92, v94
	v_mov_b32_e32 v94, v96
	v_mov_b32_e32 v96, v106
	v_mov_b32_e32 v106, v108
	v_mov_b32_e32 v108, v110
	v_mov_b32_e32 v110, v112
	v_mov_b32_e32 v112, v123
	v_mov_b32_e32 v123, v125
	v_mov_b32_e32 v125, v132
	v_pk_mul_f32 v[130:131], v[154:155], v[130:131]
	v_pk_fma_f32 v[20:21], v[154:155], v[20:21], v[40:41] op_sel_hi:[0,1,1]
	v_pk_fma_f32 v[40:41], v[154:155], v[80:81], v[98:99] op_sel_hi:[0,1,1]
	v_pk_fma_f32 v[24:25], v[2:3], v[24:25], v[42:43] op_sel_hi:[0,1,1]
	v_pk_fma_f32 v[42:43], v[2:3], v[50:51], v[60:61] op_sel_hi:[0,1,1]
	v_pk_fma_f32 v[50:51], v[2:3], v[90:91], v[58:59] op_sel_hi:[0,1,1]
	v_pk_fma_f32 v[98:99], v[156:157], v[124:125], v[130:131]
	s_waitcnt vmcnt(10)
	v_mul_f32_e32 v2, v159, v127
	v_mov_b32_e32 v58, v159
	v_pk_add_f32 v[20:21], v[20:21], v[24:25]
	v_pk_add_f32 v[24:25], v[38:39], v[42:43]
	v_pk_add_f32 v[38:39], v[40:41], v[50:51]
	s_waitcnt vmcnt(8)
	v_mov_b32_e32 v50, v161
	s_waitcnt lgkmcnt(4)
	v_mov_b32_e32 v132, v135
	v_mov_b32_e32 v135, v137
	v_pk_mul_f32 v[122:123], v[154:155], v[122:123]
	v_mov_b32_e32 v100, v158
	v_pk_add_f32 v[90:91], v[98:99], v[98:99] op_sel:[0,1] op_sel_hi:[1,0]
	v_pk_fma_f32 v[98:99], v[158:159], v[126:127], v[2:3] op_sel_hi:[1,1,0]
	v_pk_mul_f32 v[46:47], v[58:59], v[46:47] op_sel_hi:[0,1]
	v_pk_mul_f32 v[62:63], v[58:59], v[62:63] op_sel_hi:[0,1]
	v_mov_b32_e32 v101, v161
	v_mul_f32_e32 v2, v161, v129
	v_pk_add_f32 v[16:17], v[16:17], v[38:39]
	v_pk_mul_f32 v[38:39], v[50:51], v[48:49] op_sel_hi:[0,1]
	v_pk_mul_f32 v[48:49], v[50:51], v[64:65] op_sel_hi:[0,1]
	v_mov_b32_e32 v133, v136
	v_pk_fma_f32 v[80:81], v[156:157], v[112:113], v[122:123]
	v_mov_b32_e32 v60, v159
	v_pk_mul_f32 v[58:59], v[58:59], v[102:103] op_sel_hi:[0,1]
	v_mov_b32_e32 v61, v160
	v_pk_fma_f32 v[26:27], v[158:159], v[26:27], v[46:47] op_sel_hi:[0,1,1]
	v_pk_fma_f32 v[46:47], v[158:159], v[52:53], v[62:63] op_sel_hi:[0,1,1]
	v_pk_add_f32 v[12:13], v[12:13], v[20:21]
	v_pk_add_f32 v[14:15], v[14:15], v[24:25]
	v_pk_mul_f32 v[20:21], v[100:101], v[134:135]
	v_pk_fma_f32 v[24:25], v[160:161], v[128:129], v[2:3] op_sel_hi:[1,1,0]
	v_pk_fma_f32 v[28:29], v[160:161], v[28:29], v[38:39] op_sel_hi:[0,1,1]
	v_pk_fma_f32 v[38:39], v[160:161], v[54:55], v[48:49] op_sel_hi:[0,1,1]
	s_waitcnt vmcnt(6)
	v_mov_b32_e32 v2, v163
	v_pk_add_f32 v[80:81], v[80:81], v[80:81] op_sel:[0,1] op_sel_hi:[1,0]
	v_pk_fma_f32 v[52:53], v[158:159], v[92:93], v[58:59] op_sel_hi:[0,1,1]
	v_pk_mul_f32 v[50:51], v[50:51], v[104:105] op_sel_hi:[0,1]
	v_pk_fma_f32 v[20:21], v[60:61], v[132:133], v[20:21]
	v_pk_mul_f32 v[54:55], v[2:3], v[66:67] op_sel_hi:[0,1]
	v_pk_mul_f32 v[58:59], v[2:3], v[82:83] op_sel_hi:[0,1]
	v_pk_mul_f32 v[60:61], v[2:3], v[114:115] op_sel_hi:[0,1]
	v_pk_add_f32 v[26:27], v[26:27], v[28:29]
	v_pk_add_f32 v[28:29], v[46:47], v[38:39]
	s_waitcnt vmcnt(4)
	v_mov_b32_e32 v2, v165
	s_waitcnt lgkmcnt(3)
	v_mul_f32_e32 v99, v162, v138
	v_pk_fma_f32 v[48:49], v[160:161], v[94:95], v[50:51] op_sel_hi:[0,1,1]
	v_mul_f32_e32 v25, v163, v139
	s_waitcnt lgkmcnt(1)
	v_mul_f32_e32 v50, v163, v147
	v_mul_f32_e32 v23, v164, v140
	v_mul_f32_e32 v81, v165, v141
	v_pk_add_f32 v[14:15], v[14:15], v[28:29]
	v_pk_mul_f32 v[28:29], v[2:3], v[68:69] op_sel_hi:[0,1]
	s_waitcnt lgkmcnt(0)
	v_pk_mov_b32 v[18:19], v[18:19], v[150:151] op_sel:[1,0]
	v_mov_b32_e32 v40, v90
	v_pk_add_f32 v[38:39], v[52:53], v[48:49]
	v_pk_fma_f32 v[46:47], v[162:163], v[146:147], v[50:51] op_sel_hi:[1,1,0]
	v_pk_fma_f32 v[30:31], v[162:163], v[30:31], v[54:55] op_sel_hi:[0,1,1]
	v_pk_fma_f32 v[48:49], v[162:163], v[56:57], v[58:59] op_sel_hi:[0,1,1]
	v_pk_fma_f32 v[50:51], v[162:163], v[96:97], v[60:61] op_sel_hi:[0,1,1]
	v_pk_add_f32 v[24:25], v[98:99], v[24:25]
	v_pk_add_f32 v[12:13], v[12:13], v[26:27]
	v_mul_f32_e32 v26, v165, v149
	s_waitcnt vmcnt(3)
	v_mov_b32_e32 v41, v166
	v_pk_add_f32 v[22:23], v[22:23], v[80:81]
	v_pk_fma_f32 v[28:29], v[164:165], v[32:33], v[28:29] op_sel_hi:[0,1,1]
	s_waitcnt vmcnt(2)
	v_pk_mul_f32 v[32:33], v[168:169], v[70:71] op_sel_hi:[0,1]
	s_waitcnt vmcnt(0)
	v_pk_mul_f32 v[54:55], v[172:173], v[72:73] op_sel_hi:[0,1]
	v_pk_mul_f32 v[56:57], v[168:169], v[86:87] op_sel_hi:[0,1]
	v_pk_mul_f32 v[60:61], v[168:169], v[118:119] op_sel_hi:[0,1]
	v_mov_b32_e32 v136, v143
	v_mov_b32_e32 v143, v145
	v_pk_add_f32 v[42:43], v[18:19], v[90:91]
	v_pk_add_f32 v[20:21], v[20:21], v[20:21] op_sel:[0,1] op_sel_hi:[1,0]
	v_pk_fma_f32 v[26:27], v[164:165], v[148:149], v[26:27] op_sel_hi:[1,1,0]
	v_mul_f32_e32 v45, v172, v153
	v_pk_mul_f32 v[18:19], v[18:19], v[40:41]
	v_pk_add_f32 v[22:23], v[24:25], v[22:23]
	v_pk_add_f32 v[24:25], v[30:31], v[28:29]
	v_pk_fma_f32 v[28:29], v[166:167], v[34:35], v[32:33] op_sel_hi:[0,1,1]
	v_pk_fma_f32 v[30:31], v[170:171], v[36:37], v[54:55] op_sel_hi:[0,1,1]
	v_pk_fma_f32 v[34:35], v[166:167], v[76:77], v[56:57] op_sel_hi:[0,1,1]
	v_pk_fma_f32 v[40:41], v[166:167], v[108:109], v[60:61] op_sel_hi:[0,1,1]
	v_mov_b32_e32 v167, v172
	v_mov_b32_e32 v137, v144
	v_pk_add_f32 v[16:17], v[16:17], v[38:39]
	v_pk_mul_f32 v[38:39], v[2:3], v[84:85] op_sel_hi:[0,1]
	v_pk_mul_f32 v[52:53], v[2:3], v[116:117] op_sel_hi:[0,1]
	v_mov_b32_e32 v169, v170
	v_mul_f32_e32 v21, v168, v151
	v_mul_f32_e32 v47, v170, v152
	v_mov_b32_e32 v43, v19
	v_mov_b32_e32 v27, v45
	v_pk_add_f32 v[18:19], v[22:23], v[22:23] op_sel:[0,1] op_sel_hi:[1,0]
	v_pk_add_f32 v[12:13], v[12:13], v[24:25]
	v_pk_add_f32 v[22:23], v[28:29], v[30:31]
	v_pk_mul_f32 v[30:31], v[166:167], v[142:143]
	v_pk_fma_f32 v[38:39], v[164:165], v[74:75], v[38:39] op_sel_hi:[0,1,1]
	v_pk_mul_f32 v[58:59], v[172:173], v[88:89] op_sel_hi:[0,1]
	v_pk_fma_f32 v[52:53], v[164:165], v[106:107], v[52:53] op_sel_hi:[0,1,1]
	v_pk_mul_f32 v[62:63], v[172:173], v[120:121] op_sel_hi:[0,1]
	v_pk_add_f32 v[20:21], v[42:43], v[20:21]
	v_pk_add_f32 v[26:27], v[46:47], v[26:27]
	v_pk_add_f32 v[12:13], v[12:13], v[22:23]
	v_pk_fma_f32 v[22:23], v[168:169], v[136:137], v[30:31]
	v_pk_add_f32 v[32:33], v[48:49], v[38:39]
	v_pk_fma_f32 v[36:37], v[170:171], v[78:79], v[58:59] op_sel_hi:[0,1,1]
	v_pk_add_f32 v[38:39], v[50:51], v[52:53]
	v_pk_fma_f32 v[48:49], v[170:171], v[110:111], v[62:63] op_sel_hi:[0,1,1]
	v_pk_add_f32 v[20:21], v[20:21], v[26:27]
	v_pk_add_f32 v[22:23], v[22:23], v[22:23] op_sel:[0,1] op_sel_hi:[1,0]
	v_pk_add_f32 v[14:15], v[14:15], v[32:33]
	v_pk_add_f32 v[24:25], v[34:35], v[36:37]
	v_pk_add_f32 v[16:17], v[16:17], v[38:39]
	v_pk_add_f32 v[28:29], v[40:41], v[48:49]
	v_mov_b32_e32 v19, v20
	v_mov_b32_e32 v23, v21
	v_lshl_add_u64 v[10:11], v[10:11], 0, s[16:17]
	v_pk_add_f32 v[14:15], v[14:15], v[24:25]
	v_pk_add_f32 v[16:17], v[16:17], v[28:29]
	v_pk_add_f32 v[18:19], v[18:19], v[22:23]
	s_cbranch_scc1 .LBB0_54
	s_lshl_b32 s9, s22, 6
	s_and_b32 s9, s9, 0x3c0
	v_or_b32_e32 v2, s9, v44
	v_lshlrev_b32_e32 v2, 11, v2
	v_cvt_pk_bf16_f32 v10, v12, v13
	v_cvt_pk_bf16_f32 v11, v14, v15
	v_lshl_add_u64 v[14:15], s[4:5], 0, v[2:3]
	s_lshl_b32 s14, s24, 1
	v_lshl_add_u64 v[14:15], v[14:15], 0, s[14:15]
	s_lshl_b32 s14, s23, 1
	v_lshl_add_u64 v[14:15], v[14:15], 0, s[14:15]
	v_cvt_pk_bf16_f32 v12, v16, v17
	v_cvt_pk_bf16_f32 v13, v18, v19
	global_store_dwordx4 v[14:15], v[10:13], off sc1
	s_waitcnt lgkmcnt(0)
	s_add_i32 s22, s22, s10
	s_add_i32 s21, s21, s2
	s_cmpk_gt_i32 s22, 0x3ff
	s_cbranch_scc0 .LBB0_53

.LBB0_58:
	v_add_u32_e32 v7, s2, v7
	v_cmp_lt_i32_e32 vcc, s3, v7
	global_store_dwordx4 v[8:9], v[2:5], off sc1
	s_or_b64 s[16:17], vcc, s[16:17]
	v_lshl_add_u64 v[8:9], v[8:9], 0, s[14:15]
	s_andn2_b64 exec, exec, s[16:17]
	s_cbranch_execnz .LBB0_58

.LBB0_62:
	v_lshl_add_u64 v[12:13], s[6:7], 0, v[4:5]
	v_add_co_u32_e64 v24, s[4:5], s9, v12
	s_waitcnt lgkmcnt(0)
	global_load_dwordx4 v[8:11], v[6:7], off offset:-2048
	v_addc_co_u32_e64 v25, s[4:5], 0, v13, s[4:5]
	s_waitcnt vmcnt(0)
	v_cvt_pk_bf16_f32 v12, v8, v9
	v_cvt_pk_bf16_f32 v13, v10, v11
	global_store_dwordx2 v[24:25], v[12:13], off sc1
	global_load_dwordx4 v[12:15], v[6:7], off offset:-1024
	s_waitcnt vmcnt(0)
	v_cvt_pk_bf16_f32 v16, v12, v13
	v_cvt_pk_bf16_f32 v17, v14, v15
	global_store_dwordx2 v[24:25], v[16:17], off offset:512 sc1
	global_load_dwordx4 v[16:19], v[6:7], off
	s_waitcnt vmcnt(0)
	v_cvt_pk_bf16_f32 v20, v16, v17
	v_cvt_pk_bf16_f32 v21, v18, v19
	global_store_dwordx2 v[24:25], v[20:21], off offset:1024 sc1
	global_load_dwordx4 v[20:23], v[6:7], off offset:1024
	v_mov_b32_e32 v26, v248
	v_mul_f32_e32 v9, v9, v9
	v_mul_f32_e32 v11, v11, v11
	v_fmac_f32_e32 v9, v8, v8
	v_fmac_f32_e32 v11, v10, v10
	v_add_f32_e32 v8, v9, v11
	v_mul_f32_e32 v9, v13, v13
	v_mul_f32_e32 v10, v15, v15
	v_fmac_f32_e32 v9, v12, v12
	v_fmac_f32_e32 v10, v14, v14
	v_add_f32_e32 v9, v9, v10
	v_add_f32_e32 v8, v8, v9
	v_mul_f32_e32 v9, v17, v17
	v_mul_f32_e32 v10, v19, v19
	v_fmac_f32_e32 v9, v16, v16
	v_fmac_f32_e32 v10, v18, v18
	v_add_f32_e32 v9, v9, v10
	s_waitcnt vmcnt(0)
	v_mul_f32_e32 v11, v21, v21
	v_mul_f32_e32 v12, v23, v23
	v_add_f32_e32 v10, v8, v9
	v_cvt_pk_bf16_f32 v8, v20, v21
	v_cvt_pk_bf16_f32 v9, v22, v23
	v_fmac_f32_e32 v11, v20, v20
	v_fmac_f32_e32 v12, v22, v22
	global_store_dwordx2 v[24:25], v[8:9], off offset:1536 sc1
	v_add_f32_e32 v8, v11, v12
	v_lshlrev_b32_e32 v9, 2, v26
	v_add_f32_e32 v8, v10, v8
	v_xor_b32_e32 v9, 4, v9
	ds_bpermute_b32 v9, v9, v8
	v_mov_b32_e32 v10, v248
	s_waitcnt lgkmcnt(0)
	v_add_f32_e32 v8, v8, v9
	v_lshlrev_b32_e32 v10, 2, v10
	v_xor_b32_e32 v10, 8, v10
	ds_bpermute_b32 v9, v10, v8
	v_mov_b32_e32 v10, v248
	s_waitcnt lgkmcnt(0)
	v_add_f32_e32 v8, v8, v9
	v_lshlrev_b32_e32 v10, 2, v10
	v_xor_b32_e32 v10, 16, v10
	ds_bpermute_b32 v9, v10, v8
	v_mov_b32_e32 v10, v248
	s_waitcnt lgkmcnt(0)
	v_add_f32_e32 v8, v8, v9
	v_lshlrev_b32_e32 v10, 2, v10
	v_xor_b32_e32 v10, 32, v10
	ds_bpermute_b32 v9, v10, v8
	v_mov_b32_e32 v10, v248
	s_waitcnt lgkmcnt(0)
	v_add_f32_e32 v8, v8, v9
	v_lshlrev_b32_e32 v10, 2, v10
	v_xor_b32_e32 v10, 64, v10
	ds_bpermute_b32 v9, v10, v8
	v_mov_b32_e32 v10, v248
	s_waitcnt lgkmcnt(0)
	v_add_f32_e32 v8, v8, v9
	v_lshlrev_b32_e32 v10, 2, v10
	v_xor_b32_e32 v9, 0x80, v10
	ds_bpermute_b32 v9, v9, v8
	s_and_saveexec_b64 s[4:5], vcc
	s_cbranch_execz .LBB0_61
	s_waitcnt lgkmcnt(0)
	v_add_f32_e32 v8, v8, v9
	v_lshl_add_u64 v[10:11], s[6:7], 0, v[2:3]
	v_cndmask_b32_e64 v8, 0, v8, s[2:3]
	global_store_dword v[10:11], v8, off sc1
	s_branch .LBB0_61

.LBB0_94:
	s_lshl_b32 s6, s48, 8
	s_add_u32 s6, s4, s6
	s_addc_u32 s7, s5, 0
	s_add_u32 s6, s6, 0x180000
	s_addc_u32 s7, s7, 0
	s_mov_b32 s101, 0
.LXB_REP_0:
	v_mov_b32_e32 v3, 1
	v_mov_b32_e32 v4, 0x1000
	global_atomic_add v3, v4, v3, s[6:7] offset:1024 sc0
	v_cvt_f32_u32_e32 v1, v2
	v_rcp_f32_e32 v1, v1
	v_mov_b32_e32 v5, 0
	s_waitcnt vmcnt(0)
	v_cvt_f32_u32_e32 v4, v3
	v_add_f32_e32 v4, 0.5, v4
	v_mul_f32_e32 v4, v4, v1
	v_cvt_u32_f32_e32 v4, v4
	v_mul_lo_u32 v1, v4, v2
	v_add_u32_e32 v1, v1, v2
	v_add_u32_e32 v3, 1, v3
	s_nop 0
	v_readfirstlane_b32 s8, v4
	v_readfirstlane_b32 s9, v1
	v_readfirstlane_b32 s10, v3
	s_add_u32 s14, s6, 0x2400
	s_addc_u32 s15, s7, 0
	s_cmp_lg_u32 s9, s10
	s_cbranch_scc1 .LXB_POLL_0
	buffer_wbl2 sc1
	s_waitcnt vmcnt(0) lgkmcnt(0)
	v_mov_b32_e32 v3, 1
	v_mov_b32_e32 v4, 0x183000
	global_atomic_add v3, v4, v3, s[4:5] offset:1024 sc0
	v_cvt_f32_u32_e32 v1, v0
	v_rcp_f32_e32 v1, v1
	s_waitcnt vmcnt(0)
	v_cvt_f32_u32_e32 v4, v3
	v_add_f32_e32 v4, 0.5, v4
	v_mul_f32_e32 v4, v4, v1
	v_cvt_u32_f32_e32 v4, v4
	v_mul_lo_u32 v1, v4, v0
	v_add_u32_e32 v1, v1, v0
	v_add_u32_e32 v3, 1, v3
	s_nop 0
	v_readfirstlane_b32 s9, v1
	v_readfirstlane_b32 s10, v3
	s_cmp_lg_u32 s9, s10
	s_cbranch_scc1 .LXB_POLL_0
	s_add_u32 s16, s4, 0x182400
	s_addc_u32 s17, s5, 0
	s_mov_b64 exec, 0x2ffff
	v_lshlrev_b32_e32 v4, 8, v248
	v_mov_b32_e32 v3, 1
	global_atomic_add v4, v3, s[16:17]
	s_mov_b64 exec, 1
	s_branch .LXB_ACQ_0

.LBB0_160:
	s_bfe_i32 s4, s26, 0x80000
	s_bfe_u32 s4, s4, 0x2000d
	s_add_i32 s26, s26, s4
	s_bfe_i32 s4, s26, 0x80000
	s_bfe_u32 s5, s8, 0x70018
	s_sext_i32_i16 s4, s4
	s_add_i32 s5, s8, s5
	s_lshl_b32 s4, s4, 6
	s_and_b32 s5, s5, 0xff80
	s_and_b32 s4, s4, 0xffffff00
	s_sub_i32 s5, s8, s5
	s_lshl_b32 s8, s29, 7
	s_sext_i32_i16 s5, s5
	s_add_i32 s4, s4, s8
	s_add_i32 s8, s4, s5
	s_lshl_b64 s[4:5], s[6:7], 1
	s_waitcnt vmcnt(0)
	ds_write2_b32 v44, v8, v9 offset1:66
	ds_write2_b32 v44, v10, v11 offset0:132 offset1:198
	ds_write2_b32 v51, v12, v13 offset0:8 offset1:74
	ds_write2_b32 v51, v14, v15 offset0:140 offset1:206
	ds_write2_b32 v50, v16, v17 offset0:16 offset1:82
	ds_write2_b32 v50, v18, v19 offset0:148 offset1:214
	ds_write2_b32 v49, v20, v21 offset0:24 offset1:90
	ds_write2_b32 v49, v22, v23 offset0:156 offset1:222
	ds_write2_b32 v48, v24, v25 offset0:32 offset1:98
	ds_write2_b32 v48, v26, v27 offset0:164 offset1:230
	ds_write2_b32 v47, v28, v29 offset0:40 offset1:106
	ds_write2_b32 v47, v30, v31 offset0:172 offset1:238
	ds_write2_b32 v46, v32, v33 offset0:48 offset1:114
	ds_write2_b32 v46, v34, v35 offset0:180 offset1:246
	ds_write2_b32 v45, v36, v37 offset0:56 offset1:122
	ds_write2_b32 v45, v40, v41 offset0:188 offset1:254
	s_add_u32 s4, s24, s4
	s_waitcnt lgkmcnt(0)
	s_addc_u32 s5, s25, s5
	v_mov_b32_e32 v7, v97
	ds_read2_b32 v[8:9], v3 offset1:33
	v_lshl_add_u64 v[14:15], s[4:5], 0, v[6:7]
	v_or_b32_e32 v6, s8, v1
	s_waitcnt lgkmcnt(0)
	v_cvt_pk_bf16_f32 v8, v8, v9
	ds_read2_b32 v[10:11], v3 offset0:66 offset1:99
	v_ashrrev_i32_e32 v7, 31, v6
	s_waitcnt lgkmcnt(0)
	v_cvt_pk_bf16_f32 v9, v10, v11
	ds_read2_b32 v[10:11], v3 offset0:132 offset1:165
	v_lshlrev_b64 v[6:7], 11, v[6:7]
	s_waitcnt lgkmcnt(0)
	v_cvt_pk_bf16_f32 v10, v10, v11
	ds_read2_b32 v[12:13], v3 offset0:198 offset1:231
	v_lshl_add_u64 v[6:7], v[14:15], 0, v[6:7]
	s_waitcnt lgkmcnt(0)
	v_cvt_pk_bf16_f32 v11, v12, v13
	ds_read2_b32 v[12:13], v3 offset0:8 offset1:41
	global_store_dwordx4 v[6:7], v[8:11], off sc1
	s_waitcnt lgkmcnt(0)
	v_cvt_pk_bf16_f32 v6, v12, v13
	ds_read2_b32 v[8:9], v3 offset0:74 offset1:107
	s_waitcnt lgkmcnt(0)
	v_cvt_pk_bf16_f32 v7, v8, v9
	ds_read2_b32 v[8:9], v3 offset0:140 offset1:173
	s_waitcnt lgkmcnt(0)
	v_cvt_pk_bf16_f32 v8, v8, v9
	ds_read2_b32 v[10:11], v3 offset0:206 offset1:239
	s_waitcnt lgkmcnt(0)
	v_cvt_pk_bf16_f32 v9, v10, v11
	v_or_b32_e32 v10, s8, v5
	v_ashrrev_i32_e32 v11, 31, v10
	v_lshlrev_b64 v[10:11], 11, v[10:11]
	v_lshl_add_u64 v[10:11], v[14:15], 0, v[10:11]
	ds_read2_b32 v[12:13], v3 offset0:16 offset1:49
	global_store_dwordx4 v[10:11], v[6:9], off sc1
	s_waitcnt lgkmcnt(0)
	s_nop 0
	v_cvt_pk_bf16_f32 v6, v12, v13
	ds_read2_b32 v[8:9], v3 offset0:82 offset1:115
	s_waitcnt lgkmcnt(0)
	v_cvt_pk_bf16_f32 v7, v8, v9
	ds_read2_b32 v[8:9], v3 offset0:148 offset1:181
	s_waitcnt lgkmcnt(0)
	v_cvt_pk_bf16_f32 v8, v8, v9
	ds_read2_b32 v[10:11], v3 offset0:214 offset1:247
	s_waitcnt lgkmcnt(0)
	v_cvt_pk_bf16_f32 v9, v10, v11
	v_or_b32_e32 v10, s8, v42
	v_ashrrev_i32_e32 v11, 31, v10
	v_lshlrev_b64 v[10:11], 11, v[10:11]
	v_lshl_add_u64 v[10:11], v[14:15], 0, v[10:11]
	ds_read2_b32 v[12:13], v3 offset0:24 offset1:57
	global_store_dwordx4 v[10:11], v[6:9], off sc1
	s_waitcnt lgkmcnt(0)
	s_nop 0
	v_cvt_pk_bf16_f32 v6, v12, v13
	ds_read2_b32 v[8:9], v3 offset0:90 offset1:123
	s_waitcnt lgkmcnt(0)
	v_cvt_pk_bf16_f32 v7, v8, v9
	ds_read2_b32 v[8:9], v3 offset0:156 offset1:189
	s_waitcnt lgkmcnt(0)
	v_cvt_pk_bf16_f32 v8, v8, v9
	ds_read2_b32 v[10:11], v3 offset0:222 offset1:255
	s_waitcnt lgkmcnt(0)
	v_cvt_pk_bf16_f32 v9, v10, v11
	v_or_b32_e32 v10, s8, v43
	v_ashrrev_i32_e32 v11, 31, v10
	v_lshlrev_b64 v[10:11], 11, v[10:11]
	v_lshl_add_u64 v[10:11], v[14:15], 0, v[10:11]
	global_store_dwordx4 v[10:11], v[6:9], off sc1
	s_waitcnt lgkmcnt(0)

.LBB0_164:
	s_and_b32 s11, 0xffff, s26
	s_and_b64 s[8:9], s[6:7], exec
	s_cselect_b32 s8, 32, 0x48
	s_add_u32 s8, s2, s8
	s_addc_u32 s9, s3, 0
	s_load_dwordx2 s[8:9], s[8:9], 0x0
	v_mov_b32_e32 v9, v97
	s_waitcnt lgkmcnt(0)
	s_add_u32 s34, s8, s28
	s_addc_u32 s35, s9, s27
	s_lshl_b32 s8, s11, 1
	s_and_b32 s9, s8, 0xfc0
	s_lshl_b32 s8, s11, 5
	v_or_b32_e32 v7, s9, v0
	s_and_b32 s8, s8, 0x3e0
	v_lshlrev_b32_e32 v8, 12, v7
	v_lshl_add_u64 v[8:9], s[34:35], 0, v[8:9]
	s_lshl_b32 s60, s8, 2
	v_lshl_add_u64 v[8:9], v[8:9], 0, s[60:61]
	v_lshl_add_u64 v[8:9], v[8:9], 0, v[96:97]
	v_add_co_u32_e32 v10, vcc, s68, v8
	global_load_dword v7, v[8:9], off
	s_nop 0
	v_addc_co_u32_e32 v11, vcc, 0, v9, vcc
	global_load_dword v12, v[10:11], off
	v_add_co_u32_e32 v10, vcc, s75, v8
	s_mov_b32 s11, 0x10000
	s_nop 0
	v_addc_co_u32_e32 v11, vcc, 0, v9, vcc
	global_load_dword v13, v[10:11], off
	v_add_co_u32_e32 v10, vcc, s79, v8
	s_lshl_b32 s9, s9, 1
	s_nop 0
	v_addc_co_u32_e32 v11, vcc, 0, v9, vcc
	global_load_dword v14, v[10:11], off
	v_add_co_u32_e32 v10, vcc, s87, v8
	s_add_u32 s34, s24, s9
	s_nop 0
	v_addc_co_u32_e32 v11, vcc, 0, v9, vcc
	global_load_dword v15, v[10:11], off
	v_add_co_u32_e32 v10, vcc, s88, v8
	s_addc_u32 s35, s25, 0
	s_nop 0
	v_addc_co_u32_e32 v11, vcc, 0, v9, vcc
	global_load_dword v16, v[10:11], off
	v_add_co_u32_e32 v10, vcc, s62, v8
	s_nop 1
	v_addc_co_u32_e32 v11, vcc, 0, v9, vcc
	global_load_dword v17, v[10:11], off
	v_add_co_u32_e32 v10, vcc, s94, v8
	s_nop 1
	v_addc_co_u32_e32 v11, vcc, 0, v9, vcc
	global_load_dword v18, v[10:11], off
	v_add_co_u32_e32 v10, vcc, s11, v8
	s_mov_b32 s11, 0x22000
	s_nop 0
	v_addc_co_u32_e32 v11, vcc, 0, v9, vcc
	global_load_dword v19, v[10:11], off
	v_add_co_u32_e32 v10, vcc, s72, v8
	s_nop 1
	v_addc_co_u32_e32 v11, vcc, 0, v9, vcc
	global_load_dword v20, v[10:11], off
	v_add_co_u32_e32 v10, vcc, s73, v8
	s_nop 1
	v_addc_co_u32_e32 v11, vcc, 0, v9, vcc
	global_load_dword v21, v[10:11], off
	v_add_co_u32_e32 v10, vcc, s74, v8
	s_nop 1
	v_addc_co_u32_e32 v11, vcc, 0, v9, vcc
	global_load_dword v22, v[10:11], off
	v_add_co_u32_e32 v10, vcc, s85, v8
	s_nop 1
	v_addc_co_u32_e32 v11, vcc, 0, v9, vcc
	global_load_dword v23, v[10:11], off
	v_add_co_u32_e32 v10, vcc, s86, v8
	s_nop 1
	v_addc_co_u32_e32 v11, vcc, 0, v9, vcc
	global_load_dword v24, v[10:11], off
	v_add_co_u32_e32 v10, vcc, s90, v8
	s_nop 1
	v_addc_co_u32_e32 v11, vcc, 0, v9, vcc
	global_load_dword v25, v[10:11], off
	v_add_co_u32_e32 v10, vcc, s91, v8
	s_nop 1
	v_addc_co_u32_e32 v11, vcc, 0, v9, vcc
	global_load_dword v26, v[10:11], off
	v_add_co_u32_e32 v10, vcc, s95, v8
	s_nop 1
	v_addc_co_u32_e32 v11, vcc, 0, v9, vcc
	global_load_dword v27, v[10:11], off
	v_add_co_u32_e32 v10, vcc, s11, v8
	s_mov_b32 s11, 0x24000
	s_nop 0
	v_addc_co_u32_e32 v11, vcc, 0, v9, vcc
	global_load_dword v28, v[10:11], off
	v_add_co_u32_e32 v10, vcc, s11, v8
	s_mov_b32 s11, 0x28000
	s_nop 0
	v_addc_co_u32_e32 v11, vcc, 0, v9, vcc
	global_load_dword v29, v[10:11], off
	v_add_co_u32_e32 v10, vcc, s40, v8
	s_nop 1
	v_addc_co_u32_e32 v11, vcc, 0, v9, vcc
	global_load_dword v30, v[10:11], off
	v_add_co_u32_e32 v10, vcc, s11, v8
	s_mov_b32 s11, 0x2a000
	s_nop 0
	v_addc_co_u32_e32 v11, vcc, 0, v9, vcc
	global_load_dword v31, v[10:11], off
	v_add_co_u32_e32 v10, vcc, s11, v8
	s_mov_b32 s11, 0x2e000
	s_nop 0
	v_addc_co_u32_e32 v11, vcc, 0, v9, vcc
	global_load_dword v32, v[10:11], off
	v_add_co_u32_e32 v10, vcc, s41, v8
	s_nop 1
	v_addc_co_u32_e32 v11, vcc, 0, v9, vcc
	global_load_dword v33, v[10:11], off
	v_add_co_u32_e32 v10, vcc, s11, v8
	s_mov_b32 s11, 0x30000
	s_nop 0
	v_addc_co_u32_e32 v11, vcc, 0, v9, vcc
	global_load_dword v34, v[10:11], off
	v_add_co_u32_e32 v10, vcc, s11, v8
	s_mov_b32 s11, 0x32000
	s_nop 0
	v_addc_co_u32_e32 v11, vcc, 0, v9, vcc
	global_load_dword v35, v[10:11], off
	v_add_co_u32_e32 v10, vcc, s11, v8
	s_mov_b32 s11, 0x34000
	s_nop 0
	v_addc_co_u32_e32 v11, vcc, 0, v9, vcc
	global_load_dword v36, v[10:11], off
	v_add_co_u32_e32 v10, vcc, s11, v8
	s_mov_b32 s11, 0x36000
	s_nop 0
	v_addc_co_u32_e32 v11, vcc, 0, v9, vcc
	global_load_dword v37, v[10:11], off
	v_add_co_u32_e32 v10, vcc, s11, v8
	s_mov_b32 s11, 0x38000
	s_nop 0
	v_addc_co_u32_e32 v11, vcc, 0, v9, vcc
	global_load_dword v38, v[10:11], off
	v_add_co_u32_e32 v10, vcc, s11, v8
	s_mov_b32 s11, 0x3a000
	s_nop 0
	v_addc_co_u32_e32 v11, vcc, 0, v9, vcc
	global_load_dword v39, v[10:11], off
	v_add_co_u32_e32 v10, vcc, s11, v8
	s_mov_b32 s11, 0x3c000
	s_nop 0
	v_addc_co_u32_e32 v11, vcc, 0, v9, vcc
	global_load_dword v40, v[10:11], off
	v_add_co_u32_e32 v10, vcc, s11, v8
	s_mov_b32 s11, 0x3e000
	s_nop 0
	v_addc_co_u32_e32 v11, vcc, 0, v9, vcc
	v_add_co_u32_e32 v8, vcc, s11, v8
	global_load_dword v10, v[10:11], off
	s_nop 0
	v_addc_co_u32_e32 v9, vcc, 0, v9, vcc
	global_load_dword v8, v[8:9], off
	s_waitcnt vmcnt(0)
	ds_write2_b32 v44, v7, v12 offset1:66
	ds_write2_b32 v44, v13, v14 offset0:132 offset1:198
	ds_write2_b32 v51, v15, v16 offset0:8 offset1:74
	ds_write2_b32 v51, v17, v18 offset0:140 offset1:206
	ds_write2_b32 v50, v19, v20 offset0:16 offset1:82
	ds_write2_b32 v50, v21, v22 offset0:148 offset1:214
	ds_write2_b32 v49, v23, v24 offset0:24 offset1:90
	ds_write2_b32 v49, v25, v26 offset0:156 offset1:222
	ds_write2_b32 v48, v27, v28 offset0:32 offset1:98
	ds_write2_b32 v48, v29, v30 offset0:164 offset1:230
	ds_write2_b32 v47, v31, v32 offset0:40 offset1:106
	ds_write2_b32 v47, v33, v34 offset0:172 offset1:238
	ds_write2_b32 v46, v35, v36 offset0:48 offset1:114
	ds_write2_b32 v46, v37, v38 offset0:180 offset1:246
	ds_write2_b32 v45, v39, v40 offset0:56 offset1:122
	ds_write2_b32 v45, v10, v8 offset0:188 offset1:254
	v_mov_b32_e32 v7, v97
	s_waitcnt lgkmcnt(0)
	v_lshl_add_u64 v[8:9], s[34:35], 0, v[6:7]
	s_mov_b64 s[34:35], 0xb00000
	v_lshl_add_u64 v[12:13], v[8:9], 0, s[34:35]
	ds_read2_b32 v[8:9], v3 offset1:33
	s_waitcnt lgkmcnt(0)
	v_cvt_pk_bf16_f32 v8, v8, v9
	ds_read2_b32 v[10:11], v3 offset0:66 offset1:99
	s_waitcnt lgkmcnt(0)
	v_cvt_pk_bf16_f32 v9, v10, v11
	ds_read2_b32 v[10:11], v3 offset0:132 offset1:165
	v_or_b32_e32 v7, s8, v1
	s_waitcnt lgkmcnt(0)
	v_cvt_pk_bf16_f32 v10, v10, v11
	ds_read2_b32 v[14:15], v3 offset0:198 offset1:231
	v_mul_u32_u24_e32 v7, 0xb00, v7
	s_waitcnt lgkmcnt(0)
	v_cvt_pk_bf16_f32 v11, v14, v15
	v_lshlrev_b32_e32 v14, 1, v7
	v_mov_b32_e32 v15, v97
	v_lshl_add_u64 v[14:15], v[12:13], 0, v[14:15]
	global_store_dwordx4 v[14:15], v[8:11], off sc1
	ds_read2_b32 v[8:9], v3 offset0:8 offset1:41
	v_or_b32_e32 v7, s8, v5
	s_waitcnt lgkmcnt(0)
	v_cvt_pk_bf16_f32 v8, v8, v9
	ds_read2_b32 v[10:11], v3 offset0:74 offset1:107
	s_waitcnt lgkmcnt(0)
	v_cvt_pk_bf16_f32 v9, v10, v11
	ds_read2_b32 v[10:11], v3 offset0:140 offset1:173
	s_waitcnt lgkmcnt(0)
	v_cvt_pk_bf16_f32 v10, v10, v11
	ds_read2_b32 v[14:15], v3 offset0:206 offset1:239
	v_mul_u32_u24_e32 v7, 0xb00, v7
	s_waitcnt lgkmcnt(0)
	v_cvt_pk_bf16_f32 v11, v14, v15
	v_lshlrev_b32_e32 v14, 1, v7
	v_mov_b32_e32 v15, v97
	v_lshl_add_u64 v[14:15], v[12:13], 0, v[14:15]
	global_store_dwordx4 v[14:15], v[8:11], off sc1
	ds_read2_b32 v[8:9], v3 offset0:16 offset1:49
	v_or_b32_e32 v7, s8, v42
	s_waitcnt lgkmcnt(0)
	v_cvt_pk_bf16_f32 v8, v8, v9
	ds_read2_b32 v[10:11], v3 offset0:82 offset1:115
	s_waitcnt lgkmcnt(0)
	v_cvt_pk_bf16_f32 v9, v10, v11
	ds_read2_b32 v[10:11], v3 offset0:148 offset1:181
	s_waitcnt lgkmcnt(0)
	v_cvt_pk_bf16_f32 v10, v10, v11
	ds_read2_b32 v[14:15], v3 offset0:214 offset1:247
	v_mul_u32_u24_e32 v7, 0xb00, v7
	s_waitcnt lgkmcnt(0)
	v_cvt_pk_bf16_f32 v11, v14, v15
	v_lshlrev_b32_e32 v14, 1, v7
	v_mov_b32_e32 v15, v97
	v_lshl_add_u64 v[14:15], v[12:13], 0, v[14:15]
	global_store_dwordx4 v[14:15], v[8:11], off sc1
	ds_read2_b32 v[8:9], v3 offset0:24 offset1:57
	v_or_b32_e32 v7, s8, v43
	s_waitcnt lgkmcnt(0)
	v_cvt_pk_bf16_f32 v8, v8, v9
	ds_read2_b32 v[10:11], v3 offset0:90 offset1:123
	s_waitcnt lgkmcnt(0)
	v_cvt_pk_bf16_f32 v9, v10, v11
	ds_read2_b32 v[10:11], v3 offset0:156 offset1:189
	s_waitcnt lgkmcnt(0)
	v_cvt_pk_bf16_f32 v10, v10, v11
	ds_read2_b32 v[14:15], v3 offset0:222 offset1:255
	v_mul_u32_u24_e32 v7, 0xb00, v7
	s_waitcnt lgkmcnt(0)
	v_cvt_pk_bf16_f32 v11, v14, v15
	v_lshlrev_b32_e32 v14, 1, v7
	v_mov_b32_e32 v15, v97
	v_lshl_add_u64 v[12:13], v[12:13], 0, v[14:15]
	global_store_dwordx4 v[12:13], v[8:11], off sc1
	s_waitcnt lgkmcnt(0)
	s_cbranch_execnz .LBB0_161

.LBB0_172:
	s_bfe_i32 s4, s34, 0x80000
	s_bfe_u32 s4, s4, 0x2000d
	s_add_i32 s34, s34, s4
	s_bfe_i32 s4, s34, 0x80000
	s_bfe_u32 s5, s10, 0x70018
	s_sext_i32_i16 s4, s4
	s_add_i32 s5, s10, s5
	s_lshl_b32 s4, s4, 6
	s_and_b32 s5, s5, 0xff80
	s_and_b32 s4, s4, 0xffffff00
	s_sub_i32 s5, s10, s5
	s_lshl_b32 s10, s37, 7
	s_sext_i32_i16 s5, s5
	s_add_i32 s4, s4, s10
	s_add_i32 s10, s4, s5
	s_lshl_b64 s[4:5], s[6:7], 1
	s_waitcnt vmcnt(0)
	ds_write2_b32 v1, v8, v9 offset1:66
	ds_write2_b32 v1, v10, v11 offset0:132 offset1:198
	ds_write2_b32 v51, v12, v13 offset0:8 offset1:74
	ds_write2_b32 v51, v14, v15 offset0:140 offset1:206
	ds_write2_b32 v50, v16, v17 offset0:16 offset1:82
	ds_write2_b32 v50, v18, v19 offset0:148 offset1:214
	ds_write2_b32 v49, v20, v21 offset0:24 offset1:90
	ds_write2_b32 v49, v22, v23 offset0:156 offset1:222
	ds_write2_b32 v48, v24, v25 offset0:32 offset1:98
	ds_write2_b32 v48, v26, v27 offset0:164 offset1:230
	ds_write2_b32 v47, v28, v29 offset0:40 offset1:106
	ds_write2_b32 v47, v30, v31 offset0:172 offset1:238
	ds_write2_b32 v46, v32, v33 offset0:48 offset1:114
	ds_write2_b32 v46, v34, v35 offset0:180 offset1:246
	ds_write2_b32 v45, v36, v37 offset0:56 offset1:122
	ds_write2_b32 v45, v40, v41 offset0:188 offset1:254
	s_add_u32 s4, s29, s4
	s_waitcnt lgkmcnt(0)
	s_addc_u32 s5, s31, s5
	v_mov_b32_e32 v7, v97
	ds_read2_b32 v[8:9], v5 offset1:33
	v_lshl_add_u64 v[14:15], s[4:5], 0, v[6:7]
	v_or_b32_e32 v6, s10, v3
	s_waitcnt lgkmcnt(0)
	v_cvt_pk_bf16_f32 v8, v8, v9
	ds_read2_b32 v[10:11], v5 offset0:66 offset1:99
	v_ashrrev_i32_e32 v7, 31, v6
	s_waitcnt lgkmcnt(0)
	v_cvt_pk_bf16_f32 v9, v10, v11
	ds_read2_b32 v[10:11], v5 offset0:132 offset1:165
	v_lshlrev_b64 v[6:7], 11, v[6:7]
	s_waitcnt lgkmcnt(0)
	v_cvt_pk_bf16_f32 v10, v10, v11
	ds_read2_b32 v[12:13], v5 offset0:198 offset1:231
	v_lshl_add_u64 v[6:7], v[14:15], 0, v[6:7]
	s_waitcnt lgkmcnt(0)
	v_cvt_pk_bf16_f32 v11, v12, v13
	ds_read2_b32 v[12:13], v5 offset0:8 offset1:41
	global_store_dwordx4 v[6:7], v[8:11], off sc1
	s_waitcnt lgkmcnt(0)
	v_cvt_pk_bf16_f32 v6, v12, v13
	ds_read2_b32 v[8:9], v5 offset0:74 offset1:107
	s_waitcnt lgkmcnt(0)
	v_cvt_pk_bf16_f32 v7, v8, v9
	ds_read2_b32 v[8:9], v5 offset0:140 offset1:173
	s_waitcnt lgkmcnt(0)
	v_cvt_pk_bf16_f32 v8, v8, v9
	ds_read2_b32 v[10:11], v5 offset0:206 offset1:239
	s_waitcnt lgkmcnt(0)
	v_cvt_pk_bf16_f32 v9, v10, v11
	v_or_b32_e32 v10, s10, v42
	v_ashrrev_i32_e32 v11, 31, v10
	v_lshlrev_b64 v[10:11], 11, v[10:11]
	v_lshl_add_u64 v[10:11], v[14:15], 0, v[10:11]
	ds_read2_b32 v[12:13], v5 offset0:16 offset1:49
	global_store_dwordx4 v[10:11], v[6:9], off sc1
	s_waitcnt lgkmcnt(0)
	s_nop 0
	v_cvt_pk_bf16_f32 v6, v12, v13
	ds_read2_b32 v[8:9], v5 offset0:82 offset1:115
	s_waitcnt lgkmcnt(0)
	v_cvt_pk_bf16_f32 v7, v8, v9
	ds_read2_b32 v[8:9], v5 offset0:148 offset1:181
	s_waitcnt lgkmcnt(0)
	v_cvt_pk_bf16_f32 v8, v8, v9
	ds_read2_b32 v[10:11], v5 offset0:214 offset1:247
	s_waitcnt lgkmcnt(0)
	v_cvt_pk_bf16_f32 v9, v10, v11
	v_or_b32_e32 v10, s10, v43
	v_ashrrev_i32_e32 v11, 31, v10
	v_lshlrev_b64 v[10:11], 11, v[10:11]
	v_lshl_add_u64 v[10:11], v[14:15], 0, v[10:11]
	ds_read2_b32 v[12:13], v5 offset0:24 offset1:57
	global_store_dwordx4 v[10:11], v[6:9], off sc1
	s_waitcnt lgkmcnt(0)
	s_nop 0
	v_cvt_pk_bf16_f32 v6, v12, v13
	ds_read2_b32 v[8:9], v5 offset0:90 offset1:123
	s_waitcnt lgkmcnt(0)
	v_cvt_pk_bf16_f32 v7, v8, v9
	ds_read2_b32 v[8:9], v5 offset0:156 offset1:189
	s_waitcnt lgkmcnt(0)
	v_cvt_pk_bf16_f32 v8, v8, v9
	ds_read2_b32 v[10:11], v5 offset0:222 offset1:255
	s_waitcnt lgkmcnt(0)
	v_cvt_pk_bf16_f32 v9, v10, v11
	v_or_b32_e32 v10, s10, v44
	v_ashrrev_i32_e32 v11, 31, v10
	v_lshlrev_b64 v[10:11], 11, v[10:11]
	v_lshl_add_u64 v[10:11], v[14:15], 0, v[10:11]
	global_store_dwordx4 v[10:11], v[6:9], off sc1
	s_waitcnt lgkmcnt(0)

.LBB0_174:
	s_cmp_gt_i32 s20, 0x83ff
	s_mov_b64 s[4:5], -1
	s_cbranch_scc0 .LBB0_205
	s_cmpk_gt_u32 s20, 0x8cbf
	s_cbranch_scc0 .LBB0_185
	s_add_i32 s11, s20, 0xffff7340
	s_lshr_b32 s60, s11, 11
	s_and_b32 s10, s11, 0x7ff
	s_lshl_b64 s[4:5], s[60:61], 23
	s_add_u32 s6, s21, s4
	s_addc_u32 s7, s22, s5
	s_cmpk_gt_u32 s10, 0x5ff
	s_mov_b64 s[4:5], -1
	s_cbranch_scc0 .LBB0_178
	s_load_dwordx2 s[4:5], s[2:3], 0xb0
	s_lshl_b64 s[12:13], s[60:61], 22
	s_waitcnt lgkmcnt(0)
	s_add_u32 s34, s4, s12
	s_addc_u32 s35, s5, s13
	s_lshl_b32 s4, s10, 1
	s_and_b32 s4, s4, 0xfc0
	s_addk_i32 s4, 0xf400
	v_or_b32_e32 v96, s4, v0
	s_and_b32 s12, s27, 0x3e0
	v_lshlrev_b64 v[6:7], 12, v[96:97]
	v_lshl_add_u64 v[6:7], s[34:35], 0, v[6:7]
	s_lshl_b32 s34, s12, 2
	s_mov_b32 s35, s61
	v_lshl_add_u64 v[6:7], v[6:7], 0, s[34:35]
	v_lshlrev_b32_e32 v96, 2, v2
	v_lshl_add_u64 v[6:7], v[6:7], 0, v[96:97]
	v_add_co_u32_e32 v8, vcc, s68, v6
	global_load_dword v10, v[6:7], off
	s_nop 0
	v_addc_co_u32_e32 v9, vcc, 0, v7, vcc
	global_load_dword v11, v[8:9], off
	v_add_co_u32_e32 v8, vcc, s75, v6
	s_mov_b32 s5, 0x10000
	s_nop 0
	v_addc_co_u32_e32 v9, vcc, 0, v7, vcc
	global_load_dword v12, v[8:9], off
	v_add_co_u32_e32 v8, vcc, s79, v6
	v_lshlrev_b32_e32 v96, 1, v4
	s_nop 0
	v_addc_co_u32_e32 v9, vcc, 0, v7, vcc
	global_load_dword v13, v[8:9], off
	v_add_co_u32_e32 v8, vcc, s87, v6
	s_nop 1
	v_addc_co_u32_e32 v9, vcc, 0, v7, vcc
	global_load_dword v14, v[8:9], off
	v_add_co_u32_e32 v8, vcc, s88, v6
	s_nop 1
	v_addc_co_u32_e32 v9, vcc, 0, v7, vcc
	global_load_dword v15, v[8:9], off
	v_add_co_u32_e32 v8, vcc, s62, v6
	s_nop 1
	v_addc_co_u32_e32 v9, vcc, 0, v7, vcc
	global_load_dword v16, v[8:9], off
	v_add_co_u32_e32 v8, vcc, s94, v6
	s_nop 1
	v_addc_co_u32_e32 v9, vcc, 0, v7, vcc
	global_load_dword v17, v[8:9], off
	v_add_co_u32_e32 v8, vcc, s5, v6
	s_mov_b32 s5, 0x22000
	s_nop 0
	v_addc_co_u32_e32 v9, vcc, 0, v7, vcc
	global_load_dword v18, v[8:9], off
	v_add_co_u32_e32 v8, vcc, s72, v6
	s_nop 1
	v_addc_co_u32_e32 v9, vcc, 0, v7, vcc
	global_load_dword v19, v[8:9], off
	v_add_co_u32_e32 v8, vcc, s73, v6
	s_nop 1
	v_addc_co_u32_e32 v9, vcc, 0, v7, vcc
	global_load_dword v20, v[8:9], off
	v_add_co_u32_e32 v8, vcc, s74, v6
	s_nop 1
	v_addc_co_u32_e32 v9, vcc, 0, v7, vcc
	global_load_dword v21, v[8:9], off
	v_add_co_u32_e32 v8, vcc, s85, v6
	s_nop 1
	v_addc_co_u32_e32 v9, vcc, 0, v7, vcc
	global_load_dword v22, v[8:9], off
	v_add_co_u32_e32 v8, vcc, s86, v6
	s_nop 1
	v_addc_co_u32_e32 v9, vcc, 0, v7, vcc
	global_load_dword v23, v[8:9], off
	v_add_co_u32_e32 v8, vcc, s90, v6
	s_nop 1
	v_addc_co_u32_e32 v9, vcc, 0, v7, vcc
	global_load_dword v24, v[8:9], off
	v_add_co_u32_e32 v8, vcc, s91, v6
	s_nop 1
	v_addc_co_u32_e32 v9, vcc, 0, v7, vcc
	global_load_dword v25, v[8:9], off
	v_add_co_u32_e32 v8, vcc, s95, v6
	s_nop 1
	v_addc_co_u32_e32 v9, vcc, 0, v7, vcc
	global_load_dword v26, v[8:9], off
	v_add_co_u32_e32 v8, vcc, s5, v6
	s_mov_b32 s5, 0x24000
	s_nop 0
	v_addc_co_u32_e32 v9, vcc, 0, v7, vcc
	global_load_dword v27, v[8:9], off
	v_add_co_u32_e32 v8, vcc, s5, v6
	s_mov_b32 s5, 0x28000
	s_nop 0
	v_addc_co_u32_e32 v9, vcc, 0, v7, vcc
	global_load_dword v28, v[8:9], off
	v_add_co_u32_e32 v8, vcc, s40, v6
	s_nop 1
	v_addc_co_u32_e32 v9, vcc, 0, v7, vcc
	global_load_dword v29, v[8:9], off
	v_add_co_u32_e32 v8, vcc, s5, v6
	s_mov_b32 s5, 0x2a000
	s_nop 0
	v_addc_co_u32_e32 v9, vcc, 0, v7, vcc
	global_load_dword v30, v[8:9], off
	v_add_co_u32_e32 v8, vcc, s5, v6
	s_mov_b32 s5, 0x2e000
	s_nop 0
	v_addc_co_u32_e32 v9, vcc, 0, v7, vcc
	global_load_dword v31, v[8:9], off
	v_add_co_u32_e32 v8, vcc, s41, v6
	s_nop 1
	v_addc_co_u32_e32 v9, vcc, 0, v7, vcc
	global_load_dword v32, v[8:9], off
	v_add_co_u32_e32 v8, vcc, s5, v6
	s_mov_b32 s5, 0x30000
	s_nop 0
	v_addc_co_u32_e32 v9, vcc, 0, v7, vcc
	global_load_dword v33, v[8:9], off
	v_add_co_u32_e32 v8, vcc, s5, v6
	s_mov_b32 s5, 0x32000
	s_nop 0
	v_addc_co_u32_e32 v9, vcc, 0, v7, vcc
	global_load_dword v34, v[8:9], off
	v_add_co_u32_e32 v8, vcc, s5, v6
	s_mov_b32 s5, 0x34000
	s_nop 0
	v_addc_co_u32_e32 v9, vcc, 0, v7, vcc
	global_load_dword v35, v[8:9], off
	v_add_co_u32_e32 v8, vcc, s5, v6
	s_mov_b32 s5, 0x36000
	s_nop 0
	v_addc_co_u32_e32 v9, vcc, 0, v7, vcc
	global_load_dword v36, v[8:9], off
	v_add_co_u32_e32 v8, vcc, s5, v6
	s_mov_b32 s5, 0x38000
	s_nop 0
	v_addc_co_u32_e32 v9, vcc, 0, v7, vcc
	global_load_dword v37, v[8:9], off
	v_add_co_u32_e32 v8, vcc, s5, v6
	s_mov_b32 s5, 0x3a000
	s_nop 0
	v_addc_co_u32_e32 v9, vcc, 0, v7, vcc
	global_load_dword v38, v[8:9], off
	v_add_co_u32_e32 v8, vcc, s5, v6
	s_mov_b32 s5, 0x3c000
	s_nop 0
	v_addc_co_u32_e32 v9, vcc, 0, v7, vcc
	global_load_dword v39, v[8:9], off
	v_add_co_u32_e32 v8, vcc, s5, v6
	s_mov_b32 s5, 0x3e000
	s_nop 0
	v_addc_co_u32_e32 v9, vcc, 0, v7, vcc
	v_add_co_u32_e32 v6, vcc, s5, v6
	global_load_dword v8, v[8:9], off
	s_nop 0
	v_addc_co_u32_e32 v7, vcc, 0, v7, vcc
	global_load_dword v6, v[6:7], off
	v_add_u32_e32 v7, 0x400, v1
	s_waitcnt vmcnt(0)
	ds_write2_b32 v1, v10, v11 offset1:66
	ds_write2_b32 v1, v12, v13 offset0:132 offset1:198
	ds_write2_b32 v7, v14, v15 offset0:8 offset1:74
	ds_write2_b32 v7, v16, v17 offset0:140 offset1:206
	v_add_u32_e32 v7, 0x800, v1
	ds_write2_b32 v7, v18, v19 offset0:16 offset1:82
	ds_write2_b32 v7, v20, v21 offset0:148 offset1:214
	v_add_u32_e32 v7, 0xc00, v1
	ds_write2_b32 v7, v22, v23 offset0:24 offset1:90
	ds_write2_b32 v7, v24, v25 offset0:156 offset1:222
	v_add_u32_e32 v7, 0x1000, v1
	ds_write2_b32 v7, v26, v27 offset0:32 offset1:98
	ds_write2_b32 v7, v28, v29 offset0:164 offset1:230
	v_add_u32_e32 v7, 0x1400, v1
	ds_write2_b32 v7, v30, v31 offset0:40 offset1:106
	ds_write2_b32 v7, v32, v33 offset0:172 offset1:238
	v_add_u32_e32 v7, 0x1800, v1
	ds_write2_b32 v7, v34, v35 offset0:48 offset1:114
	ds_write2_b32 v7, v36, v37 offset0:180 offset1:246
	v_add_u32_e32 v7, 0x1c00, v1
	ds_write2_b32 v7, v38, v39 offset0:56 offset1:122
	ds_write2_b32 v7, v8, v6 offset0:188 offset1:254
	s_waitcnt lgkmcnt(0)
	s_mov_b32 s5, s61
	ds_read2_b32 v[8:9], v5 offset1:33
	s_lshl_b64 s[4:5], s[4:5], 1
	s_waitcnt lgkmcnt(0)
	v_cvt_pk_bf16_f32 v8, v8, v9
	ds_read2_b32 v[10:11], v5 offset0:66 offset1:99
	s_add_u32 s4, s6, s4
	s_waitcnt lgkmcnt(0)
	v_cvt_pk_bf16_f32 v9, v10, v11
	ds_read2_b32 v[10:11], v5 offset0:132 offset1:165
	s_addc_u32 s5, s7, s5
	s_waitcnt lgkmcnt(0)
	v_cvt_pk_bf16_f32 v10, v10, v11
	ds_read2_b32 v[12:13], v5 offset0:198 offset1:231
	v_lshl_add_u64 v[6:7], s[4:5], 0, v[96:97]
	s_mov_b64 s[4:5], 0x600000
	s_waitcnt lgkmcnt(0)
	v_cvt_pk_bf16_f32 v11, v12, v13
	v_or_b32_e32 v12, s12, v3
	v_lshl_add_u64 v[6:7], v[6:7], 0, s[4:5]
	v_lshlrev_b32_e32 v96, 11, v12
	v_lshl_add_u64 v[12:13], v[6:7], 0, v[96:97]
	global_store_dwordx4 v[12:13], v[8:11], off sc1
	ds_read2_b32 v[8:9], v5 offset0:8 offset1:41
	s_mov_b64 s[4:5], 0
	s_waitcnt lgkmcnt(0)
	v_cvt_pk_bf16_f32 v8, v8, v9
	ds_read2_b32 v[10:11], v5 offset0:74 offset1:107
	s_waitcnt lgkmcnt(0)
	v_cvt_pk_bf16_f32 v9, v10, v11
	ds_read2_b32 v[10:11], v5 offset0:140 offset1:173
	s_waitcnt lgkmcnt(0)
	v_cvt_pk_bf16_f32 v10, v10, v11
	ds_read2_b32 v[12:13], v5 offset0:206 offset1:239
	s_waitcnt lgkmcnt(0)
	v_cvt_pk_bf16_f32 v11, v12, v13
	v_or_b32_e32 v12, s12, v42
	v_lshlrev_b32_e32 v96, 11, v12
	v_lshl_add_u64 v[12:13], v[6:7], 0, v[96:97]
	global_store_dwordx4 v[12:13], v[8:11], off sc1
	ds_read2_b32 v[8:9], v5 offset0:16 offset1:49
	s_waitcnt lgkmcnt(0)
	v_cvt_pk_bf16_f32 v8, v8, v9
	ds_read2_b32 v[10:11], v5 offset0:82 offset1:115
	s_waitcnt lgkmcnt(0)
	v_cvt_pk_bf16_f32 v9, v10, v11
	ds_read2_b32 v[10:11], v5 offset0:148 offset1:181
	s_waitcnt lgkmcnt(0)
	v_cvt_pk_bf16_f32 v10, v10, v11
	ds_read2_b32 v[12:13], v5 offset0:214 offset1:247
	s_waitcnt lgkmcnt(0)
	v_cvt_pk_bf16_f32 v11, v12, v13
	v_or_b32_e32 v12, s12, v43
	v_lshlrev_b32_e32 v96, 11, v12
	v_lshl_add_u64 v[12:13], v[6:7], 0, v[96:97]
	global_store_dwordx4 v[12:13], v[8:11], off sc1
	ds_read2_b32 v[8:9], v5 offset0:24 offset1:57
	s_waitcnt lgkmcnt(0)
	v_cvt_pk_bf16_f32 v8, v8, v9
	ds_read2_b32 v[10:11], v5 offset0:90 offset1:123
	s_waitcnt lgkmcnt(0)
	v_cvt_pk_bf16_f32 v9, v10, v11
	ds_read2_b32 v[10:11], v5 offset0:156 offset1:189
	s_waitcnt lgkmcnt(0)
	v_cvt_pk_bf16_f32 v10, v10, v11
	ds_read2_b32 v[12:13], v5 offset0:222 offset1:255
	s_waitcnt lgkmcnt(0)
	v_cvt_pk_bf16_f32 v11, v12, v13
	v_or_b32_e32 v12, s12, v44
	v_lshlrev_b32_e32 v96, 11, v12
	v_lshl_add_u64 v[6:7], v[6:7], 0, v[96:97]
	global_store_dwordx4 v[6:7], v[8:11], off sc1
	s_waitcnt lgkmcnt(0)

.LBB0_183:
	s_load_dwordx2 s[4:5], s[2:3], 0xa0
	s_load_dwordx2 s[38:39], s[2:3], 0x28
	s_and_b32 s34, s11, 0xfffff800
	s_mul_i32 s29, s60, 0xc00000
	s_mul_hi_u32 s11, s60, 0xc00000
	s_waitcnt lgkmcnt(0)
	s_add_u32 s36, s4, s29
	s_addc_u32 s37, s5, s11
	s_lshl_b32 s4, s13, 6
	s_and_b32 s4, s4, 0xffc0
	s_mov_b32 s35, s61
	v_or_b32_e32 v6, s4, v0
	s_lshl_b64 s[34:35], s[34:35], 2
	v_mul_u32_u24_e32 v6, 0xc00, v6
	s_add_u32 s5, s38, s34
	v_lshlrev_b32_e32 v96, 2, v6
	s_addc_u32 s11, s39, s35
	v_lshl_add_u64 v[6:7], s[36:37], 0, v[96:97]
	s_lshl_b32 s60, s12, 2
	v_lshl_add_u64 v[6:7], v[6:7], 0, s[60:61]
	v_lshlrev_b32_e32 v96, 2, v2
	v_lshl_add_u64 v[6:7], v[6:7], 0, v[96:97]
	v_add_co_u32_e32 v8, vcc, s79, v6
	global_load_dword v10, v[6:7], off
	s_nop 0
	v_addc_co_u32_e32 v9, vcc, 0, v7, vcc
	global_load_dword v11, v[8:9], off
	v_add_co_u32_e32 v8, vcc, s62, v6
	s_mov_b32 s12, 0x24000
	s_nop 0
	v_addc_co_u32_e32 v9, vcc, 0, v7, vcc
	global_load_dword v12, v[8:9], off
	v_add_co_u32_e32 v8, vcc, s72, v6
	v_lshlrev_b32_e32 v96, 2, v0
	s_nop 0
	v_addc_co_u32_e32 v9, vcc, 0, v7, vcc
	global_load_dword v13, v[8:9], off
	v_add_co_u32_e32 v8, vcc, s85, v6
	s_nop 1
	v_addc_co_u32_e32 v9, vcc, 0, v7, vcc
	global_load_dword v14, v[8:9], off
	v_add_co_u32_e32 v8, vcc, s91, v6
	s_nop 1
	v_addc_co_u32_e32 v9, vcc, 0, v7, vcc
	global_load_dword v15, v[8:9], off
	v_add_co_u32_e32 v8, vcc, s12, v6
	s_mov_b32 s12, 0x2a000
	s_nop 0
	v_addc_co_u32_e32 v9, vcc, 0, v7, vcc
	global_load_dword v16, v[8:9], off
	v_add_co_u32_e32 v8, vcc, s12, v6
	s_mov_b32 s12, 0x30000
	s_nop 0
	v_addc_co_u32_e32 v9, vcc, 0, v7, vcc
	global_load_dword v17, v[8:9], off
	v_add_co_u32_e32 v8, vcc, s12, v6
	s_mov_b32 s12, 0x36000
	s_nop 0
	v_addc_co_u32_e32 v9, vcc, 0, v7, vcc
	global_load_dword v18, v[8:9], off
	v_add_co_u32_e32 v8, vcc, s12, v6
	s_mov_b32 s12, 0x3c000
	s_nop 0
	v_addc_co_u32_e32 v9, vcc, 0, v7, vcc
	global_load_dword v19, v[8:9], off
	v_add_co_u32_e32 v8, vcc, s12, v6
	s_mov_b32 s12, 0x42000
	s_nop 0
	v_addc_co_u32_e32 v9, vcc, 0, v7, vcc
	global_load_dword v20, v[8:9], off
	v_add_co_u32_e32 v8, vcc, s12, v6
	s_mov_b32 s12, 0x48000
	s_nop 0
	v_addc_co_u32_e32 v9, vcc, 0, v7, vcc
	global_load_dword v21, v[8:9], off
	v_add_co_u32_e32 v8, vcc, s12, v6
	s_mov_b32 s12, 0x4e000
	s_nop 0
	v_addc_co_u32_e32 v9, vcc, 0, v7, vcc
	global_load_dword v22, v[8:9], off
	v_add_co_u32_e32 v8, vcc, s12, v6
	s_mov_b32 s12, 0x54000
	s_nop 0
	v_addc_co_u32_e32 v9, vcc, 0, v7, vcc
	global_load_dword v23, v[8:9], off
	v_add_co_u32_e32 v8, vcc, s12, v6
	s_mov_b32 s12, 0x5a000
	s_nop 0
	v_addc_co_u32_e32 v9, vcc, 0, v7, vcc
	global_load_dword v24, v[8:9], off
	v_add_co_u32_e32 v8, vcc, s12, v6
	s_mov_b32 s12, 0x60000
	s_nop 0
	v_addc_co_u32_e32 v9, vcc, 0, v7, vcc
	global_load_dword v25, v[8:9], off
	v_add_co_u32_e32 v8, vcc, s12, v6
	s_mov_b32 s12, 0x66000
	s_nop 0
	v_addc_co_u32_e32 v9, vcc, 0, v7, vcc
	global_load_dword v26, v[8:9], off
	v_add_co_u32_e32 v8, vcc, s12, v6
	s_mov_b32 s12, 0x6c000
	s_nop 0
	v_addc_co_u32_e32 v9, vcc, 0, v7, vcc
	global_load_dword v27, v[8:9], off
	v_add_co_u32_e32 v8, vcc, s12, v6
	s_mov_b32 s12, 0x72000
	s_nop 0
	v_addc_co_u32_e32 v9, vcc, 0, v7, vcc
	global_load_dword v28, v[8:9], off
	v_add_co_u32_e32 v8, vcc, s12, v6
	s_mov_b32 s12, 0x78000
	s_nop 0
	v_addc_co_u32_e32 v9, vcc, 0, v7, vcc
	global_load_dword v29, v[8:9], off
	v_add_co_u32_e32 v8, vcc, s12, v6
	s_mov_b32 s12, 0x7e000
	s_nop 0
	v_addc_co_u32_e32 v9, vcc, 0, v7, vcc
	global_load_dword v30, v[8:9], off
	v_add_co_u32_e32 v8, vcc, s12, v6
	s_mov_b32 s12, 0x84000
	s_nop 0
	v_addc_co_u32_e32 v9, vcc, 0, v7, vcc
	global_load_dword v31, v[8:9], off
	v_add_co_u32_e32 v8, vcc, s12, v6
	s_mov_b32 s12, 0x8a000
	s_nop 0
	v_addc_co_u32_e32 v9, vcc, 0, v7, vcc
	global_load_dword v32, v[8:9], off
	v_add_co_u32_e32 v8, vcc, s12, v6
	s_mov_b32 s12, 0x90000
	s_nop 0
	v_addc_co_u32_e32 v9, vcc, 0, v7, vcc
	global_load_dword v33, v[8:9], off
	v_add_co_u32_e32 v8, vcc, s12, v6
	s_mov_b32 s12, 0x96000
	s_nop 0
	v_addc_co_u32_e32 v9, vcc, 0, v7, vcc
	global_load_dword v34, v[8:9], off
	v_add_co_u32_e32 v8, vcc, s12, v6
	s_mov_b32 s12, 0x9c000
	s_nop 0
	v_addc_co_u32_e32 v9, vcc, 0, v7, vcc
	global_load_dword v35, v[8:9], off
	v_add_co_u32_e32 v8, vcc, s12, v6
	s_mov_b32 s12, 0xa2000
	s_nop 0
	v_addc_co_u32_e32 v9, vcc, 0, v7, vcc
	global_load_dword v36, v[8:9], off
	v_add_co_u32_e32 v8, vcc, s12, v6
	s_mov_b32 s12, 0xa8000
	s_nop 0
	v_addc_co_u32_e32 v9, vcc, 0, v7, vcc
	global_load_dword v37, v[8:9], off
	v_add_co_u32_e32 v8, vcc, s12, v6
	s_mov_b32 s12, 0xae000
	s_nop 0
	v_addc_co_u32_e32 v9, vcc, 0, v7, vcc
	global_load_dword v38, v[8:9], off
	v_add_co_u32_e32 v8, vcc, s12, v6
	s_mov_b32 s12, 0xb4000
	s_nop 0
	v_addc_co_u32_e32 v9, vcc, 0, v7, vcc
	global_load_dword v39, v[8:9], off
	v_add_co_u32_e32 v8, vcc, s12, v6
	s_mov_b32 s12, 0xba000
	s_nop 0
	v_addc_co_u32_e32 v9, vcc, 0, v7, vcc
	v_add_co_u32_e32 v6, vcc, s12, v6
	s_lshl_b32 s12, s4, 2
	s_add_u32 s12, s5, s12
	v_addc_co_u32_e32 v7, vcc, 0, v7, vcc
	s_addc_u32 s13, s11, 0
	global_load_dword v40, v[8:9], off
	global_load_dword v41, v[6:7], off
	v_lshl_add_u64 v[6:7], s[12:13], 0, v[96:97]
	s_mov_b64 s[12:13], 0x1000
	s_movk_i32 s5, 0x1000
	v_lshl_add_u64 v[8:9], v[6:7], 0, s[12:13]
	v_add_co_u32_e32 v6, vcc, s5, v6
	s_lshl_b32 s4, s4, 1
	s_nop 0
	v_addc_co_u32_e32 v7, vcc, 0, v7, vcc
	global_load_dword v6, v[6:7], off
	s_add_u32 s4, s6, s4
	global_load_dword v7, v[8:9], off offset:8
	s_addc_u32 s5, s7, 0
	v_lshlrev_b32_e32 v96, 1, v4
	s_waitcnt vmcnt(0)
	v_mul_f32_e32 v6, v10, v6
	global_load_dword v10, v[8:9], off offset:16
	v_mul_f32_e32 v7, v11, v7
	global_load_dword v11, v[8:9], off offset:24
	s_waitcnt vmcnt(1)
	v_mul_f32_e32 v10, v12, v10
	global_load_dword v12, v[8:9], off offset:32
	s_waitcnt vmcnt(1)
	v_mul_f32_e32 v11, v13, v11
	global_load_dword v13, v[8:9], off offset:40
	s_waitcnt vmcnt(1)
	v_mul_f32_e32 v12, v14, v12
	global_load_dword v14, v[8:9], off offset:48
	s_waitcnt vmcnt(1)
	v_mul_f32_e32 v13, v15, v13
	global_load_dword v15, v[8:9], off offset:56
	s_waitcnt vmcnt(1)
	v_mul_f32_e32 v14, v16, v14
	global_load_dword v16, v[8:9], off offset:64
	s_waitcnt vmcnt(1)
	v_mul_f32_e32 v15, v17, v15
	global_load_dword v17, v[8:9], off offset:72
	s_waitcnt vmcnt(1)
	v_mul_f32_e32 v16, v18, v16
	global_load_dword v18, v[8:9], off offset:80
	s_waitcnt vmcnt(1)
	v_mul_f32_e32 v17, v19, v17
	global_load_dword v19, v[8:9], off offset:88
	s_waitcnt vmcnt(1)
	v_mul_f32_e32 v18, v20, v18
	global_load_dword v20, v[8:9], off offset:96
	s_waitcnt vmcnt(1)
	v_mul_f32_e32 v19, v21, v19
	global_load_dword v21, v[8:9], off offset:104
	s_waitcnt vmcnt(1)
	v_mul_f32_e32 v20, v22, v20
	global_load_dword v22, v[8:9], off offset:112
	s_waitcnt vmcnt(1)
	v_mul_f32_e32 v21, v23, v21
	global_load_dword v23, v[8:9], off offset:120
	s_waitcnt vmcnt(1)
	v_mul_f32_e32 v22, v24, v22
	global_load_dword v24, v[8:9], off offset:128
	s_waitcnt vmcnt(1)
	v_mul_f32_e32 v23, v25, v23
	global_load_dword v25, v[8:9], off offset:136
	s_waitcnt vmcnt(1)
	v_mul_f32_e32 v24, v26, v24
	global_load_dword v26, v[8:9], off offset:144
	s_waitcnt vmcnt(1)
	v_mul_f32_e32 v25, v27, v25
	global_load_dword v27, v[8:9], off offset:152
	s_waitcnt vmcnt(1)
	v_mul_f32_e32 v26, v28, v26
	global_load_dword v28, v[8:9], off offset:160
	s_waitcnt vmcnt(1)
	v_mul_f32_e32 v27, v29, v27
	global_load_dword v29, v[8:9], off offset:168
	s_waitcnt vmcnt(1)
	v_mul_f32_e32 v28, v30, v28
	global_load_dword v30, v[8:9], off offset:176
	s_waitcnt vmcnt(1)
	v_mul_f32_e32 v29, v31, v29
	global_load_dword v31, v[8:9], off offset:184
	s_waitcnt vmcnt(1)
	v_mul_f32_e32 v30, v32, v30
	global_load_dword v32, v[8:9], off offset:192
	s_waitcnt vmcnt(1)
	v_mul_f32_e32 v31, v33, v31
	global_load_dword v33, v[8:9], off offset:200
	s_waitcnt vmcnt(1)
	v_mul_f32_e32 v32, v34, v32
	global_load_dword v34, v[8:9], off offset:208
	s_waitcnt vmcnt(1)
	v_mul_f32_e32 v33, v35, v33
	global_load_dword v35, v[8:9], off offset:216
	s_waitcnt vmcnt(1)
	v_mul_f32_e32 v34, v36, v34
	global_load_dword v36, v[8:9], off offset:224
	s_waitcnt vmcnt(1)
	v_mul_f32_e32 v35, v37, v35
	global_load_dword v37, v[8:9], off offset:232
	s_waitcnt vmcnt(1)
	v_mul_f32_e32 v36, v38, v36
	global_load_dword v38, v[8:9], off offset:240
	s_waitcnt vmcnt(1)
	v_mul_f32_e32 v37, v39, v37
	global_load_dword v8, v[8:9], off offset:248
	ds_write2_b32 v1, v6, v7 offset1:66
	ds_write2_b32 v1, v10, v11 offset0:132 offset1:198
	v_add_u32_e32 v6, 0x400, v1
	ds_write2_b32 v6, v12, v13 offset0:8 offset1:74
	ds_write2_b32 v6, v14, v15 offset0:140 offset1:206
	v_add_u32_e32 v6, 0x800, v1
	ds_write2_b32 v6, v16, v17 offset0:16 offset1:82
	ds_write2_b32 v6, v18, v19 offset0:148 offset1:214
	v_add_u32_e32 v6, 0xc00, v1
	ds_write2_b32 v6, v20, v21 offset0:24 offset1:90
	ds_write2_b32 v6, v22, v23 offset0:156 offset1:222
	v_add_u32_e32 v6, 0x1000, v1
	ds_write2_b32 v6, v24, v25 offset0:32 offset1:98
	ds_write2_b32 v6, v26, v27 offset0:164 offset1:230
	v_add_u32_e32 v6, 0x1400, v1
	ds_write2_b32 v6, v28, v29 offset0:40 offset1:106
	ds_write2_b32 v6, v30, v31 offset0:172 offset1:238
	v_add_u32_e32 v6, 0x1800, v1
	ds_write2_b32 v6, v32, v33 offset0:48 offset1:114
	ds_write2_b32 v6, v34, v35 offset0:180 offset1:246
	v_add_u32_e32 v6, 0x1c00, v1
	v_lshl_add_u64 v[10:11], s[4:5], 0, v[96:97]
	v_add_u32_e32 v96, s10, v3
	s_waitcnt vmcnt(1)
	v_mul_f32_e32 v38, v40, v38
	s_waitcnt vmcnt(0)
	v_mul_f32_e32 v8, v41, v8
	ds_write2_b32 v6, v36, v37 offset0:56 offset1:122
	ds_write2_b32 v6, v38, v8 offset0:188 offset1:254
	s_waitcnt lgkmcnt(0)
	ds_read2_b32 v[6:7], v5 offset1:33
	s_waitcnt lgkmcnt(0)
	v_cvt_pk_bf16_f32 v6, v6, v7
	ds_read2_b32 v[8:9], v5 offset0:66 offset1:99
	s_waitcnt lgkmcnt(0)
	v_cvt_pk_bf16_f32 v7, v8, v9
	ds_read2_b32 v[8:9], v5 offset0:132 offset1:165
	s_waitcnt lgkmcnt(0)
	v_cvt_pk_bf16_f32 v8, v8, v9
	ds_read2_b32 v[12:13], v5 offset0:198 offset1:231
	s_waitcnt lgkmcnt(0)
	v_cvt_pk_bf16_f32 v9, v12, v13
	v_lshlrev_b64 v[12:13], 11, v[96:97]
	v_lshl_add_u64 v[12:13], v[10:11], 0, v[12:13]
	global_store_dwordx4 v[12:13], v[6:9], off sc1
	ds_read2_b32 v[6:7], v5 offset0:8 offset1:41
	v_add_u32_e32 v96, s10, v42
	s_waitcnt lgkmcnt(0)
	v_cvt_pk_bf16_f32 v6, v6, v7
	ds_read2_b32 v[8:9], v5 offset0:74 offset1:107
	s_waitcnt lgkmcnt(0)
	v_cvt_pk_bf16_f32 v7, v8, v9
	ds_read2_b32 v[8:9], v5 offset0:140 offset1:173
	s_waitcnt lgkmcnt(0)
	v_cvt_pk_bf16_f32 v8, v8, v9
	ds_read2_b32 v[12:13], v5 offset0:206 offset1:239
	s_waitcnt lgkmcnt(0)
	v_cvt_pk_bf16_f32 v9, v12, v13
	v_lshlrev_b64 v[12:13], 11, v[96:97]
	v_lshl_add_u64 v[12:13], v[10:11], 0, v[12:13]
	global_store_dwordx4 v[12:13], v[6:9], off sc1
	ds_read2_b32 v[6:7], v5 offset0:16 offset1:49
	v_add_u32_e32 v96, s10, v43
	s_waitcnt lgkmcnt(0)
	v_cvt_pk_bf16_f32 v6, v6, v7
	ds_read2_b32 v[8:9], v5 offset0:82 offset1:115
	s_waitcnt lgkmcnt(0)
	v_cvt_pk_bf16_f32 v7, v8, v9
	ds_read2_b32 v[8:9], v5 offset0:148 offset1:181
	s_waitcnt lgkmcnt(0)
	v_cvt_pk_bf16_f32 v8, v8, v9
	ds_read2_b32 v[12:13], v5 offset0:214 offset1:247
	s_waitcnt lgkmcnt(0)
	v_cvt_pk_bf16_f32 v9, v12, v13
	v_lshlrev_b64 v[12:13], 11, v[96:97]
	v_lshl_add_u64 v[12:13], v[10:11], 0, v[12:13]
	global_store_dwordx4 v[12:13], v[6:9], off sc1
	ds_read2_b32 v[6:7], v5 offset0:24 offset1:57
	v_add_u32_e32 v96, s10, v44
	s_waitcnt lgkmcnt(0)
	v_cvt_pk_bf16_f32 v6, v6, v7
	ds_read2_b32 v[8:9], v5 offset0:90 offset1:123
	s_waitcnt lgkmcnt(0)
	v_cvt_pk_bf16_f32 v7, v8, v9
	ds_read2_b32 v[8:9], v5 offset0:156 offset1:189
	s_waitcnt lgkmcnt(0)
	v_cvt_pk_bf16_f32 v8, v8, v9
	ds_read2_b32 v[12:13], v5 offset0:222 offset1:255
	s_waitcnt lgkmcnt(0)
	v_cvt_pk_bf16_f32 v9, v12, v13
	v_lshlrev_b64 v[12:13], 11, v[96:97]
	v_lshl_add_u64 v[10:11], v[10:11], 0, v[12:13]
	global_store_dwordx4 v[10:11], v[6:9], off sc1
	s_waitcnt lgkmcnt(0)

.LBB0_185:
	s_andn2_b64 vcc, exec, s[4:5]
	s_cbranch_vccnz .LBB0_204
	s_add_i32 s4, s20, 0xffff7c00
	s_cmpk_gt_u32 s4, 0x45f
	s_cselect_b64 s[12:13], -1, 0
	s_add_i32 s5, s20, 0xffff77a0
	s_cmpk_lt_u32 s4, 0x460
	s_cselect_b32 s29, s4, s5
	s_and_b64 s[4:5], s[12:13], exec
	s_cselect_b32 s4, 0x600000, 0
	s_add_u32 s10, s23, s4
	s_addc_u32 s11, s24, 0
	s_cmpk_gt_u32 s29, 0x24f
	s_mov_b64 s[4:5], -1
	s_cbranch_scc0 .LBB0_200
	s_cmpk_gt_u32 s29, 0x2df
	s_cbranch_scc0 .LBB0_195
	s_cmpk_gt_u32 s29, 0x35f
	s_cbranch_scc0 .LBB0_190
	s_load_dwordx2 s[4:5], s[2:3], 0x98
	s_and_b64 s[6:7], s[12:13], exec
	s_cselect_b32 s6, 0x400000, 0
	v_lshlrev_b32_e32 v96, 2, v2
	s_waitcnt lgkmcnt(0)
	s_add_u32 s34, s4, s6
	s_addc_u32 s35, s5, 0
	s_lshl_b32 s4, s29, 1
	s_and_b32 s4, s4, 0xfc0
	s_addk_i32 s4, 0xfb40
	v_or_b32_e32 v6, s4, v0
	s_lshl_b32 s5, s29, 5
	v_ashrrev_i32_e32 v7, 31, v6
	s_and_b32 s6, s5, 0x3e0
	v_lshlrev_b64 v[6:7], 12, v[6:7]
	v_lshl_add_u64 v[6:7], s[34:35], 0, v[6:7]
	s_lshl_b32 s60, s6, 2
	v_lshl_add_u64 v[6:7], v[6:7], 0, s[60:61]
	v_lshl_add_u64 v[6:7], v[6:7], 0, v[96:97]
	v_add_co_u32_e32 v8, vcc, s68, v6
	global_load_dword v10, v[6:7], off
	s_nop 0
	v_addc_co_u32_e32 v9, vcc, 0, v7, vcc
	global_load_dword v11, v[8:9], off
	v_add_co_u32_e32 v8, vcc, s75, v6
	s_mov_b32 s5, 0x10000
	s_nop 0
	v_addc_co_u32_e32 v9, vcc, 0, v7, vcc
	global_load_dword v12, v[8:9], off
	v_add_co_u32_e32 v8, vcc, s79, v6
	v_lshlrev_b32_e32 v96, 1, v4
	s_nop 0
	v_addc_co_u32_e32 v9, vcc, 0, v7, vcc
	global_load_dword v13, v[8:9], off
	v_add_co_u32_e32 v8, vcc, s87, v6
	s_mov_b64 s[34:35], 0x390000
	s_nop 0
	v_addc_co_u32_e32 v9, vcc, 0, v7, vcc
	global_load_dword v14, v[8:9], off
	v_add_co_u32_e32 v8, vcc, s88, v6
	s_nop 1
	v_addc_co_u32_e32 v9, vcc, 0, v7, vcc
	global_load_dword v15, v[8:9], off
	v_add_co_u32_e32 v8, vcc, s62, v6
	s_nop 1
	v_addc_co_u32_e32 v9, vcc, 0, v7, vcc
	global_load_dword v16, v[8:9], off
	v_add_co_u32_e32 v8, vcc, s94, v6
	s_nop 1
	v_addc_co_u32_e32 v9, vcc, 0, v7, vcc
	global_load_dword v17, v[8:9], off
	v_add_co_u32_e32 v8, vcc, s5, v6
	s_mov_b32 s5, 0x22000
	s_nop 0
	v_addc_co_u32_e32 v9, vcc, 0, v7, vcc
	global_load_dword v18, v[8:9], off
	v_add_co_u32_e32 v8, vcc, s72, v6
	s_nop 1
	v_addc_co_u32_e32 v9, vcc, 0, v7, vcc
	global_load_dword v19, v[8:9], off
	v_add_co_u32_e32 v8, vcc, s73, v6
	s_nop 1
	v_addc_co_u32_e32 v9, vcc, 0, v7, vcc
	global_load_dword v20, v[8:9], off
	v_add_co_u32_e32 v8, vcc, s74, v6
	s_nop 1
	v_addc_co_u32_e32 v9, vcc, 0, v7, vcc
	global_load_dword v21, v[8:9], off
	v_add_co_u32_e32 v8, vcc, s85, v6
	s_nop 1
	v_addc_co_u32_e32 v9, vcc, 0, v7, vcc
	global_load_dword v22, v[8:9], off
	v_add_co_u32_e32 v8, vcc, s86, v6
	s_nop 1
	v_addc_co_u32_e32 v9, vcc, 0, v7, vcc
	global_load_dword v23, v[8:9], off
	v_add_co_u32_e32 v8, vcc, s90, v6
	s_nop 1
	v_addc_co_u32_e32 v9, vcc, 0, v7, vcc
	global_load_dword v24, v[8:9], off
	v_add_co_u32_e32 v8, vcc, s91, v6
	s_nop 1
	v_addc_co_u32_e32 v9, vcc, 0, v7, vcc
	global_load_dword v25, v[8:9], off
	v_add_co_u32_e32 v8, vcc, s95, v6
	s_nop 1
	v_addc_co_u32_e32 v9, vcc, 0, v7, vcc
	global_load_dword v26, v[8:9], off
	v_add_co_u32_e32 v8, vcc, s5, v6
	s_mov_b32 s5, 0x24000
	s_nop 0
	v_addc_co_u32_e32 v9, vcc, 0, v7, vcc
	global_load_dword v27, v[8:9], off
	v_add_co_u32_e32 v8, vcc, s5, v6
	s_mov_b32 s5, 0x28000
	s_nop 0
	v_addc_co_u32_e32 v9, vcc, 0, v7, vcc
	global_load_dword v28, v[8:9], off
	v_add_co_u32_e32 v8, vcc, s40, v6
	s_nop 1
	v_addc_co_u32_e32 v9, vcc, 0, v7, vcc
	global_load_dword v29, v[8:9], off
	v_add_co_u32_e32 v8, vcc, s5, v6
	s_mov_b32 s5, 0x2a000
	s_nop 0
	v_addc_co_u32_e32 v9, vcc, 0, v7, vcc
	global_load_dword v30, v[8:9], off
	v_add_co_u32_e32 v8, vcc, s5, v6
	s_mov_b32 s5, 0x2e000
	s_nop 0
	v_addc_co_u32_e32 v9, vcc, 0, v7, vcc
	global_load_dword v31, v[8:9], off
	v_add_co_u32_e32 v8, vcc, s41, v6
	s_nop 1
	v_addc_co_u32_e32 v9, vcc, 0, v7, vcc
	global_load_dword v32, v[8:9], off
	v_add_co_u32_e32 v8, vcc, s5, v6
	s_mov_b32 s5, 0x30000
	s_nop 0
	v_addc_co_u32_e32 v9, vcc, 0, v7, vcc
	global_load_dword v33, v[8:9], off
	v_add_co_u32_e32 v8, vcc, s5, v6
	s_mov_b32 s5, 0x32000
	s_nop 0
	v_addc_co_u32_e32 v9, vcc, 0, v7, vcc
	global_load_dword v34, v[8:9], off
	v_add_co_u32_e32 v8, vcc, s5, v6
	s_mov_b32 s5, 0x34000
	s_nop 0
	v_addc_co_u32_e32 v9, vcc, 0, v7, vcc
	global_load_dword v35, v[8:9], off
	v_add_co_u32_e32 v8, vcc, s5, v6
	s_mov_b32 s5, 0x36000
	s_nop 0
	v_addc_co_u32_e32 v9, vcc, 0, v7, vcc
	global_load_dword v36, v[8:9], off
	v_add_co_u32_e32 v8, vcc, s5, v6
	s_mov_b32 s5, 0x38000
	s_nop 0
	v_addc_co_u32_e32 v9, vcc, 0, v7, vcc
	global_load_dword v37, v[8:9], off
	v_add_co_u32_e32 v8, vcc, s5, v6
	s_mov_b32 s5, 0x3a000
	s_nop 0
	v_addc_co_u32_e32 v9, vcc, 0, v7, vcc
	global_load_dword v38, v[8:9], off
	v_add_co_u32_e32 v8, vcc, s5, v6
	s_mov_b32 s5, 0x3c000
	s_nop 0
	v_addc_co_u32_e32 v9, vcc, 0, v7, vcc
	global_load_dword v39, v[8:9], off
	v_add_co_u32_e32 v8, vcc, s5, v6
	s_mov_b32 s5, 0x3e000
	s_nop 0
	v_addc_co_u32_e32 v9, vcc, 0, v7, vcc
	v_add_co_u32_e32 v6, vcc, s5, v6
	global_load_dword v8, v[8:9], off
	s_nop 0
	v_addc_co_u32_e32 v7, vcc, 0, v7, vcc
	global_load_dword v6, v[6:7], off
	v_add_u32_e32 v7, 0x400, v1
	s_waitcnt vmcnt(0)
	ds_write2_b32 v1, v10, v11 offset1:66
	ds_write2_b32 v1, v12, v13 offset0:132 offset1:198
	ds_write2_b32 v7, v14, v15 offset0:8 offset1:74
	ds_write2_b32 v7, v16, v17 offset0:140 offset1:206
	v_add_u32_e32 v7, 0x800, v1
	ds_write2_b32 v7, v18, v19 offset0:16 offset1:82
	ds_write2_b32 v7, v20, v21 offset0:148 offset1:214
	v_add_u32_e32 v7, 0xc00, v1
	ds_write2_b32 v7, v22, v23 offset0:24 offset1:90
	ds_write2_b32 v7, v24, v25 offset0:156 offset1:222
	v_add_u32_e32 v7, 0x1000, v1
	ds_write2_b32 v7, v26, v27 offset0:32 offset1:98
	ds_write2_b32 v7, v28, v29 offset0:164 offset1:230
	v_add_u32_e32 v7, 0x1400, v1
	ds_write2_b32 v7, v30, v31 offset0:40 offset1:106
	ds_write2_b32 v7, v32, v33 offset0:172 offset1:238
	v_add_u32_e32 v7, 0x1800, v1
	ds_write2_b32 v7, v34, v35 offset0:48 offset1:114
	ds_write2_b32 v7, v36, v37 offset0:180 offset1:246
	v_add_u32_e32 v7, 0x1c00, v1
	ds_write2_b32 v7, v38, v39 offset0:56 offset1:122
	ds_write2_b32 v7, v8, v6 offset0:188 offset1:254
	s_waitcnt lgkmcnt(0)
	v_lshl_add_u64 v[6:7], s[10:11], 0, v[96:97]
	v_lshl_add_u64 v[10:11], v[6:7], 0, s[34:35]
	ds_read2_b32 v[6:7], v5 offset1:33
	s_waitcnt lgkmcnt(0)
	v_cvt_pk_bf16_f32 v6, v6, v7
	ds_read2_b32 v[8:9], v5 offset0:66 offset1:99
	s_waitcnt lgkmcnt(0)
	v_cvt_pk_bf16_f32 v7, v8, v9
	ds_read2_b32 v[8:9], v5 offset0:132 offset1:165
	s_waitcnt lgkmcnt(0)
	v_cvt_pk_bf16_f32 v8, v8, v9
	ds_read2_b32 v[12:13], v5 offset0:198 offset1:231
	s_waitcnt lgkmcnt(0)
	v_cvt_pk_bf16_f32 v9, v12, v13
	v_or_b32_e32 v12, s6, v3
	s_ashr_i32 s5, s4, 31
	v_lshlrev_b32_e32 v96, 11, v12
	v_lshl_add_u64 v[12:13], v[10:11], 0, v[96:97]
	s_lshl_b64 s[4:5], s[4:5], 1
	v_lshl_add_u64 v[12:13], v[12:13], 0, s[4:5]
	global_store_dwordx4 v[12:13], v[6:9], off sc1
	ds_read2_b32 v[6:7], v5 offset0:8 offset1:41
	s_waitcnt lgkmcnt(0)
	v_cvt_pk_bf16_f32 v6, v6, v7
	ds_read2_b32 v[8:9], v5 offset0:74 offset1:107
	s_waitcnt lgkmcnt(0)
	v_cvt_pk_bf16_f32 v7, v8, v9
	ds_read2_b32 v[8:9], v5 offset0:140 offset1:173
	s_waitcnt lgkmcnt(0)
	v_cvt_pk_bf16_f32 v8, v8, v9
	ds_read2_b32 v[12:13], v5 offset0:206 offset1:239
	s_waitcnt lgkmcnt(0)
	v_cvt_pk_bf16_f32 v9, v12, v13
	v_or_b32_e32 v12, s6, v42
	v_lshlrev_b32_e32 v96, 11, v12
	v_lshl_add_u64 v[12:13], v[10:11], 0, v[96:97]
	v_lshl_add_u64 v[12:13], v[12:13], 0, s[4:5]
	global_store_dwordx4 v[12:13], v[6:9], off sc1
	ds_read2_b32 v[6:7], v5 offset0:16 offset1:49
	s_waitcnt lgkmcnt(0)
	v_cvt_pk_bf16_f32 v6, v6, v7
	ds_read2_b32 v[8:9], v5 offset0:82 offset1:115
	s_waitcnt lgkmcnt(0)
	v_cvt_pk_bf16_f32 v7, v8, v9
	ds_read2_b32 v[8:9], v5 offset0:148 offset1:181
	s_waitcnt lgkmcnt(0)
	v_cvt_pk_bf16_f32 v8, v8, v9
	ds_read2_b32 v[12:13], v5 offset0:214 offset1:247
	s_waitcnt lgkmcnt(0)
	v_cvt_pk_bf16_f32 v9, v12, v13
	v_or_b32_e32 v12, s6, v43
	v_lshlrev_b32_e32 v96, 11, v12
	v_lshl_add_u64 v[12:13], v[10:11], 0, v[96:97]
	v_lshl_add_u64 v[12:13], v[12:13], 0, s[4:5]
	global_store_dwordx4 v[12:13], v[6:9], off sc1
	ds_read2_b32 v[6:7], v5 offset0:24 offset1:57
	s_waitcnt lgkmcnt(0)
	v_cvt_pk_bf16_f32 v6, v6, v7
	ds_read2_b32 v[8:9], v5 offset0:90 offset1:123
	s_waitcnt lgkmcnt(0)
	v_cvt_pk_bf16_f32 v7, v8, v9
	ds_read2_b32 v[8:9], v5 offset0:156 offset1:189
	s_waitcnt lgkmcnt(0)
	v_cvt_pk_bf16_f32 v8, v8, v9
	ds_read2_b32 v[12:13], v5 offset0:222 offset1:255
	s_waitcnt lgkmcnt(0)
	v_cvt_pk_bf16_f32 v9, v12, v13
	v_or_b32_e32 v12, s6, v44
	v_lshlrev_b32_e32 v96, 11, v12
	v_lshl_add_u64 v[10:11], v[10:11], 0, v[96:97]
	v_lshl_add_u64 v[10:11], v[10:11], 0, s[4:5]
	global_store_dwordx4 v[10:11], v[6:9], off sc1
	s_waitcnt lgkmcnt(0)
	s_mov_b64 s[4:5], 0

.LBB0_193:
	s_waitcnt vmcnt(0)
	ds_write2_b32 v1, v6, v7 offset1:66
	ds_write2_b32 v1, v8, v9 offset0:132 offset1:198
	v_add_u32_e32 v6, 0x400, v1
	ds_write2_b32 v6, v10, v11 offset0:8 offset1:74
	ds_write2_b32 v6, v12, v13 offset0:140 offset1:206
	v_add_u32_e32 v6, 0x800, v1
	ds_write2_b32 v6, v14, v15 offset0:16 offset1:82
	ds_write2_b32 v6, v16, v17 offset0:148 offset1:214
	v_add_u32_e32 v6, 0xc00, v1
	s_lshl_b32 s4, s29, 5
	ds_write2_b32 v6, v18, v19 offset0:24 offset1:90
	ds_write2_b32 v6, v20, v21 offset0:156 offset1:222
	v_add_u32_e32 v6, 0x1000, v1
	s_bitcmp0_b32 s29, 1
	s_mov_b32 s5, 0x310000
	ds_write2_b32 v6, v22, v23 offset0:32 offset1:98
	ds_write2_b32 v6, v24, v25 offset0:164 offset1:230
	v_add_u32_e32 v6, 0x1400, v1
	s_cselect_b32 s5, s5, 0x350000
	ds_write2_b32 v6, v26, v27 offset0:40 offset1:106
	ds_write2_b32 v6, v28, v29 offset0:172 offset1:238
	v_add_u32_e32 v6, 0x1800, v1
	s_add_u32 s6, s10, s5
	ds_write2_b32 v6, v30, v31 offset0:48 offset1:114
	ds_write2_b32 v6, v32, v33 offset0:180 offset1:246
	v_add_u32_e32 v6, 0x1c00, v1
	s_addc_u32 s7, s11, 0
	s_lshl_b32 s5, s29, 4
	ds_write2_b32 v6, v34, v35 offset0:56 offset1:122
	ds_write2_b32 v6, v36, v37 offset0:188 offset1:254
	s_and_b32 s5, s5, 0x1c0
	s_and_b32 s4, s4, 32
	s_waitcnt lgkmcnt(0)
	s_or_b32 s31, s5, s4
	s_lshl_b64 s[4:5], s[60:61], 1
	ds_read2_b32 v[6:7], v5 offset1:33
	s_add_u32 s4, s6, s4
	s_waitcnt lgkmcnt(0)
	v_cvt_pk_bf16_f32 v6, v6, v7
	ds_read2_b32 v[8:9], v5 offset0:66 offset1:99
	s_addc_u32 s5, s7, s5
	v_lshlrev_b32_e32 v96, 1, v4
	v_or_b32_e32 v14, s31, v3
	s_waitcnt lgkmcnt(0)
	v_cvt_pk_bf16_f32 v7, v8, v9
	ds_read2_b32 v[8:9], v5 offset0:132 offset1:165
	v_lshl_add_u64 v[12:13], s[4:5], 0, v[96:97]
	v_lshlrev_b32_e32 v96, 9, v14
	s_waitcnt lgkmcnt(0)
	v_cvt_pk_bf16_f32 v8, v8, v9
	ds_read2_b32 v[10:11], v5 offset0:198 offset1:231
	s_waitcnt lgkmcnt(0)
	v_cvt_pk_bf16_f32 v9, v10, v11
	v_lshl_add_u64 v[14:15], v[12:13], 0, v[96:97]
	ds_read2_b32 v[10:11], v5 offset0:8 offset1:41
	global_store_dwordx4 v[14:15], v[6:9], off sc1
	v_or_b32_e32 v14, s31, v42
	v_lshlrev_b32_e32 v96, 9, v14
	s_waitcnt lgkmcnt(0)
	v_cvt_pk_bf16_f32 v6, v10, v11
	ds_read2_b32 v[8:9], v5 offset0:74 offset1:107
	s_waitcnt lgkmcnt(0)
	v_cvt_pk_bf16_f32 v7, v8, v9
	ds_read2_b32 v[8:9], v5 offset0:140 offset1:173
	s_waitcnt lgkmcnt(0)
	v_cvt_pk_bf16_f32 v8, v8, v9
	ds_read2_b32 v[10:11], v5 offset0:206 offset1:239
	s_waitcnt lgkmcnt(0)
	v_cvt_pk_bf16_f32 v9, v10, v11
	v_lshl_add_u64 v[14:15], v[12:13], 0, v[96:97]
	ds_read2_b32 v[10:11], v5 offset0:16 offset1:49
	global_store_dwordx4 v[14:15], v[6:9], off sc1
	v_or_b32_e32 v14, s31, v43
	v_lshlrev_b32_e32 v96, 9, v14
	s_waitcnt lgkmcnt(0)
	v_cvt_pk_bf16_f32 v6, v10, v11
	ds_read2_b32 v[8:9], v5 offset0:82 offset1:115
	s_waitcnt lgkmcnt(0)
	v_cvt_pk_bf16_f32 v7, v8, v9
	ds_read2_b32 v[8:9], v5 offset0:148 offset1:181
	s_waitcnt lgkmcnt(0)
	v_cvt_pk_bf16_f32 v8, v8, v9
	ds_read2_b32 v[10:11], v5 offset0:214 offset1:247
	s_waitcnt lgkmcnt(0)
	v_cvt_pk_bf16_f32 v9, v10, v11
	v_lshl_add_u64 v[14:15], v[12:13], 0, v[96:97]
	ds_read2_b32 v[10:11], v5 offset0:24 offset1:57
	global_store_dwordx4 v[14:15], v[6:9], off sc1
	s_waitcnt lgkmcnt(0)
	s_nop 0
	v_cvt_pk_bf16_f32 v6, v10, v11
	ds_read2_b32 v[8:9], v5 offset0:90 offset1:123
	s_waitcnt lgkmcnt(0)
	v_cvt_pk_bf16_f32 v7, v8, v9
	ds_read2_b32 v[8:9], v5 offset0:156 offset1:189
	s_waitcnt lgkmcnt(0)
	v_cvt_pk_bf16_f32 v8, v8, v9
	v_or_b32_e32 v9, s31, v44
	ds_read2_b32 v[10:11], v5 offset0:222 offset1:255
	v_lshlrev_b32_e32 v96, 9, v9
	s_waitcnt lgkmcnt(0)
	v_cvt_pk_bf16_f32 v9, v10, v11
	v_lshl_add_u64 v[10:11], v[12:13], 0, v[96:97]
	global_store_dwordx4 v[10:11], v[6:9], off sc1
	s_waitcnt lgkmcnt(0)

.LBB0_198:
	s_waitcnt vmcnt(0)
	ds_write2_b32 v1, v6, v7 offset1:66
	ds_write2_b32 v1, v8, v9 offset0:132 offset1:198
	v_add_u32_e32 v6, 0x400, v1
	ds_write2_b32 v6, v10, v11 offset0:8 offset1:74
	ds_write2_b32 v6, v12, v13 offset0:140 offset1:206
	v_add_u32_e32 v6, 0x800, v1
	ds_write2_b32 v6, v14, v15 offset0:16 offset1:82
	ds_write2_b32 v6, v16, v17 offset0:148 offset1:214
	v_add_u32_e32 v6, 0xc00, v1
	ds_write2_b32 v6, v18, v19 offset0:24 offset1:90
	ds_write2_b32 v6, v20, v21 offset0:156 offset1:222
	v_add_u32_e32 v6, 0x1000, v1
	ds_write2_b32 v6, v22, v23 offset0:32 offset1:98
	ds_write2_b32 v6, v24, v25 offset0:164 offset1:230
	v_add_u32_e32 v6, 0x1400, v1
	ds_write2_b32 v6, v26, v27 offset0:40 offset1:106
	ds_write2_b32 v6, v28, v29 offset0:172 offset1:238
	v_add_u32_e32 v6, 0x1800, v1
	ds_write2_b32 v6, v30, v31 offset0:48 offset1:114
	ds_write2_b32 v6, v32, v33 offset0:180 offset1:246
	v_add_u32_e32 v6, 0x1c00, v1
	s_lshl_b32 s7, s31, 5
	s_lshl_b32 s4, s6, 1
	ds_write2_b32 v6, v36, v37 offset0:56 offset1:122
	ds_write2_b32 v6, v38, v39 offset0:188 offset1:254
	s_add_u32 s4, s10, s4
	s_waitcnt lgkmcnt(0)
	s_addc_u32 s5, s11, 0
	v_lshlrev_b32_e32 v96, 1, v4
	v_or_b32_e32 v14, s7, v3
	ds_read2_b32 v[6:7], v5 offset1:33
	v_lshl_add_u64 v[12:13], s[4:5], 0, v[96:97]
	s_mov_b64 s[4:5], 0x280000
	v_mul_u32_u24_e32 v14, 0x180, v14
	s_waitcnt lgkmcnt(0)
	v_cvt_pk_bf16_f32 v6, v6, v7
	ds_read2_b32 v[8:9], v5 offset0:66 offset1:99
	v_lshl_add_u64 v[12:13], v[12:13], 0, s[4:5]
	v_lshlrev_b32_e32 v96, 1, v14
	s_waitcnt lgkmcnt(0)
	v_cvt_pk_bf16_f32 v7, v8, v9
	ds_read2_b32 v[8:9], v5 offset0:132 offset1:165
	v_lshl_add_u64 v[14:15], v[12:13], 0, v[96:97]
	s_waitcnt lgkmcnt(0)
	v_cvt_pk_bf16_f32 v8, v8, v9
	ds_read2_b32 v[10:11], v5 offset0:198 offset1:231
	s_waitcnt lgkmcnt(0)
	v_cvt_pk_bf16_f32 v9, v10, v11
	global_store_dwordx4 v[14:15], v[6:9], off sc1
	v_or_b32_e32 v14, s7, v42
	v_mul_u32_u24_e32 v14, 0x180, v14
	ds_read2_b32 v[10:11], v5 offset0:8 offset1:41
	s_waitcnt lgkmcnt(0)
	v_cvt_pk_bf16_f32 v6, v10, v11
	ds_read2_b32 v[8:9], v5 offset0:74 offset1:107
	v_lshlrev_b32_e32 v96, 1, v14
	s_waitcnt lgkmcnt(0)
	v_cvt_pk_bf16_f32 v7, v8, v9
	ds_read2_b32 v[8:9], v5 offset0:140 offset1:173
	v_lshl_add_u64 v[14:15], v[12:13], 0, v[96:97]
	s_waitcnt lgkmcnt(0)
	v_cvt_pk_bf16_f32 v8, v8, v9
	ds_read2_b32 v[10:11], v5 offset0:206 offset1:239
	s_waitcnt lgkmcnt(0)
	v_cvt_pk_bf16_f32 v9, v10, v11
	global_store_dwordx4 v[14:15], v[6:9], off sc1
	v_or_b32_e32 v14, s7, v43
	ds_read2_b32 v[10:11], v5 offset0:16 offset1:49
	s_waitcnt lgkmcnt(0)
	v_cvt_pk_bf16_f32 v6, v10, v11
	ds_read2_b32 v[8:9], v5 offset0:82 offset1:115
	v_mul_u32_u24_e32 v14, 0x180, v14
	s_waitcnt lgkmcnt(0)
	v_cvt_pk_bf16_f32 v7, v8, v9
	ds_read2_b32 v[8:9], v5 offset0:148 offset1:181
	v_lshlrev_b32_e32 v96, 1, v14
	s_waitcnt lgkmcnt(0)
	v_cvt_pk_bf16_f32 v8, v8, v9
	ds_read2_b32 v[10:11], v5 offset0:214 offset1:247
	s_waitcnt lgkmcnt(0)
	v_cvt_pk_bf16_f32 v9, v10, v11
	v_lshl_add_u64 v[14:15], v[12:13], 0, v[96:97]
	ds_read2_b32 v[10:11], v5 offset0:24 offset1:57
	global_store_dwordx4 v[14:15], v[6:9], off sc1
	s_waitcnt lgkmcnt(0)
	s_nop 0
	v_cvt_pk_bf16_f32 v6, v10, v11
	ds_read2_b32 v[8:9], v5 offset0:90 offset1:123
	s_waitcnt lgkmcnt(0)
	v_cvt_pk_bf16_f32 v7, v8, v9
	ds_read2_b32 v[8:9], v5 offset0:156 offset1:189
	s_waitcnt lgkmcnt(0)
	v_cvt_pk_bf16_f32 v8, v8, v9
	v_or_b32_e32 v9, s7, v44
	v_mul_u32_u24_e32 v9, 0x180, v9
	ds_read2_b32 v[10:11], v5 offset0:222 offset1:255
	v_lshlrev_b32_e32 v96, 1, v9
	s_waitcnt lgkmcnt(0)
	v_cvt_pk_bf16_f32 v9, v10, v11
	v_lshl_add_u64 v[10:11], v[12:13], 0, v[96:97]
	global_store_dwordx4 v[10:11], v[6:9], off sc1
	s_waitcnt lgkmcnt(0)

.LBB0_203:
	s_waitcnt vmcnt(0)
	ds_write2_b32 v1, v6, v7 offset1:66
	ds_write2_b32 v1, v10, v11 offset0:132 offset1:198
	v_add_u32_e32 v6, 0x400, v1
	ds_write2_b32 v6, v8, v9 offset0:8 offset1:74
	ds_write2_b32 v6, v12, v13 offset0:140 offset1:206
	v_add_u32_e32 v6, 0x800, v1
	ds_write2_b32 v6, v14, v15 offset0:16 offset1:82
	ds_write2_b32 v6, v18, v19 offset0:148 offset1:214
	v_add_u32_e32 v6, 0xc00, v1
	ds_write2_b32 v6, v16, v17 offset0:24 offset1:90
	ds_write2_b32 v6, v20, v21 offset0:156 offset1:222
	v_add_u32_e32 v6, 0x1000, v1
	ds_write2_b32 v6, v22, v23 offset0:32 offset1:98
	ds_write2_b32 v6, v26, v27 offset0:164 offset1:230
	v_add_u32_e32 v6, 0x1400, v1
	ds_write2_b32 v6, v24, v25 offset0:40 offset1:106
	ds_write2_b32 v6, v28, v29 offset0:172 offset1:238
	v_add_u32_e32 v6, 0x1800, v1
	ds_write2_b32 v6, v30, v31 offset0:48 offset1:114
	ds_write2_b32 v6, v36, v37 offset0:180 offset1:246
	v_add_u32_e32 v6, 0x1c00, v1
	ds_write2_b32 v6, v34, v35 offset0:56 offset1:122
	ds_write2_b32 v6, v32, v33 offset0:188 offset1:254
	s_lshl_b32 s4, s6, 5
	s_waitcnt lgkmcnt(0)
	s_and_b32 s6, 0xffff, s4
	s_lshl_b32 s4, s7, 1
	ds_read2_b32 v[6:7], v5 offset1:33
	s_add_u32 s4, s10, s4
	s_waitcnt lgkmcnt(0)
	v_cvt_pk_bf16_f32 v6, v6, v7
	ds_read2_b32 v[8:9], v5 offset0:66 offset1:99
	s_addc_u32 s5, s11, 0
	v_lshlrev_b32_e32 v96, 1, v4
	v_or_b32_e32 v14, s6, v3
	s_waitcnt lgkmcnt(0)
	v_cvt_pk_bf16_f32 v7, v8, v9
	ds_read2_b32 v[8:9], v5 offset0:132 offset1:165
	v_lshl_add_u64 v[12:13], s[4:5], 0, v[96:97]
	v_lshlrev_b32_e32 v96, 11, v14
	s_waitcnt lgkmcnt(0)
	v_cvt_pk_bf16_f32 v8, v8, v9
	ds_read2_b32 v[10:11], v5 offset0:198 offset1:231
	s_waitcnt lgkmcnt(0)
	v_cvt_pk_bf16_f32 v9, v10, v11
	v_lshl_add_u64 v[14:15], v[12:13], 0, v[96:97]
	ds_read2_b32 v[10:11], v5 offset0:8 offset1:41
	global_store_dwordx4 v[14:15], v[6:9], off sc1
	v_or_b32_e32 v14, s6, v42
	v_lshlrev_b32_e32 v96, 11, v14
	s_waitcnt lgkmcnt(0)
	v_cvt_pk_bf16_f32 v6, v10, v11
	ds_read2_b32 v[8:9], v5 offset0:74 offset1:107
	s_waitcnt lgkmcnt(0)
	v_cvt_pk_bf16_f32 v7, v8, v9
	ds_read2_b32 v[8:9], v5 offset0:140 offset1:173
	s_waitcnt lgkmcnt(0)
	v_cvt_pk_bf16_f32 v8, v8, v9
	ds_read2_b32 v[10:11], v5 offset0:206 offset1:239
	s_waitcnt lgkmcnt(0)
	v_cvt_pk_bf16_f32 v9, v10, v11
	v_lshl_add_u64 v[14:15], v[12:13], 0, v[96:97]
	ds_read2_b32 v[10:11], v5 offset0:16 offset1:49
	global_store_dwordx4 v[14:15], v[6:9], off sc1
	v_or_b32_e32 v14, s6, v43
	v_lshlrev_b32_e32 v96, 11, v14
	s_waitcnt lgkmcnt(0)
	v_cvt_pk_bf16_f32 v6, v10, v11
	ds_read2_b32 v[8:9], v5 offset0:82 offset1:115
	s_waitcnt lgkmcnt(0)
	v_cvt_pk_bf16_f32 v7, v8, v9
	ds_read2_b32 v[8:9], v5 offset0:148 offset1:181
	s_waitcnt lgkmcnt(0)
	v_cvt_pk_bf16_f32 v8, v8, v9
	ds_read2_b32 v[10:11], v5 offset0:214 offset1:247
	s_waitcnt lgkmcnt(0)
	v_cvt_pk_bf16_f32 v9, v10, v11
	v_lshl_add_u64 v[14:15], v[12:13], 0, v[96:97]
	ds_read2_b32 v[10:11], v5 offset0:24 offset1:57
	global_store_dwordx4 v[14:15], v[6:9], off sc1
	s_waitcnt lgkmcnt(0)
	s_nop 0
	v_cvt_pk_bf16_f32 v6, v10, v11
	ds_read2_b32 v[8:9], v5 offset0:90 offset1:123
	s_waitcnt lgkmcnt(0)
	v_cvt_pk_bf16_f32 v7, v8, v9
	ds_read2_b32 v[8:9], v5 offset0:156 offset1:189
	s_waitcnt lgkmcnt(0)
	v_cvt_pk_bf16_f32 v8, v8, v9
	v_or_b32_e32 v9, s6, v44
	ds_read2_b32 v[10:11], v5 offset0:222 offset1:255
	v_lshlrev_b32_e32 v96, 11, v9
	s_waitcnt lgkmcnt(0)
	v_cvt_pk_bf16_f32 v9, v10, v11
	v_lshl_add_u64 v[10:11], v[12:13], 0, v[96:97]
	global_store_dwordx4 v[10:11], v[6:9], off sc1
	s_waitcnt lgkmcnt(0)

.LBB0_205:
	s_andn2_b64 vcc, exec, s[4:5]
	s_cbranch_vccnz .LBB0_173
	s_mul_hi_i32 s4, s20, 0x3e0f83e1
	s_lshr_b32 s5, s4, 31
	s_ashr_i32 s4, s4, 11
	s_add_i32 s4, s4, s5
	s_mul_i32 s5, s4, 0xffffdf00
	s_add_i32 s6, s20, s5
	s_mul_i32 s5, s6, 0x3e1
	s_lshr_b32 s7, s5, 31
	s_ashr_i32 s5, s5, 22
	s_add_i32 s7, s5, s7
	s_mul_i32 s5, s7, 0x1080
	s_sub_i32 s5, s6, s5
	s_sext_i32_i16 s13, s5
	s_mul_i32 s10, s13, 0xba3
	s_lshr_b32 s11, s10, 31
	s_ashr_i32 s12, s10, 22
	s_add_i32 s12, s12, s11
	s_mul_i32 s10, s12, 0x580
	s_sub_i32 s34, s5, s10
	s_ashr_i32 s5, s4, 31
	s_mul_i32 s11, s4, 0x2100000
	s_mul_hi_i32 s10, s4, 0x2100000
	s_add_u32 s11, s25, s11
	s_sext_i32_i16 s7, s7
	s_addc_u32 s10, s26, s10
	s_mul_hi_i32 s31, s7, 0x1080000
	s_mul_i32 s7, s7, 0x1080000
	s_add_u32 s29, s11, s7
	s_addc_u32 s31, s10, s31
	s_addk_i32 s6, 0x107f
	s_cmpk_lt_u32 s6, 0x20ff
	s_cselect_b64 s[6:7], -1, 0
	s_mov_b64 s[10:11], -1
	s_cmpk_gt_i32 s13, 0xaff
	s_mul_hi_i32 s35, s4, 0xb00000
	s_mul_i32 s36, s4, 0xb00000
	v_lshlrev_b32_e32 v96, 2, v2
	v_add_u32_e32 v51, 0x400, v1
	v_add_u32_e32 v50, 0x800, v1
	v_add_u32_e32 v49, 0xc00, v1
	v_add_u32_e32 v48, 0x1000, v1
	v_add_u32_e32 v47, 0x1400, v1
	v_add_u32_e32 v46, 0x1800, v1
	v_add_u32_e32 v45, 0x1c00, v1
	v_lshlrev_b32_e32 v6, 1, v4
	s_cbranch_scc0 .LBB0_208
	s_and_b32 s13, 0xffff, s34
	s_and_b64 s[10:11], s[6:7], exec
	s_cselect_b32 s10, 32, 0x48
	s_add_u32 s10, s2, s10
	s_addc_u32 s11, s3, 0
	s_load_dwordx2 s[10:11], s[10:11], 0x0
	v_mov_b32_e32 v9, v97
	s_waitcnt lgkmcnt(0)
	s_add_u32 s38, s10, s36
	s_addc_u32 s39, s11, s35
	s_lshl_b32 s10, s13, 1
	s_and_b32 s11, s10, 0xfc0
	s_lshl_b32 s10, s13, 5
	v_or_b32_e32 v7, s11, v0
	s_and_b32 s10, s10, 0x3e0
	v_lshlrev_b32_e32 v8, 12, v7
	v_lshl_add_u64 v[8:9], s[38:39], 0, v[8:9]
	s_lshl_b32 s60, s10, 2
	v_lshl_add_u64 v[8:9], v[8:9], 0, s[60:61]
	v_lshl_add_u64 v[8:9], v[8:9], 0, v[96:97]
	v_add_co_u32_e32 v10, vcc, s68, v8
	global_load_dword v7, v[8:9], off
	s_nop 0
	v_addc_co_u32_e32 v11, vcc, 0, v9, vcc
	global_load_dword v12, v[10:11], off
	v_add_co_u32_e32 v10, vcc, s75, v8
	s_mov_b32 s13, 0x10000
	s_nop 0
	v_addc_co_u32_e32 v11, vcc, 0, v9, vcc
	global_load_dword v13, v[10:11], off
	v_add_co_u32_e32 v10, vcc, s79, v8
	s_lshl_b32 s11, s11, 1
	s_nop 0
	v_addc_co_u32_e32 v11, vcc, 0, v9, vcc
	global_load_dword v14, v[10:11], off
	v_add_co_u32_e32 v10, vcc, s87, v8
	s_add_u32 s38, s29, s11
	s_nop 0
	v_addc_co_u32_e32 v11, vcc, 0, v9, vcc
	global_load_dword v15, v[10:11], off
	v_add_co_u32_e32 v10, vcc, s88, v8
	s_addc_u32 s39, s31, 0
	s_nop 0
	v_addc_co_u32_e32 v11, vcc, 0, v9, vcc
	global_load_dword v16, v[10:11], off
	v_add_co_u32_e32 v10, vcc, s62, v8
	s_nop 1
	v_addc_co_u32_e32 v11, vcc, 0, v9, vcc
	global_load_dword v17, v[10:11], off
	v_add_co_u32_e32 v10, vcc, s94, v8
	s_nop 1
	v_addc_co_u32_e32 v11, vcc, 0, v9, vcc
	global_load_dword v18, v[10:11], off
	v_add_co_u32_e32 v10, vcc, s13, v8
	s_mov_b32 s13, 0x22000
	s_nop 0
	v_addc_co_u32_e32 v11, vcc, 0, v9, vcc
	global_load_dword v19, v[10:11], off
	v_add_co_u32_e32 v10, vcc, s72, v8
	s_nop 1
	v_addc_co_u32_e32 v11, vcc, 0, v9, vcc
	global_load_dword v20, v[10:11], off
	v_add_co_u32_e32 v10, vcc, s73, v8
	s_nop 1
	v_addc_co_u32_e32 v11, vcc, 0, v9, vcc
	global_load_dword v21, v[10:11], off
	v_add_co_u32_e32 v10, vcc, s74, v8
	s_nop 1
	v_addc_co_u32_e32 v11, vcc, 0, v9, vcc
	global_load_dword v22, v[10:11], off
	v_add_co_u32_e32 v10, vcc, s85, v8
	s_nop 1
	v_addc_co_u32_e32 v11, vcc, 0, v9, vcc
	global_load_dword v23, v[10:11], off
	v_add_co_u32_e32 v10, vcc, s86, v8
	s_nop 1
	v_addc_co_u32_e32 v11, vcc, 0, v9, vcc
	global_load_dword v24, v[10:11], off
	v_add_co_u32_e32 v10, vcc, s90, v8
	s_nop 1
	v_addc_co_u32_e32 v11, vcc, 0, v9, vcc
	global_load_dword v25, v[10:11], off
	v_add_co_u32_e32 v10, vcc, s91, v8
	s_nop 1
	v_addc_co_u32_e32 v11, vcc, 0, v9, vcc
	global_load_dword v26, v[10:11], off
	v_add_co_u32_e32 v10, vcc, s95, v8
	s_nop 1
	v_addc_co_u32_e32 v11, vcc, 0, v9, vcc
	global_load_dword v27, v[10:11], off
	v_add_co_u32_e32 v10, vcc, s13, v8
	s_mov_b32 s13, 0x24000
	s_nop 0
	v_addc_co_u32_e32 v11, vcc, 0, v9, vcc
	global_load_dword v28, v[10:11], off
	v_add_co_u32_e32 v10, vcc, s13, v8
	s_mov_b32 s13, 0x28000
	s_nop 0
	v_addc_co_u32_e32 v11, vcc, 0, v9, vcc
	global_load_dword v29, v[10:11], off
	v_add_co_u32_e32 v10, vcc, s40, v8
	s_nop 1
	v_addc_co_u32_e32 v11, vcc, 0, v9, vcc
	global_load_dword v30, v[10:11], off
	v_add_co_u32_e32 v10, vcc, s13, v8
	s_mov_b32 s13, 0x2a000
	s_nop 0
	v_addc_co_u32_e32 v11, vcc, 0, v9, vcc
	global_load_dword v31, v[10:11], off
	v_add_co_u32_e32 v10, vcc, s13, v8
	s_mov_b32 s13, 0x2e000
	s_nop 0
	v_addc_co_u32_e32 v11, vcc, 0, v9, vcc
	global_load_dword v32, v[10:11], off
	v_add_co_u32_e32 v10, vcc, s41, v8
	s_nop 1
	v_addc_co_u32_e32 v11, vcc, 0, v9, vcc
	global_load_dword v33, v[10:11], off
	v_add_co_u32_e32 v10, vcc, s13, v8
	s_mov_b32 s13, 0x30000
	s_nop 0
	v_addc_co_u32_e32 v11, vcc, 0, v9, vcc
	global_load_dword v34, v[10:11], off
	v_add_co_u32_e32 v10, vcc, s13, v8
	s_mov_b32 s13, 0x32000
	s_nop 0
	v_addc_co_u32_e32 v11, vcc, 0, v9, vcc
	global_load_dword v35, v[10:11], off
	v_add_co_u32_e32 v10, vcc, s13, v8
	s_mov_b32 s13, 0x34000
	s_nop 0
	v_addc_co_u32_e32 v11, vcc, 0, v9, vcc
	global_load_dword v36, v[10:11], off
	v_add_co_u32_e32 v10, vcc, s13, v8
	s_mov_b32 s13, 0x36000
	s_nop 0
	v_addc_co_u32_e32 v11, vcc, 0, v9, vcc
	global_load_dword v37, v[10:11], off
	v_add_co_u32_e32 v10, vcc, s13, v8
	s_mov_b32 s13, 0x38000
	s_nop 0
	v_addc_co_u32_e32 v11, vcc, 0, v9, vcc
	global_load_dword v38, v[10:11], off
	v_add_co_u32_e32 v10, vcc, s13, v8
	s_mov_b32 s13, 0x3a000
	s_nop 0
	v_addc_co_u32_e32 v11, vcc, 0, v9, vcc
	global_load_dword v39, v[10:11], off
	v_add_co_u32_e32 v10, vcc, s13, v8
	s_mov_b32 s13, 0x3c000
	s_nop 0
	v_addc_co_u32_e32 v11, vcc, 0, v9, vcc
	global_load_dword v40, v[10:11], off
	v_add_co_u32_e32 v10, vcc, s13, v8
	s_mov_b32 s13, 0x3e000
	s_nop 0
	v_addc_co_u32_e32 v11, vcc, 0, v9, vcc
	v_add_co_u32_e32 v8, vcc, s13, v8
	global_load_dword v10, v[10:11], off
	s_nop 0
	v_addc_co_u32_e32 v9, vcc, 0, v9, vcc
	global_load_dword v8, v[8:9], off
	s_waitcnt vmcnt(0)
	ds_write2_b32 v1, v7, v12 offset1:66
	ds_write2_b32 v1, v13, v14 offset0:132 offset1:198
	ds_write2_b32 v51, v15, v16 offset0:8 offset1:74
	ds_write2_b32 v51, v17, v18 offset0:140 offset1:206
	ds_write2_b32 v50, v19, v20 offset0:16 offset1:82
	ds_write2_b32 v50, v21, v22 offset0:148 offset1:214
	ds_write2_b32 v49, v23, v24 offset0:24 offset1:90
	ds_write2_b32 v49, v25, v26 offset0:156 offset1:222
	ds_write2_b32 v48, v27, v28 offset0:32 offset1:98
	ds_write2_b32 v48, v29, v30 offset0:164 offset1:230
	ds_write2_b32 v47, v31, v32 offset0:40 offset1:106
	ds_write2_b32 v47, v33, v34 offset0:172 offset1:238
	ds_write2_b32 v46, v35, v36 offset0:48 offset1:114
	ds_write2_b32 v46, v37, v38 offset0:180 offset1:246
	ds_write2_b32 v45, v39, v40 offset0:56 offset1:122
	ds_write2_b32 v45, v10, v8 offset0:188 offset1:254
	v_mov_b32_e32 v7, v97
	s_waitcnt lgkmcnt(0)
	v_lshl_add_u64 v[8:9], s[38:39], 0, v[6:7]
	s_mov_b64 s[38:39], 0xb00000
	v_lshl_add_u64 v[12:13], v[8:9], 0, s[38:39]
	ds_read2_b32 v[8:9], v5 offset1:33
	s_waitcnt lgkmcnt(0)
	v_cvt_pk_bf16_f32 v8, v8, v9
	ds_read2_b32 v[10:11], v5 offset0:66 offset1:99
	s_waitcnt lgkmcnt(0)
	v_cvt_pk_bf16_f32 v9, v10, v11
	ds_read2_b32 v[10:11], v5 offset0:132 offset1:165
	v_or_b32_e32 v7, s10, v3
	s_waitcnt lgkmcnt(0)
	v_cvt_pk_bf16_f32 v10, v10, v11
	ds_read2_b32 v[14:15], v5 offset0:198 offset1:231
	v_mul_u32_u24_e32 v7, 0xb00, v7
	s_waitcnt lgkmcnt(0)
	v_cvt_pk_bf16_f32 v11, v14, v15
	v_lshlrev_b32_e32 v14, 1, v7
	v_mov_b32_e32 v15, v97
	v_lshl_add_u64 v[14:15], v[12:13], 0, v[14:15]
	global_store_dwordx4 v[14:15], v[8:11], off sc1
	ds_read2_b32 v[8:9], v5 offset0:8 offset1:41
	v_or_b32_e32 v7, s10, v42
	s_waitcnt lgkmcnt(0)
	v_cvt_pk_bf16_f32 v8, v8, v9
	ds_read2_b32 v[10:11], v5 offset0:74 offset1:107
	s_waitcnt lgkmcnt(0)
	v_cvt_pk_bf16_f32 v9, v10, v11
	ds_read2_b32 v[10:11], v5 offset0:140 offset1:173
	s_waitcnt lgkmcnt(0)
	v_cvt_pk_bf16_f32 v10, v10, v11
	ds_read2_b32 v[14:15], v5 offset0:206 offset1:239
	v_mul_u32_u24_e32 v7, 0xb00, v7
	s_waitcnt lgkmcnt(0)
	v_cvt_pk_bf16_f32 v11, v14, v15
	v_lshlrev_b32_e32 v14, 1, v7
	v_mov_b32_e32 v15, v97
	v_lshl_add_u64 v[14:15], v[12:13], 0, v[14:15]
	global_store_dwordx4 v[14:15], v[8:11], off sc1
	ds_read2_b32 v[8:9], v5 offset0:16 offset1:49
	v_or_b32_e32 v7, s10, v43
	s_waitcnt lgkmcnt(0)
	v_cvt_pk_bf16_f32 v8, v8, v9
	ds_read2_b32 v[10:11], v5 offset0:82 offset1:115
	s_waitcnt lgkmcnt(0)
	v_cvt_pk_bf16_f32 v9, v10, v11
	ds_read2_b32 v[10:11], v5 offset0:148 offset1:181
	s_waitcnt lgkmcnt(0)
	v_cvt_pk_bf16_f32 v10, v10, v11
	ds_read2_b32 v[14:15], v5 offset0:214 offset1:247
	v_mul_u32_u24_e32 v7, 0xb00, v7
	s_waitcnt lgkmcnt(0)
	v_cvt_pk_bf16_f32 v11, v14, v15
	v_lshlrev_b32_e32 v14, 1, v7
	v_mov_b32_e32 v15, v97
	v_lshl_add_u64 v[14:15], v[12:13], 0, v[14:15]
	global_store_dwordx4 v[14:15], v[8:11], off sc1
	ds_read2_b32 v[8:9], v5 offset0:24 offset1:57
	v_or_b32_e32 v7, s10, v44
	s_waitcnt lgkmcnt(0)
	v_cvt_pk_bf16_f32 v8, v8, v9
	ds_read2_b32 v[10:11], v5 offset0:90 offset1:123
	s_waitcnt lgkmcnt(0)
	v_cvt_pk_bf16_f32 v9, v10, v11
	ds_read2_b32 v[10:11], v5 offset0:156 offset1:189
	s_waitcnt lgkmcnt(0)
	v_cvt_pk_bf16_f32 v10, v10, v11
	ds_read2_b32 v[14:15], v5 offset0:222 offset1:255
	v_mul_u32_u24_e32 v7, 0xb00, v7
	s_waitcnt lgkmcnt(0)
	v_cvt_pk_bf16_f32 v11, v14, v15
	v_lshlrev_b32_e32 v14, 1, v7
	v_mov_b32_e32 v15, v97
	v_lshl_add_u64 v[12:13], v[12:13], 0, v[14:15]
	global_store_dwordx4 v[12:13], v[8:11], off sc1
	s_waitcnt lgkmcnt(0)
	s_mov_b64 s[10:11], 0

.LBB0_215:
	s_bfe_i32 s4, s28, 0x80000
	s_bfe_u32 s4, s4, 0x2000d
	s_add_i32 s28, s28, s4
	s_bfe_i32 s4, s28, 0x80000
	s_bfe_u32 s5, s10, 0x70018
	s_sext_i32_i16 s4, s4
	s_add_i32 s5, s10, s5
	s_lshl_b32 s4, s4, 6
	s_and_b32 s5, s5, 0xff80
	s_and_b32 s4, s4, 0xffffff00
	s_sub_i32 s5, s10, s5
	s_lshl_b32 s10, s34, 7
	s_sext_i32_i16 s5, s5
	s_add_i32 s4, s4, s10
	s_add_i32 s10, s4, s5
	s_lshl_b64 s[4:5], s[6:7], 1
	s_waitcnt vmcnt(0)
	ds_write2_b32 v1, v8, v9 offset1:66
	ds_write2_b32 v1, v10, v11 offset0:132 offset1:198
	ds_write2_b32 v51, v12, v13 offset0:8 offset1:74
	ds_write2_b32 v51, v14, v15 offset0:140 offset1:206
	ds_write2_b32 v50, v16, v17 offset0:16 offset1:82
	ds_write2_b32 v50, v18, v19 offset0:148 offset1:214
	ds_write2_b32 v49, v20, v21 offset0:24 offset1:90
	ds_write2_b32 v49, v22, v23 offset0:156 offset1:222
	ds_write2_b32 v48, v24, v25 offset0:32 offset1:98
	ds_write2_b32 v48, v26, v27 offset0:164 offset1:230
	ds_write2_b32 v47, v28, v29 offset0:40 offset1:106
	ds_write2_b32 v47, v30, v31 offset0:172 offset1:238
	ds_write2_b32 v46, v32, v33 offset0:48 offset1:114
	ds_write2_b32 v46, v34, v35 offset0:180 offset1:246
	ds_write2_b32 v45, v36, v37 offset0:56 offset1:122
	ds_write2_b32 v45, v40, v41 offset0:188 offset1:254
	s_add_u32 s4, s26, s4
	s_waitcnt lgkmcnt(0)
	s_addc_u32 s5, s27, s5
	v_mov_b32_e32 v7, v97
	ds_read2_b32 v[8:9], v5 offset1:33
	v_lshl_add_u64 v[14:15], s[4:5], 0, v[6:7]
	v_or_b32_e32 v6, s10, v3
	s_waitcnt lgkmcnt(0)
	v_cvt_pk_bf16_f32 v8, v8, v9
	ds_read2_b32 v[10:11], v5 offset0:66 offset1:99
	v_ashrrev_i32_e32 v7, 31, v6
	s_waitcnt lgkmcnt(0)
	v_cvt_pk_bf16_f32 v9, v10, v11
	ds_read2_b32 v[10:11], v5 offset0:132 offset1:165
	v_lshlrev_b64 v[6:7], 11, v[6:7]
	s_waitcnt lgkmcnt(0)
	v_cvt_pk_bf16_f32 v10, v10, v11
	ds_read2_b32 v[12:13], v5 offset0:198 offset1:231
	v_lshl_add_u64 v[6:7], v[14:15], 0, v[6:7]
	s_waitcnt lgkmcnt(0)
	v_cvt_pk_bf16_f32 v11, v12, v13
	ds_read2_b32 v[12:13], v5 offset0:8 offset1:41
	global_store_dwordx4 v[6:7], v[8:11], off sc1
	s_waitcnt lgkmcnt(0)
	v_cvt_pk_bf16_f32 v6, v12, v13
	ds_read2_b32 v[8:9], v5 offset0:74 offset1:107
	s_waitcnt lgkmcnt(0)
	v_cvt_pk_bf16_f32 v7, v8, v9
	ds_read2_b32 v[8:9], v5 offset0:140 offset1:173
	s_waitcnt lgkmcnt(0)
	v_cvt_pk_bf16_f32 v8, v8, v9
	ds_read2_b32 v[10:11], v5 offset0:206 offset1:239
	s_waitcnt lgkmcnt(0)
	v_cvt_pk_bf16_f32 v9, v10, v11
	v_or_b32_e32 v10, s10, v42
	v_ashrrev_i32_e32 v11, 31, v10
	v_lshlrev_b64 v[10:11], 11, v[10:11]
	v_lshl_add_u64 v[10:11], v[14:15], 0, v[10:11]
	ds_read2_b32 v[12:13], v5 offset0:16 offset1:49
	global_store_dwordx4 v[10:11], v[6:9], off sc1
	s_waitcnt lgkmcnt(0)
	s_nop 0
	v_cvt_pk_bf16_f32 v6, v12, v13
	ds_read2_b32 v[8:9], v5 offset0:82 offset1:115
	s_waitcnt lgkmcnt(0)
	v_cvt_pk_bf16_f32 v7, v8, v9
	ds_read2_b32 v[8:9], v5 offset0:148 offset1:181
	s_waitcnt lgkmcnt(0)
	v_cvt_pk_bf16_f32 v8, v8, v9
	ds_read2_b32 v[10:11], v5 offset0:214 offset1:247
	s_waitcnt lgkmcnt(0)
	v_cvt_pk_bf16_f32 v9, v10, v11
	v_or_b32_e32 v10, s10, v43
	v_ashrrev_i32_e32 v11, 31, v10
	v_lshlrev_b64 v[10:11], 11, v[10:11]
	v_lshl_add_u64 v[10:11], v[14:15], 0, v[10:11]
	ds_read2_b32 v[12:13], v5 offset0:24 offset1:57
	global_store_dwordx4 v[10:11], v[6:9], off sc1
	s_waitcnt lgkmcnt(0)
	s_nop 0
	v_cvt_pk_bf16_f32 v6, v12, v13
	ds_read2_b32 v[8:9], v5 offset0:90 offset1:123
	s_waitcnt lgkmcnt(0)
	v_cvt_pk_bf16_f32 v7, v8, v9
	ds_read2_b32 v[8:9], v5 offset0:156 offset1:189
	s_waitcnt lgkmcnt(0)
	v_cvt_pk_bf16_f32 v8, v8, v9
	ds_read2_b32 v[10:11], v5 offset0:222 offset1:255
	s_waitcnt lgkmcnt(0)
	v_cvt_pk_bf16_f32 v9, v10, v11
	v_or_b32_e32 v10, s10, v44
	v_ashrrev_i32_e32 v11, 31, v10
	v_lshlrev_b64 v[10:11], 11, v[10:11]
	v_lshl_add_u64 v[10:11], v[14:15], 0, v[10:11]
	global_store_dwordx4 v[10:11], v[6:9], off sc1
	s_waitcnt lgkmcnt(0)

.LBB0_217:
	s_cmp_gt_i32 s21, 0x83ff
	s_mov_b64 s[4:5], -1
	s_cbranch_scc0 .LBB0_237
	s_add_i32 s4, s21, 0xffff7c00
	s_cmpk_gt_u32 s4, 0x45f
	s_cselect_b64 s[12:13], -1, 0
	s_add_i32 s5, s21, 0xffff77a0
	s_cmpk_lt_u32 s4, 0x460
	s_cselect_b32 s26, s4, s5
	s_and_b64 s[4:5], s[12:13], exec
	s_cselect_b32 s4, 0x600000, 0
	s_add_u32 s10, s22, s4
	s_addc_u32 s11, s23, 0
	s_cmpk_gt_u32 s26, 0x24f
	s_mov_b64 s[4:5], -1
	s_cbranch_scc0 .LBB0_232
	s_cmpk_gt_u32 s26, 0x2df
	s_cbranch_scc0 .LBB0_227
	s_cmpk_gt_u32 s26, 0x35f
	s_cbranch_scc0 .LBB0_222
	s_load_dwordx2 s[4:5], s[2:3], 0x98
	s_and_b64 s[6:7], s[12:13], exec
	s_cselect_b32 s6, 0x400000, 0
	v_lshlrev_b32_e32 v96, 2, v2
	s_waitcnt lgkmcnt(0)
	s_add_u32 s28, s4, s6
	s_addc_u32 s29, s5, 0
	s_lshl_b32 s4, s26, 1
	s_and_b32 s4, s4, 0xfc0
	s_addk_i32 s4, 0xfb40
	v_or_b32_e32 v6, s4, v0
	s_lshl_b32 s5, s26, 5
	v_ashrrev_i32_e32 v7, 31, v6
	s_and_b32 s6, s5, 0x3e0
	v_lshlrev_b64 v[6:7], 12, v[6:7]
	v_lshl_add_u64 v[6:7], s[28:29], 0, v[6:7]
	s_lshl_b32 s60, s6, 2
	v_lshl_add_u64 v[6:7], v[6:7], 0, s[60:61]
	v_lshl_add_u64 v[6:7], v[6:7], 0, v[96:97]
	v_add_co_u32_e32 v8, vcc, s68, v6
	global_load_dword v10, v[6:7], off
	s_nop 0
	v_addc_co_u32_e32 v9, vcc, 0, v7, vcc
	global_load_dword v11, v[8:9], off
	v_add_co_u32_e32 v8, vcc, s75, v6
	s_mov_b32 s5, 0x10000
	s_nop 0
	v_addc_co_u32_e32 v9, vcc, 0, v7, vcc
	global_load_dword v12, v[8:9], off
	v_add_co_u32_e32 v8, vcc, s79, v6
	v_lshlrev_b32_e32 v96, 1, v4
	s_nop 0
	v_addc_co_u32_e32 v9, vcc, 0, v7, vcc
	global_load_dword v13, v[8:9], off
	v_add_co_u32_e32 v8, vcc, s87, v6
	s_mov_b64 s[28:29], 0x390000
	s_nop 0
	v_addc_co_u32_e32 v9, vcc, 0, v7, vcc
	global_load_dword v14, v[8:9], off
	v_add_co_u32_e32 v8, vcc, s88, v6
	s_nop 1
	v_addc_co_u32_e32 v9, vcc, 0, v7, vcc
	global_load_dword v15, v[8:9], off
	v_add_co_u32_e32 v8, vcc, s62, v6
	s_nop 1
	v_addc_co_u32_e32 v9, vcc, 0, v7, vcc
	global_load_dword v16, v[8:9], off
	v_add_co_u32_e32 v8, vcc, s94, v6
	s_nop 1
	v_addc_co_u32_e32 v9, vcc, 0, v7, vcc
	global_load_dword v17, v[8:9], off
	v_add_co_u32_e32 v8, vcc, s5, v6
	s_mov_b32 s5, 0x22000
	s_nop 0
	v_addc_co_u32_e32 v9, vcc, 0, v7, vcc
	global_load_dword v18, v[8:9], off
	v_add_co_u32_e32 v8, vcc, s72, v6
	s_nop 1
	v_addc_co_u32_e32 v9, vcc, 0, v7, vcc
	global_load_dword v19, v[8:9], off
	v_add_co_u32_e32 v8, vcc, s73, v6
	s_nop 1
	v_addc_co_u32_e32 v9, vcc, 0, v7, vcc
	global_load_dword v20, v[8:9], off
	v_add_co_u32_e32 v8, vcc, s74, v6
	s_nop 1
	v_addc_co_u32_e32 v9, vcc, 0, v7, vcc
	global_load_dword v21, v[8:9], off
	v_add_co_u32_e32 v8, vcc, s85, v6
	s_nop 1
	v_addc_co_u32_e32 v9, vcc, 0, v7, vcc
	global_load_dword v22, v[8:9], off
	v_add_co_u32_e32 v8, vcc, s86, v6
	s_nop 1
	v_addc_co_u32_e32 v9, vcc, 0, v7, vcc
	global_load_dword v23, v[8:9], off
	v_add_co_u32_e32 v8, vcc, s90, v6
	s_nop 1
	v_addc_co_u32_e32 v9, vcc, 0, v7, vcc
	global_load_dword v24, v[8:9], off
	v_add_co_u32_e32 v8, vcc, s91, v6
	s_nop 1
	v_addc_co_u32_e32 v9, vcc, 0, v7, vcc
	global_load_dword v25, v[8:9], off
	v_add_co_u32_e32 v8, vcc, s95, v6
	s_nop 1
	v_addc_co_u32_e32 v9, vcc, 0, v7, vcc
	global_load_dword v26, v[8:9], off
	v_add_co_u32_e32 v8, vcc, s5, v6
	s_mov_b32 s5, 0x24000
	s_nop 0
	v_addc_co_u32_e32 v9, vcc, 0, v7, vcc
	global_load_dword v27, v[8:9], off
	v_add_co_u32_e32 v8, vcc, s5, v6
	s_mov_b32 s5, 0x28000
	s_nop 0
	v_addc_co_u32_e32 v9, vcc, 0, v7, vcc
	global_load_dword v28, v[8:9], off
	v_add_co_u32_e32 v8, vcc, s40, v6
	s_nop 1
	v_addc_co_u32_e32 v9, vcc, 0, v7, vcc
	global_load_dword v29, v[8:9], off
	v_add_co_u32_e32 v8, vcc, s5, v6
	s_mov_b32 s5, 0x2a000
	s_nop 0
	v_addc_co_u32_e32 v9, vcc, 0, v7, vcc
	global_load_dword v30, v[8:9], off
	v_add_co_u32_e32 v8, vcc, s5, v6
	s_mov_b32 s5, 0x2e000
	s_nop 0
	v_addc_co_u32_e32 v9, vcc, 0, v7, vcc
	global_load_dword v31, v[8:9], off
	v_add_co_u32_e32 v8, vcc, s41, v6
	s_nop 1
	v_addc_co_u32_e32 v9, vcc, 0, v7, vcc
	global_load_dword v32, v[8:9], off
	v_add_co_u32_e32 v8, vcc, s5, v6
	s_mov_b32 s5, 0x30000
	s_nop 0
	v_addc_co_u32_e32 v9, vcc, 0, v7, vcc
	global_load_dword v33, v[8:9], off
	v_add_co_u32_e32 v8, vcc, s5, v6
	s_mov_b32 s5, 0x32000
	s_nop 0
	v_addc_co_u32_e32 v9, vcc, 0, v7, vcc
	global_load_dword v34, v[8:9], off
	v_add_co_u32_e32 v8, vcc, s5, v6
	s_mov_b32 s5, 0x34000
	s_nop 0
	v_addc_co_u32_e32 v9, vcc, 0, v7, vcc
	global_load_dword v35, v[8:9], off
	v_add_co_u32_e32 v8, vcc, s5, v6
	s_mov_b32 s5, 0x36000
	s_nop 0
	v_addc_co_u32_e32 v9, vcc, 0, v7, vcc
	global_load_dword v36, v[8:9], off
	v_add_co_u32_e32 v8, vcc, s5, v6
	s_mov_b32 s5, 0x38000
	s_nop 0
	v_addc_co_u32_e32 v9, vcc, 0, v7, vcc
	global_load_dword v37, v[8:9], off
	v_add_co_u32_e32 v8, vcc, s5, v6
	s_mov_b32 s5, 0x3a000
	s_nop 0
	v_addc_co_u32_e32 v9, vcc, 0, v7, vcc
	global_load_dword v38, v[8:9], off
	v_add_co_u32_e32 v8, vcc, s5, v6
	s_mov_b32 s5, 0x3c000
	s_nop 0
	v_addc_co_u32_e32 v9, vcc, 0, v7, vcc
	global_load_dword v39, v[8:9], off
	v_add_co_u32_e32 v8, vcc, s5, v6
	s_mov_b32 s5, 0x3e000
	s_nop 0
	v_addc_co_u32_e32 v9, vcc, 0, v7, vcc
	v_add_co_u32_e32 v6, vcc, s5, v6
	global_load_dword v8, v[8:9], off
	s_nop 0
	v_addc_co_u32_e32 v7, vcc, 0, v7, vcc
	global_load_dword v6, v[6:7], off
	v_add_u32_e32 v7, 0x400, v1
	s_waitcnt vmcnt(0)
	ds_write2_b32 v1, v10, v11 offset1:66
	ds_write2_b32 v1, v12, v13 offset0:132 offset1:198
	ds_write2_b32 v7, v14, v15 offset0:8 offset1:74
	ds_write2_b32 v7, v16, v17 offset0:140 offset1:206
	v_add_u32_e32 v7, 0x800, v1
	ds_write2_b32 v7, v18, v19 offset0:16 offset1:82
	ds_write2_b32 v7, v20, v21 offset0:148 offset1:214
	v_add_u32_e32 v7, 0xc00, v1
	ds_write2_b32 v7, v22, v23 offset0:24 offset1:90
	ds_write2_b32 v7, v24, v25 offset0:156 offset1:222
	v_add_u32_e32 v7, 0x1000, v1
	ds_write2_b32 v7, v26, v27 offset0:32 offset1:98
	ds_write2_b32 v7, v28, v29 offset0:164 offset1:230
	v_add_u32_e32 v7, 0x1400, v1
	ds_write2_b32 v7, v30, v31 offset0:40 offset1:106
	ds_write2_b32 v7, v32, v33 offset0:172 offset1:238
	v_add_u32_e32 v7, 0x1800, v1
	ds_write2_b32 v7, v34, v35 offset0:48 offset1:114
	ds_write2_b32 v7, v36, v37 offset0:180 offset1:246
	v_add_u32_e32 v7, 0x1c00, v1
	ds_write2_b32 v7, v38, v39 offset0:56 offset1:122
	ds_write2_b32 v7, v8, v6 offset0:188 offset1:254
	s_waitcnt lgkmcnt(0)
	v_lshl_add_u64 v[6:7], s[10:11], 0, v[96:97]
	v_lshl_add_u64 v[10:11], v[6:7], 0, s[28:29]
	ds_read2_b32 v[6:7], v5 offset1:33
	s_waitcnt lgkmcnt(0)
	v_cvt_pk_bf16_f32 v6, v6, v7
	ds_read2_b32 v[8:9], v5 offset0:66 offset1:99
	s_waitcnt lgkmcnt(0)
	v_cvt_pk_bf16_f32 v7, v8, v9
	ds_read2_b32 v[8:9], v5 offset0:132 offset1:165
	s_waitcnt lgkmcnt(0)
	v_cvt_pk_bf16_f32 v8, v8, v9
	ds_read2_b32 v[12:13], v5 offset0:198 offset1:231
	s_waitcnt lgkmcnt(0)
	v_cvt_pk_bf16_f32 v9, v12, v13
	v_or_b32_e32 v12, s6, v3
	s_ashr_i32 s5, s4, 31
	v_lshlrev_b32_e32 v96, 11, v12
	v_lshl_add_u64 v[12:13], v[10:11], 0, v[96:97]
	s_lshl_b64 s[4:5], s[4:5], 1
	v_lshl_add_u64 v[12:13], v[12:13], 0, s[4:5]
	global_store_dwordx4 v[12:13], v[6:9], off sc1
	ds_read2_b32 v[6:7], v5 offset0:8 offset1:41
	s_waitcnt lgkmcnt(0)
	v_cvt_pk_bf16_f32 v6, v6, v7
	ds_read2_b32 v[8:9], v5 offset0:74 offset1:107
	s_waitcnt lgkmcnt(0)
	v_cvt_pk_bf16_f32 v7, v8, v9
	ds_read2_b32 v[8:9], v5 offset0:140 offset1:173
	s_waitcnt lgkmcnt(0)
	v_cvt_pk_bf16_f32 v8, v8, v9
	ds_read2_b32 v[12:13], v5 offset0:206 offset1:239
	s_waitcnt lgkmcnt(0)
	v_cvt_pk_bf16_f32 v9, v12, v13
	v_or_b32_e32 v12, s6, v42
	v_lshlrev_b32_e32 v96, 11, v12
	v_lshl_add_u64 v[12:13], v[10:11], 0, v[96:97]
	v_lshl_add_u64 v[12:13], v[12:13], 0, s[4:5]
	global_store_dwordx4 v[12:13], v[6:9], off sc1
	ds_read2_b32 v[6:7], v5 offset0:16 offset1:49
	s_waitcnt lgkmcnt(0)
	v_cvt_pk_bf16_f32 v6, v6, v7
	ds_read2_b32 v[8:9], v5 offset0:82 offset1:115
	s_waitcnt lgkmcnt(0)
	v_cvt_pk_bf16_f32 v7, v8, v9
	ds_read2_b32 v[8:9], v5 offset0:148 offset1:181
	s_waitcnt lgkmcnt(0)
	v_cvt_pk_bf16_f32 v8, v8, v9
	ds_read2_b32 v[12:13], v5 offset0:214 offset1:247
	s_waitcnt lgkmcnt(0)
	v_cvt_pk_bf16_f32 v9, v12, v13
	v_or_b32_e32 v12, s6, v43
	v_lshlrev_b32_e32 v96, 11, v12
	v_lshl_add_u64 v[12:13], v[10:11], 0, v[96:97]
	v_lshl_add_u64 v[12:13], v[12:13], 0, s[4:5]
	global_store_dwordx4 v[12:13], v[6:9], off sc1
	ds_read2_b32 v[6:7], v5 offset0:24 offset1:57
	s_waitcnt lgkmcnt(0)
	v_cvt_pk_bf16_f32 v6, v6, v7
	ds_read2_b32 v[8:9], v5 offset0:90 offset1:123
	s_waitcnt lgkmcnt(0)
	v_cvt_pk_bf16_f32 v7, v8, v9
	ds_read2_b32 v[8:9], v5 offset0:156 offset1:189
	s_waitcnt lgkmcnt(0)
	v_cvt_pk_bf16_f32 v8, v8, v9
	ds_read2_b32 v[12:13], v5 offset0:222 offset1:255
	s_waitcnt lgkmcnt(0)
	v_cvt_pk_bf16_f32 v9, v12, v13
	v_or_b32_e32 v12, s6, v44
	v_lshlrev_b32_e32 v96, 11, v12
	v_lshl_add_u64 v[10:11], v[10:11], 0, v[96:97]
	v_lshl_add_u64 v[10:11], v[10:11], 0, s[4:5]
	global_store_dwordx4 v[10:11], v[6:9], off sc1
	s_waitcnt lgkmcnt(0)
	s_mov_b64 s[4:5], 0

.LBB0_225:
	s_waitcnt vmcnt(0)
	ds_write2_b32 v1, v6, v7 offset1:66
	ds_write2_b32 v1, v8, v9 offset0:132 offset1:198
	v_add_u32_e32 v6, 0x400, v1
	ds_write2_b32 v6, v10, v11 offset0:8 offset1:74
	ds_write2_b32 v6, v12, v13 offset0:140 offset1:206
	v_add_u32_e32 v6, 0x800, v1
	ds_write2_b32 v6, v14, v15 offset0:16 offset1:82
	ds_write2_b32 v6, v16, v17 offset0:148 offset1:214
	v_add_u32_e32 v6, 0xc00, v1
	s_lshl_b32 s4, s26, 5
	ds_write2_b32 v6, v18, v19 offset0:24 offset1:90
	ds_write2_b32 v6, v20, v21 offset0:156 offset1:222
	v_add_u32_e32 v6, 0x1000, v1
	s_bitcmp0_b32 s26, 1
	s_mov_b32 s5, 0x310000
	ds_write2_b32 v6, v22, v23 offset0:32 offset1:98
	ds_write2_b32 v6, v24, v25 offset0:164 offset1:230
	v_add_u32_e32 v6, 0x1400, v1
	s_cselect_b32 s5, s5, 0x350000
	ds_write2_b32 v6, v26, v27 offset0:40 offset1:106
	ds_write2_b32 v6, v28, v29 offset0:172 offset1:238
	v_add_u32_e32 v6, 0x1800, v1
	s_add_u32 s6, s10, s5
	ds_write2_b32 v6, v30, v31 offset0:48 offset1:114
	ds_write2_b32 v6, v32, v33 offset0:180 offset1:246
	v_add_u32_e32 v6, 0x1c00, v1
	s_addc_u32 s7, s11, 0
	s_lshl_b32 s5, s26, 4
	ds_write2_b32 v6, v34, v35 offset0:56 offset1:122
	ds_write2_b32 v6, v36, v37 offset0:188 offset1:254
	s_and_b32 s5, s5, 0x1c0
	s_and_b32 s4, s4, 32
	s_waitcnt lgkmcnt(0)
	s_or_b32 s27, s5, s4
	s_lshl_b64 s[4:5], s[60:61], 1
	ds_read2_b32 v[6:7], v5 offset1:33
	s_add_u32 s4, s6, s4
	s_waitcnt lgkmcnt(0)
	v_cvt_pk_bf16_f32 v6, v6, v7
	ds_read2_b32 v[8:9], v5 offset0:66 offset1:99
	s_addc_u32 s5, s7, s5
	v_lshlrev_b32_e32 v96, 1, v4
	v_or_b32_e32 v14, s27, v3
	s_waitcnt lgkmcnt(0)
	v_cvt_pk_bf16_f32 v7, v8, v9
	ds_read2_b32 v[8:9], v5 offset0:132 offset1:165
	v_lshl_add_u64 v[12:13], s[4:5], 0, v[96:97]
	v_lshlrev_b32_e32 v96, 9, v14
	s_waitcnt lgkmcnt(0)
	v_cvt_pk_bf16_f32 v8, v8, v9
	ds_read2_b32 v[10:11], v5 offset0:198 offset1:231
	s_waitcnt lgkmcnt(0)
	v_cvt_pk_bf16_f32 v9, v10, v11
	v_lshl_add_u64 v[14:15], v[12:13], 0, v[96:97]
	ds_read2_b32 v[10:11], v5 offset0:8 offset1:41
	global_store_dwordx4 v[14:15], v[6:9], off sc1
	v_or_b32_e32 v14, s27, v42
	v_lshlrev_b32_e32 v96, 9, v14
	s_waitcnt lgkmcnt(0)
	v_cvt_pk_bf16_f32 v6, v10, v11
	ds_read2_b32 v[8:9], v5 offset0:74 offset1:107
	s_waitcnt lgkmcnt(0)
	v_cvt_pk_bf16_f32 v7, v8, v9
	ds_read2_b32 v[8:9], v5 offset0:140 offset1:173
	s_waitcnt lgkmcnt(0)
	v_cvt_pk_bf16_f32 v8, v8, v9
	ds_read2_b32 v[10:11], v5 offset0:206 offset1:239
	s_waitcnt lgkmcnt(0)
	v_cvt_pk_bf16_f32 v9, v10, v11
	v_lshl_add_u64 v[14:15], v[12:13], 0, v[96:97]
	ds_read2_b32 v[10:11], v5 offset0:16 offset1:49
	global_store_dwordx4 v[14:15], v[6:9], off sc1
	v_or_b32_e32 v14, s27, v43
	v_lshlrev_b32_e32 v96, 9, v14
	s_waitcnt lgkmcnt(0)
	v_cvt_pk_bf16_f32 v6, v10, v11
	ds_read2_b32 v[8:9], v5 offset0:82 offset1:115
	s_waitcnt lgkmcnt(0)
	v_cvt_pk_bf16_f32 v7, v8, v9
	ds_read2_b32 v[8:9], v5 offset0:148 offset1:181
	s_waitcnt lgkmcnt(0)
	v_cvt_pk_bf16_f32 v8, v8, v9
	ds_read2_b32 v[10:11], v5 offset0:214 offset1:247
	s_waitcnt lgkmcnt(0)
	v_cvt_pk_bf16_f32 v9, v10, v11
	v_lshl_add_u64 v[14:15], v[12:13], 0, v[96:97]
	ds_read2_b32 v[10:11], v5 offset0:24 offset1:57
	global_store_dwordx4 v[14:15], v[6:9], off sc1
	s_waitcnt lgkmcnt(0)
	s_nop 0
	v_cvt_pk_bf16_f32 v6, v10, v11
	ds_read2_b32 v[8:9], v5 offset0:90 offset1:123
	s_waitcnt lgkmcnt(0)
	v_cvt_pk_bf16_f32 v7, v8, v9
	ds_read2_b32 v[8:9], v5 offset0:156 offset1:189
	s_waitcnt lgkmcnt(0)
	v_cvt_pk_bf16_f32 v8, v8, v9
	v_or_b32_e32 v9, s27, v44
	ds_read2_b32 v[10:11], v5 offset0:222 offset1:255
	v_lshlrev_b32_e32 v96, 9, v9
	s_waitcnt lgkmcnt(0)
	v_cvt_pk_bf16_f32 v9, v10, v11
	v_lshl_add_u64 v[10:11], v[12:13], 0, v[96:97]
	global_store_dwordx4 v[10:11], v[6:9], off sc1
	s_waitcnt lgkmcnt(0)

.LBB0_230:
	s_waitcnt vmcnt(0)
	ds_write2_b32 v1, v6, v7 offset1:66
	ds_write2_b32 v1, v8, v9 offset0:132 offset1:198
	v_add_u32_e32 v6, 0x400, v1
	ds_write2_b32 v6, v10, v11 offset0:8 offset1:74
	ds_write2_b32 v6, v12, v13 offset0:140 offset1:206
	v_add_u32_e32 v6, 0x800, v1
	ds_write2_b32 v6, v14, v15 offset0:16 offset1:82
	ds_write2_b32 v6, v16, v17 offset0:148 offset1:214
	v_add_u32_e32 v6, 0xc00, v1
	ds_write2_b32 v6, v18, v19 offset0:24 offset1:90
	ds_write2_b32 v6, v20, v21 offset0:156 offset1:222
	v_add_u32_e32 v6, 0x1000, v1
	ds_write2_b32 v6, v22, v23 offset0:32 offset1:98
	ds_write2_b32 v6, v24, v25 offset0:164 offset1:230
	v_add_u32_e32 v6, 0x1400, v1
	ds_write2_b32 v6, v26, v27 offset0:40 offset1:106
	ds_write2_b32 v6, v28, v29 offset0:172 offset1:238
	v_add_u32_e32 v6, 0x1800, v1
	ds_write2_b32 v6, v30, v31 offset0:48 offset1:114
	ds_write2_b32 v6, v32, v33 offset0:180 offset1:246
	v_add_u32_e32 v6, 0x1c00, v1
	s_lshl_b32 s7, s27, 5
	s_lshl_b32 s4, s6, 1
	ds_write2_b32 v6, v36, v37 offset0:56 offset1:122
	ds_write2_b32 v6, v38, v39 offset0:188 offset1:254
	s_add_u32 s4, s10, s4
	s_waitcnt lgkmcnt(0)
	s_addc_u32 s5, s11, 0
	v_lshlrev_b32_e32 v96, 1, v4
	v_or_b32_e32 v14, s7, v3
	ds_read2_b32 v[6:7], v5 offset1:33
	v_lshl_add_u64 v[12:13], s[4:5], 0, v[96:97]
	s_mov_b64 s[4:5], 0x280000
	v_mul_u32_u24_e32 v14, 0x180, v14
	s_waitcnt lgkmcnt(0)
	v_cvt_pk_bf16_f32 v6, v6, v7
	ds_read2_b32 v[8:9], v5 offset0:66 offset1:99
	v_lshl_add_u64 v[12:13], v[12:13], 0, s[4:5]
	v_lshlrev_b32_e32 v96, 1, v14
	s_waitcnt lgkmcnt(0)
	v_cvt_pk_bf16_f32 v7, v8, v9
	ds_read2_b32 v[8:9], v5 offset0:132 offset1:165
	v_lshl_add_u64 v[14:15], v[12:13], 0, v[96:97]
	s_waitcnt lgkmcnt(0)
	v_cvt_pk_bf16_f32 v8, v8, v9
	ds_read2_b32 v[10:11], v5 offset0:198 offset1:231
	s_waitcnt lgkmcnt(0)
	v_cvt_pk_bf16_f32 v9, v10, v11
	global_store_dwordx4 v[14:15], v[6:9], off sc1
	v_or_b32_e32 v14, s7, v42
	v_mul_u32_u24_e32 v14, 0x180, v14
	ds_read2_b32 v[10:11], v5 offset0:8 offset1:41
	s_waitcnt lgkmcnt(0)
	v_cvt_pk_bf16_f32 v6, v10, v11
	ds_read2_b32 v[8:9], v5 offset0:74 offset1:107
	v_lshlrev_b32_e32 v96, 1, v14
	s_waitcnt lgkmcnt(0)
	v_cvt_pk_bf16_f32 v7, v8, v9
	ds_read2_b32 v[8:9], v5 offset0:140 offset1:173
	v_lshl_add_u64 v[14:15], v[12:13], 0, v[96:97]
	s_waitcnt lgkmcnt(0)
	v_cvt_pk_bf16_f32 v8, v8, v9
	ds_read2_b32 v[10:11], v5 offset0:206 offset1:239
	s_waitcnt lgkmcnt(0)
	v_cvt_pk_bf16_f32 v9, v10, v11
	global_store_dwordx4 v[14:15], v[6:9], off sc1
	v_or_b32_e32 v14, s7, v43
	ds_read2_b32 v[10:11], v5 offset0:16 offset1:49
	s_waitcnt lgkmcnt(0)
	v_cvt_pk_bf16_f32 v6, v10, v11
	ds_read2_b32 v[8:9], v5 offset0:82 offset1:115
	v_mul_u32_u24_e32 v14, 0x180, v14
	s_waitcnt lgkmcnt(0)
	v_cvt_pk_bf16_f32 v7, v8, v9
	ds_read2_b32 v[8:9], v5 offset0:148 offset1:181
	v_lshlrev_b32_e32 v96, 1, v14
	s_waitcnt lgkmcnt(0)
	v_cvt_pk_bf16_f32 v8, v8, v9
	ds_read2_b32 v[10:11], v5 offset0:214 offset1:247
	s_waitcnt lgkmcnt(0)
	v_cvt_pk_bf16_f32 v9, v10, v11
	v_lshl_add_u64 v[14:15], v[12:13], 0, v[96:97]
	ds_read2_b32 v[10:11], v5 offset0:24 offset1:57
	global_store_dwordx4 v[14:15], v[6:9], off sc1
	s_waitcnt lgkmcnt(0)
	s_nop 0
	v_cvt_pk_bf16_f32 v6, v10, v11
	ds_read2_b32 v[8:9], v5 offset0:90 offset1:123
	s_waitcnt lgkmcnt(0)
	v_cvt_pk_bf16_f32 v7, v8, v9
	ds_read2_b32 v[8:9], v5 offset0:156 offset1:189
	s_waitcnt lgkmcnt(0)
	v_cvt_pk_bf16_f32 v8, v8, v9
	v_or_b32_e32 v9, s7, v44
	v_mul_u32_u24_e32 v9, 0x180, v9
	ds_read2_b32 v[10:11], v5 offset0:222 offset1:255
	v_lshlrev_b32_e32 v96, 1, v9
	s_waitcnt lgkmcnt(0)
	v_cvt_pk_bf16_f32 v9, v10, v11
	v_lshl_add_u64 v[10:11], v[12:13], 0, v[96:97]
	global_store_dwordx4 v[10:11], v[6:9], off sc1
	s_waitcnt lgkmcnt(0)

.LBB0_237:
	s_andn2_b64 vcc, exec, s[4:5]
	s_cbranch_vccnz .LBB0_216
	s_mul_hi_i32 s4, s21, 0x3e0f83e1
	s_lshr_b32 s5, s4, 31
	s_ashr_i32 s4, s4, 11
	s_add_i32 s4, s4, s5
	s_mul_i32 s5, s4, 0xffffdf00
	s_add_i32 s6, s21, s5
	s_mul_i32 s5, s6, 0x3e1
	s_lshr_b32 s7, s5, 31
	s_ashr_i32 s5, s5, 22
	s_add_i32 s7, s5, s7
	s_mul_i32 s5, s7, 0x1080
	s_sub_i32 s5, s6, s5
	s_sext_i32_i16 s13, s5
	s_mul_i32 s10, s13, 0xba3
	s_lshr_b32 s11, s10, 31
	s_ashr_i32 s12, s10, 22
	s_add_i32 s12, s12, s11
	s_mul_i32 s10, s12, 0x580
	s_sub_i32 s28, s5, s10
	s_ashr_i32 s5, s4, 31
	s_mul_i32 s11, s4, 0x2100000
	s_mul_hi_i32 s10, s4, 0x2100000
	s_add_u32 s11, s24, s11
	s_sext_i32_i16 s7, s7
	s_addc_u32 s10, s25, s10
	s_mul_hi_i32 s27, s7, 0x1080000
	s_mul_i32 s7, s7, 0x1080000
	s_add_u32 s26, s11, s7
	s_addc_u32 s27, s10, s27
	s_addk_i32 s6, 0x107f
	s_cmpk_lt_u32 s6, 0x20ff
	s_cselect_b64 s[6:7], -1, 0
	s_mov_b64 s[10:11], -1
	s_cmpk_gt_i32 s13, 0xaff
	s_mul_hi_i32 s29, s4, 0xb00000
	s_mul_i32 s31, s4, 0xb00000
	v_lshlrev_b32_e32 v96, 2, v2
	v_add_u32_e32 v51, 0x400, v1
	v_add_u32_e32 v50, 0x800, v1
	v_add_u32_e32 v49, 0xc00, v1
	v_add_u32_e32 v48, 0x1000, v1
	v_add_u32_e32 v47, 0x1400, v1
	v_add_u32_e32 v46, 0x1800, v1
	v_add_u32_e32 v45, 0x1c00, v1
	v_lshlrev_b32_e32 v6, 1, v4
	s_cbranch_scc0 .LBB0_240
	s_and_b32 s13, 0xffff, s28
	s_and_b64 s[10:11], s[6:7], exec
	s_cselect_b32 s10, 32, 0x48
	s_add_u32 s10, s2, s10
	s_addc_u32 s11, s3, 0
	s_load_dwordx2 s[10:11], s[10:11], 0x0
	v_mov_b32_e32 v9, v97
	s_waitcnt lgkmcnt(0)
	s_add_u32 s34, s10, s31
	s_addc_u32 s35, s11, s29
	s_lshl_b32 s10, s13, 1
	s_and_b32 s11, s10, 0xfc0
	s_lshl_b32 s10, s13, 5
	v_or_b32_e32 v7, s11, v0
	s_and_b32 s10, s10, 0x3e0
	v_lshlrev_b32_e32 v8, 12, v7
	v_lshl_add_u64 v[8:9], s[34:35], 0, v[8:9]
	s_lshl_b32 s60, s10, 2
	v_lshl_add_u64 v[8:9], v[8:9], 0, s[60:61]
	v_lshl_add_u64 v[8:9], v[8:9], 0, v[96:97]
	v_add_co_u32_e32 v10, vcc, s68, v8
	global_load_dword v7, v[8:9], off
	s_nop 0
	v_addc_co_u32_e32 v11, vcc, 0, v9, vcc
	global_load_dword v12, v[10:11], off
	v_add_co_u32_e32 v10, vcc, s75, v8
	s_mov_b32 s13, 0x10000
	s_nop 0
	v_addc_co_u32_e32 v11, vcc, 0, v9, vcc
	global_load_dword v13, v[10:11], off
	v_add_co_u32_e32 v10, vcc, s79, v8
	s_lshl_b32 s11, s11, 1
	s_nop 0
	v_addc_co_u32_e32 v11, vcc, 0, v9, vcc
	global_load_dword v14, v[10:11], off
	v_add_co_u32_e32 v10, vcc, s87, v8
	s_add_u32 s34, s26, s11
	s_nop 0
	v_addc_co_u32_e32 v11, vcc, 0, v9, vcc
	global_load_dword v15, v[10:11], off
	v_add_co_u32_e32 v10, vcc, s88, v8
	s_addc_u32 s35, s27, 0
	s_nop 0
	v_addc_co_u32_e32 v11, vcc, 0, v9, vcc
	global_load_dword v16, v[10:11], off
	v_add_co_u32_e32 v10, vcc, s62, v8
	s_nop 1
	v_addc_co_u32_e32 v11, vcc, 0, v9, vcc
	global_load_dword v17, v[10:11], off
	v_add_co_u32_e32 v10, vcc, s94, v8
	s_nop 1
	v_addc_co_u32_e32 v11, vcc, 0, v9, vcc
	global_load_dword v18, v[10:11], off
	v_add_co_u32_e32 v10, vcc, s13, v8
	s_mov_b32 s13, 0x22000
	s_nop 0
	v_addc_co_u32_e32 v11, vcc, 0, v9, vcc
	global_load_dword v19, v[10:11], off
	v_add_co_u32_e32 v10, vcc, s72, v8
	s_nop 1
	v_addc_co_u32_e32 v11, vcc, 0, v9, vcc
	global_load_dword v20, v[10:11], off
	v_add_co_u32_e32 v10, vcc, s73, v8
	s_nop 1
	v_addc_co_u32_e32 v11, vcc, 0, v9, vcc
	global_load_dword v21, v[10:11], off
	v_add_co_u32_e32 v10, vcc, s74, v8
	s_nop 1
	v_addc_co_u32_e32 v11, vcc, 0, v9, vcc
	global_load_dword v22, v[10:11], off
	v_add_co_u32_e32 v10, vcc, s85, v8
	s_nop 1
	v_addc_co_u32_e32 v11, vcc, 0, v9, vcc
	global_load_dword v23, v[10:11], off
	v_add_co_u32_e32 v10, vcc, s86, v8
	s_nop 1
	v_addc_co_u32_e32 v11, vcc, 0, v9, vcc
	global_load_dword v24, v[10:11], off
	v_add_co_u32_e32 v10, vcc, s90, v8
	s_nop 1
	v_addc_co_u32_e32 v11, vcc, 0, v9, vcc
	global_load_dword v25, v[10:11], off
	v_add_co_u32_e32 v10, vcc, s91, v8
	s_nop 1
	v_addc_co_u32_e32 v11, vcc, 0, v9, vcc
	global_load_dword v26, v[10:11], off
	v_add_co_u32_e32 v10, vcc, s95, v8
	s_nop 1
	v_addc_co_u32_e32 v11, vcc, 0, v9, vcc
	global_load_dword v27, v[10:11], off
	v_add_co_u32_e32 v10, vcc, s13, v8
	s_mov_b32 s13, 0x24000
	s_nop 0
	v_addc_co_u32_e32 v11, vcc, 0, v9, vcc
	global_load_dword v28, v[10:11], off
	v_add_co_u32_e32 v10, vcc, s13, v8
	s_mov_b32 s13, 0x28000
	s_nop 0
	v_addc_co_u32_e32 v11, vcc, 0, v9, vcc
	global_load_dword v29, v[10:11], off
	v_add_co_u32_e32 v10, vcc, s40, v8
	s_nop 1
	v_addc_co_u32_e32 v11, vcc, 0, v9, vcc
	global_load_dword v30, v[10:11], off
	v_add_co_u32_e32 v10, vcc, s13, v8
	s_mov_b32 s13, 0x2a000
	s_nop 0
	v_addc_co_u32_e32 v11, vcc, 0, v9, vcc
	global_load_dword v31, v[10:11], off
	v_add_co_u32_e32 v10, vcc, s13, v8
	s_mov_b32 s13, 0x2e000
	s_nop 0
	v_addc_co_u32_e32 v11, vcc, 0, v9, vcc
	global_load_dword v32, v[10:11], off
	v_add_co_u32_e32 v10, vcc, s41, v8
	s_nop 1
	v_addc_co_u32_e32 v11, vcc, 0, v9, vcc
	global_load_dword v33, v[10:11], off
	v_add_co_u32_e32 v10, vcc, s13, v8
	s_mov_b32 s13, 0x30000
	s_nop 0
	v_addc_co_u32_e32 v11, vcc, 0, v9, vcc
	global_load_dword v34, v[10:11], off
	v_add_co_u32_e32 v10, vcc, s13, v8
	s_mov_b32 s13, 0x32000
	s_nop 0
	v_addc_co_u32_e32 v11, vcc, 0, v9, vcc
	global_load_dword v35, v[10:11], off
	v_add_co_u32_e32 v10, vcc, s13, v8
	s_mov_b32 s13, 0x34000
	s_nop 0
	v_addc_co_u32_e32 v11, vcc, 0, v9, vcc
	global_load_dword v36, v[10:11], off
	v_add_co_u32_e32 v10, vcc, s13, v8
	s_mov_b32 s13, 0x36000
	s_nop 0
	v_addc_co_u32_e32 v11, vcc, 0, v9, vcc
	global_load_dword v37, v[10:11], off
	v_add_co_u32_e32 v10, vcc, s13, v8
	s_mov_b32 s13, 0x38000
	s_nop 0
	v_addc_co_u32_e32 v11, vcc, 0, v9, vcc
	global_load_dword v38, v[10:11], off
	v_add_co_u32_e32 v10, vcc, s13, v8
	s_mov_b32 s13, 0x3a000
	s_nop 0
	v_addc_co_u32_e32 v11, vcc, 0, v9, vcc
	global_load_dword v39, v[10:11], off
	v_add_co_u32_e32 v10, vcc, s13, v8
	s_mov_b32 s13, 0x3c000
	s_nop 0
	v_addc_co_u32_e32 v11, vcc, 0, v9, vcc
	global_load_dword v40, v[10:11], off
	v_add_co_u32_e32 v10, vcc, s13, v8
	s_mov_b32 s13, 0x3e000
	s_nop 0
	v_addc_co_u32_e32 v11, vcc, 0, v9, vcc
	v_add_co_u32_e32 v8, vcc, s13, v8
	global_load_dword v10, v[10:11], off
	s_nop 0
	v_addc_co_u32_e32 v9, vcc, 0, v9, vcc
	global_load_dword v8, v[8:9], off
	s_waitcnt vmcnt(0)
	ds_write2_b32 v1, v7, v12 offset1:66
	ds_write2_b32 v1, v13, v14 offset0:132 offset1:198
	ds_write2_b32 v51, v15, v16 offset0:8 offset1:74
	ds_write2_b32 v51, v17, v18 offset0:140 offset1:206
	ds_write2_b32 v50, v19, v20 offset0:16 offset1:82
	ds_write2_b32 v50, v21, v22 offset0:148 offset1:214
	ds_write2_b32 v49, v23, v24 offset0:24 offset1:90
	ds_write2_b32 v49, v25, v26 offset0:156 offset1:222
	ds_write2_b32 v48, v27, v28 offset0:32 offset1:98
	ds_write2_b32 v48, v29, v30 offset0:164 offset1:230
	ds_write2_b32 v47, v31, v32 offset0:40 offset1:106
	ds_write2_b32 v47, v33, v34 offset0:172 offset1:238
	ds_write2_b32 v46, v35, v36 offset0:48 offset1:114
	ds_write2_b32 v46, v37, v38 offset0:180 offset1:246
	ds_write2_b32 v45, v39, v40 offset0:56 offset1:122
	ds_write2_b32 v45, v10, v8 offset0:188 offset1:254
	v_mov_b32_e32 v7, v97
	s_waitcnt lgkmcnt(0)
	v_lshl_add_u64 v[8:9], s[34:35], 0, v[6:7]
	s_mov_b64 s[34:35], 0xb00000
	v_lshl_add_u64 v[12:13], v[8:9], 0, s[34:35]
	ds_read2_b32 v[8:9], v5 offset1:33
	s_waitcnt lgkmcnt(0)
	v_cvt_pk_bf16_f32 v8, v8, v9
	ds_read2_b32 v[10:11], v5 offset0:66 offset1:99
	s_waitcnt lgkmcnt(0)
	v_cvt_pk_bf16_f32 v9, v10, v11
	ds_read2_b32 v[10:11], v5 offset0:132 offset1:165
	v_or_b32_e32 v7, s10, v3
	s_waitcnt lgkmcnt(0)
	v_cvt_pk_bf16_f32 v10, v10, v11
	ds_read2_b32 v[14:15], v5 offset0:198 offset1:231
	v_mul_u32_u24_e32 v7, 0xb00, v7
	s_waitcnt lgkmcnt(0)
	v_cvt_pk_bf16_f32 v11, v14, v15
	v_lshlrev_b32_e32 v14, 1, v7
	v_mov_b32_e32 v15, v97
	v_lshl_add_u64 v[14:15], v[12:13], 0, v[14:15]
	global_store_dwordx4 v[14:15], v[8:11], off sc1
	ds_read2_b32 v[8:9], v5 offset0:8 offset1:41
	v_or_b32_e32 v7, s10, v42
	s_waitcnt lgkmcnt(0)
	v_cvt_pk_bf16_f32 v8, v8, v9
	ds_read2_b32 v[10:11], v5 offset0:74 offset1:107
	s_waitcnt lgkmcnt(0)
	v_cvt_pk_bf16_f32 v9, v10, v11
	ds_read2_b32 v[10:11], v5 offset0:140 offset1:173
	s_waitcnt lgkmcnt(0)
	v_cvt_pk_bf16_f32 v10, v10, v11
	ds_read2_b32 v[14:15], v5 offset0:206 offset1:239
	v_mul_u32_u24_e32 v7, 0xb00, v7
	s_waitcnt lgkmcnt(0)
	v_cvt_pk_bf16_f32 v11, v14, v15
	v_lshlrev_b32_e32 v14, 1, v7
	v_mov_b32_e32 v15, v97
	v_lshl_add_u64 v[14:15], v[12:13], 0, v[14:15]
	global_store_dwordx4 v[14:15], v[8:11], off sc1
	ds_read2_b32 v[8:9], v5 offset0:16 offset1:49
	v_or_b32_e32 v7, s10, v43
	s_waitcnt lgkmcnt(0)
	v_cvt_pk_bf16_f32 v8, v8, v9
	ds_read2_b32 v[10:11], v5 offset0:82 offset1:115
	s_waitcnt lgkmcnt(0)
	v_cvt_pk_bf16_f32 v9, v10, v11
	ds_read2_b32 v[10:11], v5 offset0:148 offset1:181
	s_waitcnt lgkmcnt(0)
	v_cvt_pk_bf16_f32 v10, v10, v11
	ds_read2_b32 v[14:15], v5 offset0:214 offset1:247
	v_mul_u32_u24_e32 v7, 0xb00, v7
	s_waitcnt lgkmcnt(0)
	v_cvt_pk_bf16_f32 v11, v14, v15
	v_lshlrev_b32_e32 v14, 1, v7
	v_mov_b32_e32 v15, v97
	v_lshl_add_u64 v[14:15], v[12:13], 0, v[14:15]
	global_store_dwordx4 v[14:15], v[8:11], off sc1
	ds_read2_b32 v[8:9], v5 offset0:24 offset1:57
	v_or_b32_e32 v7, s10, v44
	s_waitcnt lgkmcnt(0)
	v_cvt_pk_bf16_f32 v8, v8, v9
	ds_read2_b32 v[10:11], v5 offset0:90 offset1:123
	s_waitcnt lgkmcnt(0)
	v_cvt_pk_bf16_f32 v9, v10, v11
	ds_read2_b32 v[10:11], v5 offset0:156 offset1:189
	s_waitcnt lgkmcnt(0)
	v_cvt_pk_bf16_f32 v10, v10, v11
	ds_read2_b32 v[14:15], v5 offset0:222 offset1:255
	v_mul_u32_u24_e32 v7, 0xb00, v7
	s_waitcnt lgkmcnt(0)
	v_cvt_pk_bf16_f32 v11, v14, v15
	v_lshlrev_b32_e32 v14, 1, v7
	v_mov_b32_e32 v15, v97
	v_lshl_add_u64 v[12:13], v[12:13], 0, v[14:15]
	global_store_dwordx4 v[12:13], v[8:11], off sc1
	s_waitcnt lgkmcnt(0)
	s_mov_b64 s[10:11], 0

.LBB0_246:
	v_add_co_u32_e32 v0, vcc, 0xffff1000, v82
	s_movk_i32 s23, 0x8000
	s_nop 0
	v_addc_co_u32_e32 v1, vcc, -1, v83, vcc
	global_load_dword v98, v[0:1], off
	v_add_co_u32_e32 v0, vcc, 0xffff2000, v82
	v_mov_b32_e32 v77, s22
	s_nop 0
	v_addc_co_u32_e32 v1, vcc, -1, v83, vcc
	global_load_dword v102, v[0:1], off
	v_add_co_u32_e32 v0, vcc, 0xffff3000, v82
	s_add_i32 s21, s21, 16
	s_nop 0
	v_addc_co_u32_e32 v1, vcc, -1, v83, vcc
	global_load_dword v103, v[0:1], off
	v_add_co_u32_e32 v0, vcc, 0xffff4000, v82
	s_add_i32 s22, s22, 64
	s_nop 0
	v_addc_co_u32_e32 v1, vcc, -1, v83, vcc
	global_load_dword v99, v[0:1], off
	v_add_co_u32_e32 v0, vcc, 0xffff5000, v82
	s_mov_b64 s[24:25], 0x10000
	s_nop 0
	v_addc_co_u32_e32 v1, vcc, -1, v83, vcc
	global_load_dword v100, v[0:1], off
	v_add_co_u32_e32 v0, vcc, 0xffff6000, v82
	s_cmpk_lt_u32 s21, 0x70
	s_nop 0
	v_addc_co_u32_e32 v1, vcc, -1, v83, vcc
	global_load_dword v101, v[0:1], off
	v_add_co_u32_e32 v0, vcc, 0xffff7000, v82
	s_waitcnt vmcnt(1)
	v_mov_b32_e32 v40, v100
	v_addc_co_u32_e32 v1, vcc, -1, v83, vcc
	global_load_dword v104, v[0:1], off
	v_add_co_u32_e32 v0, vcc, s23, v82
	s_waitcnt vmcnt(1)
	v_mov_b32_e32 v20, v101
	v_addc_co_u32_e32 v1, vcc, -1, v83, vcc
	global_load_dword v105, v[0:1], off
	v_add_co_u32_e32 v0, vcc, 0xffff9000, v82
	s_waitcnt vmcnt(1)
	v_mov_b32_e32 v21, v104
	v_addc_co_u32_e32 v1, vcc, -1, v83, vcc
	global_load_dword v92, v[0:1], off
	v_add_co_u32_e32 v0, vcc, 0xffffa000, v82
	s_waitcnt vmcnt(1)
	v_mov_b32_e32 v41, v105
	v_addc_co_u32_e32 v1, vcc, -1, v83, vcc
	global_load_dword v93, v[0:1], off
	v_add_co_u32_e32 v0, vcc, 0xffffb000, v82
	s_nop 1
	v_addc_co_u32_e32 v1, vcc, -1, v83, vcc
	global_load_dword v94, v[0:1], off
	v_add_co_u32_e32 v0, vcc, 0xffffc000, v82
	s_nop 1
	v_addc_co_u32_e32 v1, vcc, -1, v83, vcc
	global_load_dword v95, v[0:1], off
	v_add_co_u32_e32 v0, vcc, 0xffffd000, v82
	s_nop 1
	v_addc_co_u32_e32 v1, vcc, -1, v83, vcc
	global_load_dword v106, v[0:1], off
	v_add_co_u32_e32 v0, vcc, 0xffffe000, v82
	s_nop 1
	v_addc_co_u32_e32 v1, vcc, -1, v83, vcc
	global_load_dword v110, v[0:1], off
	global_load_dword v96, v[82:83], off offset:-4096
	global_load_dword v108, v[82:83], off
	ds_read_b128 v[60:63], v77
	ds_read_b128 v[56:59], v77 offset:16
	ds_read_b128 v[52:55], v77 offset:32
	ds_read_b128 v[48:51], v77 offset:48
	ds_read_b128 v[64:67], v77 offset:512
	ds_read_b128 v[24:27], v77 offset:1024
	ds_read_b128 v[28:31], v77 offset:1536
	ds_read_b128 v[0:3], v77 offset:2048
	ds_read_b128 v[4:7], v77 offset:2560
	ds_read_b128 v[8:11], v77 offset:3072
	s_waitcnt lgkmcnt(5)
	v_mov_b32_e32 v129, v64
	v_mov_b32_e32 v64, v61
	v_mov_b32_e32 v128, v60
	v_pk_mul_f32 v[60:61], v[102:103], v[64:65] op_sel_hi:[0,1]
	s_waitcnt lgkmcnt(0)
	v_mov_b32_e32 v12, v9
	v_mov_b32_e32 v9, v11
	v_mov_b32_e32 v13, v10
	v_pk_mul_f32 v[8:9], v[98:99], v[8:9]
	v_pk_fma_f32 v[60:61], v[98:99], v[128:129], v[60:61] op_sel_hi:[0,1,1]
	v_pk_fma_f32 v[116:117], v[102:103], v[12:13], v[8:9]
	ds_read_b128 v[8:11], v77 offset:3584
	v_mov_b32_e32 v128, v62
	v_mov_b32_e32 v129, v66
	v_mov_b32_e32 v62, v99
	v_mov_b32_e32 v66, v63
	s_waitcnt lgkmcnt(0)
	v_mov_b32_e32 v12, v9
	v_mov_b32_e32 v9, v11
	v_mov_b32_e32 v13, v10
	v_pk_mul_f32 v[8:9], v[98:99], v[8:9]
	v_mov_b32_e32 v64, v103
	v_pk_fma_f32 v[112:113], v[102:103], v[12:13], v[8:9]
	ds_read_b128 v[68:71], v77 offset:528
	ds_read_b128 v[32:35], v77 offset:1040
	ds_read_b128 v[36:39], v77 offset:1552
	ds_read_b128 v[8:11], v77 offset:2064
	ds_read_b128 v[12:15], v77 offset:2576
	ds_read_b128 v[120:123], v77 offset:3088
	ds_read_b128 v[16:19], v77 offset:3600
	v_pk_mul_f32 v[66:67], v[62:63], v[66:67] op_sel_hi:[0,1]
	v_pk_fma_f32 v[66:67], v[64:65], v[128:129], v[66:67] op_sel_hi:[0,1,1]
	v_pk_add_f32 v[60:61], v[60:61], v[66:67]
	v_mov_b32_e32 v66, v56
	s_waitcnt lgkmcnt(0)
	v_mov_b32_e32 v22, v17
	v_mov_b32_e32 v17, v19
	v_mov_b32_e32 v67, v68
	v_mov_b32_e32 v56, v101
	v_mov_b32_e32 v68, v57
	v_mov_b32_e32 v23, v18
	v_pk_mul_f32 v[16:17], v[40:41], v[16:17]
	v_pk_mul_f32 v[68:69], v[56:57], v[68:69] op_sel_hi:[0,1]
	v_pk_fma_f32 v[114:115], v[20:21], v[22:23], v[16:17]
	ds_read_b128 v[72:75], v77 offset:544
	ds_read_b128 v[40:43], v77 offset:1056
	ds_read_b128 v[44:47], v77 offset:1568
	ds_read_b128 v[16:19], v77 offset:2080
	ds_read_b128 v[20:23], v77 offset:2592
	ds_read_b128 v[124:127], v77 offset:3104
	v_pk_fma_f32 v[66:67], v[100:101], v[66:67], v[68:69] op_sel_hi:[0,1,1]
	v_mov_b32_e32 v68, v58
	v_mov_b32_e32 v69, v70
	v_mov_b32_e32 v58, v105
	v_mov_b32_e32 v70, v59
	v_pk_mul_f32 v[70:71], v[58:59], v[70:71] op_sel_hi:[0,1]
	v_pk_fma_f32 v[68:69], v[104:105], v[68:69], v[70:71] op_sel_hi:[0,1,1]
	v_pk_add_f32 v[60:61], v[86:87], v[60:61]
	v_pk_add_f32 v[66:67], v[66:67], v[68:69]
	v_pk_add_f32 v[116:117], v[116:117], v[116:117] op_sel:[0,1] op_sel_hi:[1,0]
	v_pk_add_f32 v[60:61], v[60:61], v[66:67]
	s_waitcnt lgkmcnt(5)
	v_mov_b32_e32 v67, v72
	v_mov_b32_e32 v72, v53
	s_waitcnt vmcnt(7) lgkmcnt(0)
	v_mul_f32_e32 v107, v92, v124
	v_mul_f32_e32 v124, v101, v121
	v_mov_b32_e32 v66, v52
	v_lshl_add_u64 v[82:83], v[82:83], 0, s[24:25]
	s_waitcnt vmcnt(6)
	v_mov_b32_e32 v68, v93
	v_mul_f32_e32 v111, v93, v125
	v_pk_mul_f32 v[52:53], v[68:69], v[72:73] op_sel_hi:[0,1]
	v_pk_fma_f32 v[52:53], v[92:93], v[66:67], v[52:53] op_sel_hi:[0,1,1]
	v_mov_b32_e32 v67, v74
	v_mov_b32_e32 v74, v55
	s_waitcnt vmcnt(5)
	v_mul_f32_e32 v125, v94, v126
	v_pk_fma_f32 v[120:121], v[100:101], v[120:121], v[124:125] op_sel_hi:[1,1,0]
	v_mul_f32_e32 v124, v105, v123
	v_pk_fma_f32 v[122:123], v[104:105], v[122:123], v[124:125] op_sel_hi:[1,1,0]
	v_mov_b32_e32 v66, v54
	v_mov_b32_e32 v121, v107
	s_waitcnt vmcnt(4)
	v_mov_b32_e32 v70, v95
	v_mul_f32_e32 v119, v95, v127
	v_pk_mul_f32 v[54:55], v[70:71], v[74:75] op_sel_hi:[0,1]
	v_mov_b32_e32 v123, v111
	v_mov_b32_e32 v124, v88
	v_mov_b32_e32 v117, v119
	v_pk_fma_f32 v[54:55], v[94:95], v[66:67], v[54:55] op_sel_hi:[0,1,1]
	v_pk_add_f32 v[120:121], v[120:121], v[122:123]
	v_pk_add_f32 v[116:117], v[124:125], v[116:117]
	v_pk_add_f32 v[52:53], v[52:53], v[54:55]
	v_pk_add_f32 v[116:117], v[120:121], v[116:117]
	ds_read_b128 v[120:123], v77 offset:3616
	ds_read_b128 v[124:127], v77 offset:560
	v_pk_add_f32 v[52:53], v[60:61], v[52:53]
	v_mov_b32_e32 v61, v28
	v_mov_b32_e32 v28, v25
	v_mov_b32_e32 v60, v24
	v_pk_mul_f32 v[24:25], v[102:103], v[28:29] op_sel_hi:[0,1]
	v_mov_b32_e32 v29, v30
	v_mov_b32_e32 v30, v27
	v_mov_b32_e32 v28, v26
	v_pk_mul_f32 v[26:27], v[62:63], v[30:31] op_sel_hi:[0,1]
	v_pk_fma_f32 v[24:25], v[98:99], v[60:61], v[24:25] op_sel_hi:[0,1,1]
	v_pk_fma_f32 v[26:27], v[64:65], v[28:29], v[26:27] op_sel_hi:[0,1,1]
	v_pk_add_f32 v[24:25], v[24:25], v[26:27]
	v_mov_b32_e32 v27, v36
	v_mov_b32_e32 v36, v33
	s_waitcnt lgkmcnt(0)
	v_mov_b32_e32 v55, v124
	v_mov_b32_e32 v124, v49
	v_mov_b32_e32 v26, v32
	v_pk_mul_f32 v[28:29], v[56:57], v[36:37] op_sel_hi:[0,1]
	v_mov_b32_e32 v54, v48
	s_waitcnt vmcnt(2)
	v_pk_mul_f32 v[48:49], v[110:111], v[124:125] op_sel_hi:[0,1]
	v_pk_fma_f32 v[26:27], v[100:101], v[26:27], v[28:29] op_sel_hi:[0,1,1]
	v_mov_b32_e32 v29, v38
	v_mov_b32_e32 v38, v35
	v_pk_fma_f32 v[48:49], v[106:107], v[54:55], v[48:49] op_sel_hi:[0,1,1]
	v_mov_b32_e32 v55, v126
	v_mov_b32_e32 v126, v51
	v_mov_b32_e32 v28, v34
	v_pk_mul_f32 v[30:31], v[58:59], v[38:39] op_sel_hi:[0,1]
	v_mov_b32_e32 v54, v50
	s_waitcnt vmcnt(0)
	v_pk_mul_f32 v[50:51], v[108:109], v[126:127] op_sel_hi:[0,1]
	v_pk_fma_f32 v[28:29], v[104:105], v[28:29], v[30:31] op_sel_hi:[0,1,1]
	v_pk_fma_f32 v[50:51], v[96:97], v[54:55], v[50:51] op_sel_hi:[0,1,1]
	v_pk_add_f32 v[24:25], v[84:85], v[24:25]
	v_pk_add_f32 v[26:27], v[26:27], v[28:29]
	v_pk_add_f32 v[48:49], v[48:49], v[50:51]
	v_pk_add_f32 v[24:25], v[24:25], v[26:27]
	v_mov_b32_e32 v27, v44
	v_mov_b32_e32 v44, v41
	v_pk_add_f32 v[86:87], v[52:53], v[48:49]
	ds_read_b128 v[48:51], v77 offset:1072
	ds_read_b128 v[52:55], v77 offset:1584
	v_mov_b32_e32 v26, v40
	v_pk_mul_f32 v[28:29], v[68:69], v[44:45] op_sel_hi:[0,1]
	v_mov_b32_e32 v33, v4
	v_mov_b32_e32 v4, v1
	v_pk_fma_f32 v[26:27], v[92:93], v[26:27], v[28:29] op_sel_hi:[0,1,1]
	v_mov_b32_e32 v29, v46
	v_mov_b32_e32 v46, v43
	v_mov_b32_e32 v32, v0
	v_pk_mul_f32 v[0:1], v[102:103], v[4:5] op_sel_hi:[0,1]
	v_mov_b32_e32 v5, v6
	v_mov_b32_e32 v6, v3
	v_mov_b32_e32 v28, v42
	v_pk_mul_f32 v[30:31], v[70:71], v[46:47] op_sel_hi:[0,1]
	v_mov_b32_e32 v4, v2
	v_pk_mul_f32 v[2:3], v[62:63], v[6:7] op_sel_hi:[0,1]
	v_pk_fma_f32 v[28:29], v[94:95], v[28:29], v[30:31] op_sel_hi:[0,1,1]
	v_pk_fma_f32 v[0:1], v[98:99], v[32:33], v[0:1] op_sel_hi:[0,1,1]
	v_pk_fma_f32 v[2:3], v[64:65], v[4:5], v[2:3] op_sel_hi:[0,1,1]
	v_pk_add_f32 v[26:27], v[26:27], v[28:29]
	v_pk_add_f32 v[0:1], v[0:1], v[2:3]
	v_mov_b32_e32 v3, v12
	v_mov_b32_e32 v12, v9
	v_pk_add_f32 v[24:25], v[24:25], v[26:27]
	s_waitcnt lgkmcnt(0)
	v_mov_b32_e32 v27, v52
	v_mov_b32_e32 v52, v49
	v_mov_b32_e32 v2, v8
	v_pk_mul_f32 v[4:5], v[56:57], v[12:13] op_sel_hi:[0,1]
	v_mov_b32_e32 v26, v48
	v_pk_mul_f32 v[28:29], v[110:111], v[52:53] op_sel_hi:[0,1]
	v_pk_fma_f32 v[2:3], v[100:101], v[2:3], v[4:5] op_sel_hi:[0,1,1]
	v_mov_b32_e32 v5, v14
	v_mov_b32_e32 v14, v11
	v_pk_fma_f32 v[26:27], v[106:107], v[26:27], v[28:29] op_sel_hi:[0,1,1]
	v_mov_b32_e32 v29, v54
	v_mov_b32_e32 v54, v51
	v_mov_b32_e32 v4, v10
	v_pk_mul_f32 v[6:7], v[58:59], v[14:15] op_sel_hi:[0,1]
	v_mov_b32_e32 v28, v50
	v_pk_mul_f32 v[30:31], v[108:109], v[54:55] op_sel_hi:[0,1]
	v_pk_fma_f32 v[4:5], v[104:105], v[4:5], v[6:7] op_sel_hi:[0,1,1]
	v_pk_fma_f32 v[28:29], v[96:97], v[28:29], v[30:31] op_sel_hi:[0,1,1]
	v_pk_add_f32 v[0:1], v[90:91], v[0:1]
	v_pk_add_f32 v[2:3], v[2:3], v[4:5]
	v_pk_add_f32 v[26:27], v[26:27], v[28:29]
	v_pk_add_f32 v[0:1], v[0:1], v[2:3]
	v_mov_b32_e32 v3, v20
	v_mov_b32_e32 v20, v17
	v_pk_add_f32 v[84:85], v[24:25], v[26:27]
	ds_read_b128 v[24:27], v77 offset:2096
	ds_read_b128 v[28:31], v77 offset:2608
	v_mov_b32_e32 v2, v16
	v_pk_mul_f32 v[4:5], v[68:69], v[20:21] op_sel_hi:[0,1]
	v_pk_fma_f32 v[2:3], v[92:93], v[2:3], v[4:5] op_sel_hi:[0,1,1]
	v_mov_b32_e32 v5, v22
	v_mov_b32_e32 v22, v19
	v_mov_b32_e32 v4, v18
	v_pk_mul_f32 v[6:7], v[70:71], v[22:23] op_sel_hi:[0,1]
	v_pk_fma_f32 v[4:5], v[94:95], v[4:5], v[6:7] op_sel_hi:[0,1,1]
	v_pk_add_f32 v[2:3], v[2:3], v[4:5]
	v_pk_add_f32 v[116:117], v[116:117], v[116:117] op_sel:[0,1] op_sel_hi:[1,0]
	v_pk_add_f32 v[0:1], v[0:1], v[2:3]
	s_waitcnt lgkmcnt(0)
	v_mov_b32_e32 v3, v28
	v_mov_b32_e32 v28, v25
	v_mov_b32_e32 v2, v24
	v_pk_mul_f32 v[4:5], v[110:111], v[28:29] op_sel_hi:[0,1]
	v_pk_fma_f32 v[2:3], v[106:107], v[2:3], v[4:5] op_sel_hi:[0,1,1]
	v_mov_b32_e32 v5, v30
	v_mov_b32_e32 v30, v27
	v_mov_b32_e32 v4, v26
	v_pk_mul_f32 v[6:7], v[108:109], v[30:31] op_sel_hi:[0,1]
	v_pk_fma_f32 v[4:5], v[96:97], v[4:5], v[6:7] op_sel_hi:[0,1,1]
	v_pk_add_f32 v[2:3], v[2:3], v[4:5]
	v_mov_b32_e32 v107, v108
	v_pk_add_f32 v[90:91], v[0:1], v[2:3]
	ds_read_b128 v[0:3], v77 offset:3120
	v_mov_b32_e32 v111, v96
	v_mov_b32_e32 v7, v106
	s_waitcnt lgkmcnt(0)
	v_mov_b32_e32 v4, v1
	v_mov_b32_e32 v1, v3
	v_mov_b32_e32 v5, v2
	v_pk_mul_f32 v[0:1], v[106:107], v[0:1]
	s_nop 0
	v_pk_fma_f32 v[0:1], v[110:111], v[4:5], v[0:1]
	s_nop 0
	v_pk_add_f32 v[4:5], v[0:1], v[0:1] op_sel:[0,1] op_sel_hi:[1,0]
	ds_read_b128 v[0:3], v77 offset:3632
	s_waitcnt lgkmcnt(0)
	v_mul_f32_e32 v8, v96, v2
	v_mul_f32_e32 v9, v108, v3
	v_pk_add_f32 v[2:3], v[112:113], v[112:113] op_sel:[0,1] op_sel_hi:[1,0]
	v_mul_f32_e32 v5, v110, v1
	v_pk_mov_b32 v[0:1], v[88:89], v[0:1] op_sel:[1,0]
	v_mov_b32_e32 v6, v2
	v_pk_add_f32 v[2:3], v[0:1], v[2:3]
	v_pk_mul_f32 v[0:1], v[0:1], v[6:7]
	v_mul_f32_e32 v6, v95, v123
	v_mov_b32_e32 v3, v1
	v_pk_add_f32 v[0:1], v[114:115], v[114:115] op_sel:[0,1] op_sel_hi:[1,0]
	v_pk_fma_f32 v[6:7], v[94:95], v[122:123], v[6:7] op_sel_hi:[1,1,0]
	v_mov_b32_e32 v1, v5
	v_pk_add_f32 v[0:1], v[2:3], v[0:1]
	v_mul_f32_e32 v2, v93, v121
	v_pk_fma_f32 v[2:3], v[92:93], v[120:121], v[2:3] op_sel_hi:[1,1,0]
	v_mov_b32_e32 v7, v9
	v_mov_b32_e32 v3, v8
	v_pk_add_f32 v[2:3], v[2:3], v[6:7]
	s_nop 0
	v_pk_add_f32 v[0:1], v[0:1], v[2:3]
	s_nop 0
	v_mov_b32_e32 v117, v0
	v_mov_b32_e32 v5, v1
	v_pk_add_f32 v[88:89], v[116:117], v[4:5]
	s_cbranch_scc1 .LBB0_246
	s_lshl_b32 s21, s18, 6
	s_and_b32 s21, s21, 0x3c0
	v_or_b32_e32 v4, s21, v118
	v_lshlrev_b32_e32 v96, 11, v4
	v_lshl_add_u64 v[4:5], s[6:7], 0, v[96:97]
	s_lshl_b32 s60, s20, 1
	v_lshl_add_u64 v[4:5], v[4:5], 0, s[60:61]
	s_lshl_b32 s60, s19, 1
	v_lshl_add_u64 v[4:5], v[4:5], 0, s[60:61]
	v_cvt_pk_bf16_f32 v0, v86, v87
	v_cvt_pk_bf16_f32 v1, v84, v85
	v_cvt_pk_bf16_f32 v2, v90, v91
	v_cvt_pk_bf16_f32 v3, v88, v89
	global_store_dwordx4 v[4:5], v[0:3], off sc1
	s_waitcnt lgkmcnt(0)
	s_add_i32 s18, s18, s14
	s_add_i32 s13, s13, s12
	s_cmpk_gt_i32 s18, 0x3ff
	s_cbranch_scc0 .LBB0_245

.LBB0_250:
	v_add_u32_e32 v6, s8, v6
	s_movk_i32 s9, 0x2fff
	v_cmp_lt_i32_e32 vcc, s9, v6
	global_store_dwordx4 v[4:5], v[0:3], off sc1
	s_or_b64 s[10:11], vcc, s[10:11]
	v_lshl_add_u64 v[4:5], v[4:5], 0, s[4:5]
	s_andn2_b64 exec, exec, s[10:11]
	s_cbranch_execnz .LBB0_250

.LBB0_255:
	s_bfe_i32 s4, s18, 0x80000
	s_bfe_u32 s4, s4, 0x2000d
	s_add_i32 s18, s18, s4
	s_bfe_i32 s4, s18, 0x80000
	s_bfe_u32 s5, s8, 0x70018
	s_sext_i32_i16 s4, s4
	s_add_i32 s5, s8, s5
	s_lshl_b32 s4, s4, 6
	s_and_b32 s5, s5, 0xff80
	s_and_b32 s4, s4, 0xffffff00
	s_sub_i32 s5, s8, s5
	s_lshl_b32 s8, s21, 7
	s_sext_i32_i16 s5, s5
	s_add_i32 s4, s4, s8
	s_add_i32 s8, s4, s5
	s_lshl_b64 s[4:5], s[6:7], 1
	s_waitcnt vmcnt(0)
	ds_write2_b32 v44, v8, v9 offset1:66
	ds_write2_b32 v44, v10, v11 offset0:132 offset1:198
	ds_write2_b32 v51, v12, v13 offset0:8 offset1:74
	ds_write2_b32 v51, v14, v15 offset0:140 offset1:206
	ds_write2_b32 v50, v16, v17 offset0:16 offset1:82
	ds_write2_b32 v50, v18, v19 offset0:148 offset1:214
	ds_write2_b32 v49, v20, v21 offset0:24 offset1:90
	ds_write2_b32 v49, v22, v23 offset0:156 offset1:222
	ds_write2_b32 v48, v24, v25 offset0:32 offset1:98
	ds_write2_b32 v48, v26, v27 offset0:164 offset1:230
	ds_write2_b32 v47, v28, v29 offset0:40 offset1:106
	ds_write2_b32 v47, v30, v31 offset0:172 offset1:238
	ds_write2_b32 v46, v32, v33 offset0:48 offset1:114
	ds_write2_b32 v46, v34, v35 offset0:180 offset1:246
	ds_write2_b32 v45, v36, v37 offset0:56 offset1:122
	ds_write2_b32 v45, v40, v41 offset0:188 offset1:254
	s_add_u32 s4, s16, s4
	s_waitcnt lgkmcnt(0)
	s_addc_u32 s5, s17, s5
	v_mov_b32_e32 v7, v97
	ds_read2_b32 v[8:9], v3 offset1:33
	v_lshl_add_u64 v[14:15], s[4:5], 0, v[6:7]
	v_or_b32_e32 v6, s8, v1
	s_waitcnt lgkmcnt(0)
	v_cvt_pk_bf16_f32 v8, v8, v9
	ds_read2_b32 v[10:11], v3 offset0:66 offset1:99
	v_ashrrev_i32_e32 v7, 31, v6
	s_waitcnt lgkmcnt(0)
	v_cvt_pk_bf16_f32 v9, v10, v11
	ds_read2_b32 v[10:11], v3 offset0:132 offset1:165
	v_lshlrev_b64 v[6:7], 11, v[6:7]
	s_waitcnt lgkmcnt(0)
	v_cvt_pk_bf16_f32 v10, v10, v11
	ds_read2_b32 v[12:13], v3 offset0:198 offset1:231
	v_lshl_add_u64 v[6:7], v[14:15], 0, v[6:7]
	s_waitcnt lgkmcnt(0)
	v_cvt_pk_bf16_f32 v11, v12, v13
	ds_read2_b32 v[12:13], v3 offset0:8 offset1:41
	global_store_dwordx4 v[6:7], v[8:11], off sc1
	s_waitcnt lgkmcnt(0)
	v_cvt_pk_bf16_f32 v6, v12, v13
	ds_read2_b32 v[8:9], v3 offset0:74 offset1:107
	s_waitcnt lgkmcnt(0)
	v_cvt_pk_bf16_f32 v7, v8, v9
	ds_read2_b32 v[8:9], v3 offset0:140 offset1:173
	s_waitcnt lgkmcnt(0)
	v_cvt_pk_bf16_f32 v8, v8, v9
	ds_read2_b32 v[10:11], v3 offset0:206 offset1:239
	s_waitcnt lgkmcnt(0)
	v_cvt_pk_bf16_f32 v9, v10, v11
	v_or_b32_e32 v10, s8, v5
	v_ashrrev_i32_e32 v11, 31, v10
	v_lshlrev_b64 v[10:11], 11, v[10:11]
	v_lshl_add_u64 v[10:11], v[14:15], 0, v[10:11]
	ds_read2_b32 v[12:13], v3 offset0:16 offset1:49
	global_store_dwordx4 v[10:11], v[6:9], off sc1
	s_waitcnt lgkmcnt(0)
	s_nop 0
	v_cvt_pk_bf16_f32 v6, v12, v13
	ds_read2_b32 v[8:9], v3 offset0:82 offset1:115
	s_waitcnt lgkmcnt(0)
	v_cvt_pk_bf16_f32 v7, v8, v9
	ds_read2_b32 v[8:9], v3 offset0:148 offset1:181
	s_waitcnt lgkmcnt(0)
	v_cvt_pk_bf16_f32 v8, v8, v9
	ds_read2_b32 v[10:11], v3 offset0:214 offset1:247
	s_waitcnt lgkmcnt(0)
	v_cvt_pk_bf16_f32 v9, v10, v11
	v_or_b32_e32 v10, s8, v42
	v_ashrrev_i32_e32 v11, 31, v10
	v_lshlrev_b64 v[10:11], 11, v[10:11]
	v_lshl_add_u64 v[10:11], v[14:15], 0, v[10:11]
	ds_read2_b32 v[12:13], v3 offset0:24 offset1:57
	global_store_dwordx4 v[10:11], v[6:9], off sc1
	s_waitcnt lgkmcnt(0)
	s_nop 0
	v_cvt_pk_bf16_f32 v6, v12, v13
	ds_read2_b32 v[8:9], v3 offset0:90 offset1:123
	s_waitcnt lgkmcnt(0)
	v_cvt_pk_bf16_f32 v7, v8, v9
	ds_read2_b32 v[8:9], v3 offset0:156 offset1:189
	s_waitcnt lgkmcnt(0)
	v_cvt_pk_bf16_f32 v8, v8, v9
	ds_read2_b32 v[10:11], v3 offset0:222 offset1:255
	s_waitcnt lgkmcnt(0)
	v_cvt_pk_bf16_f32 v9, v10, v11
	v_or_b32_e32 v10, s8, v43
	v_ashrrev_i32_e32 v11, 31, v10
	v_lshlrev_b64 v[10:11], 11, v[10:11]
	v_lshl_add_u64 v[10:11], v[14:15], 0, v[10:11]
	global_store_dwordx4 v[10:11], v[6:9], off sc1
	s_waitcnt lgkmcnt(0)

.LBB0_259:
	s_and_b32 s11, 0xffff, s18
	s_and_b64 s[8:9], s[6:7], exec
	s_cselect_b32 s8, 32, 0x48
	s_add_u32 s8, s2, s8
	s_addc_u32 s9, s3, 0
	s_load_dwordx2 s[8:9], s[8:9], 0x0
	v_mov_b32_e32 v9, v97
	s_waitcnt lgkmcnt(0)
	s_add_u32 s22, s8, s20
	s_addc_u32 s23, s9, s19
	s_lshl_b32 s8, s11, 1
	s_and_b32 s9, s8, 0xfc0
	s_lshl_b32 s8, s11, 5
	v_or_b32_e32 v7, s9, v0
	s_and_b32 s8, s8, 0x3e0
	v_lshlrev_b32_e32 v8, 12, v7
	v_lshl_add_u64 v[8:9], s[22:23], 0, v[8:9]
	s_lshl_b32 s60, s8, 2
	v_lshl_add_u64 v[8:9], v[8:9], 0, s[60:61]
	v_lshl_add_u64 v[8:9], v[8:9], 0, v[96:97]
	v_add_co_u32_e32 v10, vcc, s68, v8
	global_load_dword v7, v[8:9], off
	s_nop 0
	v_addc_co_u32_e32 v11, vcc, 0, v9, vcc
	global_load_dword v12, v[10:11], off
	v_add_co_u32_e32 v10, vcc, s75, v8
	s_mov_b32 s11, 0x22000
	s_nop 0
	v_addc_co_u32_e32 v11, vcc, 0, v9, vcc
	global_load_dword v13, v[10:11], off
	v_add_co_u32_e32 v10, vcc, s79, v8
	s_lshl_b32 s9, s9, 1
	s_nop 0
	v_addc_co_u32_e32 v11, vcc, 0, v9, vcc
	global_load_dword v14, v[10:11], off
	v_add_co_u32_e32 v10, vcc, s87, v8
	s_add_u32 s22, s16, s9
	s_nop 0
	v_addc_co_u32_e32 v11, vcc, 0, v9, vcc
	global_load_dword v15, v[10:11], off
	v_add_co_u32_e32 v10, vcc, s88, v8
	s_addc_u32 s23, s17, 0
	s_nop 0
	v_addc_co_u32_e32 v11, vcc, 0, v9, vcc
	global_load_dword v16, v[10:11], off
	v_add_co_u32_e32 v10, vcc, s62, v8
	s_nop 1
	v_addc_co_u32_e32 v11, vcc, 0, v9, vcc
	global_load_dword v17, v[10:11], off
	v_add_co_u32_e32 v10, vcc, s94, v8
	s_nop 1
	v_addc_co_u32_e32 v11, vcc, 0, v9, vcc
	global_load_dword v18, v[10:11], off
	v_add_co_u32_e32 v10, vcc, s26, v8
	s_nop 1
	v_addc_co_u32_e32 v11, vcc, 0, v9, vcc
	global_load_dword v19, v[10:11], off
	v_add_co_u32_e32 v10, vcc, s72, v8
	s_nop 1
	v_addc_co_u32_e32 v11, vcc, 0, v9, vcc
	global_load_dword v20, v[10:11], off
	v_add_co_u32_e32 v10, vcc, s73, v8
	s_nop 1
	v_addc_co_u32_e32 v11, vcc, 0, v9, vcc
	global_load_dword v21, v[10:11], off
	v_add_co_u32_e32 v10, vcc, s74, v8
	s_nop 1
	v_addc_co_u32_e32 v11, vcc, 0, v9, vcc
	global_load_dword v22, v[10:11], off
	v_add_co_u32_e32 v10, vcc, s85, v8
	s_nop 1
	v_addc_co_u32_e32 v11, vcc, 0, v9, vcc
	global_load_dword v23, v[10:11], off
	v_add_co_u32_e32 v10, vcc, s86, v8
	s_nop 1
	v_addc_co_u32_e32 v11, vcc, 0, v9, vcc
	global_load_dword v24, v[10:11], off
	v_add_co_u32_e32 v10, vcc, s90, v8
	s_nop 1
	v_addc_co_u32_e32 v11, vcc, 0, v9, vcc
	global_load_dword v25, v[10:11], off
	v_add_co_u32_e32 v10, vcc, s91, v8
	s_nop 1
	v_addc_co_u32_e32 v11, vcc, 0, v9, vcc
	global_load_dword v26, v[10:11], off
	v_add_co_u32_e32 v10, vcc, s95, v8
	s_nop 1
	v_addc_co_u32_e32 v11, vcc, 0, v9, vcc
	global_load_dword v27, v[10:11], off
	v_add_co_u32_e32 v10, vcc, s11, v8
	s_mov_b32 s11, 0x24000
	s_nop 0
	v_addc_co_u32_e32 v11, vcc, 0, v9, vcc
	global_load_dword v28, v[10:11], off
	v_add_co_u32_e32 v10, vcc, s11, v8
	s_mov_b32 s11, 0x28000
	s_nop 0
	v_addc_co_u32_e32 v11, vcc, 0, v9, vcc
	global_load_dword v29, v[10:11], off
	v_add_co_u32_e32 v10, vcc, s40, v8
	s_nop 1
	v_addc_co_u32_e32 v11, vcc, 0, v9, vcc
	global_load_dword v30, v[10:11], off
	v_add_co_u32_e32 v10, vcc, s11, v8
	s_mov_b32 s11, 0x2a000
	s_nop 0
	v_addc_co_u32_e32 v11, vcc, 0, v9, vcc
	global_load_dword v31, v[10:11], off
	v_add_co_u32_e32 v10, vcc, s11, v8
	s_mov_b32 s11, 0x2e000
	s_nop 0
	v_addc_co_u32_e32 v11, vcc, 0, v9, vcc
	global_load_dword v32, v[10:11], off
	v_add_co_u32_e32 v10, vcc, s41, v8
	s_nop 1
	v_addc_co_u32_e32 v11, vcc, 0, v9, vcc
	global_load_dword v33, v[10:11], off
	v_add_co_u32_e32 v10, vcc, s11, v8
	s_mov_b32 s11, 0x30000
	s_nop 0
	v_addc_co_u32_e32 v11, vcc, 0, v9, vcc
	global_load_dword v34, v[10:11], off
	v_add_co_u32_e32 v10, vcc, s11, v8
	s_mov_b32 s11, 0x32000
	s_nop 0
	v_addc_co_u32_e32 v11, vcc, 0, v9, vcc
	global_load_dword v35, v[10:11], off
	v_add_co_u32_e32 v10, vcc, s11, v8
	s_mov_b32 s11, 0x34000
	s_nop 0
	v_addc_co_u32_e32 v11, vcc, 0, v9, vcc
	global_load_dword v36, v[10:11], off
	v_add_co_u32_e32 v10, vcc, s11, v8
	s_mov_b32 s11, 0x36000
	s_nop 0
	v_addc_co_u32_e32 v11, vcc, 0, v9, vcc
	global_load_dword v37, v[10:11], off
	v_add_co_u32_e32 v10, vcc, s11, v8
	s_mov_b32 s11, 0x38000
	s_nop 0
	v_addc_co_u32_e32 v11, vcc, 0, v9, vcc
	global_load_dword v38, v[10:11], off
	v_add_co_u32_e32 v10, vcc, s11, v8
	s_mov_b32 s11, 0x3e000
	s_nop 0
	v_addc_co_u32_e32 v11, vcc, 0, v9, vcc
	global_load_dword v39, v[10:11], off
	v_add_co_u32_e32 v10, vcc, s24, v8
	s_nop 1
	v_addc_co_u32_e32 v11, vcc, 0, v9, vcc
	global_load_dword v40, v[10:11], off
	v_add_co_u32_e32 v10, vcc, s25, v8
	s_nop 1
	v_addc_co_u32_e32 v11, vcc, 0, v9, vcc
	v_add_co_u32_e32 v8, vcc, s11, v8
	global_load_dword v10, v[10:11], off
	s_nop 0
	v_addc_co_u32_e32 v9, vcc, 0, v9, vcc
	global_load_dword v8, v[8:9], off
	s_waitcnt vmcnt(0)
	ds_write2_b32 v44, v7, v12 offset1:66
	ds_write2_b32 v44, v13, v14 offset0:132 offset1:198
	ds_write2_b32 v51, v15, v16 offset0:8 offset1:74
	ds_write2_b32 v51, v17, v18 offset0:140 offset1:206
	ds_write2_b32 v50, v19, v20 offset0:16 offset1:82
	ds_write2_b32 v50, v21, v22 offset0:148 offset1:214
	ds_write2_b32 v49, v23, v24 offset0:24 offset1:90
	ds_write2_b32 v49, v25, v26 offset0:156 offset1:222
	ds_write2_b32 v48, v27, v28 offset0:32 offset1:98
	ds_write2_b32 v48, v29, v30 offset0:164 offset1:230
	ds_write2_b32 v47, v31, v32 offset0:40 offset1:106
	ds_write2_b32 v47, v33, v34 offset0:172 offset1:238
	ds_write2_b32 v46, v35, v36 offset0:48 offset1:114
	ds_write2_b32 v46, v37, v38 offset0:180 offset1:246
	ds_write2_b32 v45, v39, v40 offset0:56 offset1:122
	ds_write2_b32 v45, v10, v8 offset0:188 offset1:254
	v_mov_b32_e32 v7, v97
	s_waitcnt lgkmcnt(0)
	v_lshl_add_u64 v[8:9], s[22:23], 0, v[6:7]
	s_mov_b64 s[22:23], 0xb00000
	v_lshl_add_u64 v[12:13], v[8:9], 0, s[22:23]
	ds_read2_b32 v[8:9], v3 offset1:33
	s_waitcnt lgkmcnt(0)
	v_cvt_pk_bf16_f32 v8, v8, v9
	ds_read2_b32 v[10:11], v3 offset0:66 offset1:99
	s_waitcnt lgkmcnt(0)
	v_cvt_pk_bf16_f32 v9, v10, v11
	ds_read2_b32 v[10:11], v3 offset0:132 offset1:165
	v_or_b32_e32 v7, s8, v1
	s_waitcnt lgkmcnt(0)
	v_cvt_pk_bf16_f32 v10, v10, v11
	ds_read2_b32 v[14:15], v3 offset0:198 offset1:231
	v_mul_u32_u24_e32 v7, 0xb00, v7
	s_waitcnt lgkmcnt(0)
	v_cvt_pk_bf16_f32 v11, v14, v15
	v_lshlrev_b32_e32 v14, 1, v7
	v_mov_b32_e32 v15, v97
	v_lshl_add_u64 v[14:15], v[12:13], 0, v[14:15]
	global_store_dwordx4 v[14:15], v[8:11], off sc1
	ds_read2_b32 v[8:9], v3 offset0:8 offset1:41
	v_or_b32_e32 v7, s8, v5
	s_waitcnt lgkmcnt(0)
	v_cvt_pk_bf16_f32 v8, v8, v9
	ds_read2_b32 v[10:11], v3 offset0:74 offset1:107
	s_waitcnt lgkmcnt(0)
	v_cvt_pk_bf16_f32 v9, v10, v11
	ds_read2_b32 v[10:11], v3 offset0:140 offset1:173
	s_waitcnt lgkmcnt(0)
	v_cvt_pk_bf16_f32 v10, v10, v11
	ds_read2_b32 v[14:15], v3 offset0:206 offset1:239
	v_mul_u32_u24_e32 v7, 0xb00, v7
	s_waitcnt lgkmcnt(0)
	v_cvt_pk_bf16_f32 v11, v14, v15
	v_lshlrev_b32_e32 v14, 1, v7
	v_mov_b32_e32 v15, v97
	v_lshl_add_u64 v[14:15], v[12:13], 0, v[14:15]
	global_store_dwordx4 v[14:15], v[8:11], off sc1
	ds_read2_b32 v[8:9], v3 offset0:16 offset1:49
	v_or_b32_e32 v7, s8, v42
	s_waitcnt lgkmcnt(0)
	v_cvt_pk_bf16_f32 v8, v8, v9
	ds_read2_b32 v[10:11], v3 offset0:82 offset1:115
	s_waitcnt lgkmcnt(0)
	v_cvt_pk_bf16_f32 v9, v10, v11
	ds_read2_b32 v[10:11], v3 offset0:148 offset1:181
	s_waitcnt lgkmcnt(0)
	v_cvt_pk_bf16_f32 v10, v10, v11
	ds_read2_b32 v[14:15], v3 offset0:214 offset1:247
	v_mul_u32_u24_e32 v7, 0xb00, v7
	s_waitcnt lgkmcnt(0)
	v_cvt_pk_bf16_f32 v11, v14, v15
	v_lshlrev_b32_e32 v14, 1, v7
	v_mov_b32_e32 v15, v97
	v_lshl_add_u64 v[14:15], v[12:13], 0, v[14:15]
	global_store_dwordx4 v[14:15], v[8:11], off sc1
	ds_read2_b32 v[8:9], v3 offset0:24 offset1:57
	v_or_b32_e32 v7, s8, v43
	s_waitcnt lgkmcnt(0)
	v_cvt_pk_bf16_f32 v8, v8, v9
	ds_read2_b32 v[10:11], v3 offset0:90 offset1:123
	s_waitcnt lgkmcnt(0)
	v_cvt_pk_bf16_f32 v9, v10, v11
	ds_read2_b32 v[10:11], v3 offset0:156 offset1:189
	s_waitcnt lgkmcnt(0)
	v_cvt_pk_bf16_f32 v10, v10, v11
	ds_read2_b32 v[14:15], v3 offset0:222 offset1:255
	v_mul_u32_u24_e32 v7, 0xb00, v7
	s_waitcnt lgkmcnt(0)
	v_cvt_pk_bf16_f32 v11, v14, v15
	v_lshlrev_b32_e32 v14, 1, v7
	v_mov_b32_e32 v15, v97
	v_lshl_add_u64 v[12:13], v[12:13], 0, v[14:15]
	global_store_dwordx4 v[12:13], v[8:11], off sc1
	s_waitcnt lgkmcnt(0)
	s_cbranch_execnz .LBB0_256

.LBB0_280:
	s_lshl_b32 s6, s49, 8
	s_add_u32 s6, s4, s6
	s_addc_u32 s7, s5, 0
	s_add_u32 s6, s6, 0x180000
	s_addc_u32 s7, s7, 0
	s_mov_b32 s101, 0

.LBB0_342:
	v_lshl_add_u32 v242, s52, 8, v251
	v_lshl_or_b32 v216, s51, 8, v253
	v_ashrrev_i32_e32 v217, 31, v216
	v_ashrrev_i32_e32 v243, 31, v242
	v_or_b32_e32 v238, 16, v242
	v_lshl_add_u64 v[72:73], v[216:217], 1, s[16:17]
	v_lshlrev_b64 v[74:75], 11, v[242:243]
	v_ashrrev_i32_e32 v239, 31, v238
	v_or_b32_e32 v234, 32, v242
	v_lshl_add_u64 v[244:245], v[72:73], 0, v[74:75]
	v_lshlrev_b64 v[74:75], 11, v[238:239]
	v_ashrrev_i32_e32 v235, 31, v234
	v_or_b32_e32 v230, 48, v242
	v_lshl_add_u64 v[240:241], v[72:73], 0, v[74:75]
	v_lshlrev_b64 v[74:75], 11, v[234:235]
	v_ashrrev_i32_e32 v231, 31, v230
	v_add_u32_e32 v226, 0x80, v242
	v_lshl_add_u64 v[236:237], v[72:73], 0, v[74:75]
	v_lshlrev_b64 v[74:75], 11, v[230:231]
	v_ashrrev_i32_e32 v227, 31, v226
	v_add_u32_e32 v222, 0x90, v242
	global_load_dwordx4 v[190:193], v[244:245], off
	global_load_dwordx4 v[186:189], v[244:245], off offset:256
	v_lshl_add_u64 v[232:233], v[72:73], 0, v[74:75]
	v_lshlrev_b64 v[74:75], 11, v[226:227]
	v_ashrrev_i32_e32 v223, 31, v222
	v_add_u32_e32 v218, 0xa0, v242
	v_lshl_add_u64 v[228:229], v[72:73], 0, v[74:75]
	v_lshlrev_b64 v[74:75], 11, v[222:223]
	v_ashrrev_i32_e32 v219, 31, v218
	v_add_u32_e32 v212, 0xb0, v242
	v_lshl_add_u64 v[224:225], v[72:73], 0, v[74:75]
	v_lshlrev_b64 v[74:75], 11, v[218:219]
	v_ashrrev_i32_e32 v213, 31, v212
	v_lshl_add_u64 v[220:221], v[72:73], 0, v[74:75]
	v_lshlrev_b64 v[74:75], 11, v[212:213]
	v_lshl_add_u64 v[214:215], v[72:73], 0, v[74:75]
	global_load_dwordx4 v[182:185], v[240:241], off
	global_load_dwordx4 v[178:181], v[240:241], off offset:256
	global_load_dwordx4 v[174:177], v[236:237], off
	global_load_dwordx4 v[170:173], v[236:237], off offset:256
	global_load_dwordx4 v[166:169], v[232:233], off
	global_load_dwordx4 v[162:165], v[232:233], off offset:256
	global_load_dwordx4 v[150:153], v[228:229], off
	global_load_dwordx4 v[142:145], v[228:229], off offset:256
	global_load_dwordx4 v[126:129], v[224:225], off
	global_load_dwordx4 v[122:125], v[224:225], off offset:256
	global_load_dwordx4 v[106:109], v[220:221], off
	global_load_dwordx4 v[98:101], v[220:221], off offset:256
	global_load_dwordx4 v[84:87], v[214:215], off
	global_load_dwordx4 v[72:75], v[214:215], off offset:256
	v_lshlrev_b64 v[194:195], 10, v[242:243]
	v_lshl_add_u64 v[194:195], v[194:195], 0, v[216:217]
	s_andn2_b64 vcc, exec, s[20:21]
	v_lshl_add_u64 v[246:247], v[194:195], 2, s[8:9]
	s_waitcnt vmcnt(0)
	v_lshlrev_b32_e32 v196, 16, v190
	v_and_b32_e32 v197, 0xffff0000, v190
	v_lshlrev_b32_e32 v190, 16, v191
	v_and_b32_e32 v191, 0xffff0000, v191
	v_pk_fma_f32 v[160:161], v[160:161], 0.5, v[190:191] op_sel_hi:[1,0,1]
	v_lshlrev_b32_e32 v190, 16, v192
	v_and_b32_e32 v191, 0xffff0000, v192
	v_pk_fma_f32 v[190:191], v[154:155], 0.5, v[190:191] op_sel_hi:[1,0,1]
	v_lshlrev_b32_e32 v154, 16, v193
	v_and_b32_e32 v155, 0xffff0000, v193
	v_pk_fma_f32 v[158:159], v[158:159], 0.5, v[196:197] op_sel_hi:[1,0,1]
	v_pk_fma_f32 v[192:193], v[156:157], 0.5, v[154:155] op_sel_hi:[1,0,1]
	v_cvt_pk_bf16_f32 v154, v158, v159
	v_cvt_pk_bf16_f32 v155, v160, v161
	v_cvt_pk_bf16_f32 v156, v190, v191
	v_cndmask_b32_e64 v196, 0, 1, s[20:21]
	v_cvt_pk_bf16_f32 v157, v192, v193
	v_cmp_ne_u32_e64 s[6:7], 1, v196
	global_store_dwordx4 v[244:245], v[154:157], off sc1
	s_nop 1
	s_cbranch_vccnz .LBB0_344
	global_store_dwordx4 v[246:247], v[158:161], off sc1
	global_store_dwordx4 v[246:247], v[190:193], off offset:16 sc1
.LBB0_344:
	s_nop 0
	v_lshlrev_b32_e32 v158, 16, v186
	v_and_b32_e32 v159, 0xffff0000, v186
	v_pk_fma_f32 v[146:147], v[146:147], 0.5, v[158:159] op_sel_hi:[1,0,1]
	v_lshlrev_b32_e32 v158, 16, v187
	v_and_b32_e32 v159, 0xffff0000, v187
	v_pk_fma_f32 v[148:149], v[148:149], 0.5, v[158:159] op_sel_hi:[1,0,1]
	v_lshlrev_b32_e32 v158, 16, v188
	v_and_b32_e32 v159, 0xffff0000, v188
	v_pk_fma_f32 v[158:159], v[138:139], 0.5, v[158:159] op_sel_hi:[1,0,1]
	v_lshlrev_b32_e32 v138, 16, v189
	v_and_b32_e32 v139, 0xffff0000, v189
	v_pk_fma_f32 v[160:161], v[140:141], 0.5, v[138:139] op_sel_hi:[1,0,1]
	v_cvt_pk_bf16_f32 v138, v146, v147
	v_cvt_pk_bf16_f32 v139, v148, v149
	v_cvt_pk_bf16_f32 v140, v158, v159
	v_lshl_add_u64 v[186:187], v[244:245], 0, s[66:67]
	v_cvt_pk_bf16_f32 v141, v160, v161
	s_and_b64 vcc, exec, s[6:7]
	global_store_dwordx4 v[186:187], v[138:141], off sc1
	s_nop 1
	s_cbranch_vccnz .LBB0_346
	global_store_dwordx4 v[246:247], v[146:149], off offset:512 sc1
	global_store_dwordx4 v[246:247], v[158:161], off offset:528 sc1
.LBB0_346:
	s_nop 0
	v_and_b32_e32 v147, 0xffff0000, v154
	v_lshlrev_b32_e32 v146, 16, v154
	v_and_b32_e32 v149, 0xffff0000, v155
	v_mul_f32_e32 v147, v147, v147
	v_lshlrev_b32_e32 v148, 16, v155
	v_fmac_f32_e32 v147, v146, v146
	v_mul_f32_e32 v146, v149, v149
	v_lshlrev_b32_e32 v154, 16, v156
	v_and_b32_e32 v155, 0xffff0000, v156
	v_lshlrev_b32_e32 v156, 16, v157
	v_and_b32_e32 v157, 0xffff0000, v157
	v_fmac_f32_e32 v146, v148, v148
	v_add_f32_e32 v146, v147, v146
	v_mul_f32_e32 v147, v155, v155
	v_mul_f32_e32 v148, v157, v157
	v_fmac_f32_e32 v147, v154, v154
	v_fmac_f32_e32 v148, v156, v156
	v_add_f32_e32 v147, v147, v148
	v_add_f32_e32 v146, v146, v147
	v_lshlrev_b32_e32 v147, 16, v138
	v_and_b32_e32 v138, 0xffff0000, v138
	v_lshlrev_b32_e32 v148, 16, v139
	v_and_b32_e32 v139, 0xffff0000, v139
	v_mul_f32_e32 v138, v138, v138
	v_mul_f32_e32 v139, v139, v139
	v_lshlrev_b32_e32 v149, 16, v140
	v_and_b32_e32 v140, 0xffff0000, v140
	v_lshlrev_b32_e32 v154, 16, v141
	v_and_b32_e32 v141, 0xffff0000, v141
	v_fmac_f32_e32 v138, v147, v147
	v_fmac_f32_e32 v139, v148, v148
	v_add_f32_e32 v138, v138, v139
	v_mul_f32_e32 v139, v140, v140
	v_mul_f32_e32 v140, v141, v141
	v_fmac_f32_e32 v139, v149, v149
	v_fmac_f32_e32 v140, v154, v154
	v_add_f32_e32 v139, v139, v140
	v_add_f32_e32 v138, v138, v139
	v_mov_b32_e32 v139, v248
	v_add_f32_e32 v138, v146, v138
	v_lshlrev_b32_e32 v139, 2, v139
	v_xor_b32_e32 v139, 64, v139
	ds_bpermute_b32 v139, v139, v138
	s_lshl_b32 s26, s51, 2
	s_ashr_i32 s27, s26, 31
	s_waitcnt lgkmcnt(0)
	v_add_f32_e32 v138, v138, v139
	v_mov_b32_e32 v139, v248
	s_nop 0
	v_lshlrev_b32_e32 v139, 2, v139
	v_xor_b32_e32 v139, 0x80, v139
	ds_bpermute_b32 v139, v139, v138
	s_and_saveexec_b64 s[28:29], s[2:3]
	s_cbranch_execz .LBB0_348
	v_lshlrev_b64 v[140:141], 6, v[242:243]
	v_lshl_add_u64 v[140:141], s[10:11], 0, v[140:141]
	v_lshl_add_u64 v[140:141], s[26:27], 2, v[140:141]
	s_lshl_b32 s60, s44, 2
	v_lshl_add_u64 v[140:141], v[140:141], 0, s[60:61]
	s_waitcnt lgkmcnt(0)
	v_add_f32_e32 v138, v138, v139
	global_store_dword v[140:141], v138, off sc1
.LBB0_348:
	s_or_b64 exec, exec, s[28:29]
	s_waitcnt lgkmcnt(0)
	v_lshlrev_b64 v[138:139], 10, v[238:239]
	v_lshl_add_u64 v[146:147], v[138:139], 0, v[216:217]
	v_lshlrev_b32_e32 v138, 16, v182
	v_and_b32_e32 v139, 0xffff0000, v182
	v_pk_fma_f32 v[134:135], v[134:135], 0.5, v[138:139] op_sel_hi:[1,0,1]
	v_lshlrev_b32_e32 v138, 16, v183
	v_and_b32_e32 v139, 0xffff0000, v183
	v_pk_fma_f32 v[136:137], v[136:137], 0.5, v[138:139] op_sel_hi:[1,0,1]
	v_lshlrev_b32_e32 v138, 16, v184
	v_and_b32_e32 v139, 0xffff0000, v184
	v_pk_fma_f32 v[138:139], v[130:131], 0.5, v[138:139] op_sel_hi:[1,0,1]
	v_lshlrev_b32_e32 v130, 16, v185
	v_and_b32_e32 v131, 0xffff0000, v185
	v_pk_fma_f32 v[140:141], v[132:133], 0.5, v[130:131] op_sel_hi:[1,0,1]
	v_cvt_pk_bf16_f32 v130, v134, v135
	v_cvt_pk_bf16_f32 v131, v136, v137
	v_cvt_pk_bf16_f32 v132, v138, v139
	s_and_b64 vcc, exec, s[6:7]
	v_cvt_pk_bf16_f32 v133, v140, v141
	v_lshl_add_u64 v[146:147], v[146:147], 2, s[8:9]
	global_store_dwordx4 v[240:241], v[130:133], off sc1
	s_nop 1
	s_cbranch_vccnz .LBB0_350
	global_store_dwordx4 v[146:147], v[134:137], off sc1
	global_store_dwordx4 v[146:147], v[138:141], off offset:16 sc1
.LBB0_350:
	s_nop 0
	v_lshlrev_b32_e32 v134, 16, v178
	v_and_b32_e32 v135, 0xffff0000, v178
	v_pk_fma_f32 v[118:119], v[118:119], 0.5, v[134:135] op_sel_hi:[1,0,1]
	v_lshlrev_b32_e32 v134, 16, v179
	v_and_b32_e32 v135, 0xffff0000, v179
	v_pk_fma_f32 v[120:121], v[120:121], 0.5, v[134:135] op_sel_hi:[1,0,1]
	v_lshlrev_b32_e32 v134, 16, v180
	v_and_b32_e32 v135, 0xffff0000, v180
	v_pk_fma_f32 v[134:135], v[114:115], 0.5, v[134:135] op_sel_hi:[1,0,1]
	v_lshlrev_b32_e32 v114, 16, v181
	v_and_b32_e32 v115, 0xffff0000, v181
	v_pk_fma_f32 v[136:137], v[116:117], 0.5, v[114:115] op_sel_hi:[1,0,1]
	v_cvt_pk_bf16_f32 v114, v118, v119
	v_cvt_pk_bf16_f32 v115, v120, v121
	v_cvt_pk_bf16_f32 v116, v134, v135
	v_lshl_add_u64 v[138:139], v[240:241], 0, s[66:67]
	v_cvt_pk_bf16_f32 v117, v136, v137
	s_and_b64 vcc, exec, s[6:7]
	global_store_dwordx4 v[138:139], v[114:117], off sc1
	s_nop 1
	s_cbranch_vccnz .LBB0_352
	global_store_dwordx4 v[146:147], v[118:121], off offset:512 sc1
	global_store_dwordx4 v[146:147], v[134:137], off offset:528 sc1
.LBB0_352:
	s_nop 0
	v_and_b32_e32 v119, 0xffff0000, v130
	v_lshlrev_b32_e32 v118, 16, v130
	v_and_b32_e32 v121, 0xffff0000, v131
	v_mul_f32_e32 v119, v119, v119
	v_lshlrev_b32_e32 v120, 16, v131
	v_fmac_f32_e32 v119, v118, v118
	v_mul_f32_e32 v118, v121, v121
	v_lshlrev_b32_e32 v130, 16, v132
	v_and_b32_e32 v131, 0xffff0000, v132
	v_lshlrev_b32_e32 v132, 16, v133
	v_and_b32_e32 v133, 0xffff0000, v133
	v_fmac_f32_e32 v118, v120, v120
	v_add_f32_e32 v118, v119, v118
	v_mul_f32_e32 v119, v131, v131
	v_mul_f32_e32 v120, v133, v133
	v_fmac_f32_e32 v119, v130, v130
	v_fmac_f32_e32 v120, v132, v132
	v_add_f32_e32 v119, v119, v120
	v_add_f32_e32 v118, v118, v119
	v_lshlrev_b32_e32 v119, 16, v114
	v_and_b32_e32 v114, 0xffff0000, v114
	v_lshlrev_b32_e32 v120, 16, v115
	v_and_b32_e32 v115, 0xffff0000, v115
	v_mul_f32_e32 v114, v114, v114
	v_mul_f32_e32 v115, v115, v115
	v_lshlrev_b32_e32 v121, 16, v116
	v_and_b32_e32 v116, 0xffff0000, v116
	v_lshlrev_b32_e32 v130, 16, v117
	v_and_b32_e32 v117, 0xffff0000, v117
	v_fmac_f32_e32 v114, v119, v119
	v_fmac_f32_e32 v115, v120, v120
	v_add_f32_e32 v114, v114, v115
	v_mul_f32_e32 v115, v116, v116
	v_mul_f32_e32 v116, v117, v117
	v_fmac_f32_e32 v115, v121, v121
	v_fmac_f32_e32 v116, v130, v130
	v_add_f32_e32 v115, v115, v116
	v_add_f32_e32 v114, v114, v115
	v_mov_b32_e32 v115, v248
	v_add_f32_e32 v114, v118, v114
	v_lshlrev_b32_e32 v115, 2, v115
	v_xor_b32_e32 v115, 64, v115
	ds_bpermute_b32 v115, v115, v114
	s_waitcnt lgkmcnt(0)
	v_add_f32_e32 v114, v114, v115
	v_mov_b32_e32 v115, v248
	s_nop 0
	v_lshlrev_b32_e32 v115, 2, v115
	v_xor_b32_e32 v115, 0x80, v115
	ds_bpermute_b32 v115, v115, v114
	s_and_saveexec_b64 s[28:29], s[2:3]
	s_cbranch_execz .LBB0_354
	v_lshlrev_b64 v[116:117], 6, v[238:239]
	v_lshl_add_u64 v[116:117], s[10:11], 0, v[116:117]
	v_lshl_add_u64 v[116:117], s[26:27], 2, v[116:117]
	s_lshl_b32 s60, s44, 2
	v_lshl_add_u64 v[116:117], v[116:117], 0, s[60:61]
	s_waitcnt lgkmcnt(0)
	v_add_f32_e32 v114, v114, v115
	global_store_dword v[116:117], v114, off sc1
.LBB0_354:
	s_or_b64 exec, exec, s[28:29]
	s_waitcnt lgkmcnt(0)
	v_lshlrev_b64 v[114:115], 10, v[234:235]
	v_lshl_add_u64 v[118:119], v[114:115], 0, v[216:217]
	v_lshlrev_b32_e32 v114, 16, v174
	v_and_b32_e32 v115, 0xffff0000, v174
	v_pk_fma_f32 v[110:111], v[110:111], 0.5, v[114:115] op_sel_hi:[1,0,1]
	v_lshlrev_b32_e32 v114, 16, v175
	v_and_b32_e32 v115, 0xffff0000, v175
	v_pk_fma_f32 v[112:113], v[112:113], 0.5, v[114:115] op_sel_hi:[1,0,1]
	v_lshlrev_b32_e32 v114, 16, v176
	v_and_b32_e32 v115, 0xffff0000, v176
	v_pk_fma_f32 v[114:115], v[102:103], 0.5, v[114:115] op_sel_hi:[1,0,1]
	v_lshlrev_b32_e32 v102, 16, v177
	v_and_b32_e32 v103, 0xffff0000, v177
	v_pk_fma_f32 v[116:117], v[104:105], 0.5, v[102:103] op_sel_hi:[1,0,1]
	v_cvt_pk_bf16_f32 v102, v110, v111
	v_cvt_pk_bf16_f32 v103, v112, v113
	v_cvt_pk_bf16_f32 v104, v114, v115
	s_and_b64 vcc, exec, s[6:7]
	v_cvt_pk_bf16_f32 v105, v116, v117
	v_lshl_add_u64 v[118:119], v[118:119], 2, s[8:9]
	global_store_dwordx4 v[236:237], v[102:105], off sc1
	s_nop 1
	s_cbranch_vccnz .LBB0_356
	global_store_dwordx4 v[118:119], v[110:113], off sc1
	global_store_dwordx4 v[118:119], v[114:117], off offset:16 sc1
.LBB0_356:
	s_nop 0
	v_lshlrev_b32_e32 v110, 16, v170
	v_and_b32_e32 v111, 0xffff0000, v170
	v_pk_fma_f32 v[92:93], v[92:93], 0.5, v[110:111] op_sel_hi:[1,0,1]
	v_lshlrev_b32_e32 v110, 16, v171
	v_and_b32_e32 v111, 0xffff0000, v171
	v_pk_fma_f32 v[94:95], v[94:95], 0.5, v[110:111] op_sel_hi:[1,0,1]
	v_lshlrev_b32_e32 v110, 16, v172
	v_and_b32_e32 v111, 0xffff0000, v172
	v_pk_fma_f32 v[110:111], v[88:89], 0.5, v[110:111] op_sel_hi:[1,0,1]
	v_lshlrev_b32_e32 v88, 16, v173
	v_and_b32_e32 v89, 0xffff0000, v173
	v_pk_fma_f32 v[112:113], v[90:91], 0.5, v[88:89] op_sel_hi:[1,0,1]
	v_cvt_pk_bf16_f32 v88, v92, v93
	v_cvt_pk_bf16_f32 v89, v94, v95
	v_cvt_pk_bf16_f32 v90, v110, v111
	v_lshl_add_u64 v[114:115], v[236:237], 0, s[66:67]
	v_cvt_pk_bf16_f32 v91, v112, v113
	s_and_b64 vcc, exec, s[6:7]
	global_store_dwordx4 v[114:115], v[88:91], off sc1
	s_nop 1
	s_cbranch_vccnz .LBB0_358
	global_store_dwordx4 v[118:119], v[92:95], off offset:512 sc1
	global_store_dwordx4 v[118:119], v[110:113], off offset:528 sc1
.LBB0_358:
	s_nop 0
	v_and_b32_e32 v93, 0xffff0000, v102
	v_lshlrev_b32_e32 v92, 16, v102
	v_and_b32_e32 v95, 0xffff0000, v103
	v_mul_f32_e32 v93, v93, v93
	v_lshlrev_b32_e32 v94, 16, v103
	v_fmac_f32_e32 v93, v92, v92
	v_mul_f32_e32 v92, v95, v95
	v_lshlrev_b32_e32 v102, 16, v104
	v_and_b32_e32 v103, 0xffff0000, v104
	v_lshlrev_b32_e32 v104, 16, v105
	v_and_b32_e32 v105, 0xffff0000, v105
	v_fmac_f32_e32 v92, v94, v94
	v_add_f32_e32 v92, v93, v92
	v_mul_f32_e32 v93, v103, v103
	v_mul_f32_e32 v94, v105, v105
	v_fmac_f32_e32 v93, v102, v102
	v_fmac_f32_e32 v94, v104, v104
	v_add_f32_e32 v93, v93, v94
	v_add_f32_e32 v92, v92, v93
	v_lshlrev_b32_e32 v93, 16, v88
	v_and_b32_e32 v88, 0xffff0000, v88
	v_lshlrev_b32_e32 v94, 16, v89
	v_and_b32_e32 v89, 0xffff0000, v89
	v_mul_f32_e32 v88, v88, v88
	v_mul_f32_e32 v89, v89, v89
	v_lshlrev_b32_e32 v95, 16, v90
	v_and_b32_e32 v90, 0xffff0000, v90
	v_lshlrev_b32_e32 v102, 16, v91
	v_and_b32_e32 v91, 0xffff0000, v91
	v_fmac_f32_e32 v88, v93, v93
	v_fmac_f32_e32 v89, v94, v94
	v_add_f32_e32 v88, v88, v89
	v_mul_f32_e32 v89, v90, v90
	v_mul_f32_e32 v90, v91, v91
	v_fmac_f32_e32 v89, v95, v95
	v_fmac_f32_e32 v90, v102, v102
	v_add_f32_e32 v89, v89, v90
	v_add_f32_e32 v88, v88, v89
	v_mov_b32_e32 v89, v248
	v_add_f32_e32 v88, v92, v88
	v_lshlrev_b32_e32 v89, 2, v89
	v_xor_b32_e32 v89, 64, v89
	ds_bpermute_b32 v89, v89, v88
	s_waitcnt lgkmcnt(0)
	v_add_f32_e32 v88, v88, v89
	v_mov_b32_e32 v89, v248
	s_nop 0
	v_lshlrev_b32_e32 v89, 2, v89
	v_xor_b32_e32 v89, 0x80, v89
	ds_bpermute_b32 v89, v89, v88
	s_and_saveexec_b64 s[28:29], s[2:3]
	s_cbranch_execz .LBB0_360
	v_lshlrev_b64 v[90:91], 6, v[234:235]
	v_lshl_add_u64 v[90:91], s[10:11], 0, v[90:91]
	v_lshl_add_u64 v[90:91], s[26:27], 2, v[90:91]
	s_lshl_b32 s60, s44, 2
	v_lshl_add_u64 v[90:91], v[90:91], 0, s[60:61]
	s_waitcnt lgkmcnt(0)
	v_add_f32_e32 v88, v88, v89
	global_store_dword v[90:91], v88, off sc1
.LBB0_360:
	s_or_b64 exec, exec, s[28:29]
	s_waitcnt lgkmcnt(0)
	v_lshlrev_b64 v[88:89], 10, v[230:231]
	v_lshl_add_u64 v[92:93], v[88:89], 0, v[216:217]
	v_lshlrev_b32_e32 v88, 16, v166
	v_and_b32_e32 v89, 0xffff0000, v166
	v_pk_fma_f32 v[80:81], v[80:81], 0.5, v[88:89] op_sel_hi:[1,0,1]
	v_lshlrev_b32_e32 v88, 16, v167
	v_and_b32_e32 v89, 0xffff0000, v167
	v_pk_fma_f32 v[82:83], v[82:83], 0.5, v[88:89] op_sel_hi:[1,0,1]
	v_lshlrev_b32_e32 v88, 16, v168
	v_and_b32_e32 v89, 0xffff0000, v168
	v_pk_fma_f32 v[88:89], v[76:77], 0.5, v[88:89] op_sel_hi:[1,0,1]
	v_lshlrev_b32_e32 v76, 16, v169
	v_and_b32_e32 v77, 0xffff0000, v169
	v_pk_fma_f32 v[90:91], v[78:79], 0.5, v[76:77] op_sel_hi:[1,0,1]
	v_cvt_pk_bf16_f32 v76, v80, v81
	v_cvt_pk_bf16_f32 v77, v82, v83
	v_cvt_pk_bf16_f32 v78, v88, v89
	s_and_b64 vcc, exec, s[6:7]
	v_cvt_pk_bf16_f32 v79, v90, v91
	v_lshl_add_u64 v[92:93], v[92:93], 2, s[8:9]
	global_store_dwordx4 v[232:233], v[76:79], off sc1
	s_nop 1
	s_cbranch_vccnz .LBB0_362
	global_store_dwordx4 v[92:93], v[80:83], off sc1
	global_store_dwordx4 v[92:93], v[88:91], off offset:16 sc1
.LBB0_362:
	s_nop 0
	v_lshlrev_b32_e32 v80, 16, v162
	v_and_b32_e32 v81, 0xffff0000, v162
	v_pk_fma_f32 v[68:69], v[68:69], 0.5, v[80:81] op_sel_hi:[1,0,1]
	v_lshlrev_b32_e32 v80, 16, v163
	v_and_b32_e32 v81, 0xffff0000, v163
	v_pk_fma_f32 v[70:71], v[70:71], 0.5, v[80:81] op_sel_hi:[1,0,1]
	v_lshlrev_b32_e32 v80, 16, v164
	v_and_b32_e32 v81, 0xffff0000, v164
	v_pk_fma_f32 v[80:81], v[64:65], 0.5, v[80:81] op_sel_hi:[1,0,1]
	v_lshlrev_b32_e32 v64, 16, v165
	v_and_b32_e32 v65, 0xffff0000, v165
	v_pk_fma_f32 v[82:83], v[66:67], 0.5, v[64:65] op_sel_hi:[1,0,1]
	v_cvt_pk_bf16_f32 v64, v68, v69
	v_cvt_pk_bf16_f32 v65, v70, v71
	v_cvt_pk_bf16_f32 v66, v80, v81
	v_lshl_add_u64 v[88:89], v[232:233], 0, s[66:67]
	v_cvt_pk_bf16_f32 v67, v82, v83
	s_and_b64 vcc, exec, s[6:7]
	global_store_dwordx4 v[88:89], v[64:67], off sc1
	s_nop 1
	s_cbranch_vccnz .LBB0_364
	global_store_dwordx4 v[92:93], v[68:71], off offset:512 sc1
	global_store_dwordx4 v[92:93], v[80:83], off offset:528 sc1
.LBB0_364:
	s_nop 0
	v_and_b32_e32 v69, 0xffff0000, v76
	v_lshlrev_b32_e32 v68, 16, v76
	v_and_b32_e32 v71, 0xffff0000, v77
	v_mul_f32_e32 v69, v69, v69
	v_lshlrev_b32_e32 v70, 16, v77
	v_fmac_f32_e32 v69, v68, v68
	v_mul_f32_e32 v68, v71, v71
	v_lshlrev_b32_e32 v76, 16, v78
	v_and_b32_e32 v77, 0xffff0000, v78
	v_lshlrev_b32_e32 v78, 16, v79
	v_and_b32_e32 v79, 0xffff0000, v79
	v_fmac_f32_e32 v68, v70, v70
	v_add_f32_e32 v68, v69, v68
	v_mul_f32_e32 v69, v77, v77
	v_mul_f32_e32 v70, v79, v79
	v_fmac_f32_e32 v69, v76, v76
	v_fmac_f32_e32 v70, v78, v78
	v_add_f32_e32 v69, v69, v70
	v_add_f32_e32 v68, v68, v69
	v_lshlrev_b32_e32 v69, 16, v64
	v_and_b32_e32 v64, 0xffff0000, v64
	v_lshlrev_b32_e32 v70, 16, v65
	v_and_b32_e32 v65, 0xffff0000, v65
	v_mul_f32_e32 v64, v64, v64
	v_mul_f32_e32 v65, v65, v65
	v_lshlrev_b32_e32 v71, 16, v66
	v_and_b32_e32 v66, 0xffff0000, v66
	v_lshlrev_b32_e32 v76, 16, v67
	v_and_b32_e32 v67, 0xffff0000, v67
	v_fmac_f32_e32 v64, v69, v69
	v_fmac_f32_e32 v65, v70, v70
	v_add_f32_e32 v64, v64, v65
	v_mul_f32_e32 v65, v66, v66
	v_mul_f32_e32 v66, v67, v67
	v_fmac_f32_e32 v65, v71, v71
	v_fmac_f32_e32 v66, v76, v76
	v_add_f32_e32 v65, v65, v66
	v_add_f32_e32 v64, v64, v65
	v_mov_b32_e32 v65, v248
	v_add_f32_e32 v64, v68, v64
	v_lshlrev_b32_e32 v65, 2, v65
	v_xor_b32_e32 v65, 64, v65
	ds_bpermute_b32 v65, v65, v64
	s_waitcnt lgkmcnt(0)
	v_add_f32_e32 v64, v64, v65
	v_mov_b32_e32 v65, v248
	s_nop 0
	v_lshlrev_b32_e32 v65, 2, v65
	v_xor_b32_e32 v65, 0x80, v65
	ds_bpermute_b32 v65, v65, v64
	s_and_saveexec_b64 s[28:29], s[2:3]
	s_cbranch_execz .LBB0_366
	v_lshlrev_b64 v[66:67], 6, v[230:231]
	v_lshl_add_u64 v[66:67], s[10:11], 0, v[66:67]
	v_lshl_add_u64 v[66:67], s[26:27], 2, v[66:67]
	s_lshl_b32 s60, s44, 2
	v_lshl_add_u64 v[66:67], v[66:67], 0, s[60:61]
	s_waitcnt lgkmcnt(0)
	v_add_f32_e32 v64, v64, v65
	global_store_dword v[66:67], v64, off sc1
.LBB0_366:
	s_or_b64 exec, exec, s[28:29]
	s_waitcnt lgkmcnt(0)
	v_lshlrev_b64 v[64:65], 10, v[226:227]
	v_lshl_add_u64 v[68:69], v[64:65], 0, v[216:217]
	v_lshlrev_b32_e32 v64, 16, v150
	v_and_b32_e32 v65, 0xffff0000, v150
	v_pk_fma_f32 v[60:61], v[60:61], 0.5, v[64:65] op_sel_hi:[1,0,1]
	v_lshlrev_b32_e32 v64, 16, v151
	v_and_b32_e32 v65, 0xffff0000, v151
	v_pk_fma_f32 v[62:63], v[62:63], 0.5, v[64:65] op_sel_hi:[1,0,1]
	v_lshlrev_b32_e32 v64, 16, v152
	v_and_b32_e32 v65, 0xffff0000, v152
	v_pk_fma_f32 v[64:65], v[56:57], 0.5, v[64:65] op_sel_hi:[1,0,1]
	v_lshlrev_b32_e32 v56, 16, v153
	v_and_b32_e32 v57, 0xffff0000, v153
	v_pk_fma_f32 v[66:67], v[58:59], 0.5, v[56:57] op_sel_hi:[1,0,1]
	v_cvt_pk_bf16_f32 v56, v60, v61
	v_cvt_pk_bf16_f32 v57, v62, v63
	v_cvt_pk_bf16_f32 v58, v64, v65
	s_and_b64 vcc, exec, s[6:7]
	v_cvt_pk_bf16_f32 v59, v66, v67
	v_lshl_add_u64 v[68:69], v[68:69], 2, s[8:9]
	global_store_dwordx4 v[228:229], v[56:59], off sc1
	s_nop 1
	s_cbranch_vccnz .LBB0_368
	global_store_dwordx4 v[68:69], v[60:63], off sc1
	global_store_dwordx4 v[68:69], v[64:67], off offset:16 sc1
.LBB0_368:
	s_nop 0
	v_lshlrev_b32_e32 v60, 16, v142
	v_and_b32_e32 v61, 0xffff0000, v142
	v_pk_fma_f32 v[52:53], v[52:53], 0.5, v[60:61] op_sel_hi:[1,0,1]
	v_lshlrev_b32_e32 v60, 16, v143
	v_and_b32_e32 v61, 0xffff0000, v143
	v_pk_fma_f32 v[54:55], v[54:55], 0.5, v[60:61] op_sel_hi:[1,0,1]
	v_lshlrev_b32_e32 v60, 16, v144
	v_and_b32_e32 v61, 0xffff0000, v144
	v_pk_fma_f32 v[60:61], v[48:49], 0.5, v[60:61] op_sel_hi:[1,0,1]
	v_lshlrev_b32_e32 v48, 16, v145
	v_and_b32_e32 v49, 0xffff0000, v145
	v_pk_fma_f32 v[62:63], v[50:51], 0.5, v[48:49] op_sel_hi:[1,0,1]
	v_cvt_pk_bf16_f32 v48, v52, v53
	v_cvt_pk_bf16_f32 v49, v54, v55
	v_cvt_pk_bf16_f32 v50, v60, v61
	v_lshl_add_u64 v[64:65], v[228:229], 0, s[66:67]
	v_cvt_pk_bf16_f32 v51, v62, v63
	s_and_b64 vcc, exec, s[6:7]
	global_store_dwordx4 v[64:65], v[48:51], off sc1
	s_nop 1
	s_cbranch_vccnz .LBB0_370
	global_store_dwordx4 v[68:69], v[52:55], off offset:512 sc1
	global_store_dwordx4 v[68:69], v[60:63], off offset:528 sc1
.LBB0_370:
	s_nop 0
	v_and_b32_e32 v53, 0xffff0000, v56
	v_lshlrev_b32_e32 v52, 16, v56
	v_and_b32_e32 v55, 0xffff0000, v57
	v_mul_f32_e32 v53, v53, v53
	v_lshlrev_b32_e32 v54, 16, v57
	v_fmac_f32_e32 v53, v52, v52
	v_mul_f32_e32 v52, v55, v55
	v_lshlrev_b32_e32 v56, 16, v58
	v_and_b32_e32 v57, 0xffff0000, v58
	v_lshlrev_b32_e32 v58, 16, v59
	v_and_b32_e32 v59, 0xffff0000, v59
	v_fmac_f32_e32 v52, v54, v54
	v_add_f32_e32 v52, v53, v52
	v_mul_f32_e32 v53, v57, v57
	v_mul_f32_e32 v54, v59, v59
	v_fmac_f32_e32 v53, v56, v56
	v_fmac_f32_e32 v54, v58, v58
	v_add_f32_e32 v53, v53, v54
	v_add_f32_e32 v52, v52, v53
	v_lshlrev_b32_e32 v53, 16, v48
	v_and_b32_e32 v48, 0xffff0000, v48
	v_lshlrev_b32_e32 v54, 16, v49
	v_and_b32_e32 v49, 0xffff0000, v49
	v_mul_f32_e32 v48, v48, v48
	v_mul_f32_e32 v49, v49, v49
	v_lshlrev_b32_e32 v55, 16, v50
	v_and_b32_e32 v50, 0xffff0000, v50
	v_lshlrev_b32_e32 v56, 16, v51
	v_and_b32_e32 v51, 0xffff0000, v51
	v_fmac_f32_e32 v48, v53, v53
	v_fmac_f32_e32 v49, v54, v54
	v_add_f32_e32 v48, v48, v49
	v_mul_f32_e32 v49, v50, v50
	v_mul_f32_e32 v50, v51, v51
	v_fmac_f32_e32 v49, v55, v55
	v_fmac_f32_e32 v50, v56, v56
	v_add_f32_e32 v49, v49, v50
	v_add_f32_e32 v48, v48, v49
	v_mov_b32_e32 v49, v248
	v_add_f32_e32 v48, v52, v48
	v_lshlrev_b32_e32 v49, 2, v49
	v_xor_b32_e32 v49, 64, v49
	ds_bpermute_b32 v49, v49, v48
	s_waitcnt lgkmcnt(0)
	v_add_f32_e32 v48, v48, v49
	v_mov_b32_e32 v49, v248
	s_nop 0
	v_lshlrev_b32_e32 v49, 2, v49
	v_xor_b32_e32 v49, 0x80, v49
	ds_bpermute_b32 v49, v49, v48
	s_and_saveexec_b64 s[28:29], s[2:3]
	s_cbranch_execz .LBB0_372
	v_lshlrev_b64 v[50:51], 6, v[226:227]
	v_lshl_add_u64 v[50:51], s[10:11], 0, v[50:51]
	v_lshl_add_u64 v[50:51], s[26:27], 2, v[50:51]
	s_lshl_b32 s60, s44, 2
	v_lshl_add_u64 v[50:51], v[50:51], 0, s[60:61]
	s_waitcnt lgkmcnt(0)
	v_add_f32_e32 v48, v48, v49
	global_store_dword v[50:51], v48, off sc1
.LBB0_372:
	s_or_b64 exec, exec, s[28:29]
	s_waitcnt lgkmcnt(0)
	v_lshlrev_b64 v[48:49], 10, v[222:223]
	v_lshl_add_u64 v[52:53], v[48:49], 0, v[216:217]
	v_lshlrev_b32_e32 v48, 16, v126
	v_and_b32_e32 v49, 0xffff0000, v126
	v_pk_fma_f32 v[44:45], v[44:45], 0.5, v[48:49] op_sel_hi:[1,0,1]
	v_lshlrev_b32_e32 v48, 16, v127
	v_and_b32_e32 v49, 0xffff0000, v127
	v_pk_fma_f32 v[46:47], v[46:47], 0.5, v[48:49] op_sel_hi:[1,0,1]
	v_lshlrev_b32_e32 v48, 16, v128
	v_and_b32_e32 v49, 0xffff0000, v128
	v_pk_fma_f32 v[48:49], v[40:41], 0.5, v[48:49] op_sel_hi:[1,0,1]
	v_lshlrev_b32_e32 v40, 16, v129
	v_and_b32_e32 v41, 0xffff0000, v129
	v_pk_fma_f32 v[50:51], v[42:43], 0.5, v[40:41] op_sel_hi:[1,0,1]
	v_cvt_pk_bf16_f32 v40, v44, v45
	v_cvt_pk_bf16_f32 v41, v46, v47
	v_cvt_pk_bf16_f32 v42, v48, v49
	s_and_b64 vcc, exec, s[6:7]
	v_cvt_pk_bf16_f32 v43, v50, v51
	v_lshl_add_u64 v[52:53], v[52:53], 2, s[8:9]
	global_store_dwordx4 v[224:225], v[40:43], off sc1
	s_nop 1
	s_cbranch_vccnz .LBB0_374
	global_store_dwordx4 v[52:53], v[44:47], off sc1
	global_store_dwordx4 v[52:53], v[48:51], off offset:16 sc1
.LBB0_374:
	s_nop 0
	v_lshlrev_b32_e32 v44, 16, v122
	v_and_b32_e32 v45, 0xffff0000, v122
	v_pk_fma_f32 v[36:37], v[36:37], 0.5, v[44:45] op_sel_hi:[1,0,1]
	v_lshlrev_b32_e32 v44, 16, v123
	v_and_b32_e32 v45, 0xffff0000, v123
	v_pk_fma_f32 v[38:39], v[38:39], 0.5, v[44:45] op_sel_hi:[1,0,1]
	v_lshlrev_b32_e32 v44, 16, v124
	v_and_b32_e32 v45, 0xffff0000, v124
	v_pk_fma_f32 v[44:45], v[32:33], 0.5, v[44:45] op_sel_hi:[1,0,1]
	v_lshlrev_b32_e32 v32, 16, v125
	v_and_b32_e32 v33, 0xffff0000, v125
	v_pk_fma_f32 v[46:47], v[34:35], 0.5, v[32:33] op_sel_hi:[1,0,1]
	v_cvt_pk_bf16_f32 v32, v36, v37
	v_cvt_pk_bf16_f32 v33, v38, v39
	v_cvt_pk_bf16_f32 v34, v44, v45
	v_lshl_add_u64 v[48:49], v[224:225], 0, s[66:67]
	v_cvt_pk_bf16_f32 v35, v46, v47
	s_and_b64 vcc, exec, s[6:7]
	global_store_dwordx4 v[48:49], v[32:35], off sc1
	s_nop 1
	s_cbranch_vccnz .LBB0_376
	global_store_dwordx4 v[52:53], v[36:39], off offset:512 sc1
	global_store_dwordx4 v[52:53], v[44:47], off offset:528 sc1
.LBB0_376:
	s_nop 0
	v_and_b32_e32 v37, 0xffff0000, v40
	v_lshlrev_b32_e32 v36, 16, v40
	v_and_b32_e32 v39, 0xffff0000, v41
	v_mul_f32_e32 v37, v37, v37
	v_lshlrev_b32_e32 v38, 16, v41
	v_fmac_f32_e32 v37, v36, v36
	v_mul_f32_e32 v36, v39, v39
	v_lshlrev_b32_e32 v40, 16, v42
	v_and_b32_e32 v41, 0xffff0000, v42
	v_lshlrev_b32_e32 v42, 16, v43
	v_and_b32_e32 v43, 0xffff0000, v43
	v_fmac_f32_e32 v36, v38, v38
	v_add_f32_e32 v36, v37, v36
	v_mul_f32_e32 v37, v41, v41
	v_mul_f32_e32 v38, v43, v43
	v_fmac_f32_e32 v37, v40, v40
	v_fmac_f32_e32 v38, v42, v42
	v_add_f32_e32 v37, v37, v38
	v_add_f32_e32 v36, v36, v37
	v_lshlrev_b32_e32 v37, 16, v32
	v_and_b32_e32 v32, 0xffff0000, v32
	v_lshlrev_b32_e32 v38, 16, v33
	v_and_b32_e32 v33, 0xffff0000, v33
	v_mul_f32_e32 v32, v32, v32
	v_mul_f32_e32 v33, v33, v33
	v_lshlrev_b32_e32 v39, 16, v34
	v_and_b32_e32 v34, 0xffff0000, v34
	v_lshlrev_b32_e32 v40, 16, v35
	v_and_b32_e32 v35, 0xffff0000, v35
	v_fmac_f32_e32 v32, v37, v37
	v_fmac_f32_e32 v33, v38, v38
	v_add_f32_e32 v32, v32, v33
	v_mul_f32_e32 v33, v34, v34
	v_mul_f32_e32 v34, v35, v35
	v_fmac_f32_e32 v33, v39, v39
	v_fmac_f32_e32 v34, v40, v40
	v_add_f32_e32 v33, v33, v34
	v_add_f32_e32 v32, v32, v33
	v_mov_b32_e32 v33, v248
	v_add_f32_e32 v32, v36, v32
	v_lshlrev_b32_e32 v33, 2, v33
	v_xor_b32_e32 v33, 64, v33
	ds_bpermute_b32 v33, v33, v32
	s_waitcnt lgkmcnt(0)
	v_add_f32_e32 v32, v32, v33
	v_mov_b32_e32 v33, v248
	s_nop 0
	v_lshlrev_b32_e32 v33, 2, v33
	v_xor_b32_e32 v33, 0x80, v33
	ds_bpermute_b32 v33, v33, v32
	s_and_saveexec_b64 s[28:29], s[2:3]
	s_cbranch_execz .LBB0_378
	v_lshlrev_b64 v[34:35], 6, v[222:223]
	v_lshl_add_u64 v[34:35], s[10:11], 0, v[34:35]
	v_lshl_add_u64 v[34:35], s[26:27], 2, v[34:35]
	s_lshl_b32 s60, s44, 2
	v_lshl_add_u64 v[34:35], v[34:35], 0, s[60:61]
	s_waitcnt lgkmcnt(0)
	v_add_f32_e32 v32, v32, v33
	global_store_dword v[34:35], v32, off sc1
.LBB0_378:
	s_or_b64 exec, exec, s[28:29]
	s_waitcnt lgkmcnt(0)
	v_lshlrev_b64 v[32:33], 10, v[218:219]
	v_lshl_add_u64 v[36:37], v[32:33], 0, v[216:217]
	v_lshlrev_b32_e32 v32, 16, v106
	v_and_b32_e32 v33, 0xffff0000, v106
	v_pk_fma_f32 v[28:29], v[28:29], 0.5, v[32:33] op_sel_hi:[1,0,1]
	v_lshlrev_b32_e32 v32, 16, v107
	v_and_b32_e32 v33, 0xffff0000, v107
	v_pk_fma_f32 v[30:31], v[30:31], 0.5, v[32:33] op_sel_hi:[1,0,1]
	v_lshlrev_b32_e32 v32, 16, v108
	v_and_b32_e32 v33, 0xffff0000, v108
	v_pk_fma_f32 v[32:33], v[24:25], 0.5, v[32:33] op_sel_hi:[1,0,1]
	v_lshlrev_b32_e32 v24, 16, v109
	v_and_b32_e32 v25, 0xffff0000, v109
	v_pk_fma_f32 v[34:35], v[26:27], 0.5, v[24:25] op_sel_hi:[1,0,1]
	v_cvt_pk_bf16_f32 v24, v28, v29
	v_cvt_pk_bf16_f32 v25, v30, v31
	v_cvt_pk_bf16_f32 v26, v32, v33
	s_and_b64 vcc, exec, s[6:7]
	v_cvt_pk_bf16_f32 v27, v34, v35
	v_lshl_add_u64 v[36:37], v[36:37], 2, s[8:9]
	global_store_dwordx4 v[220:221], v[24:27], off sc1
	s_nop 1
	s_cbranch_vccnz .LBB0_380
	global_store_dwordx4 v[36:37], v[28:31], off sc1
	global_store_dwordx4 v[36:37], v[32:35], off offset:16 sc1
.LBB0_380:
	s_nop 0
	v_lshlrev_b32_e32 v28, 16, v98
	v_and_b32_e32 v29, 0xffff0000, v98
	v_pk_fma_f32 v[20:21], v[20:21], 0.5, v[28:29] op_sel_hi:[1,0,1]
	v_lshlrev_b32_e32 v28, 16, v99
	v_and_b32_e32 v29, 0xffff0000, v99
	v_pk_fma_f32 v[22:23], v[22:23], 0.5, v[28:29] op_sel_hi:[1,0,1]
	v_lshlrev_b32_e32 v28, 16, v100
	v_and_b32_e32 v29, 0xffff0000, v100
	v_pk_fma_f32 v[28:29], v[16:17], 0.5, v[28:29] op_sel_hi:[1,0,1]
	v_lshlrev_b32_e32 v16, 16, v101
	v_and_b32_e32 v17, 0xffff0000, v101
	v_pk_fma_f32 v[30:31], v[18:19], 0.5, v[16:17] op_sel_hi:[1,0,1]
	v_cvt_pk_bf16_f32 v16, v20, v21
	v_cvt_pk_bf16_f32 v17, v22, v23
	v_cvt_pk_bf16_f32 v18, v28, v29
	v_lshl_add_u64 v[32:33], v[220:221], 0, s[66:67]
	v_cvt_pk_bf16_f32 v19, v30, v31
	s_and_b64 vcc, exec, s[6:7]
	global_store_dwordx4 v[32:33], v[16:19], off sc1
	s_nop 1
	s_cbranch_vccnz .LBB0_382
	global_store_dwordx4 v[36:37], v[20:23], off offset:512 sc1
	global_store_dwordx4 v[36:37], v[28:31], off offset:528 sc1
.LBB0_382:
	s_nop 0
	v_and_b32_e32 v21, 0xffff0000, v24
	v_lshlrev_b32_e32 v20, 16, v24
	v_and_b32_e32 v23, 0xffff0000, v25
	v_mul_f32_e32 v21, v21, v21
	v_lshlrev_b32_e32 v22, 16, v25
	v_fmac_f32_e32 v21, v20, v20
	v_mul_f32_e32 v20, v23, v23
	v_lshlrev_b32_e32 v24, 16, v26
	v_and_b32_e32 v25, 0xffff0000, v26
	v_lshlrev_b32_e32 v26, 16, v27
	v_and_b32_e32 v27, 0xffff0000, v27
	v_fmac_f32_e32 v20, v22, v22
	v_add_f32_e32 v20, v21, v20
	v_mul_f32_e32 v21, v25, v25
	v_mul_f32_e32 v22, v27, v27
	v_fmac_f32_e32 v21, v24, v24
	v_fmac_f32_e32 v22, v26, v26
	v_add_f32_e32 v21, v21, v22
	v_add_f32_e32 v20, v20, v21
	v_lshlrev_b32_e32 v21, 16, v16
	v_and_b32_e32 v16, 0xffff0000, v16
	v_lshlrev_b32_e32 v22, 16, v17
	v_and_b32_e32 v17, 0xffff0000, v17
	v_mul_f32_e32 v16, v16, v16
	v_mul_f32_e32 v17, v17, v17
	v_lshlrev_b32_e32 v23, 16, v18
	v_and_b32_e32 v18, 0xffff0000, v18
	v_lshlrev_b32_e32 v24, 16, v19
	v_and_b32_e32 v19, 0xffff0000, v19
	v_fmac_f32_e32 v16, v21, v21
	v_fmac_f32_e32 v17, v22, v22
	v_add_f32_e32 v16, v16, v17
	v_mul_f32_e32 v17, v18, v18
	v_mul_f32_e32 v18, v19, v19
	v_fmac_f32_e32 v17, v23, v23
	v_fmac_f32_e32 v18, v24, v24
	v_add_f32_e32 v17, v17, v18
	v_add_f32_e32 v16, v16, v17
	v_mov_b32_e32 v17, v248
	v_add_f32_e32 v16, v20, v16
	v_lshlrev_b32_e32 v17, 2, v17
	v_xor_b32_e32 v17, 64, v17
	ds_bpermute_b32 v17, v17, v16
	s_waitcnt lgkmcnt(0)
	v_add_f32_e32 v16, v16, v17
	v_mov_b32_e32 v17, v248
	s_nop 0
	v_lshlrev_b32_e32 v17, 2, v17
	v_xor_b32_e32 v17, 0x80, v17
	ds_bpermute_b32 v17, v17, v16
	s_and_saveexec_b64 s[28:29], s[2:3]
	s_cbranch_execz .LBB0_384
	v_lshlrev_b64 v[18:19], 6, v[218:219]
	v_lshl_add_u64 v[18:19], s[10:11], 0, v[18:19]
	v_lshl_add_u64 v[18:19], s[26:27], 2, v[18:19]
	s_lshl_b32 s60, s44, 2
	v_lshl_add_u64 v[18:19], v[18:19], 0, s[60:61]
	s_waitcnt lgkmcnt(0)
	v_add_f32_e32 v16, v16, v17
	global_store_dword v[18:19], v16, off sc1
.LBB0_384:
	s_or_b64 exec, exec, s[28:29]
	s_waitcnt lgkmcnt(0)
	v_lshlrev_b64 v[16:17], 10, v[212:213]
	v_lshl_add_u64 v[20:21], v[16:17], 0, v[216:217]
	v_lshlrev_b32_e32 v16, 16, v84
	v_and_b32_e32 v17, 0xffff0000, v84
	v_pk_fma_f32 v[12:13], v[12:13], 0.5, v[16:17] op_sel_hi:[1,0,1]
	v_lshlrev_b32_e32 v16, 16, v85
	v_and_b32_e32 v17, 0xffff0000, v85
	v_pk_fma_f32 v[14:15], v[14:15], 0.5, v[16:17] op_sel_hi:[1,0,1]
	v_lshlrev_b32_e32 v16, 16, v86
	v_and_b32_e32 v17, 0xffff0000, v86
	v_pk_fma_f32 v[16:17], v[8:9], 0.5, v[16:17] op_sel_hi:[1,0,1]
	v_lshlrev_b32_e32 v8, 16, v87
	v_and_b32_e32 v9, 0xffff0000, v87
	v_pk_fma_f32 v[18:19], v[10:11], 0.5, v[8:9] op_sel_hi:[1,0,1]
	v_cvt_pk_bf16_f32 v8, v12, v13
	v_cvt_pk_bf16_f32 v9, v14, v15
	v_cvt_pk_bf16_f32 v10, v16, v17
	s_and_b64 vcc, exec, s[6:7]
	v_cvt_pk_bf16_f32 v11, v18, v19
	v_lshl_add_u64 v[20:21], v[20:21], 2, s[8:9]
	global_store_dwordx4 v[214:215], v[8:11], off sc1
	s_nop 1
	s_cbranch_vccnz .LBB0_386
	global_store_dwordx4 v[20:21], v[12:15], off sc1
	global_store_dwordx4 v[20:21], v[16:19], off offset:16 sc1
.LBB0_386:
	s_nop 0
	v_lshlrev_b32_e32 v12, 16, v72
	v_and_b32_e32 v13, 0xffff0000, v72
	v_pk_fma_f32 v[4:5], v[4:5], 0.5, v[12:13] op_sel_hi:[1,0,1]
	v_lshlrev_b32_e32 v12, 16, v73
	v_and_b32_e32 v13, 0xffff0000, v73
	v_pk_fma_f32 v[6:7], v[6:7], 0.5, v[12:13] op_sel_hi:[1,0,1]
	v_lshlrev_b32_e32 v12, 16, v74
	v_and_b32_e32 v13, 0xffff0000, v74
	v_pk_fma_f32 v[12:13], v[0:1], 0.5, v[12:13] op_sel_hi:[1,0,1]
	v_lshlrev_b32_e32 v0, 16, v75
	v_and_b32_e32 v1, 0xffff0000, v75
	v_pk_fma_f32 v[14:15], v[2:3], 0.5, v[0:1] op_sel_hi:[1,0,1]
	v_cvt_pk_bf16_f32 v0, v4, v5
	v_cvt_pk_bf16_f32 v1, v6, v7
	v_cvt_pk_bf16_f32 v2, v12, v13
	v_lshl_add_u64 v[16:17], v[214:215], 0, s[66:67]
	v_cvt_pk_bf16_f32 v3, v14, v15
	s_and_b64 vcc, exec, s[6:7]
	global_store_dwordx4 v[16:17], v[0:3], off sc1
	s_nop 1
	s_cbranch_vccnz .LBB0_388
	global_store_dwordx4 v[20:21], v[4:7], off offset:512 sc1
	global_store_dwordx4 v[20:21], v[12:15], off offset:528 sc1
.LBB0_388:
	s_nop 0
	v_and_b32_e32 v5, 0xffff0000, v8
	v_lshlrev_b32_e32 v4, 16, v8
	v_and_b32_e32 v7, 0xffff0000, v9
	v_mul_f32_e32 v5, v5, v5
	v_lshlrev_b32_e32 v6, 16, v9
	v_fmac_f32_e32 v5, v4, v4
	v_mul_f32_e32 v4, v7, v7
	v_lshlrev_b32_e32 v8, 16, v10
	v_and_b32_e32 v9, 0xffff0000, v10
	v_lshlrev_b32_e32 v10, 16, v11
	v_and_b32_e32 v11, 0xffff0000, v11
	v_fmac_f32_e32 v4, v6, v6
	v_add_f32_e32 v4, v5, v4
	v_mul_f32_e32 v5, v9, v9
	v_mul_f32_e32 v6, v11, v11
	v_fmac_f32_e32 v5, v8, v8
	v_fmac_f32_e32 v6, v10, v10
	v_add_f32_e32 v5, v5, v6
	v_add_f32_e32 v4, v4, v5
	v_lshlrev_b32_e32 v5, 16, v0
	v_and_b32_e32 v0, 0xffff0000, v0
	v_lshlrev_b32_e32 v6, 16, v1
	v_and_b32_e32 v1, 0xffff0000, v1
	v_mul_f32_e32 v0, v0, v0
	v_mul_f32_e32 v1, v1, v1
	v_lshlrev_b32_e32 v7, 16, v2
	v_and_b32_e32 v2, 0xffff0000, v2
	v_lshlrev_b32_e32 v8, 16, v3
	v_and_b32_e32 v3, 0xffff0000, v3
	v_fmac_f32_e32 v0, v5, v5
	v_fmac_f32_e32 v1, v6, v6
	v_add_f32_e32 v0, v0, v1
	v_mul_f32_e32 v1, v2, v2
	v_mul_f32_e32 v2, v3, v3
	v_fmac_f32_e32 v1, v7, v7
	v_fmac_f32_e32 v2, v8, v8
	v_add_f32_e32 v1, v1, v2
	v_add_f32_e32 v0, v0, v1
	v_mov_b32_e32 v1, v248
	v_add_f32_e32 v0, v4, v0
	v_lshlrev_b32_e32 v1, 2, v1
	v_xor_b32_e32 v1, 64, v1
	ds_bpermute_b32 v1, v1, v0
	s_waitcnt lgkmcnt(0)
	v_add_f32_e32 v0, v0, v1
	v_mov_b32_e32 v1, v248
	s_nop 0
	v_lshlrev_b32_e32 v1, 2, v1
	v_xor_b32_e32 v1, 0x80, v1
	ds_bpermute_b32 v1, v1, v0
	s_and_saveexec_b64 s[6:7], s[2:3]
	s_cbranch_execz .LBB0_390
	v_lshlrev_b64 v[2:3], 6, v[212:213]
	v_lshl_add_u64 v[2:3], s[10:11], 0, v[2:3]
	v_lshl_add_u64 v[2:3], s[26:27], 2, v[2:3]
	s_lshl_b32 s60, s44, 2
	v_lshl_add_u64 v[2:3], v[2:3], 0, s[60:61]
	s_waitcnt lgkmcnt(0)
	v_add_f32_e32 v0, v0, v1
	global_store_dword v[2:3], v0, off sc1

.LBB0_412:
	s_lshl_b32 s6, s50, 8
	s_add_u32 s6, s4, s6
	s_addc_u32 s7, s5, 0
	s_add_u32 s6, s6, 0x180000
	s_addc_u32 s7, s7, 0
	s_mov_b32 s101, 0

.LBB0_637:
	v_lshl_or_b32 v208, s22, 8, v198
	v_lshl_add_u32 v238, s24, 8, v244
	v_ashrrev_i32_e32 v209, 31, v208
	v_lshlrev_b64 v[240:241], 1, v[208:209]
	v_ashrrev_i32_e32 v239, 31, v238
	v_lshl_add_u64 v[122:123], s[10:11], 0, v[240:241]
	v_lshlrev_b64 v[242:243], 11, v[238:239]
	v_lshl_add_u64 v[124:125], v[122:123], 0, v[242:243]
	global_load_dwordx4 v[194:197], v[124:125], off
	global_load_dwordx4 v[186:189], v[124:125], off offset:256
	v_or_b32_e32 v234, 16, v238
	v_ashrrev_i32_e32 v235, 31, v234
	v_or_b32_e32 v230, 32, v238
	v_lshlrev_b64 v[236:237], 11, v[234:235]
	v_ashrrev_i32_e32 v231, 31, v230
	v_or_b32_e32 v226, 48, v238
	v_lshl_add_u64 v[124:125], v[122:123], 0, v[236:237]
	v_lshlrev_b64 v[232:233], 11, v[230:231]
	v_ashrrev_i32_e32 v227, 31, v226
	v_add_u32_e32 v222, 0x80, v238
	global_load_dwordx4 v[182:185], v[124:125], off
	global_load_dwordx4 v[178:181], v[124:125], off offset:256
	v_lshl_add_u64 v[124:125], v[122:123], 0, v[232:233]
	v_lshlrev_b64 v[228:229], 11, v[226:227]
	v_ashrrev_i32_e32 v223, 31, v222
	v_add_u32_e32 v218, 0x90, v238
	global_load_dwordx4 v[174:177], v[124:125], off
	global_load_dwordx4 v[170:173], v[124:125], off offset:256
	v_lshl_add_u64 v[124:125], v[122:123], 0, v[228:229]
	v_lshlrev_b64 v[224:225], 11, v[222:223]
	v_ashrrev_i32_e32 v219, 31, v218
	v_add_u32_e32 v212, 0xa0, v238
	v_add_u32_e32 v210, 0xb0, v238
	global_load_dwordx4 v[166:169], v[124:125], off
	global_load_dwordx4 v[162:165], v[124:125], off offset:256
	v_lshl_add_u64 v[124:125], v[122:123], 0, v[224:225]
	v_lshlrev_b64 v[220:221], 11, v[218:219]
	v_ashrrev_i32_e32 v213, 31, v212
	v_ashrrev_i32_e32 v211, 31, v210
	global_load_dwordx4 v[150:153], v[124:125], off
	global_load_dwordx4 v[146:149], v[124:125], off offset:256
	v_lshl_add_u64 v[124:125], v[122:123], 0, v[220:221]
	v_lshlrev_b64 v[216:217], 11, v[212:213]
	v_lshlrev_b64 v[214:215], 11, v[210:211]
	global_load_dwordx4 v[142:145], v[124:125], off
	global_load_dwordx4 v[138:141], v[124:125], off offset:256
	v_lshl_add_u64 v[124:125], v[122:123], 0, v[216:217]
	v_lshl_add_u64 v[122:123], v[122:123], 0, v[214:215]
	global_load_dwordx4 v[134:137], v[124:125], off
	global_load_dwordx4 v[126:129], v[124:125], off offset:256
	global_load_dwordx4 v[130:133], v[122:123], off
	s_nop 0
	global_load_dwordx4 v[122:125], v[122:123], off offset:256
	s_lshl_b32 s22, s22, 2
	s_ashr_i32 s23, s22, 31
	s_waitcnt vmcnt(0)
	v_lshlrev_b32_e32 v200, 16, v194
	v_and_b32_e32 v194, 0xffff0000, v194
	v_add_f32_e32 v159, v159, v194
	v_lshlrev_b32_e32 v194, 16, v195
	v_add_f32_e32 v160, v160, v194
	v_and_b32_e32 v194, 0xffff0000, v195
	v_add_f32_e32 v161, v161, v194
	v_lshlrev_b32_e32 v194, 16, v196
	v_add_f32_e32 v194, v154, v194
	v_and_b32_e32 v154, 0xffff0000, v196
	v_add_f32_e32 v195, v155, v154
	v_lshlrev_b32_e32 v154, 16, v197
	v_add_f32_e32 v158, v158, v200
	v_add_f32_e32 v196, v156, v154
	v_and_b32_e32 v154, 0xffff0000, v197
	v_add_f32_e32 v157, v157, v154
	v_cvt_pk_bf16_f32 v154, v158, v159
	v_cvt_pk_bf16_f32 v155, v160, v161
	v_lshl_add_u64 v[158:159], s[10:11], 0, v[242:243]
	v_cvt_pk_bf16_f32 v156, v194, v195
	v_cvt_pk_bf16_f32 v157, v196, v157
	v_lshl_add_u64 v[158:159], v[158:159], 0, v[240:241]
	global_store_dwordx4 v[158:159], v[154:157], off sc1
	s_nop 1
	v_lshlrev_b32_e32 v160, 16, v154
	v_and_b32_e32 v154, 0xffff0000, v154
	v_lshlrev_b32_e32 v161, 16, v155
	v_and_b32_e32 v155, 0xffff0000, v155
	v_mul_f32_e32 v154, v154, v154
	v_mul_f32_e32 v155, v155, v155
	v_lshlrev_b32_e32 v194, 16, v156
	v_and_b32_e32 v156, 0xffff0000, v156
	v_lshlrev_b32_e32 v195, 16, v157
	v_and_b32_e32 v157, 0xffff0000, v157
	v_fmac_f32_e32 v154, v160, v160
	v_fmac_f32_e32 v155, v161, v161
	v_add_f32_e32 v154, v154, v155
	v_mul_f32_e32 v155, v156, v156
	v_mul_f32_e32 v156, v157, v157
	v_fmac_f32_e32 v155, v194, v194
	v_fmac_f32_e32 v156, v195, v195
	v_add_f32_e32 v155, v155, v156
	v_add_f32_e32 v154, v154, v155
	v_lshlrev_b32_e32 v155, 16, v186
	v_add_f32_e32 v118, v118, v155
	v_and_b32_e32 v155, 0xffff0000, v186
	v_add_f32_e32 v119, v119, v155
	v_lshlrev_b32_e32 v155, 16, v187
	v_add_f32_e32 v120, v120, v155
	v_and_b32_e32 v155, 0xffff0000, v187
	v_add_f32_e32 v121, v121, v155
	v_lshlrev_b32_e32 v155, 16, v188
	v_add_f32_e32 v155, v114, v155
	v_and_b32_e32 v114, 0xffff0000, v188
	v_add_f32_e32 v156, v115, v114
	v_lshlrev_b32_e32 v114, 16, v189
	v_add_f32_e32 v157, v116, v114
	v_and_b32_e32 v114, 0xffff0000, v189
	v_add_f32_e32 v117, v117, v114
	v_cvt_pk_bf16_f32 v114, v118, v119
	v_cvt_pk_bf16_f32 v115, v120, v121
	v_lshl_add_u64 v[118:119], v[158:159], 0, s[66:67]
	v_cvt_pk_bf16_f32 v116, v155, v156
	v_cvt_pk_bf16_f32 v117, v157, v117
	s_nop 0
	global_store_dwordx4 v[118:119], v[114:117], off sc1
	s_nop 1
	v_lshlrev_b32_e32 v118, 16, v114
	v_and_b32_e32 v114, 0xffff0000, v114
	v_lshlrev_b32_e32 v119, 16, v115
	v_and_b32_e32 v115, 0xffff0000, v115
	v_mul_f32_e32 v114, v114, v114
	v_mul_f32_e32 v115, v115, v115
	v_lshlrev_b32_e32 v120, 16, v116
	v_and_b32_e32 v116, 0xffff0000, v116
	v_lshlrev_b32_e32 v121, 16, v117
	v_and_b32_e32 v117, 0xffff0000, v117
	v_fmac_f32_e32 v114, v118, v118
	v_fmac_f32_e32 v115, v119, v119
	v_add_f32_e32 v114, v114, v115
	v_mul_f32_e32 v115, v116, v116
	v_mul_f32_e32 v116, v117, v117
	v_fmac_f32_e32 v115, v120, v120
	v_fmac_f32_e32 v116, v121, v121
	v_add_f32_e32 v115, v115, v116
	v_add_f32_e32 v114, v114, v115
	v_mov_b32_e32 v115, v248
	v_add_f32_e32 v114, v154, v114
	v_lshlrev_b32_e32 v115, 2, v115
	v_xor_b32_e32 v115, 64, v115
	ds_bpermute_b32 v115, v115, v114
	s_waitcnt lgkmcnt(0)
	v_add_f32_e32 v114, v114, v115
	v_mov_b32_e32 v115, v248
	s_nop 0
	v_lshlrev_b32_e32 v115, 2, v115
	v_xor_b32_e32 v115, 0x80, v115
	ds_bpermute_b32 v115, v115, v114
	s_and_saveexec_b64 s[24:25], s[2:3]
	s_cbranch_execz .LBB0_639
	v_lshlrev_b64 v[116:117], 6, v[238:239]
	v_lshl_add_u64 v[116:117], s[6:7], 0, v[116:117]
	v_lshl_add_u64 v[116:117], s[22:23], 2, v[116:117]
	s_lshl_b32 s60, s44, 2
	v_lshl_add_u64 v[116:117], v[116:117], 0, s[60:61]
	s_waitcnt lgkmcnt(0)
	v_add_f32_e32 v114, v114, v115
	global_store_dword v[116:117], v114, off sc1
.LBB0_639:
	s_or_b64 exec, exec, s[24:25]
	v_lshlrev_b32_e32 v114, 16, v182
	v_add_f32_e32 v110, v110, v114
	v_and_b32_e32 v114, 0xffff0000, v182
	v_add_f32_e32 v111, v111, v114
	v_lshlrev_b32_e32 v114, 16, v183
	v_add_f32_e32 v112, v112, v114
	v_and_b32_e32 v114, 0xffff0000, v183
	v_add_f32_e32 v113, v113, v114
	v_lshlrev_b32_e32 v114, 16, v184
	v_add_f32_e32 v114, v106, v114
	v_and_b32_e32 v106, 0xffff0000, v184
	s_waitcnt lgkmcnt(0)
	v_add_f32_e32 v115, v107, v106
	v_lshlrev_b32_e32 v106, 16, v185
	v_add_f32_e32 v116, v108, v106
	v_and_b32_e32 v106, 0xffff0000, v185
	v_add_f32_e32 v109, v109, v106
	v_cvt_pk_bf16_f32 v106, v110, v111
	v_cvt_pk_bf16_f32 v107, v112, v113
	v_lshl_add_u64 v[110:111], s[10:11], 0, v[236:237]
	v_cvt_pk_bf16_f32 v108, v114, v115
	v_cvt_pk_bf16_f32 v109, v116, v109
	v_lshl_add_u64 v[110:111], v[208:209], 1, v[110:111]
	global_store_dwordx4 v[110:111], v[106:109], off sc1
	s_nop 1
	v_lshlrev_b32_e32 v112, 16, v106
	v_and_b32_e32 v106, 0xffff0000, v106
	v_lshlrev_b32_e32 v113, 16, v107
	v_and_b32_e32 v107, 0xffff0000, v107
	v_mul_f32_e32 v106, v106, v106
	v_mul_f32_e32 v107, v107, v107
	v_lshlrev_b32_e32 v114, 16, v108
	v_and_b32_e32 v108, 0xffff0000, v108
	v_lshlrev_b32_e32 v115, 16, v109
	v_and_b32_e32 v109, 0xffff0000, v109
	v_fmac_f32_e32 v106, v112, v112
	v_fmac_f32_e32 v107, v113, v113
	v_add_f32_e32 v106, v106, v107
	v_mul_f32_e32 v107, v108, v108
	v_mul_f32_e32 v108, v109, v109
	v_fmac_f32_e32 v107, v114, v114
	v_fmac_f32_e32 v108, v115, v115
	v_add_f32_e32 v107, v107, v108
	v_add_f32_e32 v106, v106, v107
	v_lshlrev_b32_e32 v107, 16, v178
	v_add_f32_e32 v102, v102, v107
	v_and_b32_e32 v107, 0xffff0000, v178
	v_add_f32_e32 v103, v103, v107
	v_lshlrev_b32_e32 v107, 16, v179
	v_add_f32_e32 v104, v104, v107
	v_and_b32_e32 v107, 0xffff0000, v179
	v_add_f32_e32 v105, v105, v107
	v_lshlrev_b32_e32 v107, 16, v180
	v_add_f32_e32 v107, v98, v107
	v_and_b32_e32 v98, 0xffff0000, v180
	v_add_f32_e32 v108, v99, v98
	v_lshlrev_b32_e32 v98, 16, v181
	v_add_f32_e32 v109, v100, v98
	v_and_b32_e32 v98, 0xffff0000, v181
	v_add_f32_e32 v101, v101, v98
	v_cvt_pk_bf16_f32 v98, v102, v103
	v_cvt_pk_bf16_f32 v99, v104, v105
	v_lshl_add_u64 v[102:103], v[110:111], 0, s[66:67]
	v_cvt_pk_bf16_f32 v100, v107, v108
	v_cvt_pk_bf16_f32 v101, v109, v101
	s_nop 0
	global_store_dwordx4 v[102:103], v[98:101], off sc1
	s_nop 1
	v_lshlrev_b32_e32 v102, 16, v98
	v_and_b32_e32 v98, 0xffff0000, v98
	v_lshlrev_b32_e32 v103, 16, v99
	v_and_b32_e32 v99, 0xffff0000, v99
	v_mul_f32_e32 v98, v98, v98
	v_mul_f32_e32 v99, v99, v99
	v_lshlrev_b32_e32 v104, 16, v100
	v_and_b32_e32 v100, 0xffff0000, v100
	v_lshlrev_b32_e32 v105, 16, v101
	v_and_b32_e32 v101, 0xffff0000, v101
	v_fmac_f32_e32 v98, v102, v102
	v_fmac_f32_e32 v99, v103, v103
	v_add_f32_e32 v98, v98, v99
	v_mul_f32_e32 v99, v100, v100
	v_mul_f32_e32 v100, v101, v101
	v_fmac_f32_e32 v99, v104, v104
	v_fmac_f32_e32 v100, v105, v105
	v_add_f32_e32 v99, v99, v100
	v_add_f32_e32 v98, v98, v99
	v_mov_b32_e32 v99, v248
	v_add_f32_e32 v98, v106, v98
	v_lshlrev_b32_e32 v99, 2, v99
	v_xor_b32_e32 v99, 64, v99
	ds_bpermute_b32 v99, v99, v98
	s_waitcnt lgkmcnt(0)
	v_add_f32_e32 v98, v98, v99
	v_mov_b32_e32 v99, v248
	s_nop 0
	v_lshlrev_b32_e32 v99, 2, v99
	v_xor_b32_e32 v99, 0x80, v99
	ds_bpermute_b32 v99, v99, v98
	s_and_saveexec_b64 s[24:25], s[2:3]
	s_cbranch_execz .LBB0_641
	v_lshlrev_b64 v[100:101], 6, v[234:235]
	v_lshl_add_u64 v[100:101], s[6:7], 0, v[100:101]
	v_lshl_add_u64 v[100:101], s[22:23], 2, v[100:101]
	s_lshl_b32 s60, s44, 2
	v_lshl_add_u64 v[100:101], v[100:101], 0, s[60:61]
	s_waitcnt lgkmcnt(0)
	v_add_f32_e32 v98, v98, v99
	global_store_dword v[100:101], v98, off sc1
.LBB0_641:
	s_or_b64 exec, exec, s[24:25]
	v_lshlrev_b32_e32 v98, 16, v174
	v_add_f32_e32 v92, v92, v98
	v_and_b32_e32 v98, 0xffff0000, v174
	v_add_f32_e32 v93, v93, v98
	v_lshlrev_b32_e32 v98, 16, v175
	v_add_f32_e32 v94, v94, v98
	v_and_b32_e32 v98, 0xffff0000, v175
	v_add_f32_e32 v95, v95, v98
	v_lshlrev_b32_e32 v98, 16, v176
	v_add_f32_e32 v98, v88, v98
	v_and_b32_e32 v88, 0xffff0000, v176
	s_waitcnt lgkmcnt(0)
	v_add_f32_e32 v99, v89, v88
	v_lshlrev_b32_e32 v88, 16, v177
	v_add_f32_e32 v100, v90, v88
	v_and_b32_e32 v88, 0xffff0000, v177
	v_add_f32_e32 v91, v91, v88
	v_cvt_pk_bf16_f32 v88, v92, v93
	v_cvt_pk_bf16_f32 v89, v94, v95
	v_lshl_add_u64 v[92:93], s[10:11], 0, v[232:233]
	v_cvt_pk_bf16_f32 v90, v98, v99
	v_cvt_pk_bf16_f32 v91, v100, v91
	v_lshl_add_u64 v[92:93], v[208:209], 1, v[92:93]
	global_store_dwordx4 v[92:93], v[88:91], off sc1
	s_nop 1
	v_lshlrev_b32_e32 v94, 16, v88
	v_and_b32_e32 v88, 0xffff0000, v88
	v_lshlrev_b32_e32 v95, 16, v89
	v_and_b32_e32 v89, 0xffff0000, v89
	v_mul_f32_e32 v88, v88, v88
	v_mul_f32_e32 v89, v89, v89
	v_lshlrev_b32_e32 v98, 16, v90
	v_and_b32_e32 v90, 0xffff0000, v90
	v_lshlrev_b32_e32 v99, 16, v91
	v_and_b32_e32 v91, 0xffff0000, v91
	v_fmac_f32_e32 v88, v94, v94
	v_fmac_f32_e32 v89, v95, v95
	v_add_f32_e32 v88, v88, v89
	v_mul_f32_e32 v89, v90, v90
	v_mul_f32_e32 v90, v91, v91
	v_fmac_f32_e32 v89, v98, v98
	v_fmac_f32_e32 v90, v99, v99
	v_add_f32_e32 v89, v89, v90
	v_add_f32_e32 v88, v88, v89
	v_lshlrev_b32_e32 v89, 16, v170
	v_add_f32_e32 v84, v84, v89
	v_and_b32_e32 v89, 0xffff0000, v170
	v_add_f32_e32 v85, v85, v89
	v_lshlrev_b32_e32 v89, 16, v171
	v_add_f32_e32 v86, v86, v89
	v_and_b32_e32 v89, 0xffff0000, v171
	v_add_f32_e32 v87, v87, v89
	v_lshlrev_b32_e32 v89, 16, v172
	v_add_f32_e32 v89, v80, v89
	v_and_b32_e32 v80, 0xffff0000, v172
	v_add_f32_e32 v90, v81, v80
	v_lshlrev_b32_e32 v80, 16, v173
	v_add_f32_e32 v91, v82, v80
	v_and_b32_e32 v80, 0xffff0000, v173
	v_add_f32_e32 v83, v83, v80
	v_cvt_pk_bf16_f32 v80, v84, v85
	v_cvt_pk_bf16_f32 v81, v86, v87
	v_lshl_add_u64 v[84:85], v[92:93], 0, s[66:67]
	v_cvt_pk_bf16_f32 v82, v89, v90
	v_cvt_pk_bf16_f32 v83, v91, v83
	s_nop 0
	global_store_dwordx4 v[84:85], v[80:83], off sc1
	s_nop 1
	v_lshlrev_b32_e32 v84, 16, v80
	v_and_b32_e32 v80, 0xffff0000, v80
	v_lshlrev_b32_e32 v85, 16, v81
	v_and_b32_e32 v81, 0xffff0000, v81
	v_mul_f32_e32 v80, v80, v80
	v_mul_f32_e32 v81, v81, v81
	v_lshlrev_b32_e32 v86, 16, v82
	v_and_b32_e32 v82, 0xffff0000, v82
	v_lshlrev_b32_e32 v87, 16, v83
	v_and_b32_e32 v83, 0xffff0000, v83
	v_fmac_f32_e32 v80, v84, v84
	v_fmac_f32_e32 v81, v85, v85
	v_add_f32_e32 v80, v80, v81
	v_mul_f32_e32 v81, v82, v82
	v_mul_f32_e32 v82, v83, v83
	v_fmac_f32_e32 v81, v86, v86
	v_fmac_f32_e32 v82, v87, v87
	v_add_f32_e32 v81, v81, v82
	v_add_f32_e32 v80, v80, v81
	v_mov_b32_e32 v81, v248
	v_add_f32_e32 v80, v88, v80
	v_lshlrev_b32_e32 v81, 2, v81
	v_xor_b32_e32 v81, 64, v81
	ds_bpermute_b32 v81, v81, v80
	s_waitcnt lgkmcnt(0)
	v_add_f32_e32 v80, v80, v81
	v_mov_b32_e32 v81, v248
	s_nop 0
	v_lshlrev_b32_e32 v81, 2, v81
	v_xor_b32_e32 v81, 0x80, v81
	ds_bpermute_b32 v81, v81, v80
	s_and_saveexec_b64 s[24:25], s[2:3]
	s_cbranch_execz .LBB0_643
	v_lshlrev_b64 v[82:83], 6, v[230:231]
	v_lshl_add_u64 v[82:83], s[6:7], 0, v[82:83]
	v_lshl_add_u64 v[82:83], s[22:23], 2, v[82:83]
	s_lshl_b32 s60, s44, 2
	v_lshl_add_u64 v[82:83], v[82:83], 0, s[60:61]
	s_waitcnt lgkmcnt(0)
	v_add_f32_e32 v80, v80, v81
	global_store_dword v[82:83], v80, off sc1
.LBB0_643:
	s_or_b64 exec, exec, s[24:25]
	v_lshlrev_b32_e32 v80, 16, v166
	v_add_f32_e32 v76, v76, v80
	v_and_b32_e32 v80, 0xffff0000, v166
	v_add_f32_e32 v77, v77, v80
	v_lshlrev_b32_e32 v80, 16, v167
	v_add_f32_e32 v78, v78, v80
	v_and_b32_e32 v80, 0xffff0000, v167
	v_add_f32_e32 v79, v79, v80
	v_lshlrev_b32_e32 v80, 16, v168
	v_add_f32_e32 v80, v72, v80
	v_and_b32_e32 v72, 0xffff0000, v168
	s_waitcnt lgkmcnt(0)
	v_add_f32_e32 v81, v73, v72
	v_lshlrev_b32_e32 v72, 16, v169
	v_add_f32_e32 v82, v74, v72
	v_and_b32_e32 v72, 0xffff0000, v169
	v_add_f32_e32 v75, v75, v72
	v_cvt_pk_bf16_f32 v72, v76, v77
	v_cvt_pk_bf16_f32 v73, v78, v79
	v_lshl_add_u64 v[76:77], s[10:11], 0, v[228:229]
	v_cvt_pk_bf16_f32 v74, v80, v81
	v_cvt_pk_bf16_f32 v75, v82, v75
	v_lshl_add_u64 v[76:77], v[208:209], 1, v[76:77]
	global_store_dwordx4 v[76:77], v[72:75], off sc1
	s_nop 1
	v_lshlrev_b32_e32 v78, 16, v72
	v_and_b32_e32 v72, 0xffff0000, v72
	v_lshlrev_b32_e32 v79, 16, v73
	v_and_b32_e32 v73, 0xffff0000, v73
	v_mul_f32_e32 v72, v72, v72
	v_mul_f32_e32 v73, v73, v73
	v_lshlrev_b32_e32 v80, 16, v74
	v_and_b32_e32 v74, 0xffff0000, v74
	v_lshlrev_b32_e32 v81, 16, v75
	v_and_b32_e32 v75, 0xffff0000, v75
	v_fmac_f32_e32 v72, v78, v78
	v_fmac_f32_e32 v73, v79, v79
	v_add_f32_e32 v72, v72, v73
	v_mul_f32_e32 v73, v74, v74
	v_mul_f32_e32 v74, v75, v75
	v_fmac_f32_e32 v73, v80, v80
	v_fmac_f32_e32 v74, v81, v81
	v_add_f32_e32 v73, v73, v74
	v_add_f32_e32 v72, v72, v73
	v_lshlrev_b32_e32 v73, 16, v162
	v_add_f32_e32 v68, v68, v73
	v_and_b32_e32 v73, 0xffff0000, v162
	v_add_f32_e32 v69, v69, v73
	v_lshlrev_b32_e32 v73, 16, v163
	v_add_f32_e32 v70, v70, v73
	v_and_b32_e32 v73, 0xffff0000, v163
	v_add_f32_e32 v71, v71, v73
	v_lshlrev_b32_e32 v73, 16, v164
	v_add_f32_e32 v73, v64, v73
	v_and_b32_e32 v64, 0xffff0000, v164
	v_add_f32_e32 v74, v65, v64
	v_lshlrev_b32_e32 v64, 16, v165
	v_add_f32_e32 v75, v66, v64
	v_and_b32_e32 v64, 0xffff0000, v165
	v_add_f32_e32 v67, v67, v64
	v_cvt_pk_bf16_f32 v64, v68, v69
	v_cvt_pk_bf16_f32 v65, v70, v71
	v_lshl_add_u64 v[68:69], v[76:77], 0, s[66:67]
	v_cvt_pk_bf16_f32 v66, v73, v74
	v_cvt_pk_bf16_f32 v67, v75, v67
	s_nop 0
	global_store_dwordx4 v[68:69], v[64:67], off sc1
	s_nop 1
	v_lshlrev_b32_e32 v68, 16, v64
	v_and_b32_e32 v64, 0xffff0000, v64
	v_lshlrev_b32_e32 v69, 16, v65
	v_and_b32_e32 v65, 0xffff0000, v65
	v_mul_f32_e32 v64, v64, v64
	v_mul_f32_e32 v65, v65, v65
	v_lshlrev_b32_e32 v70, 16, v66
	v_and_b32_e32 v66, 0xffff0000, v66
	v_lshlrev_b32_e32 v71, 16, v67
	v_and_b32_e32 v67, 0xffff0000, v67
	v_fmac_f32_e32 v64, v68, v68
	v_fmac_f32_e32 v65, v69, v69
	v_add_f32_e32 v64, v64, v65
	v_mul_f32_e32 v65, v66, v66
	v_mul_f32_e32 v66, v67, v67
	v_fmac_f32_e32 v65, v70, v70
	v_fmac_f32_e32 v66, v71, v71
	v_add_f32_e32 v65, v65, v66
	v_add_f32_e32 v64, v64, v65
	v_mov_b32_e32 v65, v248
	v_add_f32_e32 v64, v72, v64
	v_lshlrev_b32_e32 v65, 2, v65
	v_xor_b32_e32 v65, 64, v65
	ds_bpermute_b32 v65, v65, v64
	s_waitcnt lgkmcnt(0)
	v_add_f32_e32 v64, v64, v65
	v_mov_b32_e32 v65, v248
	s_nop 0
	v_lshlrev_b32_e32 v65, 2, v65
	v_xor_b32_e32 v65, 0x80, v65
	ds_bpermute_b32 v65, v65, v64
	s_and_saveexec_b64 s[24:25], s[2:3]
	s_cbranch_execz .LBB0_645
	v_lshlrev_b64 v[66:67], 6, v[226:227]
	v_lshl_add_u64 v[66:67], s[6:7], 0, v[66:67]
	v_lshl_add_u64 v[66:67], s[22:23], 2, v[66:67]
	s_lshl_b32 s60, s44, 2
	v_lshl_add_u64 v[66:67], v[66:67], 0, s[60:61]
	s_waitcnt lgkmcnt(0)
	v_add_f32_e32 v64, v64, v65
	global_store_dword v[66:67], v64, off sc1
.LBB0_645:
	s_or_b64 exec, exec, s[24:25]
	v_lshlrev_b32_e32 v64, 16, v150
	v_add_f32_e32 v60, v60, v64
	v_and_b32_e32 v64, 0xffff0000, v150
	v_add_f32_e32 v61, v61, v64
	v_lshlrev_b32_e32 v64, 16, v151
	v_add_f32_e32 v62, v62, v64
	v_and_b32_e32 v64, 0xffff0000, v151
	v_add_f32_e32 v63, v63, v64
	v_lshlrev_b32_e32 v64, 16, v152
	v_add_f32_e32 v64, v56, v64
	v_and_b32_e32 v56, 0xffff0000, v152
	s_waitcnt lgkmcnt(0)
	v_add_f32_e32 v65, v57, v56
	v_lshlrev_b32_e32 v56, 16, v153
	v_add_f32_e32 v66, v58, v56
	v_and_b32_e32 v56, 0xffff0000, v153
	v_add_f32_e32 v59, v59, v56
	v_cvt_pk_bf16_f32 v56, v60, v61
	v_cvt_pk_bf16_f32 v57, v62, v63
	v_lshl_add_u64 v[60:61], s[10:11], 0, v[224:225]
	v_cvt_pk_bf16_f32 v58, v64, v65
	v_cvt_pk_bf16_f32 v59, v66, v59
	v_lshl_add_u64 v[60:61], v[208:209], 1, v[60:61]
	global_store_dwordx4 v[60:61], v[56:59], off sc1
	s_nop 1
	v_lshlrev_b32_e32 v62, 16, v56
	v_and_b32_e32 v56, 0xffff0000, v56
	v_lshlrev_b32_e32 v63, 16, v57
	v_and_b32_e32 v57, 0xffff0000, v57
	v_mul_f32_e32 v56, v56, v56
	v_mul_f32_e32 v57, v57, v57
	v_lshlrev_b32_e32 v64, 16, v58
	v_and_b32_e32 v58, 0xffff0000, v58
	v_lshlrev_b32_e32 v65, 16, v59
	v_and_b32_e32 v59, 0xffff0000, v59
	v_fmac_f32_e32 v56, v62, v62
	v_fmac_f32_e32 v57, v63, v63
	v_add_f32_e32 v56, v56, v57
	v_mul_f32_e32 v57, v58, v58
	v_mul_f32_e32 v58, v59, v59
	v_fmac_f32_e32 v57, v64, v64
	v_fmac_f32_e32 v58, v65, v65
	v_add_f32_e32 v57, v57, v58
	v_add_f32_e32 v56, v56, v57
	v_lshlrev_b32_e32 v57, 16, v146
	v_add_f32_e32 v52, v52, v57
	v_and_b32_e32 v57, 0xffff0000, v146
	v_add_f32_e32 v53, v53, v57
	v_lshlrev_b32_e32 v57, 16, v147
	v_add_f32_e32 v54, v54, v57
	v_and_b32_e32 v57, 0xffff0000, v147
	v_add_f32_e32 v55, v55, v57
	v_lshlrev_b32_e32 v57, 16, v148
	v_add_f32_e32 v57, v48, v57
	v_and_b32_e32 v48, 0xffff0000, v148
	v_add_f32_e32 v58, v49, v48
	v_lshlrev_b32_e32 v48, 16, v149
	v_add_f32_e32 v59, v50, v48
	v_and_b32_e32 v48, 0xffff0000, v149
	v_add_f32_e32 v51, v51, v48
	v_cvt_pk_bf16_f32 v48, v52, v53
	v_cvt_pk_bf16_f32 v49, v54, v55
	v_lshl_add_u64 v[52:53], v[60:61], 0, s[66:67]
	v_cvt_pk_bf16_f32 v50, v57, v58
	v_cvt_pk_bf16_f32 v51, v59, v51
	s_nop 0
	global_store_dwordx4 v[52:53], v[48:51], off sc1
	s_nop 1
	v_lshlrev_b32_e32 v52, 16, v48
	v_and_b32_e32 v48, 0xffff0000, v48
	v_lshlrev_b32_e32 v53, 16, v49
	v_and_b32_e32 v49, 0xffff0000, v49
	v_mul_f32_e32 v48, v48, v48
	v_mul_f32_e32 v49, v49, v49
	v_lshlrev_b32_e32 v54, 16, v50
	v_and_b32_e32 v50, 0xffff0000, v50
	v_lshlrev_b32_e32 v55, 16, v51
	v_and_b32_e32 v51, 0xffff0000, v51
	v_fmac_f32_e32 v48, v52, v52
	v_fmac_f32_e32 v49, v53, v53
	v_add_f32_e32 v48, v48, v49
	v_mul_f32_e32 v49, v50, v50
	v_mul_f32_e32 v50, v51, v51
	v_fmac_f32_e32 v49, v54, v54
	v_fmac_f32_e32 v50, v55, v55
	v_add_f32_e32 v49, v49, v50
	v_add_f32_e32 v48, v48, v49
	v_mov_b32_e32 v49, v248
	v_add_f32_e32 v48, v56, v48
	v_lshlrev_b32_e32 v49, 2, v49
	v_xor_b32_e32 v49, 64, v49
	ds_bpermute_b32 v49, v49, v48
	s_waitcnt lgkmcnt(0)
	v_add_f32_e32 v48, v48, v49
	v_mov_b32_e32 v49, v248
	s_nop 0
	v_lshlrev_b32_e32 v49, 2, v49
	v_xor_b32_e32 v49, 0x80, v49
	ds_bpermute_b32 v49, v49, v48
	s_and_saveexec_b64 s[24:25], s[2:3]
	s_cbranch_execz .LBB0_647
	v_lshlrev_b64 v[50:51], 6, v[222:223]
	v_lshl_add_u64 v[50:51], s[6:7], 0, v[50:51]
	v_lshl_add_u64 v[50:51], s[22:23], 2, v[50:51]
	s_lshl_b32 s60, s44, 2
	v_lshl_add_u64 v[50:51], v[50:51], 0, s[60:61]
	s_waitcnt lgkmcnt(0)
	v_add_f32_e32 v48, v48, v49
	global_store_dword v[50:51], v48, off sc1
.LBB0_647:
	s_or_b64 exec, exec, s[24:25]
	v_lshlrev_b32_e32 v48, 16, v142
	v_add_f32_e32 v44, v44, v48
	v_and_b32_e32 v48, 0xffff0000, v142
	v_add_f32_e32 v45, v45, v48
	v_lshlrev_b32_e32 v48, 16, v143
	v_add_f32_e32 v46, v46, v48
	v_and_b32_e32 v48, 0xffff0000, v143
	v_add_f32_e32 v47, v47, v48
	v_lshlrev_b32_e32 v48, 16, v144
	v_add_f32_e32 v48, v40, v48
	v_and_b32_e32 v40, 0xffff0000, v144
	s_waitcnt lgkmcnt(0)
	v_add_f32_e32 v49, v41, v40
	v_lshlrev_b32_e32 v40, 16, v145
	v_add_f32_e32 v50, v42, v40
	v_and_b32_e32 v40, 0xffff0000, v145
	v_add_f32_e32 v43, v43, v40
	v_cvt_pk_bf16_f32 v40, v44, v45
	v_cvt_pk_bf16_f32 v41, v46, v47
	v_lshl_add_u64 v[44:45], s[10:11], 0, v[220:221]
	v_cvt_pk_bf16_f32 v42, v48, v49
	v_cvt_pk_bf16_f32 v43, v50, v43
	v_lshl_add_u64 v[44:45], v[208:209], 1, v[44:45]
	global_store_dwordx4 v[44:45], v[40:43], off sc1
	s_nop 1
	v_lshlrev_b32_e32 v46, 16, v40
	v_and_b32_e32 v40, 0xffff0000, v40
	v_lshlrev_b32_e32 v47, 16, v41
	v_and_b32_e32 v41, 0xffff0000, v41
	v_mul_f32_e32 v40, v40, v40
	v_mul_f32_e32 v41, v41, v41
	v_lshlrev_b32_e32 v48, 16, v42
	v_and_b32_e32 v42, 0xffff0000, v42
	v_lshlrev_b32_e32 v49, 16, v43
	v_and_b32_e32 v43, 0xffff0000, v43
	v_fmac_f32_e32 v40, v46, v46
	v_fmac_f32_e32 v41, v47, v47
	v_add_f32_e32 v40, v40, v41
	v_mul_f32_e32 v41, v42, v42
	v_mul_f32_e32 v42, v43, v43
	v_fmac_f32_e32 v41, v48, v48
	v_fmac_f32_e32 v42, v49, v49
	v_add_f32_e32 v41, v41, v42
	v_add_f32_e32 v40, v40, v41
	v_lshlrev_b32_e32 v41, 16, v138
	v_add_f32_e32 v36, v36, v41
	v_and_b32_e32 v41, 0xffff0000, v138
	v_add_f32_e32 v37, v37, v41
	v_lshlrev_b32_e32 v41, 16, v139
	v_add_f32_e32 v38, v38, v41
	v_and_b32_e32 v41, 0xffff0000, v139
	v_add_f32_e32 v39, v39, v41
	v_lshlrev_b32_e32 v41, 16, v140
	v_add_f32_e32 v41, v32, v41
	v_and_b32_e32 v32, 0xffff0000, v140
	v_add_f32_e32 v42, v33, v32
	v_lshlrev_b32_e32 v32, 16, v141
	v_add_f32_e32 v43, v34, v32
	v_and_b32_e32 v32, 0xffff0000, v141
	v_add_f32_e32 v35, v35, v32
	v_cvt_pk_bf16_f32 v32, v36, v37
	v_cvt_pk_bf16_f32 v33, v38, v39
	v_lshl_add_u64 v[36:37], v[44:45], 0, s[66:67]
	v_cvt_pk_bf16_f32 v34, v41, v42
	v_cvt_pk_bf16_f32 v35, v43, v35
	s_nop 0
	global_store_dwordx4 v[36:37], v[32:35], off sc1
	s_nop 1
	v_lshlrev_b32_e32 v36, 16, v32
	v_and_b32_e32 v32, 0xffff0000, v32
	v_lshlrev_b32_e32 v37, 16, v33
	v_and_b32_e32 v33, 0xffff0000, v33
	v_mul_f32_e32 v32, v32, v32
	v_mul_f32_e32 v33, v33, v33
	v_lshlrev_b32_e32 v38, 16, v34
	v_and_b32_e32 v34, 0xffff0000, v34
	v_lshlrev_b32_e32 v39, 16, v35
	v_and_b32_e32 v35, 0xffff0000, v35
	v_fmac_f32_e32 v32, v36, v36
	v_fmac_f32_e32 v33, v37, v37
	v_add_f32_e32 v32, v32, v33
	v_mul_f32_e32 v33, v34, v34
	v_mul_f32_e32 v34, v35, v35
	v_fmac_f32_e32 v33, v38, v38
	v_fmac_f32_e32 v34, v39, v39
	v_add_f32_e32 v33, v33, v34
	v_add_f32_e32 v32, v32, v33
	v_mov_b32_e32 v33, v248
	v_add_f32_e32 v32, v40, v32
	v_lshlrev_b32_e32 v33, 2, v33
	v_xor_b32_e32 v33, 64, v33
	ds_bpermute_b32 v33, v33, v32
	s_waitcnt lgkmcnt(0)
	v_add_f32_e32 v32, v32, v33
	v_mov_b32_e32 v33, v248
	s_nop 0
	v_lshlrev_b32_e32 v33, 2, v33
	v_xor_b32_e32 v33, 0x80, v33
	ds_bpermute_b32 v33, v33, v32
	s_and_saveexec_b64 s[24:25], s[2:3]
	s_cbranch_execz .LBB0_649
	v_lshlrev_b64 v[34:35], 6, v[218:219]
	v_lshl_add_u64 v[34:35], s[6:7], 0, v[34:35]
	v_lshl_add_u64 v[34:35], s[22:23], 2, v[34:35]
	s_lshl_b32 s60, s44, 2
	v_lshl_add_u64 v[34:35], v[34:35], 0, s[60:61]
	s_waitcnt lgkmcnt(0)
	v_add_f32_e32 v32, v32, v33
	global_store_dword v[34:35], v32, off sc1
.LBB0_649:
	s_or_b64 exec, exec, s[24:25]
	v_lshlrev_b32_e32 v32, 16, v134
	v_add_f32_e32 v28, v28, v32
	v_and_b32_e32 v32, 0xffff0000, v134
	v_add_f32_e32 v29, v29, v32
	v_lshlrev_b32_e32 v32, 16, v135
	v_add_f32_e32 v30, v30, v32
	v_and_b32_e32 v32, 0xffff0000, v135
	v_add_f32_e32 v31, v31, v32
	v_lshlrev_b32_e32 v32, 16, v136
	v_add_f32_e32 v32, v24, v32
	v_and_b32_e32 v24, 0xffff0000, v136
	s_waitcnt lgkmcnt(0)
	v_add_f32_e32 v33, v25, v24
	v_lshlrev_b32_e32 v24, 16, v137
	v_add_f32_e32 v34, v26, v24
	v_and_b32_e32 v24, 0xffff0000, v137
	v_add_f32_e32 v27, v27, v24
	v_cvt_pk_bf16_f32 v24, v28, v29
	v_cvt_pk_bf16_f32 v25, v30, v31
	v_lshl_add_u64 v[28:29], s[10:11], 0, v[216:217]
	v_cvt_pk_bf16_f32 v26, v32, v33
	v_cvt_pk_bf16_f32 v27, v34, v27
	v_lshl_add_u64 v[28:29], v[208:209], 1, v[28:29]
	global_store_dwordx4 v[28:29], v[24:27], off sc1
	s_nop 1
	v_lshlrev_b32_e32 v30, 16, v24
	v_and_b32_e32 v24, 0xffff0000, v24
	v_lshlrev_b32_e32 v31, 16, v25
	v_and_b32_e32 v25, 0xffff0000, v25
	v_mul_f32_e32 v24, v24, v24
	v_mul_f32_e32 v25, v25, v25
	v_lshlrev_b32_e32 v32, 16, v26
	v_and_b32_e32 v26, 0xffff0000, v26
	v_lshlrev_b32_e32 v33, 16, v27
	v_and_b32_e32 v27, 0xffff0000, v27
	v_fmac_f32_e32 v24, v30, v30
	v_fmac_f32_e32 v25, v31, v31
	v_add_f32_e32 v24, v24, v25
	v_mul_f32_e32 v25, v26, v26
	v_mul_f32_e32 v26, v27, v27
	v_fmac_f32_e32 v25, v32, v32
	v_fmac_f32_e32 v26, v33, v33
	v_add_f32_e32 v25, v25, v26
	v_add_f32_e32 v24, v24, v25
	v_lshlrev_b32_e32 v25, 16, v126
	v_add_f32_e32 v20, v20, v25
	v_and_b32_e32 v25, 0xffff0000, v126
	v_add_f32_e32 v21, v21, v25
	v_lshlrev_b32_e32 v25, 16, v127
	v_add_f32_e32 v22, v22, v25
	v_and_b32_e32 v25, 0xffff0000, v127
	v_add_f32_e32 v23, v23, v25
	v_lshlrev_b32_e32 v25, 16, v128
	v_add_f32_e32 v25, v16, v25
	v_and_b32_e32 v16, 0xffff0000, v128
	v_add_f32_e32 v26, v17, v16
	v_lshlrev_b32_e32 v16, 16, v129
	v_add_f32_e32 v27, v18, v16
	v_and_b32_e32 v16, 0xffff0000, v129
	v_add_f32_e32 v19, v19, v16
	v_cvt_pk_bf16_f32 v16, v20, v21
	v_cvt_pk_bf16_f32 v17, v22, v23
	v_lshl_add_u64 v[20:21], v[28:29], 0, s[66:67]
	v_cvt_pk_bf16_f32 v18, v25, v26
	v_cvt_pk_bf16_f32 v19, v27, v19
	s_nop 0
	global_store_dwordx4 v[20:21], v[16:19], off sc1
	s_nop 1
	v_lshlrev_b32_e32 v20, 16, v16
	v_and_b32_e32 v16, 0xffff0000, v16
	v_lshlrev_b32_e32 v21, 16, v17
	v_and_b32_e32 v17, 0xffff0000, v17
	v_mul_f32_e32 v16, v16, v16
	v_mul_f32_e32 v17, v17, v17
	v_lshlrev_b32_e32 v22, 16, v18
	v_and_b32_e32 v18, 0xffff0000, v18
	v_lshlrev_b32_e32 v23, 16, v19
	v_and_b32_e32 v19, 0xffff0000, v19
	v_fmac_f32_e32 v16, v20, v20
	v_fmac_f32_e32 v17, v21, v21
	v_add_f32_e32 v16, v16, v17
	v_mul_f32_e32 v17, v18, v18
	v_mul_f32_e32 v18, v19, v19
	v_fmac_f32_e32 v17, v22, v22
	v_fmac_f32_e32 v18, v23, v23
	v_add_f32_e32 v17, v17, v18
	v_add_f32_e32 v16, v16, v17
	v_mov_b32_e32 v17, v248
	v_add_f32_e32 v16, v24, v16
	v_lshlrev_b32_e32 v17, 2, v17
	v_xor_b32_e32 v17, 64, v17
	ds_bpermute_b32 v17, v17, v16
	s_waitcnt lgkmcnt(0)
	v_add_f32_e32 v16, v16, v17
	v_mov_b32_e32 v17, v248
	s_nop 0
	v_lshlrev_b32_e32 v17, 2, v17
	v_xor_b32_e32 v17, 0x80, v17
	ds_bpermute_b32 v17, v17, v16
	s_and_saveexec_b64 s[24:25], s[2:3]
	s_cbranch_execz .LBB0_651
	v_lshlrev_b64 v[18:19], 6, v[212:213]
	v_lshl_add_u64 v[18:19], s[6:7], 0, v[18:19]
	v_lshl_add_u64 v[18:19], s[22:23], 2, v[18:19]
	s_lshl_b32 s60, s44, 2
	v_lshl_add_u64 v[18:19], v[18:19], 0, s[60:61]
	s_waitcnt lgkmcnt(0)
	v_add_f32_e32 v16, v16, v17
	global_store_dword v[18:19], v16, off sc1
.LBB0_651:
	s_or_b64 exec, exec, s[24:25]
	v_lshlrev_b32_e32 v16, 16, v130
	v_add_f32_e32 v12, v12, v16
	v_and_b32_e32 v16, 0xffff0000, v130
	v_add_f32_e32 v13, v13, v16
	v_lshlrev_b32_e32 v16, 16, v131
	v_add_f32_e32 v14, v14, v16
	v_and_b32_e32 v16, 0xffff0000, v131
	v_add_f32_e32 v15, v15, v16
	v_lshlrev_b32_e32 v16, 16, v132
	v_add_f32_e32 v16, v8, v16
	v_and_b32_e32 v8, 0xffff0000, v132
	s_waitcnt lgkmcnt(0)
	v_add_f32_e32 v17, v9, v8
	v_lshlrev_b32_e32 v8, 16, v133
	v_add_f32_e32 v18, v10, v8
	v_and_b32_e32 v8, 0xffff0000, v133
	v_add_f32_e32 v11, v11, v8
	v_cvt_pk_bf16_f32 v8, v12, v13
	v_cvt_pk_bf16_f32 v9, v14, v15
	v_lshl_add_u64 v[12:13], s[10:11], 0, v[214:215]
	v_cvt_pk_bf16_f32 v10, v16, v17
	v_cvt_pk_bf16_f32 v11, v18, v11
	v_lshl_add_u64 v[12:13], v[208:209], 1, v[12:13]
	global_store_dwordx4 v[12:13], v[8:11], off sc1
	s_nop 1
	v_lshlrev_b32_e32 v14, 16, v8
	v_and_b32_e32 v8, 0xffff0000, v8
	v_lshlrev_b32_e32 v15, 16, v9
	v_and_b32_e32 v9, 0xffff0000, v9
	v_mul_f32_e32 v8, v8, v8
	v_mul_f32_e32 v9, v9, v9
	v_lshlrev_b32_e32 v16, 16, v10
	v_and_b32_e32 v10, 0xffff0000, v10
	v_lshlrev_b32_e32 v17, 16, v11
	v_and_b32_e32 v11, 0xffff0000, v11
	v_fmac_f32_e32 v8, v14, v14
	v_fmac_f32_e32 v9, v15, v15
	v_add_f32_e32 v8, v8, v9
	v_mul_f32_e32 v9, v10, v10
	v_mul_f32_e32 v10, v11, v11
	v_fmac_f32_e32 v9, v16, v16
	v_fmac_f32_e32 v10, v17, v17
	v_add_f32_e32 v9, v9, v10
	v_add_f32_e32 v8, v8, v9
	v_lshlrev_b32_e32 v9, 16, v122
	v_add_f32_e32 v4, v4, v9
	v_and_b32_e32 v9, 0xffff0000, v122
	v_add_f32_e32 v5, v5, v9
	v_lshlrev_b32_e32 v9, 16, v123
	v_add_f32_e32 v6, v6, v9
	v_and_b32_e32 v9, 0xffff0000, v123
	v_add_f32_e32 v7, v7, v9
	v_lshlrev_b32_e32 v9, 16, v124
	v_add_f32_e32 v9, v0, v9
	v_and_b32_e32 v0, 0xffff0000, v124
	v_add_f32_e32 v10, v1, v0
	v_lshlrev_b32_e32 v0, 16, v125
	v_add_f32_e32 v11, v2, v0
	v_and_b32_e32 v0, 0xffff0000, v125
	v_add_f32_e32 v3, v3, v0
	v_cvt_pk_bf16_f32 v0, v4, v5
	v_cvt_pk_bf16_f32 v1, v6, v7
	v_lshl_add_u64 v[4:5], v[12:13], 0, s[66:67]
	v_cvt_pk_bf16_f32 v2, v9, v10
	v_cvt_pk_bf16_f32 v3, v11, v3
	s_nop 0
	global_store_dwordx4 v[4:5], v[0:3], off sc1
	s_nop 1
	v_lshlrev_b32_e32 v4, 16, v0
	v_and_b32_e32 v0, 0xffff0000, v0
	v_lshlrev_b32_e32 v5, 16, v1
	v_and_b32_e32 v1, 0xffff0000, v1
	v_mul_f32_e32 v0, v0, v0
	v_mul_f32_e32 v1, v1, v1
	v_lshlrev_b32_e32 v6, 16, v2
	v_and_b32_e32 v2, 0xffff0000, v2
	v_lshlrev_b32_e32 v7, 16, v3
	v_and_b32_e32 v3, 0xffff0000, v3
	v_fmac_f32_e32 v0, v4, v4
	v_fmac_f32_e32 v1, v5, v5
	v_add_f32_e32 v0, v0, v1
	v_mul_f32_e32 v1, v2, v2
	v_mul_f32_e32 v2, v3, v3
	v_fmac_f32_e32 v1, v6, v6
	v_fmac_f32_e32 v2, v7, v7
	v_add_f32_e32 v1, v1, v2
	v_add_f32_e32 v0, v0, v1
	v_mov_b32_e32 v1, v248
	v_add_f32_e32 v0, v8, v0
	v_lshlrev_b32_e32 v1, 2, v1
	v_xor_b32_e32 v1, 64, v1
	ds_bpermute_b32 v1, v1, v0
	s_waitcnt lgkmcnt(0)
	v_add_f32_e32 v0, v0, v1
	v_mov_b32_e32 v1, v248
	s_nop 0
	v_lshlrev_b32_e32 v1, 2, v1
	v_xor_b32_e32 v1, 0x80, v1
	ds_bpermute_b32 v1, v1, v0
	s_and_saveexec_b64 s[24:25], s[2:3]
	s_cbranch_execz .LBB0_653
	v_lshlrev_b64 v[2:3], 6, v[210:211]
	v_lshl_add_u64 v[2:3], s[6:7], 0, v[2:3]
	v_lshl_add_u64 v[2:3], s[22:23], 2, v[2:3]
	s_lshl_b32 s60, s44, 2
	v_lshl_add_u64 v[2:3], v[2:3], 0, s[60:61]
	s_waitcnt lgkmcnt(0)
	v_add_f32_e32 v0, v0, v1
	global_store_dword v[2:3], v0, off sc1

.LBB0_972:
	v_ashrrev_i32_e32 v74, 3, v49
	v_mad_i64_i32 v[0:1], s[2:3], v74, s84, v[44:45]
	global_load_dwordx4 v[66:69], v[0:1], off
	global_load_dwordx4 v[70:73], v[0:1], off offset:64
	global_load_dwordx4 v[12:15], v[0:1], off offset:128
	v_cvt_f64_i32_e32 v[64:65], v74
	v_mul_f64 v[50:51], v[16:17], v[64:65]
	v_mul_f64 v[52:53], v[50:51], s[58:59]
	v_rndne_f64_e32 v[52:53], v[52:53]
	v_fma_f64 v[50:51], v[50:51], s[58:59], -v[52:53]
	v_mul_f64 v[52:53], v[18:19], v[64:65]
	v_mul_f64 v[54:55], v[52:53], s[58:59]
	v_rndne_f64_e32 v[54:55], v[54:55]
	v_fma_f64 v[52:53], v[52:53], s[58:59], -v[54:55]
	v_mul_f64 v[54:55], v[20:21], v[64:65]
	v_mul_f64 v[56:57], v[54:55], s[58:59]
	v_rndne_f64_e32 v[56:57], v[56:57]
	v_fma_f64 v[54:55], v[54:55], s[58:59], -v[56:57]
	v_mul_f64 v[56:57], v[22:23], v[64:65]
	v_mul_f64 v[58:59], v[56:57], s[58:59]
	v_rndne_f64_e32 v[58:59], v[58:59]
	v_fma_f64 v[56:57], v[56:57], s[58:59], -v[58:59]
	v_mul_f64 v[58:59], v[24:25], v[64:65]
	v_mul_f64 v[60:61], v[58:59], s[58:59]
	v_rndne_f64_e32 v[60:61], v[60:61]
	v_fma_f64 v[58:59], v[58:59], s[58:59], -v[60:61]
	v_mul_f64 v[60:61], v[26:27], v[64:65]
	v_mul_f64 v[62:63], v[60:61], s[58:59]
	v_rndne_f64_e32 v[62:63], v[62:63]
	v_fma_f64 v[60:61], v[60:61], s[58:59], -v[62:63]
	v_mul_f64 v[62:63], v[28:29], v[64:65]
	v_ashrrev_i32_e32 v75, 31, v74
	v_mul_f64 v[76:77], v[62:63], s[58:59]
	v_lshlrev_b64 v[0:1], 10, v[74:75]
	v_rndne_f64_e32 v[76:77], v[76:77]
	v_mul_f64 v[64:65], v[30:31], v[64:65]
	v_lshl_add_u64 v[0:1], v[46:47], 0, v[0:1]
	v_fma_f64 v[62:63], v[62:63], s[58:59], -v[76:77]
	v_mul_f64 v[76:77], v[64:65], s[58:59]
	global_load_dwordx4 v[8:11], v[0:1], off
	global_load_dwordx4 v[4:7], v[0:1], off offset:64
	v_mov_b64_e32 v[0:1], s[4:5]
	v_rndne_f64_e32 v[76:77], v[76:77]
	v_mad_i64_i32 v[0:1], s[2:3], v74, s77, v[0:1]
	v_fma_f64 v[64:65], v[64:65], s[58:59], -v[76:77]
	v_add_u32_e32 v88, v48, v74
	v_lshl_add_u64 v[0:1], v[0:1], 0, v[96:97]
	s_mov_b32 s2, 0xc200000
	v_add_co_u32_e64 v0, s[2:3], s2, v0
	v_cvt_f32_f64_e32 v51, v[50:51]
	s_nop 0
	v_addc_co_u32_e64 v1, s[2:3], 0, v1, s[2:3]
	global_load_dwordx4 v[0:3], v[0:1], off offset:2304
	v_cos_f32_e32 v50, v51
	v_sin_f32_e32 v51, v51
	v_cvt_f32_f64_e32 v53, v[52:53]
	v_cos_f32_e32 v52, v53
	v_sin_f32_e32 v53, v53
	v_cvt_f32_f64_e32 v55, v[54:55]
	v_cos_f32_e32 v54, v55
	v_sin_f32_e32 v55, v55
	v_cvt_f32_f64_e32 v57, v[56:57]
	v_cvt_f32_f64_e32 v59, v[58:59]
	v_cos_f32_e32 v56, v57
	v_sin_f32_e32 v57, v57
	v_cos_f32_e32 v58, v59
	v_sin_f32_e32 v59, v59
	v_cvt_f32_f64_e32 v61, v[60:61]
	v_cos_f32_e32 v60, v61
	v_sin_f32_e32 v61, v61
	v_cvt_f32_f64_e32 v63, v[62:63]
	v_cos_f32_e32 v62, v63
	v_sin_f32_e32 v63, v63
	v_cvt_f32_f64_e32 v65, v[64:65]
	v_cos_f32_e32 v64, v65
	v_sin_f32_e32 v65, v65
	v_add_u32_e32 v49, s12, v49
	s_waitcnt vmcnt(5)
	v_and_b32_e32 v81, 0xffff0000, v67
	v_and_b32_e32 v83, 0xffff0000, v66
	v_and_b32_e32 v82, 0xffff0000, v68
	v_lshlrev_b32_e32 v80, 16, v67
	v_mul_f32_e32 v74, v81, v81
	v_lshlrev_b32_e32 v85, 16, v66
	v_lshlrev_b32_e32 v84, 16, v68
	v_pk_mul_f32 v[66:67], v[82:83], v[82:83]
	s_waitcnt vmcnt(4)
	v_and_b32_e32 v79, 0xffff0000, v70
	v_and_b32_e32 v77, 0xffff0000, v71
	v_pk_fma_f32 v[74:75], v[80:81], v[80:81], v[74:75] op_sel_hi:[1,1,0]
	v_pk_fma_f32 v[66:67], v[84:85], v[84:85], v[66:67]
	v_lshlrev_b32_e32 v78, 16, v70
	v_lshlrev_b32_e32 v76, 16, v71
	s_waitcnt vmcnt(3)
	v_lshlrev_b32_e32 v90, 16, v13
	v_and_b32_e32 v91, 0xffff0000, v13
	v_mul_f32_e32 v98, v79, v79
	v_mul_f32_e32 v100, v77, v77
	v_pk_add_f32 v[74:75], v[66:67], v[74:75] op_sel:[1,0] op_sel_hi:[0,1]
	v_lshlrev_b32_e32 v92, 16, v69
	v_and_b32_e32 v93, 0xffff0000, v69
	v_mul_f32_e32 v95, v90, v90
	v_mul_f32_e32 v102, v91, v91
	v_and_b32_e32 v69, 0xffff0000, v12
	v_and_b32_e32 v68, 0xffff0000, v72
	v_pk_fma_f32 v[98:99], v[78:79], v[78:79], v[98:99] op_sel_hi:[1,1,0]
	v_pk_fma_f32 v[100:101], v[76:77], v[76:77], v[100:101] op_sel_hi:[1,1,0]
	v_pk_add_f32 v[86:87], v[66:67], v[74:75]
	v_lshlrev_b32_e32 v71, 16, v12
	v_lshlrev_b32_e32 v70, 16, v72
	v_pk_mul_f32 v[74:75], v[68:69], v[68:69]
	v_mov_b32_e32 v99, v95
	v_mov_b32_e32 v101, v102
	v_pk_fma_f32 v[74:75], v[70:71], v[70:71], v[74:75]
	v_pk_add_f32 v[98:99], v[98:99], v[100:101]
	v_pk_mov_b32 v[100:101], v[72:73], v[14:15] op_sel:[1,0]
	v_pk_add_f32 v[98:99], v[74:75], v[98:99]
	v_lshlrev_b32_e32 v74, 16, v73
	v_and_b32_e32 v73, 0xffff0000, v101
	v_and_b32_e32 v72, 0xffff0000, v100
	v_lshlrev_b32_e32 v67, 16, v15
	v_lshlrev_b32_e32 v75, 16, v14
	v_pk_mul_f32 v[100:101], v[72:73], v[72:73]
	v_mul_f32_e32 v66, v92, v92
	v_mul_f32_e32 v94, v93, v93
	v_pk_fma_f32 v[100:101], v[74:75], v[74:75], v[100:101]
	v_mov_b32_e32 v95, v67
	v_and_b32_e32 v89, 0xffff0000, v15
	v_pk_add_f32 v[98:99], v[100:101], v[98:99]
	v_pk_add_f32 v[94:95], v[66:67], v[94:95]
	v_pk_mul_f32 v[100:101], v[66:67], v[66:67]
	v_mul_f32_e32 v87, v89, v89
	v_mov_b32_e32 v95, v101
	v_pk_add_f32 v[86:87], v[94:95], v[86:87]
	s_nop 0
	v_pk_add_f32 v[86:87], v[86:87], v[98:99]
	s_nop 0
	v_add_f32_e32 v66, v86, v87
	v_mov_b32_e32 v86, v248
	s_nop 0
	v_lshlrev_b32_e32 v86, 2, v86
	v_xor_b32_e32 v86, 4, v86
	ds_bpermute_b32 v86, v86, v66
	s_waitcnt lgkmcnt(0)
	v_add_f32_e32 v66, v66, v86
	v_mov_b32_e32 v86, v248
	global_load_dwordx4 v[98:101], v[34:35], off offset:16
	global_load_dwordx4 v[102:105], v[34:35], off
	v_lshlrev_b32_e32 v86, 2, v86
	v_xor_b32_e32 v86, 8, v86
	ds_bpermute_b32 v86, v86, v66
	s_waitcnt lgkmcnt(0)
	v_add_f32_e32 v66, v66, v86
	v_fmamk_f32 v66, v66, 0x3c2aaaab, v249
	v_rsq_f32_e32 v66, v66
	v_mad_i64_i32 v[86:87], s[2:3], v88, s63, v[32:33]
	v_mul_f32_e32 v106, 0x3e16c740, v66
	v_mul_f32_e32 v66, v106, v85
	v_mul_f32_e32 v83, v106, v83
	v_mul_f32_e32 v68, v106, v68
	s_waitcnt vmcnt(0)
	v_mul_f32_e32 v66, v102, v66
	v_mul_f32_e32 v83, v103, v83
	v_cvt_pk_bf16_f32 v102, v66, v83
	v_mul_f32_e32 v66, v106, v80
	v_mul_f32_e32 v80, v106, v81
	v_mul_f32_e32 v66, v104, v66
	v_mul_f32_e32 v80, v105, v80
	v_cvt_pk_bf16_f32 v103, v66, v80
	v_mul_f32_e32 v66, v106, v84
	v_mul_f32_e32 v80, v106, v82
	v_mul_f32_e32 v66, v98, v66
	v_mul_f32_e32 v80, v99, v80
	v_cvt_pk_bf16_f32 v104, v66, v80
	v_mul_f32_e32 v66, v106, v92
	v_mul_f32_e32 v80, v106, v93
	v_mul_f32_e32 v66, v100, v66
	v_mul_f32_e32 v80, v101, v80
	v_cvt_pk_bf16_f32 v105, v66, v80
	global_store_dwordx4 v[86:87], v[102:105], off sc1
	global_load_dwordx4 v[80:83], v[34:35], off offset:144
	global_load_dwordx4 v[92:95], v[34:35], off offset:128
	v_mul_f32_e32 v66, v106, v78
	v_mul_f32_e32 v78, v106, v79
	s_waitcnt vmcnt(1)
	v_mul_f32_e32 v68, v68, v81
	s_waitcnt vmcnt(0)
	v_mul_f32_e32 v66, v92, v66
	v_mul_f32_e32 v78, v93, v78
	v_cvt_pk_bf16_f32 v78, v66, v78
	v_mul_f32_e32 v66, v106, v76
	v_mul_f32_e32 v66, v94, v66
	v_mul_f32_e32 v76, v106, v77
	v_mul_f32_e32 v76, v95, v76
	v_cvt_pk_bf16_f32 v79, v66, v76
	v_mul_f32_e32 v66, v106, v70
	v_mul_f32_e32 v66, v66, v80
	v_cvt_pk_bf16_f32 v80, v66, v68
	v_mul_f32_e32 v66, v106, v74
	v_mul_f32_e32 v66, v66, v82
	v_mul_f32_e32 v68, v106, v72
	v_mul_f32_e32 v68, v68, v83
	v_cvt_pk_bf16_f32 v81, v66, v68
	v_mov_b32_e32 v66, v248
	global_store_dwordx4 v[86:87], v[78:81], off offset:64 sc1
	v_mul_f32_e32 v68, v106, v69
	v_lshlrev_b32_e32 v66, 2, v66
	v_xor_b32_e32 v66, 8, v66
	ds_bpermute_b32 v84, v66, v12
	v_mov_b32_e32 v12, v248
	v_mul_f32_e32 v69, v106, v90
	v_lshlrev_b32_e32 v12, 2, v12
	v_xor_b32_e32 v12, 8, v12
	ds_bpermute_b32 v85, v12, v13
	v_mov_b32_e32 v12, v248
	v_mul_f32_e32 v66, v106, v71
	v_lshlrev_b32_e32 v12, 2, v12
	v_xor_b32_e32 v12, 8, v12
	ds_bpermute_b32 v98, v12, v14
	v_mov_b32_e32 v12, v248
	s_nop 0
	v_lshlrev_b32_e32 v12, 2, v12
	v_xor_b32_e32 v12, 8, v12
	ds_bpermute_b32 v99, v12, v15
	global_load_dwordx4 v[12:15], v[34:35], off offset:272
	global_load_dwordx4 v[76:79], v[34:35], off offset:256
	global_load_dwordx4 v[80:83], v[36:37], off offset:272
	global_load_dwordx4 v[92:95], v[36:37], off offset:256
	s_waitcnt vmcnt(2)
	v_mul_f32_e32 v70, v69, v78
	v_mul_f32_e32 v69, v106, v91
	v_mul_f32_e32 v72, v69, v79
	v_mul_f32_e32 v69, v106, v75
	v_mul_f32_e32 v12, v69, v12
	v_mul_f32_e32 v69, v106, v73
	v_mul_f32_e32 v74, v69, v13
	v_mul_f32_e32 v13, v106, v67
	s_waitcnt lgkmcnt(2)
	v_lshlrev_b32_e32 v67, 16, v85
	v_mul_f32_e32 v67, v106, v67
	s_waitcnt vmcnt(0)
	v_mul_f32_e32 v71, v67, v94
	v_and_b32_e32 v67, 0xffff0000, v85
	v_mul_f32_e32 v67, v106, v67
	v_mul_f32_e32 v73, v67, v95
	s_waitcnt lgkmcnt(1)
	v_lshlrev_b32_e32 v67, 16, v98
	v_mul_f32_e32 v67, v106, v67
	v_mul_f32_e32 v75, v67, v80
	v_and_b32_e32 v67, 0xffff0000, v98
	v_mul_f32_e32 v67, v106, v67
	v_mul_f32_e32 v68, v68, v77
	v_mul_f32_e32 v14, v13, v14
	v_mul_f32_e32 v13, v106, v89
	v_mul_f32_e32 v77, v67, v81
	s_waitcnt lgkmcnt(0)
	v_lshlrev_b32_e32 v67, 16, v99
	v_mul_f32_e32 v66, v66, v76
	v_mul_f32_e32 v76, v13, v15
	v_lshlrev_b32_e32 v13, 16, v84
	v_mul_f32_e32 v67, v106, v67
	v_mul_f32_e32 v13, v106, v13
	v_and_b32_e32 v15, 0xffff0000, v84
	v_mul_f32_e32 v78, v67, v82
	v_and_b32_e32 v67, 0xffff0000, v99
	v_mul_f32_e32 v13, v13, v92
	v_mul_f32_e32 v15, v106, v15
	v_mul_f32_e32 v67, v106, v67
	v_mul_f32_e32 v15, v15, v93
	v_mul_f32_e32 v79, v67, v83
	v_cndmask_b32_e64 v67, v13, -v13, vcc
	v_pk_mul_f32 v[66:67], v[50:51], v[66:67]
	v_cndmask_b32_e64 v69, v15, -v15, vcc
	v_add_f32_e32 v80, v66, v67
	v_pk_mul_f32 v[66:67], v[52:53], v[68:69]
	v_cndmask_b32_e64 v71, v71, -v71, vcc
	v_add_f32_e32 v68, v66, v67
	v_pk_mul_f32 v[66:67], v[54:55], v[70:71]
	v_cndmask_b32_e64 v73, v73, -v73, vcc
	v_cndmask_b32_e64 v13, v75, -v75, vcc
	v_add_f32_e32 v69, v66, v67
	v_pk_mul_f32 v[66:67], v[56:57], v[72:73]
	v_pk_mul_f32 v[12:13], v[58:59], v[12:13]
	v_cndmask_b32_e64 v75, v77, -v77, vcc
	v_add_f32_e32 v66, v66, v67
	v_add_f32_e32 v67, v12, v13
	v_pk_mul_f32 v[12:13], v[60:61], v[74:75]
	v_cndmask_b32_e64 v15, v78, -v78, vcc
	v_add_f32_e32 v70, v12, v13
	v_pk_mul_f32 v[12:13], v[62:63], v[14:15]
	v_cndmask_b32_e64 v77, v79, -v79, vcc
	v_add_f32_e32 v15, v12, v13
	v_pk_mul_f32 v[12:13], v[64:65], v[76:77]
	v_and_b32_e32 v77, 0xffff0000, v9
	v_add_f32_e32 v71, v12, v13
	v_cvt_pk_bf16_f32 v12, v80, v68
	v_cvt_pk_bf16_f32 v13, v69, v66
	v_cvt_pk_bf16_f32 v14, v67, v70
	v_cvt_pk_bf16_f32 v15, v15, v71
	v_and_b32_e32 v71, 0xffff0000, v4
	global_store_dwordx4 v[86:87], v[12:15], off offset:128 sc1
	v_and_b32_e32 v73, 0xffff0000, v8
	v_and_b32_e32 v72, 0xffff0000, v10
	v_lshlrev_b32_e32 v70, 16, v4
	v_lshlrev_b32_e32 v81, 16, v1
	v_mul_f32_e32 v14, v71, v71
	v_lshlrev_b32_e32 v76, 16, v9
	v_mul_f32_e32 v12, v77, v77
	v_lshlrev_b32_e32 v75, 16, v8
	v_lshlrev_b32_e32 v74, 16, v10
	v_pk_mul_f32 v[8:9], v[72:73], v[72:73]
	v_and_b32_e32 v69, 0xffff0000, v5
	v_mul_f32_e32 v66, v81, v81
	v_pk_fma_f32 v[14:15], v[70:71], v[70:71], v[14:15] op_sel_hi:[1,1,0]
	v_pk_fma_f32 v[12:13], v[76:77], v[76:77], v[12:13] op_sel_hi:[1,1,0]
	v_pk_fma_f32 v[8:9], v[74:75], v[74:75], v[8:9]
	v_lshlrev_b32_e32 v68, 16, v5
	v_and_b32_e32 v82, 0xffff0000, v1
	v_mov_b32_e32 v15, v66
	v_mul_f32_e32 v66, v69, v69
	v_pk_add_f32 v[12:13], v[8:9], v[12:13] op_sel:[1,0] op_sel_hi:[0,1]
	v_lshlrev_b32_e32 v84, 16, v11
	v_and_b32_e32 v83, 0xffff0000, v11
	v_mul_f32_e32 v85, v82, v82
	v_and_b32_e32 v11, 0xffff0000, v0
	v_and_b32_e32 v10, 0xffff0000, v6
	v_pk_fma_f32 v[66:67], v[68:69], v[68:69], v[66:67] op_sel_hi:[1,1,0]
	v_pk_add_f32 v[78:79], v[8:9], v[12:13]
	v_lshlrev_b32_e32 v13, 16, v0
	v_lshlrev_b32_e32 v12, 16, v6
	v_pk_mul_f32 v[4:5], v[10:11], v[10:11]
	v_mov_b32_e32 v67, v85
	v_pk_fma_f32 v[4:5], v[12:13], v[12:13], v[4:5]
	v_pk_add_f32 v[14:15], v[14:15], v[66:67]
	v_lshlrev_b32_e32 v9, 16, v3
	v_pk_add_f32 v[4:5], v[4:5], v[14:15]
	v_pk_mov_b32 v[14:15], v[6:7], v[2:3] op_sel:[1,0]
	v_lshlrev_b32_e32 v67, 16, v2
	v_and_b32_e32 v15, 0xffff0000, v15
	v_and_b32_e32 v14, 0xffff0000, v14
	v_lshlrev_b32_e32 v66, 16, v7
	v_pk_mul_f32 v[6:7], v[14:15], v[14:15]
	v_mul_f32_e32 v8, v84, v84
	v_mul_f32_e32 v86, v83, v83
	v_pk_fma_f32 v[6:7], v[66:67], v[66:67], v[6:7]
	v_mov_b32_e32 v87, v9
	v_and_b32_e32 v80, 0xffff0000, v3
	v_pk_add_f32 v[4:5], v[6:7], v[4:5]
	v_pk_add_f32 v[6:7], v[8:9], v[86:87]
	v_pk_mul_f32 v[86:87], v[8:9], v[8:9]
	v_mul_f32_e32 v79, v80, v80
	v_mov_b32_e32 v7, v87
	v_pk_add_f32 v[6:7], v[6:7], v[78:79]
	v_mad_i64_i32 v[78:79], s[2:3], v88, s63, v[38:39]
	v_pk_add_f32 v[4:5], v[6:7], v[4:5]
	s_mov_b32 s2, 0x1ffff
	v_add_f32_e32 v4, v4, v5
	v_mov_b32_e32 v5, v248
	v_cmp_lt_i32_e64 s[2:3], s2, v49
	v_lshlrev_b32_e32 v5, 2, v5
	v_xor_b32_e32 v5, 4, v5
	ds_bpermute_b32 v5, v5, v4
	s_or_b64 s[8:9], s[2:3], s[8:9]
	s_waitcnt lgkmcnt(0)
	v_add_f32_e32 v4, v4, v5
	v_mov_b32_e32 v5, v248
	s_nop 0
	v_lshlrev_b32_e32 v5, 2, v5
	v_xor_b32_e32 v5, 8, v5
	ds_bpermute_b32 v5, v5, v4
	s_waitcnt lgkmcnt(0)
	v_add_f32_e32 v4, v4, v5
	v_fmamk_f32 v4, v4, 0x3c2aaaab, v249
	v_rsq_f32_e32 v8, v4
	global_load_dwordx4 v[4:7], v[40:41], off offset:16
	global_load_dwordx4 v[86:89], v[40:41], off
	v_mul_f32_e32 v73, v8, v73
	v_mul_f32_e32 v75, v8, v75
	v_mul_f32_e32 v72, v8, v72
	v_mul_f32_e32 v70, v8, v70
	v_mul_f32_e32 v71, v8, v71
	v_mul_f32_e32 v12, v8, v12
	v_mul_f32_e32 v68, v8, v68
	v_mul_f32_e32 v69, v8, v69
	v_mul_f32_e32 v10, v8, v10
	s_waitcnt vmcnt(1)
	v_mul_f32_e32 v5, v5, v72
	s_waitcnt vmcnt(0)
	v_mul_f32_e32 v73, v87, v73
	v_mul_f32_e32 v75, v86, v75
	v_cvt_pk_bf16_f32 v86, v75, v73
	v_mul_f32_e32 v73, v8, v76
	v_mul_f32_e32 v73, v88, v73
	v_mul_f32_e32 v75, v8, v77
	v_mul_f32_e32 v75, v89, v75
	v_cvt_pk_bf16_f32 v87, v73, v75
	v_mul_f32_e32 v73, v8, v74
	v_mul_f32_e32 v4, v4, v73
	v_cvt_pk_bf16_f32 v88, v4, v5
	v_mul_f32_e32 v4, v8, v84
	v_mul_f32_e32 v5, v8, v83
	v_mul_f32_e32 v4, v6, v4
	v_mul_f32_e32 v5, v7, v5
	v_cvt_pk_bf16_f32 v89, v4, v5
	global_store_dwordx4 v[78:79], v[86:89], off sc1
	global_load_dwordx4 v[4:7], v[40:41], off offset:144
	global_load_dwordx4 v[72:75], v[40:41], off offset:128
	s_waitcnt vmcnt(1)
	v_mul_f32_e32 v4, v12, v4
	s_waitcnt vmcnt(0)
	v_mul_f32_e32 v70, v70, v72
	v_mul_f32_e32 v71, v71, v73
	v_cvt_pk_bf16_f32 v70, v70, v71
	v_mul_f32_e32 v68, v68, v74
	v_mul_f32_e32 v69, v69, v75
	v_cvt_pk_bf16_f32 v71, v68, v69
	v_mul_f32_e32 v5, v10, v5
	v_cvt_pk_bf16_f32 v72, v4, v5
	v_mul_f32_e32 v4, v8, v66
	v_mul_f32_e32 v4, v4, v6
	v_mul_f32_e32 v5, v8, v14
	v_mul_f32_e32 v5, v5, v7
	v_cvt_pk_bf16_f32 v73, v4, v5
	v_mov_b32_e32 v4, v248
	global_store_dwordx4 v[78:79], v[70:73], off offset:64 sc1
	v_mul_f32_e32 v10, v8, v13
	v_lshlrev_b32_e32 v4, 2, v4
	v_xor_b32_e32 v4, 8, v4
	ds_bpermute_b32 v76, v4, v0
	v_mov_b32_e32 v0, v248
	s_nop 0
	v_lshlrev_b32_e32 v0, 2, v0
	v_xor_b32_e32 v0, 8, v0
	ds_bpermute_b32 v77, v0, v1
	v_mov_b32_e32 v0, v248
	s_nop 0
	v_lshlrev_b32_e32 v0, 2, v0
	v_xor_b32_e32 v0, 8, v0
	ds_bpermute_b32 v83, v0, v2
	v_mov_b32_e32 v0, v248
	s_nop 0
	v_lshlrev_b32_e32 v0, 2, v0
	v_xor_b32_e32 v0, 8, v0
	ds_bpermute_b32 v84, v0, v3
	global_load_dwordx4 v[0:3], v[40:41], off offset:272
	global_load_dwordx4 v[4:7], v[40:41], off offset:256
	global_load_dwordx4 v[68:71], v[42:43], off offset:272
	global_load_dwordx4 v[72:75], v[42:43], off offset:256
	s_waitcnt vmcnt(2)
	v_mul_f32_e32 v4, v10, v4
	v_mul_f32_e32 v10, v8, v11
	v_mul_f32_e32 v10, v10, v5
	v_mul_f32_e32 v5, v8, v81
	v_mul_f32_e32 v6, v5, v6
	v_mul_f32_e32 v5, v8, v82
	v_mul_f32_e32 v12, v5, v7
	v_mul_f32_e32 v5, v8, v67
	v_mul_f32_e32 v0, v5, v0
	v_mul_f32_e32 v5, v8, v15
	v_mul_f32_e32 v14, v5, v1
	s_waitcnt lgkmcnt(2)
	v_lshlrev_b32_e32 v5, 16, v77
	v_mul_f32_e32 v5, v8, v5
	s_waitcnt vmcnt(0)
	v_mul_f32_e32 v7, v5, v74
	v_and_b32_e32 v5, 0xffff0000, v77
	v_mul_f32_e32 v5, v8, v5
	v_mul_f32_e32 v1, v8, v9
	v_mul_f32_e32 v9, v5, v75
	s_waitcnt lgkmcnt(1)
	v_lshlrev_b32_e32 v5, 16, v83
	v_mul_f32_e32 v5, v8, v5
	v_mul_f32_e32 v15, v5, v68
	v_and_b32_e32 v5, 0xffff0000, v83
	v_mul_f32_e32 v5, v8, v5
	v_mul_f32_e32 v2, v1, v2
	v_mul_f32_e32 v1, v8, v80
	v_mul_f32_e32 v67, v5, v69
	s_waitcnt lgkmcnt(0)
	v_lshlrev_b32_e32 v5, 16, v84
	v_mul_f32_e32 v66, v1, v3
	v_lshlrev_b32_e32 v1, 16, v76
	v_mul_f32_e32 v5, v8, v5
	v_mul_f32_e32 v1, v8, v1
	v_and_b32_e32 v3, 0xffff0000, v76
	v_mul_f32_e32 v68, v5, v70
	v_and_b32_e32 v5, 0xffff0000, v84
	v_mul_f32_e32 v1, v1, v72
	v_mul_f32_e32 v3, v8, v3
	v_mul_f32_e32 v5, v8, v5
	v_mul_f32_e32 v3, v3, v73
	v_mul_f32_e32 v8, v5, v71
	v_cndmask_b32_e64 v5, v1, -v1, vcc
	v_pk_mul_f32 v[4:5], v[50:51], v[4:5]
	v_cndmask_b32_e64 v11, v3, -v3, vcc
	v_add_f32_e32 v50, v4, v5
	v_pk_mul_f32 v[4:5], v[52:53], v[10:11]
	v_cndmask_b32_e64 v7, v7, -v7, vcc
	v_add_f32_e32 v10, v4, v5
	v_pk_mul_f32 v[4:5], v[54:55], v[6:7]
	v_cndmask_b32_e64 v13, v9, -v9, vcc
	v_cndmask_b32_e64 v1, v15, -v15, vcc
	v_add_f32_e32 v6, v4, v5
	v_pk_mul_f32 v[4:5], v[56:57], v[12:13]
	v_pk_mul_f32 v[0:1], v[58:59], v[0:1]
	v_cndmask_b32_e64 v15, v67, -v67, vcc
	v_add_f32_e32 v4, v4, v5
	v_add_f32_e32 v5, v0, v1
	v_pk_mul_f32 v[0:1], v[60:61], v[14:15]
	v_cndmask_b32_e64 v3, v68, -v68, vcc
	v_add_f32_e32 v7, v0, v1
	v_pk_mul_f32 v[0:1], v[62:63], v[2:3]
	v_cndmask_b32_e64 v67, v8, -v8, vcc
	v_add_f32_e32 v3, v0, v1
	v_pk_mul_f32 v[0:1], v[64:65], v[66:67]
	s_nop 0
	v_add_f32_e32 v8, v0, v1
	v_cvt_pk_bf16_f32 v0, v50, v10
	v_cvt_pk_bf16_f32 v1, v6, v4
	v_cvt_pk_bf16_f32 v2, v5, v7
	v_cvt_pk_bf16_f32 v3, v3, v8
	global_store_dwordx4 v[78:79], v[0:3], off offset:128 sc1
	s_andn2_b64 exec, exec, s[8:9]
	s_cbranch_execnz .LBB0_972

.LBB0_1095:
	s_or_b64 exec, exec, s[2:3]
	s_add_u32 s74, s94, 0x13a00000
	s_addc_u32 s75, s95, 0
	s_lshl_b32 s5, s68, 8

	s_waitcnt vmcnt(0)
	s_lshl_b64 s[2:3], s[50:51], 11
	v_add_u32_e32 v38, s4, v184
	s_add_u32 s2, s74, s2
	s_addc_u32 s3, s75, s3

	s_lshl_b32 s6, s57, 7
	s_add_u32 s2, s2, s6
	s_addc_u32 s3, s3, 0
	s_waitcnt lgkmcnt(0)
	ds_read_b128 v[32:35], v38 offset:58368
	ds_read_b128 v[36:39], v38 offset:58400
	ds_read_b128 v[40:43], v38 offset:58432
	ds_read_b128 v[44:47], v38 offset:58464
	s_lshl_b32 s6, s86, 7
	s_mov_b32 s98, 0xaaaaaaaa
	s_mov_b32 s99, 0xaaaaaaaa
	v_and_b32_e32 v51, 1, v203
	v_sub_u32_e32 v48, v203, v51
	v_lshlrev_b32_e32 v48, 1, v48
	v_lshl_or_b32 v48, v51, 6, v48
	v_lshl_or_b32 v48, v202, 9, v48
	v_add_u32_e32 v48, s6, v48
	v_lshlrev_b32_e32 v49, 4, v248
	v_add_u32_e32 v49, s6, v49
	v_lshrrev_b32_e32 v50, 3, v248
	v_and_b32_e32 v51, 7, v248
	v_lshlrev_b32_e32 v51, 4, v51
	v_lshl_or_b32 v50, v50, 11, v51
	s_waitcnt lgkmcnt(0)

	v_mul_f32_e32 v52, v16, v32
	v_mul_f32_dpp v53, v16, v32 quad_perm:[1,0,3,2] row_mask:0xf bank_mask:0xf
	v_mul_f32_e32 v54, v0, v32
	v_mul_f32_dpp v55, v0, v32 quad_perm:[1,0,3,2] row_mask:0xf bank_mask:0xf
	v_cndmask_b32_e64 v52, v52, v55, s[98:99]
	v_cndmask_b32_e64 v54, v53, v54, s[98:99]
	v_cvt_pk_bf16_f32 v52, v52, v54
	ds_write_b32 v48, v52
	v_mul_f32_e32 v56, v17, v33
	v_mul_f32_dpp v57, v17, v33 quad_perm:[1,0,3,2] row_mask:0xf bank_mask:0xf
	v_mul_f32_e32 v58, v1, v33
	v_mul_f32_dpp v59, v1, v33 quad_perm:[1,0,3,2] row_mask:0xf bank_mask:0xf
	v_cndmask_b32_e64 v56, v56, v59, s[98:99]
	v_cndmask_b32_e64 v58, v57, v58, s[98:99]
	v_cvt_pk_bf16_f32 v56, v56, v58
	ds_write_b32 v48, v56 offset:128
	v_mul_f32_e32 v60, v18, v34
	v_mul_f32_dpp v61, v18, v34 quad_perm:[1,0,3,2] row_mask:0xf bank_mask:0xf
	v_mul_f32_e32 v62, v2, v34
	v_mul_f32_dpp v63, v2, v34 quad_perm:[1,0,3,2] row_mask:0xf bank_mask:0xf
	v_cndmask_b32_e64 v60, v60, v63, s[98:99]
	v_cndmask_b32_e64 v62, v61, v62, s[98:99]
	v_cvt_pk_bf16_f32 v60, v60, v62
	ds_write_b32 v48, v60 offset:256
	v_mul_f32_e32 v64, v19, v35
	v_mul_f32_dpp v65, v19, v35 quad_perm:[1,0,3,2] row_mask:0xf bank_mask:0xf
	v_mul_f32_e32 v66, v3, v35
	v_mul_f32_dpp v67, v3, v35 quad_perm:[1,0,3,2] row_mask:0xf bank_mask:0xf
	v_cndmask_b32_e64 v64, v64, v67, s[98:99]
	v_cndmask_b32_e64 v66, v65, v66, s[98:99]
	v_cvt_pk_bf16_f32 v64, v64, v66
	ds_write_b32 v48, v64 offset:384
	v_mul_f32_e32 v52, v20, v36
	v_mul_f32_dpp v53, v20, v36 quad_perm:[1,0,3,2] row_mask:0xf bank_mask:0xf
	v_mul_f32_e32 v54, v4, v36
	v_mul_f32_dpp v55, v4, v36 quad_perm:[1,0,3,2] row_mask:0xf bank_mask:0xf
	v_cndmask_b32_e64 v52, v52, v55, s[98:99]
	v_cndmask_b32_e64 v54, v53, v54, s[98:99]
	v_cvt_pk_bf16_f32 v52, v52, v54
	ds_write_b32 v48, v52 offset:1024
	v_mul_f32_e32 v56, v21, v37
	v_mul_f32_dpp v57, v21, v37 quad_perm:[1,0,3,2] row_mask:0xf bank_mask:0xf
	v_mul_f32_e32 v58, v5, v37
	v_mul_f32_dpp v59, v5, v37 quad_perm:[1,0,3,2] row_mask:0xf bank_mask:0xf
	v_cndmask_b32_e64 v56, v56, v59, s[98:99]
	v_cndmask_b32_e64 v58, v57, v58, s[98:99]
	v_cvt_pk_bf16_f32 v56, v56, v58
	ds_write_b32 v48, v56 offset:1152
	v_mul_f32_e32 v60, v22, v38
	v_mul_f32_dpp v61, v22, v38 quad_perm:[1,0,3,2] row_mask:0xf bank_mask:0xf
	v_mul_f32_e32 v62, v6, v38
	v_mul_f32_dpp v63, v6, v38 quad_perm:[1,0,3,2] row_mask:0xf bank_mask:0xf
	v_cndmask_b32_e64 v60, v60, v63, s[98:99]
	v_cndmask_b32_e64 v62, v61, v62, s[98:99]
	v_cvt_pk_bf16_f32 v60, v60, v62
	ds_write_b32 v48, v60 offset:1280
	v_mul_f32_e32 v64, v23, v39
	v_mul_f32_dpp v65, v23, v39 quad_perm:[1,0,3,2] row_mask:0xf bank_mask:0xf
	v_mul_f32_e32 v66, v7, v39
	v_mul_f32_dpp v67, v7, v39 quad_perm:[1,0,3,2] row_mask:0xf bank_mask:0xf
	v_cndmask_b32_e64 v64, v64, v67, s[98:99]
	v_cndmask_b32_e64 v66, v65, v66, s[98:99]
	v_cvt_pk_bf16_f32 v64, v64, v66
	ds_write_b32 v48, v64 offset:1408
	s_waitcnt lgkmcnt(0)
	v_mul_f32_e32 v52, v24, v40
	v_mul_f32_dpp v53, v24, v40 quad_perm:[1,0,3,2] row_mask:0xf bank_mask:0xf
	v_mul_f32_e32 v54, v8, v40
	v_mul_f32_dpp v55, v8, v40 quad_perm:[1,0,3,2] row_mask:0xf bank_mask:0xf
	v_cndmask_b32_e64 v52, v52, v55, s[98:99]
	v_cndmask_b32_e64 v54, v53, v54, s[98:99]
	v_cvt_pk_bf16_f32 v52, v52, v54
	ds_write_b32 v48, v52 offset:2048
	v_mul_f32_e32 v56, v25, v41
	v_mul_f32_dpp v57, v25, v41 quad_perm:[1,0,3,2] row_mask:0xf bank_mask:0xf
	v_mul_f32_e32 v58, v9, v41
	v_mul_f32_dpp v59, v9, v41 quad_perm:[1,0,3,2] row_mask:0xf bank_mask:0xf
	v_cndmask_b32_e64 v56, v56, v59, s[98:99]
	v_cndmask_b32_e64 v58, v57, v58, s[98:99]
	v_cvt_pk_bf16_f32 v56, v56, v58
	ds_write_b32 v48, v56 offset:2176
	v_mul_f32_e32 v60, v26, v42
	v_mul_f32_dpp v61, v26, v42 quad_perm:[1,0,3,2] row_mask:0xf bank_mask:0xf
	v_mul_f32_e32 v62, v10, v42
	v_mul_f32_dpp v63, v10, v42 quad_perm:[1,0,3,2] row_mask:0xf bank_mask:0xf
	v_cndmask_b32_e64 v60, v60, v63, s[98:99]
	v_cndmask_b32_e64 v62, v61, v62, s[98:99]
	v_cvt_pk_bf16_f32 v60, v60, v62
	ds_write_b32 v48, v60 offset:2304
	v_mul_f32_e32 v64, v27, v43
	v_mul_f32_dpp v65, v27, v43 quad_perm:[1,0,3,2] row_mask:0xf bank_mask:0xf
	v_mul_f32_e32 v66, v11, v43
	v_mul_f32_dpp v67, v11, v43 quad_perm:[1,0,3,2] row_mask:0xf bank_mask:0xf
	v_cndmask_b32_e64 v64, v64, v67, s[98:99]
	v_cndmask_b32_e64 v66, v65, v66, s[98:99]
	v_cvt_pk_bf16_f32 v64, v64, v66
	ds_write_b32 v48, v64 offset:2432
	v_mul_f32_e32 v52, v28, v44
	v_mul_f32_dpp v53, v28, v44 quad_perm:[1,0,3,2] row_mask:0xf bank_mask:0xf
	v_mul_f32_e32 v54, v12, v44
	v_mul_f32_dpp v55, v12, v44 quad_perm:[1,0,3,2] row_mask:0xf bank_mask:0xf
	v_cndmask_b32_e64 v52, v52, v55, s[98:99]
	v_cndmask_b32_e64 v54, v53, v54, s[98:99]
	v_cvt_pk_bf16_f32 v52, v52, v54
	ds_write_b32 v48, v52 offset:3072
	v_mul_f32_e32 v56, v29, v45
	v_mul_f32_dpp v57, v29, v45 quad_perm:[1,0,3,2] row_mask:0xf bank_mask:0xf
	v_mul_f32_e32 v58, v13, v45
	v_mul_f32_dpp v59, v13, v45 quad_perm:[1,0,3,2] row_mask:0xf bank_mask:0xf
	v_cndmask_b32_e64 v56, v56, v59, s[98:99]
	v_cndmask_b32_e64 v58, v57, v58, s[98:99]
	v_cvt_pk_bf16_f32 v56, v56, v58
	ds_write_b32 v48, v56 offset:3200
	v_mul_f32_e32 v60, v30, v46
	v_mul_f32_dpp v61, v30, v46 quad_perm:[1,0,3,2] row_mask:0xf bank_mask:0xf
	v_mul_f32_e32 v62, v14, v46
	v_mul_f32_dpp v63, v14, v46 quad_perm:[1,0,3,2] row_mask:0xf bank_mask:0xf
	v_cndmask_b32_e64 v60, v60, v63, s[98:99]
	v_cndmask_b32_e64 v62, v61, v62, s[98:99]
	v_cvt_pk_bf16_f32 v60, v60, v62
	ds_write_b32 v48, v60 offset:3328
	v_mul_f32_e32 v64, v31, v47
	v_mul_f32_dpp v65, v31, v47 quad_perm:[1,0,3,2] row_mask:0xf bank_mask:0xf
	v_mul_f32_e32 v66, v15, v47
	v_mul_f32_dpp v67, v15, v47 quad_perm:[1,0,3,2] row_mask:0xf bank_mask:0xf
	v_cndmask_b32_e64 v64, v64, v67, s[98:99]
	v_cndmask_b32_e64 v66, v65, v66, s[98:99]
	v_cvt_pk_bf16_f32 v64, v64, v66
	ds_write_b32 v48, v64 offset:3456
	s_waitcnt lgkmcnt(0)
	ds_read_b128 v[68:71], v49
	ds_read_b128 v[72:75], v49 offset:1024
	ds_read_b128 v[76:79], v49 offset:2048
	ds_read_b128 v[80:83], v49 offset:3072
	v_add_u32_e32 v51, 0x4000, v50
	v_add_u32_e32 v84, 0x8000, v50
	v_add_u32_e32 v85, 0xc000, v50
	s_waitcnt lgkmcnt(3)
	global_store_dwordx4 v50, v[68:71], s[2:3] offset:1024 sc1
	s_waitcnt lgkmcnt(2)
	global_store_dwordx4 v51, v[72:75], s[2:3] offset:1024 sc1
	s_waitcnt lgkmcnt(1)
	global_store_dwordx4 v84, v[76:79], s[2:3] offset:1024 sc1
	s_waitcnt lgkmcnt(0)
	global_store_dwordx4 v85, v[80:83], s[2:3] offset:1024 sc1
	s_nop 1

	v_mov_b32_e32 v16, 0
	v_mov_b32_e32 v17, 0
	v_mov_b32_e32 v18, 0
	v_mov_b32_e32 v19, 0
	v_mov_b32_e32 v185, v97

	s_barrier
	s_getreg_b32 s2, hwreg(HW_REG_HW_ID, 0, 6)
	s_and_b32 s2, s2, 63
	s_lshl_b32 s2, s2, 2
	s_add_i32 s2, s2, 0
	s_add_i32 s2, s2, 0x20840
	v_mov_b32_e32 v0, s2
	ds_read_b32 v0, v0
	s_waitcnt lgkmcnt(0)
	v_readfirstlane_b32 s2, v0
	s_lshl_b32 s86, s2, 5
	v_mov_b32_e32 v0, v248
	s_add_i32 s72, s86, s5
	s_ashr_i32 s73, s72, 31
	v_lshl_add_u32 v24, s2, 6, v0
	s_add_u32 s2, s69, s72
	v_and_b32_e32 v207, 31, v24
	v_or_b32_e32 v2, s2, v207
	v_mov_b64_e32 v[0:1], s[42:43]
	v_bfe_u32 v206, v24, 5, 1
	s_addc_u32 s4, 0, s73
	v_mad_u64_u32 v[0:1], s[2:3], v2, s63, v[0:1]
	v_mov_b32_e32 v2, 0xc0
	v_mad_i32_i24 v1, s4, v2, v1
	v_lshlrev_b32_e32 v184, 4, v206
	v_lshl_add_u64 v[0:1], v[0:1], 0, v[184:185]
	global_load_dwordx4 v[100:103], v[0:1], off
	global_load_dwordx4 v[104:107], v[0:1], off offset:32
	global_load_dwordx4 v[108:111], v[0:1], off offset:64
	global_load_dwordx4 v[112:115], v[0:1], off offset:96
	global_load_dwordx4 v[116:119], v[0:1], off offset:128
	global_load_dwordx4 v[120:123], v[0:1], off offset:160
	v_lshlrev_b32_e32 v186, 4, v24
	v_ashrrev_i32_e32 v187, 31, v186
	v_lshl_add_u64 v[0:1], s[40:41], 0, v[186:187]
	global_load_dwordx4 v[0:3], v[0:1], off
	v_add_u32_e32 v25, 0x200, v24
	s_movk_i32 s2, 0x100
	v_lshlrev_b32_e32 v188, 4, v25
	v_cmp_gt_i32_e64 s[2:3], s2, v24
	v_ashrrev_i32_e32 v189, 31, v188
	s_and_saveexec_b64 s[4:5], s[2:3]
	s_cbranch_execz .LBB0_1097
	v_lshl_add_u64 v[4:5], s[40:41], 0, v[188:189]
	global_load_dwordx4 v[16:19], v[4:5], off

.LBB0_1163:
	s_or_b64 exec, exec, s[2:3]
	s_waitcnt vmcnt(0)
	s_lshl_b64 s[2:3], s[72:73], 11
	v_add_u32_e32 v38, s4, v184
	s_add_u32 s2, s74, s2
	s_addc_u32 s3, s75, s3

	s_lshl_b32 s6, s50, 1
	s_add_u32 s2, s2, s6
	s_addc_u32 s3, s3, 0
	s_waitcnt lgkmcnt(0)
	ds_read_b128 v[32:35], v38 offset:58368
	ds_read_b128 v[36:39], v38 offset:58400
	ds_read_b128 v[40:43], v38 offset:58432
	ds_read_b128 v[44:47], v38 offset:58464
	s_lshl_b32 s6, s86, 7
	s_mov_b32 s98, 0xaaaaaaaa
	s_mov_b32 s99, 0xaaaaaaaa
	v_and_b32_e32 v51, 1, v207
	v_sub_u32_e32 v48, v207, v51
	v_lshlrev_b32_e32 v48, 1, v48
	v_lshl_or_b32 v48, v51, 6, v48
	v_lshl_or_b32 v48, v206, 9, v48
	v_add_u32_e32 v48, s6, v48
	v_lshlrev_b32_e32 v49, 4, v248
	v_add_u32_e32 v49, s6, v49
	v_lshrrev_b32_e32 v50, 3, v248
	v_and_b32_e32 v51, 7, v248
	v_lshlrev_b32_e32 v51, 4, v51
	v_lshl_or_b32 v50, v50, 11, v51
	s_waitcnt lgkmcnt(0)

	v_mul_f32_e32 v52, v16, v32
	v_mul_f32_dpp v53, v16, v32 quad_perm:[1,0,3,2] row_mask:0xf bank_mask:0xf
	v_mul_f32_e32 v54, v0, v32
	v_mul_f32_dpp v55, v0, v32 quad_perm:[1,0,3,2] row_mask:0xf bank_mask:0xf
	v_cndmask_b32_e64 v52, v52, v55, s[98:99]
	v_cndmask_b32_e64 v54, v53, v54, s[98:99]
	v_cvt_pk_bf16_f32 v52, v52, v54
	ds_write_b32 v48, v52
	v_mul_f32_e32 v56, v17, v33
	v_mul_f32_dpp v57, v17, v33 quad_perm:[1,0,3,2] row_mask:0xf bank_mask:0xf
	v_mul_f32_e32 v58, v1, v33
	v_mul_f32_dpp v59, v1, v33 quad_perm:[1,0,3,2] row_mask:0xf bank_mask:0xf
	v_cndmask_b32_e64 v56, v56, v59, s[98:99]
	v_cndmask_b32_e64 v58, v57, v58, s[98:99]
	v_cvt_pk_bf16_f32 v56, v56, v58
	ds_write_b32 v48, v56 offset:128
	v_mul_f32_e32 v60, v18, v34
	v_mul_f32_dpp v61, v18, v34 quad_perm:[1,0,3,2] row_mask:0xf bank_mask:0xf
	v_mul_f32_e32 v62, v2, v34
	v_mul_f32_dpp v63, v2, v34 quad_perm:[1,0,3,2] row_mask:0xf bank_mask:0xf
	v_cndmask_b32_e64 v60, v60, v63, s[98:99]
	v_cndmask_b32_e64 v62, v61, v62, s[98:99]
	v_cvt_pk_bf16_f32 v60, v60, v62
	ds_write_b32 v48, v60 offset:256
	v_mul_f32_e32 v64, v19, v35
	v_mul_f32_dpp v65, v19, v35 quad_perm:[1,0,3,2] row_mask:0xf bank_mask:0xf
	v_mul_f32_e32 v66, v3, v35
	v_mul_f32_dpp v67, v3, v35 quad_perm:[1,0,3,2] row_mask:0xf bank_mask:0xf
	v_cndmask_b32_e64 v64, v64, v67, s[98:99]
	v_cndmask_b32_e64 v66, v65, v66, s[98:99]
	v_cvt_pk_bf16_f32 v64, v64, v66
	ds_write_b32 v48, v64 offset:384
	v_mul_f32_e32 v52, v20, v36
	v_mul_f32_dpp v53, v20, v36 quad_perm:[1,0,3,2] row_mask:0xf bank_mask:0xf
	v_mul_f32_e32 v54, v4, v36
	v_mul_f32_dpp v55, v4, v36 quad_perm:[1,0,3,2] row_mask:0xf bank_mask:0xf
	v_cndmask_b32_e64 v52, v52, v55, s[98:99]
	v_cndmask_b32_e64 v54, v53, v54, s[98:99]
	v_cvt_pk_bf16_f32 v52, v52, v54
	ds_write_b32 v48, v52 offset:1024
	v_mul_f32_e32 v56, v21, v37
	v_mul_f32_dpp v57, v21, v37 quad_perm:[1,0,3,2] row_mask:0xf bank_mask:0xf
	v_mul_f32_e32 v58, v5, v37
	v_mul_f32_dpp v59, v5, v37 quad_perm:[1,0,3,2] row_mask:0xf bank_mask:0xf
	v_cndmask_b32_e64 v56, v56, v59, s[98:99]
	v_cndmask_b32_e64 v58, v57, v58, s[98:99]
	v_cvt_pk_bf16_f32 v56, v56, v58
	ds_write_b32 v48, v56 offset:1152
	v_mul_f32_e32 v60, v22, v38
	v_mul_f32_dpp v61, v22, v38 quad_perm:[1,0,3,2] row_mask:0xf bank_mask:0xf
	v_mul_f32_e32 v62, v6, v38
	v_mul_f32_dpp v63, v6, v38 quad_perm:[1,0,3,2] row_mask:0xf bank_mask:0xf
	v_cndmask_b32_e64 v60, v60, v63, s[98:99]
	v_cndmask_b32_e64 v62, v61, v62, s[98:99]
	v_cvt_pk_bf16_f32 v60, v60, v62
	ds_write_b32 v48, v60 offset:1280
	v_mul_f32_e32 v64, v23, v39
	v_mul_f32_dpp v65, v23, v39 quad_perm:[1,0,3,2] row_mask:0xf bank_mask:0xf
	v_mul_f32_e32 v66, v7, v39
	v_mul_f32_dpp v67, v7, v39 quad_perm:[1,0,3,2] row_mask:0xf bank_mask:0xf
	v_cndmask_b32_e64 v64, v64, v67, s[98:99]
	v_cndmask_b32_e64 v66, v65, v66, s[98:99]
	v_cvt_pk_bf16_f32 v64, v64, v66
	ds_write_b32 v48, v64 offset:1408
	s_waitcnt lgkmcnt(0)
	v_mul_f32_e32 v52, v24, v40
	v_mul_f32_dpp v53, v24, v40 quad_perm:[1,0,3,2] row_mask:0xf bank_mask:0xf
	v_mul_f32_e32 v54, v8, v40
	v_mul_f32_dpp v55, v8, v40 quad_perm:[1,0,3,2] row_mask:0xf bank_mask:0xf
	v_cndmask_b32_e64 v52, v52, v55, s[98:99]
	v_cndmask_b32_e64 v54, v53, v54, s[98:99]
	v_cvt_pk_bf16_f32 v52, v52, v54
	ds_write_b32 v48, v52 offset:2048
	v_mul_f32_e32 v56, v25, v41
	v_mul_f32_dpp v57, v25, v41 quad_perm:[1,0,3,2] row_mask:0xf bank_mask:0xf
	v_mul_f32_e32 v58, v9, v41
	v_mul_f32_dpp v59, v9, v41 quad_perm:[1,0,3,2] row_mask:0xf bank_mask:0xf
	v_cndmask_b32_e64 v56, v56, v59, s[98:99]
	v_cndmask_b32_e64 v58, v57, v58, s[98:99]
	v_cvt_pk_bf16_f32 v56, v56, v58
	ds_write_b32 v48, v56 offset:2176
	v_mul_f32_e32 v60, v26, v42
	v_mul_f32_dpp v61, v26, v42 quad_perm:[1,0,3,2] row_mask:0xf bank_mask:0xf
	v_mul_f32_e32 v62, v10, v42
	v_mul_f32_dpp v63, v10, v42 quad_perm:[1,0,3,2] row_mask:0xf bank_mask:0xf
	v_cndmask_b32_e64 v60, v60, v63, s[98:99]
	v_cndmask_b32_e64 v62, v61, v62, s[98:99]
	v_cvt_pk_bf16_f32 v60, v60, v62
	ds_write_b32 v48, v60 offset:2304
	v_mul_f32_e32 v64, v27, v43
	v_mul_f32_dpp v65, v27, v43 quad_perm:[1,0,3,2] row_mask:0xf bank_mask:0xf
	v_mul_f32_e32 v66, v11, v43
	v_mul_f32_dpp v67, v11, v43 quad_perm:[1,0,3,2] row_mask:0xf bank_mask:0xf
	v_cndmask_b32_e64 v64, v64, v67, s[98:99]
	v_cndmask_b32_e64 v66, v65, v66, s[98:99]
	v_cvt_pk_bf16_f32 v64, v64, v66
	ds_write_b32 v48, v64 offset:2432
	v_mul_f32_e32 v52, v28, v44
	v_mul_f32_dpp v53, v28, v44 quad_perm:[1,0,3,2] row_mask:0xf bank_mask:0xf
	v_mul_f32_e32 v54, v12, v44
	v_mul_f32_dpp v55, v12, v44 quad_perm:[1,0,3,2] row_mask:0xf bank_mask:0xf
	v_cndmask_b32_e64 v52, v52, v55, s[98:99]
	v_cndmask_b32_e64 v54, v53, v54, s[98:99]
	v_cvt_pk_bf16_f32 v52, v52, v54
	ds_write_b32 v48, v52 offset:3072
	v_mul_f32_e32 v56, v29, v45
	v_mul_f32_dpp v57, v29, v45 quad_perm:[1,0,3,2] row_mask:0xf bank_mask:0xf
	v_mul_f32_e32 v58, v13, v45
	v_mul_f32_dpp v59, v13, v45 quad_perm:[1,0,3,2] row_mask:0xf bank_mask:0xf
	v_cndmask_b32_e64 v56, v56, v59, s[98:99]
	v_cndmask_b32_e64 v58, v57, v58, s[98:99]
	v_cvt_pk_bf16_f32 v56, v56, v58
	ds_write_b32 v48, v56 offset:3200
	v_mul_f32_e32 v60, v30, v46
	v_mul_f32_dpp v61, v30, v46 quad_perm:[1,0,3,2] row_mask:0xf bank_mask:0xf
	v_mul_f32_e32 v62, v14, v46
	v_mul_f32_dpp v63, v14, v46 quad_perm:[1,0,3,2] row_mask:0xf bank_mask:0xf
	v_cndmask_b32_e64 v60, v60, v63, s[98:99]
	v_cndmask_b32_e64 v62, v61, v62, s[98:99]
	v_cvt_pk_bf16_f32 v60, v60, v62
	ds_write_b32 v48, v60 offset:3328
	v_mul_f32_e32 v64, v31, v47
	v_mul_f32_dpp v65, v31, v47 quad_perm:[1,0,3,2] row_mask:0xf bank_mask:0xf
	v_mul_f32_e32 v66, v15, v47
	v_mul_f32_dpp v67, v15, v47 quad_perm:[1,0,3,2] row_mask:0xf bank_mask:0xf
	v_cndmask_b32_e64 v64, v64, v67, s[98:99]
	v_cndmask_b32_e64 v66, v65, v66, s[98:99]
	v_cvt_pk_bf16_f32 v64, v64, v66
	ds_write_b32 v48, v64 offset:3456
	s_waitcnt lgkmcnt(0)
	ds_read_b128 v[68:71], v49
	ds_read_b128 v[72:75], v49 offset:1024
	ds_read_b128 v[76:79], v49 offset:2048
	ds_read_b128 v[80:83], v49 offset:3072
	v_add_u32_e32 v51, 0x4000, v50
	v_add_u32_e32 v84, 0x8000, v50
	v_add_u32_e32 v85, 0xc000, v50
	s_waitcnt lgkmcnt(3)
	global_store_dwordx4 v50, v[68:71], s[2:3] offset:1024 sc1
	s_waitcnt lgkmcnt(2)
	global_store_dwordx4 v51, v[72:75], s[2:3] offset:1024 sc1
	s_waitcnt lgkmcnt(1)
	global_store_dwordx4 v84, v[76:79], s[2:3] offset:1024 sc1
	s_waitcnt lgkmcnt(0)
	global_store_dwordx4 v85, v[80:83], s[2:3] offset:1024 sc1
	s_nop 1

	s_barrier
